# K-loop MMA tails: s_setprio 0 and address SALU moved behind the post-MMA barrier so the partner half is released right after the 16th MFMA issues
# baseline (speedup 1.0000x reference)
; #define PG8_STAGE(bufoff, gbase, voff) do { _Pragma("unroll") for (int _i = 0; _i < 2; ++_i) \
;         __builtin_amdgcn_global_load_lds((const unsigned*)((const char*)(gbase) + (voff)[_i]), (LAS unsigned*)(lds + (bufoff) + ldsw + _i * 8192), 16, 0, 0); } while (0)
; #define PG8_LDA(dst, b, h) do { _Pragma("unroll") for (int m = 0; m < 4; ++m) _Pragma("unroll") for (int k = 0; k < 2; ++k) dst[m][k] = *(const LAS bf16x8*)(lds + PG8_SA(b, h) + aoff + m * 2048 + k * 1024); } while (0)
; #define PG8_LDB(dst, b, h) do { _Pragma("unroll") for (int n = 0; n < 2; ++n) _Pragma("unroll") for (int k = 0; k < 2; ++k) dst[n][k] = *(const LAS bf16x8*)(lds + PG8_SB(b, h) + boff + n * 2048 + k * 1024); } while (0)
; #define PG8_MMA(ai, bj, At, Bt) do { __builtin_amdgcn_s_setprio(1); _Pragma("unroll") for (int m = 0; m < 4; ++m) _Pragma("unroll") for (int n = 0; n < 2; ++n) _Pragma("unroll") for (int k = 0; k < 2; ++k) \
;         acc[ai][bj][m][n] = __builtin_amdgcn_mfma_f32_16x16x32_bf16(Bt[n][k], At[m][k], acc[ai][bj][m][n], 0, 0, 0); __builtin_amdgcn_s_setprio(0); } while (0)
; #define PG8_WAIT_L(n) asm volatile("s_waitcnt lgkmcnt(" #n ")" ::: "memory")
; #define PG8_BAR __builtin_amdgcn_s_barrier()
; #define PG8_SCHED __builtin_amdgcn_sched_barrier(0)
; template <class Epi>
; __device__ __forceinline__ void gemm_phase(LAS unsigned char* lds, const Gemm g, const StaticOrder& S, const Epi& E) {
;     ...
;             const bool last = (t == nt - 2);
;             const char* a1 = cA + (size_t)(t + 1) * kstep;
;             const char* a2 = last ? nA : cA + (size_t)(t + 2) * kstep; const char* b2 = last ? nB : cB + (size_t)(t + 2) * kstep;
;             const char* a3 = a2 + kstep; const char* b3 = b2 + kstep;
;             PG8_LDB(B0, 0, 0); PG8_SCHED; PG8_LDA(At, 0, 0); PG8_STAGE(PG8_SA(1, 1), a1 + hstep, voffA);
;             PG8_WAIT_L(8); PG8_BAR; PG8_WAIT_L(0); PG8_MMA(0, 0, At, B0); PG8_BAR; PG8_SCHED;
.LBB0_259:
	ds_read_b128 v[160:163], v148
	ds_read_b128 v[166:169], v148 offset:1024
	ds_read_b128 v[170:173], v148 offset:2048
	ds_read_b128 v[174:177], v148 offset:3072
	s_add_u32 s18, s16, 0xfff80080
	s_addc_u32 s19, s17, -1
	s_cmp_eq_u32 s67, 28
	s_cselect_b32 s21, s9, s19
	s_cselect_b32 s20, s63, s18
	s_cselect_b32 s19, s7, s66
	s_cselect_b32 s18, s64, s65
	v_lshl_add_u64 v[212:213], s[16:17], 0, v[136:137]
	s_add_i32 m0, s35, 0xc000
	ds_read_b128 v[180:183], v149
	ds_read_b128 v[184:187], v149 offset:1024
	ds_read_b128 v[188:191], v149 offset:2048
	ds_read_b128 v[192:195], v149 offset:3072
	ds_read_b128 v[196:199], v149 offset:4096
	ds_read_b128 v[200:203], v149 offset:5120
	ds_read_b128 v[204:207], v149 offset:6144
	ds_read_b128 v[208:211], v149 offset:7168
	global_load_lds_dwordx4 v[212:213], off
	v_lshl_add_u64 v[212:213], s[16:17], 0, v[138:139]
	s_add_i32 m0, s35, 0xe000
	s_nop 0
	global_load_lds_dwordx4 v[212:213], off
	s_waitcnt lgkmcnt(8)
	s_setprio 1
	s_barrier
	s_waitcnt lgkmcnt(0)


; #define PG8_MMA(ai, bj, At, Bt) do { __builtin_amdgcn_s_setprio(1); _Pragma("unroll") for (int m = 0; m < 4; ++m) _Pragma("unroll") for (int n = 0; n < 2; ++n) _Pragma("unroll") for (int k = 0; k < 2; ++k) \
;         acc[ai][bj][m][n] = __builtin_amdgcn_mfma_f32_16x16x32_bf16(Bt[n][k], At[m][k], acc[ai][bj][m][n], 0, 0, 0); __builtin_amdgcn_s_setprio(0); } while (0)
; #define PG8_WAIT_L(n) asm volatile("s_waitcnt lgkmcnt(" #n ")" ::: "memory")
; #define PG8_BAR __builtin_amdgcn_s_barrier()
; #define PG8_SCHED __builtin_amdgcn_sched_barrier(0)
; template <class Epi>
; __device__ __forceinline__ void gemm_phase(LAS unsigned char* lds, const Gemm g, const StaticOrder& S, const Epi& E) {
;     ...
;             PG8_WAIT_L(8); PG8_BAR; PG8_WAIT_L(0); PG8_MMA(0, 0, At, B0); PG8_BAR; PG8_SCHED;
	v_mfma_f32_16x16x32_bf16 v[124:127], v[160:163], v[180:183], v[124:127]
	v_mfma_f32_16x16x32_bf16 v[116:119], v[170:173], v[180:183], v[116:119]
	v_mfma_f32_16x16x32_bf16 v[108:111], v[160:163], v[188:191], v[108:111]
	v_mfma_f32_16x16x32_bf16 v[100:103], v[170:173], v[188:191], v[100:103]
	v_mfma_f32_16x16x32_bf16 v[92:95], v[160:163], v[196:199], v[92:95]
	v_mfma_f32_16x16x32_bf16 v[84:87], v[170:173], v[196:199], v[84:87]
	v_mfma_f32_16x16x32_bf16 v[76:79], v[160:163], v[204:207], v[76:79]
	v_mfma_f32_16x16x32_bf16 v[68:71], v[170:173], v[204:207], v[68:71]
	v_mfma_f32_16x16x32_bf16 v[124:127], v[166:169], v[184:187], v[124:127]
	v_mfma_f32_16x16x32_bf16 v[116:119], v[174:177], v[184:187], v[116:119]
	v_mfma_f32_16x16x32_bf16 v[108:111], v[166:169], v[192:195], v[108:111]
	v_mfma_f32_16x16x32_bf16 v[100:103], v[174:177], v[192:195], v[100:103]
	v_mfma_f32_16x16x32_bf16 v[92:95], v[166:169], v[200:203], v[92:95]
	v_mfma_f32_16x16x32_bf16 v[84:87], v[174:177], v[200:203], v[84:87]
	v_mfma_f32_16x16x32_bf16 v[76:79], v[166:169], v[208:211], v[76:79]
	v_mfma_f32_16x16x32_bf16 v[68:71], v[174:177], v[208:211], v[68:71]
	s_barrier
	s_setprio 0

; #define PG8_STAGE(bufoff, gbase, voff) do { _Pragma("unroll") for (int _i = 0; _i < 2; ++_i) \
;         __builtin_amdgcn_global_load_lds((const unsigned*)((const char*)(gbase) + (voff)[_i]), (LAS unsigned*)(lds + (bufoff) + ldsw + _i * 8192), 16, 0, 0); } while (0)
; #define PG8_LDB(dst, b, h) do { _Pragma("unroll") for (int n = 0; n < 2; ++n) _Pragma("unroll") for (int k = 0; k < 2; ++k) dst[n][k] = *(const LAS bf16x8*)(lds + PG8_SB(b, h) + boff + n * 2048 + k * 1024); } while (0)
; #define PG8_MMA(ai, bj, At, Bt) do { __builtin_amdgcn_s_setprio(1); _Pragma("unroll") for (int m = 0; m < 4; ++m) _Pragma("unroll") for (int n = 0; n < 2; ++n) _Pragma("unroll") for (int k = 0; k < 2; ++k) \
;         acc[ai][bj][m][n] = __builtin_amdgcn_mfma_f32_16x16x32_bf16(Bt[n][k], At[m][k], acc[ai][bj][m][n], 0, 0, 0); __builtin_amdgcn_s_setprio(0); } while (0)
; #define PG8_WAIT_L(n) asm volatile("s_waitcnt lgkmcnt(" #n ")" ::: "memory")
; #define PG8_BAR __builtin_amdgcn_s_barrier()
; template <class Epi>
; __device__ __forceinline__ void gemm_phase(LAS unsigned char* lds, const Gemm g, const StaticOrder& S, const Epi& E) {
;     ...
;             PG8_LDB(B1, 0, 1); PG8_STAGE(PG8_SB(0, 0), b2, voffB);
;             PG8_BAR; PG8_WAIT_L(0); PG8_MMA(0, 1, At, B1); PG8_BAR;
	s_add_i32 s68, s60, s31
	v_lshl_add_u64 v[228:229], s[18:19], 0, v[132:133]
	s_mov_b32 m0, s68
	ds_read_b128 v[212:215], v150
	ds_read_b128 v[216:219], v150 offset:1024
	ds_read_b128 v[220:223], v150 offset:2048
	ds_read_b128 v[224:227], v150 offset:3072
	global_load_lds_dwordx4 v[228:229], off
	v_lshl_add_u64 v[230:231], s[18:19], 0, v[128:129]
	s_add_i32 m0, s68, 0x2000
	s_nop 0
	global_load_lds_dwordx4 v[230:231], off
	s_waitcnt lgkmcnt(0)
	s_setprio 1
	s_barrier


; #define PG8_STAGE(bufoff, gbase, voff) do { _Pragma("unroll") for (int _i = 0; _i < 2; ++_i) \
;         __builtin_amdgcn_global_load_lds((const unsigned*)((const char*)(gbase) + (voff)[_i]), (LAS unsigned*)(lds + (bufoff) + ldsw + _i * 8192), 16, 0, 0); } while (0)
; #define PG8_LDA(dst, b, h) do { _Pragma("unroll") for (int m = 0; m < 4; ++m) _Pragma("unroll") for (int k = 0; k < 2; ++k) dst[m][k] = *(const LAS bf16x8*)(lds + PG8_SA(b, h) + aoff + m * 2048 + k * 1024); } while (0)
; #define PG8_MMA(ai, bj, At, Bt) do { __builtin_amdgcn_s_setprio(1); _Pragma("unroll") for (int m = 0; m < 4; ++m) _Pragma("unroll") for (int n = 0; n < 2; ++n) _Pragma("unroll") for (int k = 0; k < 2; ++k) \
;         acc[ai][bj][m][n] = __builtin_amdgcn_mfma_f32_16x16x32_bf16(Bt[n][k], At[m][k], acc[ai][bj][m][n], 0, 0, 0); __builtin_amdgcn_s_setprio(0); } while (0)
; #define PG8_WAIT_L(n) asm volatile("s_waitcnt lgkmcnt(" #n ")" ::: "memory")
; #define PG8_BAR __builtin_amdgcn_s_barrier()
; #define PG8_SCHED __builtin_amdgcn_sched_barrier(0)
; template <class Epi>
; __device__ __forceinline__ void gemm_phase(LAS unsigned char* lds, const Gemm g, const StaticOrder& S, const Epi& E) {
;     ...
;             PG8_BAR; PG8_WAIT_L(0); PG8_MMA(0, 1, At, B1); PG8_BAR;
;             PG8_LDA(At, 0, 1); PG8_STAGE(PG8_SA(0, 0), a2, voffA);
;             PG8_BAR; PG8_WAIT_L(0); PG8_MMA(1, 0, At, B0); PG8_BAR; PG8_SCHED;
	v_mfma_f32_16x16x32_bf16 v[120:123], v[212:215], v[180:183], v[120:123]
	v_mfma_f32_16x16x32_bf16 v[112:115], v[220:223], v[180:183], v[112:115]
	v_mfma_f32_16x16x32_bf16 v[104:107], v[212:215], v[188:191], v[104:107]
	v_mfma_f32_16x16x32_bf16 v[96:99], v[220:223], v[188:191], v[96:99]
	v_mfma_f32_16x16x32_bf16 v[88:91], v[212:215], v[196:199], v[88:91]
	v_mfma_f32_16x16x32_bf16 v[80:83], v[220:223], v[196:199], v[80:83]
	v_mfma_f32_16x16x32_bf16 v[72:75], v[212:215], v[204:207], v[72:75]
	v_mfma_f32_16x16x32_bf16 v[64:67], v[220:223], v[204:207], v[64:67]
	v_mfma_f32_16x16x32_bf16 v[120:123], v[216:219], v[184:187], v[120:123]
	v_mfma_f32_16x16x32_bf16 v[112:115], v[224:227], v[184:187], v[112:115]
	v_mfma_f32_16x16x32_bf16 v[104:107], v[216:219], v[192:195], v[104:107]
	v_mfma_f32_16x16x32_bf16 v[96:99], v[224:227], v[192:195], v[96:99]
	v_mfma_f32_16x16x32_bf16 v[88:91], v[216:219], v[200:203], v[88:91]
	v_mfma_f32_16x16x32_bf16 v[80:83], v[224:227], v[200:203], v[80:83]
	v_mfma_f32_16x16x32_bf16 v[72:75], v[216:219], v[208:211], v[72:75]
	v_mfma_f32_16x16x32_bf16 v[64:67], v[224:227], v[208:211], v[64:67]
	s_barrier
	s_setprio 0
	s_mov_b32 m0, s35
	v_lshl_add_u64 v[232:233], s[20:21], 0, v[134:135]


; #define PG8_STAGE(bufoff, gbase, voff) do { _Pragma("unroll") for (int _i = 0; _i < 2; ++_i) \
;         __builtin_amdgcn_global_load_lds((const unsigned*)((const char*)(gbase) + (voff)[_i]), (LAS unsigned*)(lds + (bufoff) + ldsw + _i * 8192), 16, 0, 0); } while (0)
; #define PG8_LDA(dst, b, h) do { _Pragma("unroll") for (int m = 0; m < 4; ++m) _Pragma("unroll") for (int k = 0; k < 2; ++k) dst[m][k] = *(const LAS bf16x8*)(lds + PG8_SA(b, h) + aoff + m * 2048 + k * 1024); } while (0)
; #define PG8_MMA(ai, bj, At, Bt) do { __builtin_amdgcn_s_setprio(1); _Pragma("unroll") for (int m = 0; m < 4; ++m) _Pragma("unroll") for (int n = 0; n < 2; ++n) _Pragma("unroll") for (int k = 0; k < 2; ++k) \
;         acc[ai][bj][m][n] = __builtin_amdgcn_mfma_f32_16x16x32_bf16(Bt[n][k], At[m][k], acc[ai][bj][m][n], 0, 0, 0); __builtin_amdgcn_s_setprio(0); } while (0)
; #define PG8_WAIT_L(n) asm volatile("s_waitcnt lgkmcnt(" #n ")" ::: "memory")
; #define PG8_BAR __builtin_amdgcn_s_barrier()
; #define PG8_SCHED __builtin_amdgcn_sched_barrier(0)
; template <class Epi>
; __device__ __forceinline__ void gemm_phase(LAS unsigned char* lds, const Gemm g, const StaticOrder& S, const Epi& E) {
;     ...
;             PG8_LDA(At, 0, 1); PG8_STAGE(PG8_SA(0, 0), a2, voffA);
;             PG8_BAR; PG8_WAIT_L(0); PG8_MMA(1, 0, At, B0); PG8_BAR; PG8_SCHED;
	ds_read_b128 v[180:183], v149 offset:16384
	ds_read_b128 v[184:187], v149 offset:17408
	ds_read_b128 v[188:191], v149 offset:18432
	ds_read_b128 v[192:195], v149 offset:19456
	ds_read_b128 v[196:199], v149 offset:20480
	ds_read_b128 v[200:203], v149 offset:21504
	ds_read_b128 v[204:207], v149 offset:22528
	ds_read_b128 v[208:211], v149 offset:23552
	global_load_lds_dwordx4 v[232:233], off
	v_lshl_add_u64 v[234:235], s[20:21], 0, v[130:131]
	s_mov_b32 m0, s38
	s_nop 0
	global_load_lds_dwordx4 v[234:235], off
	s_waitcnt lgkmcnt(0)
	s_setprio 1
	s_barrier


; #define PG8_MMA(ai, bj, At, Bt) do { __builtin_amdgcn_s_setprio(1); _Pragma("unroll") for (int m = 0; m < 4; ++m) _Pragma("unroll") for (int n = 0; n < 2; ++n) _Pragma("unroll") for (int k = 0; k < 2; ++k) \
;         acc[ai][bj][m][n] = __builtin_amdgcn_mfma_f32_16x16x32_bf16(Bt[n][k], At[m][k], acc[ai][bj][m][n], 0, 0, 0); __builtin_amdgcn_s_setprio(0); } while (0)
; #define PG8_WAIT_L(n) asm volatile("s_waitcnt lgkmcnt(" #n ")" ::: "memory")
; #define PG8_BAR __builtin_amdgcn_s_barrier()
; #define PG8_SCHED __builtin_amdgcn_sched_barrier(0)
; template <class Epi>
; __device__ __forceinline__ void gemm_phase(LAS unsigned char* lds, const Gemm g, const StaticOrder& S, const Epi& E) {
;     ...
;             PG8_BAR; PG8_WAIT_L(0); PG8_MMA(1, 0, At, B0); PG8_BAR; PG8_SCHED;
	v_mfma_f32_16x16x32_bf16 v[60:63], v[160:163], v[180:183], v[60:63]
	v_mfma_f32_16x16x32_bf16 v[52:55], v[170:173], v[180:183], v[52:55]
	v_mfma_f32_16x16x32_bf16 v[44:47], v[160:163], v[188:191], v[44:47]
	v_mfma_f32_16x16x32_bf16 v[36:39], v[170:173], v[188:191], v[36:39]
	v_mfma_f32_16x16x32_bf16 v[28:31], v[160:163], v[196:199], v[28:31]
	v_mfma_f32_16x16x32_bf16 v[20:23], v[170:173], v[196:199], v[20:23]
	v_mfma_f32_16x16x32_bf16 v[12:15], v[160:163], v[204:207], v[12:15]
	v_mfma_f32_16x16x32_bf16 v[4:7], v[170:173], v[204:207], v[4:7]
	v_mfma_f32_16x16x32_bf16 v[60:63], v[166:169], v[184:187], v[60:63]
	v_mfma_f32_16x16x32_bf16 v[52:55], v[174:177], v[184:187], v[52:55]
	v_mfma_f32_16x16x32_bf16 v[44:47], v[166:169], v[192:195], v[44:47]
	v_mfma_f32_16x16x32_bf16 v[36:39], v[174:177], v[192:195], v[36:39]
	v_mfma_f32_16x16x32_bf16 v[28:31], v[166:169], v[200:203], v[28:31]
	v_mfma_f32_16x16x32_bf16 v[20:23], v[174:177], v[200:203], v[20:23]
	v_mfma_f32_16x16x32_bf16 v[12:15], v[166:169], v[208:211], v[12:15]
	v_mfma_f32_16x16x32_bf16 v[4:7], v[174:177], v[208:211], v[4:7]
	s_barrier
	s_setprio 0

; #define PG8_STAGE(bufoff, gbase, voff) do { _Pragma("unroll") for (int _i = 0; _i < 2; ++_i) \
;         __builtin_amdgcn_global_load_lds((const unsigned*)((const char*)(gbase) + (voff)[_i]), (LAS unsigned*)(lds + (bufoff) + ldsw + _i * 8192), 16, 0, 0); } while (0)
; #define PG8_MMA(ai, bj, At, Bt) do { __builtin_amdgcn_s_setprio(1); _Pragma("unroll") for (int m = 0; m < 4; ++m) _Pragma("unroll") for (int n = 0; n < 2; ++n) _Pragma("unroll") for (int k = 0; k < 2; ++k) \
;         acc[ai][bj][m][n] = __builtin_amdgcn_mfma_f32_16x16x32_bf16(Bt[n][k], At[m][k], acc[ai][bj][m][n], 0, 0, 0); __builtin_amdgcn_s_setprio(0); } while (0)
; #define PG8_WAIT_V(n) asm volatile("s_waitcnt vmcnt(" #n ")" ::: "memory")
; #define PG8_BAR __builtin_amdgcn_s_barrier()
; template <class Epi>
; __device__ __forceinline__ void gemm_phase(LAS unsigned char* lds, const Gemm g, const StaticOrder& S, const Epi& E) {
;     ...
;             PG8_STAGE(PG8_SB(0, 1), b2 + hstep, voffB);
;             PG8_WAIT_V(6); PG8_BAR; PG8_MMA(1, 1, At, B1); PG8_BAR;
	s_add_u32 s68, s18, 0x80000
	s_addc_u32 s69, s19, 0
	s_add_i32 s70, s61, s31
	v_lshl_add_u64 v[160:161], s[68:69], 0, v[132:133]
	s_mov_b32 m0, s70
	s_nop 0
	global_load_lds_dwordx4 v[160:161], off
	v_lshl_add_u64 v[160:161], s[68:69], 0, v[128:129]
	s_add_i32 m0, s70, 0x2000
	s_nop 0
	global_load_lds_dwordx4 v[160:161], off
	s_waitcnt vmcnt(6)
	s_setprio 1
	s_barrier

; #define PG8_STAGE(bufoff, gbase, voff) do { _Pragma("unroll") for (int _i = 0; _i < 2; ++_i) \
;         __builtin_amdgcn_global_load_lds((const unsigned*)((const char*)(gbase) + (voff)[_i]), (LAS unsigned*)(lds + (bufoff) + ldsw + _i * 8192), 16, 0, 0); } while (0)
; #define PG8_LDA(dst, b, h) do { _Pragma("unroll") for (int m = 0; m < 4; ++m) _Pragma("unroll") for (int k = 0; k < 2; ++k) dst[m][k] = *(const LAS bf16x8*)(lds + PG8_SA(b, h) + aoff + m * 2048 + k * 1024); } while (0)
; #define PG8_LDB(dst, b, h) do { _Pragma("unroll") for (int n = 0; n < 2; ++n) _Pragma("unroll") for (int k = 0; k < 2; ++k) dst[n][k] = *(const LAS bf16x8*)(lds + PG8_SB(b, h) + boff + n * 2048 + k * 1024); } while (0)
; #define PG8_MMA(ai, bj, At, Bt) do { __builtin_amdgcn_s_setprio(1); _Pragma("unroll") for (int m = 0; m < 4; ++m) _Pragma("unroll") for (int n = 0; n < 2; ++n) _Pragma("unroll") for (int k = 0; k < 2; ++k) \
;         acc[ai][bj][m][n] = __builtin_amdgcn_mfma_f32_16x16x32_bf16(Bt[n][k], At[m][k], acc[ai][bj][m][n], 0, 0, 0); __builtin_amdgcn_s_setprio(0); } while (0)
; #define PG8_WAIT_V(n) asm volatile("s_waitcnt vmcnt(" #n ")" ::: "memory")
; #define PG8_BAR __builtin_amdgcn_s_barrier()
; #define PG8_SCHED __builtin_amdgcn_sched_barrier(0)
; template <class Epi>
; __device__ __forceinline__ void gemm_phase(LAS unsigned char* lds, const Gemm g, const StaticOrder& S, const Epi& E) {
;     ...
;             PG8_WAIT_V(6); PG8_BAR; PG8_MMA(1, 1, At, B1); PG8_BAR;
;             PG8_LDB(B0, 1, 0); PG8_SCHED; PG8_LDA(At, 1, 0); PG8_STAGE(PG8_SA(0, 1), a2 + hstep, voffA);
	v_mfma_f32_16x16x32_bf16 v[56:59], v[212:215], v[180:183], v[56:59]
	v_mfma_f32_16x16x32_bf16 v[48:51], v[220:223], v[180:183], v[48:51]
	v_mfma_f32_16x16x32_bf16 v[40:43], v[212:215], v[188:191], v[40:43]
	v_mfma_f32_16x16x32_bf16 v[32:35], v[220:223], v[188:191], v[32:35]
	v_mfma_f32_16x16x32_bf16 v[24:27], v[212:215], v[196:199], v[24:27]
	v_mfma_f32_16x16x32_bf16 v[16:19], v[220:223], v[196:199], v[16:19]
	v_mfma_f32_16x16x32_bf16 v[8:11], v[212:215], v[204:207], v[8:11]
	v_mfma_f32_16x16x32_bf16 v[0:3], v[220:223], v[204:207], v[0:3]
	v_mfma_f32_16x16x32_bf16 v[56:59], v[216:219], v[184:187], v[56:59]
	v_mfma_f32_16x16x32_bf16 v[48:51], v[224:227], v[184:187], v[48:51]
	v_mfma_f32_16x16x32_bf16 v[40:43], v[216:219], v[192:195], v[40:43]
	v_mfma_f32_16x16x32_bf16 v[32:35], v[224:227], v[192:195], v[32:35]
	v_mfma_f32_16x16x32_bf16 v[24:27], v[216:219], v[200:203], v[24:27]
	v_mfma_f32_16x16x32_bf16 v[16:19], v[224:227], v[200:203], v[16:19]
	v_mfma_f32_16x16x32_bf16 v[8:11], v[216:219], v[208:211], v[8:11]
	v_mfma_f32_16x16x32_bf16 v[0:3], v[224:227], v[208:211], v[0:3]
	s_barrier
	s_setprio 0
	s_add_i32 s68, 0, 0x18000
	v_add_u32_e32 v165, s68, v146


; #define PG8_STAGE(bufoff, gbase, voff) do { _Pragma("unroll") for (int _i = 0; _i < 2; ++_i) \
;         __builtin_amdgcn_global_load_lds((const unsigned*)((const char*)(gbase) + (voff)[_i]), (LAS unsigned*)(lds + (bufoff) + ldsw + _i * 8192), 16, 0, 0); } while (0)
; #define PG8_LDA(dst, b, h) do { _Pragma("unroll") for (int m = 0; m < 4; ++m) _Pragma("unroll") for (int k = 0; k < 2; ++k) dst[m][k] = *(const LAS bf16x8*)(lds + PG8_SA(b, h) + aoff + m * 2048 + k * 1024); } while (0)
; #define PG8_LDB(dst, b, h) do { _Pragma("unroll") for (int n = 0; n < 2; ++n) _Pragma("unroll") for (int k = 0; k < 2; ++k) dst[n][k] = *(const LAS bf16x8*)(lds + PG8_SB(b, h) + boff + n * 2048 + k * 1024); } while (0)
; #define PG8_MMA(ai, bj, At, Bt) do { __builtin_amdgcn_s_setprio(1); _Pragma("unroll") for (int m = 0; m < 4; ++m) _Pragma("unroll") for (int n = 0; n < 2; ++n) _Pragma("unroll") for (int k = 0; k < 2; ++k) \
;         acc[ai][bj][m][n] = __builtin_amdgcn_mfma_f32_16x16x32_bf16(Bt[n][k], At[m][k], acc[ai][bj][m][n], 0, 0, 0); __builtin_amdgcn_s_setprio(0); } while (0)
; #define PG8_WAIT_L(n) asm volatile("s_waitcnt lgkmcnt(" #n ")" ::: "memory")
; #define PG8_BAR __builtin_amdgcn_s_barrier()
; #define PG8_SCHED __builtin_amdgcn_sched_barrier(0)
; template <class Epi>
; __device__ __forceinline__ void gemm_phase(LAS unsigned char* lds, const Gemm g, const StaticOrder& S, const Epi& E) {
;     ...
;             PG8_LDB(B0, 1, 0); PG8_SCHED; PG8_LDA(At, 1, 0); PG8_STAGE(PG8_SA(0, 1), a2 + hstep, voffA);
;             PG8_WAIT_L(8); PG8_BAR; PG8_WAIT_L(0); PG8_MMA(0, 0, At, B0); PG8_BAR; PG8_SCHED;
	ds_read_b128 v[160:163], v165
	ds_read_b128 v[166:169], v165 offset:1024
	ds_read_b128 v[170:173], v165 offset:2048
	ds_read_b128 v[174:177], v165 offset:3072
	s_add_u32 s20, s20, 0x80000
	s_addc_u32 s21, s21, 0
	s_mov_b32 m0, s39
	v_lshl_add_u64 v[212:213], s[20:21], 0, v[134:135]
	ds_read_b128 v[180:183], v149 offset:32768
	ds_read_b128 v[184:187], v149 offset:33792
	ds_read_b128 v[188:191], v149 offset:34816
	ds_read_b128 v[192:195], v149 offset:35840
	ds_read_b128 v[196:199], v149 offset:36864
	ds_read_b128 v[200:203], v149 offset:37888
	ds_read_b128 v[204:207], v149 offset:38912
	ds_read_b128 v[208:211], v149 offset:39936
	global_load_lds_dwordx4 v[212:213], off
	v_lshl_add_u64 v[212:213], s[20:21], 0, v[130:131]
	s_mov_b32 m0, s42
	s_nop 0
	global_load_lds_dwordx4 v[212:213], off
	s_waitcnt lgkmcnt(8)
	s_setprio 1
	s_barrier
	s_waitcnt lgkmcnt(0)


; #define PG8_MMA(ai, bj, At, Bt) do { __builtin_amdgcn_s_setprio(1); _Pragma("unroll") for (int m = 0; m < 4; ++m) _Pragma("unroll") for (int n = 0; n < 2; ++n) _Pragma("unroll") for (int k = 0; k < 2; ++k) \
;         acc[ai][bj][m][n] = __builtin_amdgcn_mfma_f32_16x16x32_bf16(Bt[n][k], At[m][k], acc[ai][bj][m][n], 0, 0, 0); __builtin_amdgcn_s_setprio(0); } while (0)
; #define PG8_WAIT_L(n) asm volatile("s_waitcnt lgkmcnt(" #n ")" ::: "memory")
; #define PG8_BAR __builtin_amdgcn_s_barrier()
; #define PG8_SCHED __builtin_amdgcn_sched_barrier(0)
; template <class Epi>
; __device__ __forceinline__ void gemm_phase(LAS unsigned char* lds, const Gemm g, const StaticOrder& S, const Epi& E) {
;     ...
;             PG8_WAIT_L(8); PG8_BAR; PG8_WAIT_L(0); PG8_MMA(0, 0, At, B0); PG8_BAR; PG8_SCHED;
	v_mfma_f32_16x16x32_bf16 v[124:127], v[160:163], v[180:183], v[124:127]
	v_mfma_f32_16x16x32_bf16 v[116:119], v[170:173], v[180:183], v[116:119]
	v_mfma_f32_16x16x32_bf16 v[108:111], v[160:163], v[188:191], v[108:111]
	v_mfma_f32_16x16x32_bf16 v[100:103], v[170:173], v[188:191], v[100:103]
	v_mfma_f32_16x16x32_bf16 v[92:95], v[160:163], v[196:199], v[92:95]
	v_mfma_f32_16x16x32_bf16 v[84:87], v[170:173], v[196:199], v[84:87]
	v_mfma_f32_16x16x32_bf16 v[76:79], v[160:163], v[204:207], v[76:79]
	v_mfma_f32_16x16x32_bf16 v[68:71], v[170:173], v[204:207], v[68:71]
	v_mfma_f32_16x16x32_bf16 v[124:127], v[166:169], v[184:187], v[124:127]
	v_mfma_f32_16x16x32_bf16 v[116:119], v[174:177], v[184:187], v[116:119]
	v_mfma_f32_16x16x32_bf16 v[108:111], v[166:169], v[192:195], v[108:111]
	v_mfma_f32_16x16x32_bf16 v[100:103], v[174:177], v[192:195], v[100:103]
	v_mfma_f32_16x16x32_bf16 v[92:95], v[166:169], v[200:203], v[92:95]
	v_mfma_f32_16x16x32_bf16 v[84:87], v[174:177], v[200:203], v[84:87]
	v_mfma_f32_16x16x32_bf16 v[76:79], v[166:169], v[208:211], v[76:79]
	v_mfma_f32_16x16x32_bf16 v[68:71], v[174:177], v[208:211], v[68:71]
	s_barrier
	s_setprio 0

; #define PG8_STAGE(bufoff, gbase, voff) do { _Pragma("unroll") for (int _i = 0; _i < 2; ++_i) \
;         __builtin_amdgcn_global_load_lds((const unsigned*)((const char*)(gbase) + (voff)[_i]), (LAS unsigned*)(lds + (bufoff) + ldsw + _i * 8192), 16, 0, 0); } while (0)
; #define PG8_LDB(dst, b, h) do { _Pragma("unroll") for (int n = 0; n < 2; ++n) _Pragma("unroll") for (int k = 0; k < 2; ++k) dst[n][k] = *(const LAS bf16x8*)(lds + PG8_SB(b, h) + boff + n * 2048 + k * 1024); } while (0)
; #define PG8_MMA(ai, bj, At, Bt) do { __builtin_amdgcn_s_setprio(1); _Pragma("unroll") for (int m = 0; m < 4; ++m) _Pragma("unroll") for (int n = 0; n < 2; ++n) _Pragma("unroll") for (int k = 0; k < 2; ++k) \
;         acc[ai][bj][m][n] = __builtin_amdgcn_mfma_f32_16x16x32_bf16(Bt[n][k], At[m][k], acc[ai][bj][m][n], 0, 0, 0); __builtin_amdgcn_s_setprio(0); } while (0)
; #define PG8_WAIT_L(n) asm volatile("s_waitcnt lgkmcnt(" #n ")" ::: "memory")
; #define PG8_BAR __builtin_amdgcn_s_barrier()
; template <class Epi>
; __device__ __forceinline__ void gemm_phase(LAS unsigned char* lds, const Gemm g, const StaticOrder& S, const Epi& E) {
;     ...
;             PG8_LDB(B1, 1, 1); PG8_STAGE(PG8_SB(1, 0), b3, voffB);
;             PG8_BAR; PG8_WAIT_L(0); PG8_MMA(0, 1, At, B1); PG8_BAR;
	s_add_i32 s20, 0, 0x1c000
	s_add_i32 s21, s68, s31
	v_add_u32_e32 v165, s20, v146
	v_lshl_add_u64 v[228:229], v[228:229], 0, s[4:5]
	s_mov_b32 m0, s21
	ds_read_b128 v[212:215], v165
	ds_read_b128 v[216:219], v165 offset:1024
	ds_read_b128 v[220:223], v165 offset:2048
	ds_read_b128 v[224:227], v165 offset:3072
	global_load_lds_dwordx4 v[228:229], off
	v_lshl_add_u64 v[228:229], v[230:231], 0, s[4:5]
	s_add_i32 m0, s21, 0x2000
	s_nop 0
	global_load_lds_dwordx4 v[228:229], off
	s_waitcnt lgkmcnt(0)
	s_setprio 1
	s_barrier


; #define PG8_MMA(ai, bj, At, Bt) do { __builtin_amdgcn_s_setprio(1); _Pragma("unroll") for (int m = 0; m < 4; ++m) _Pragma("unroll") for (int n = 0; n < 2; ++n) _Pragma("unroll") for (int k = 0; k < 2; ++k) \
;         acc[ai][bj][m][n] = __builtin_amdgcn_mfma_f32_16x16x32_bf16(Bt[n][k], At[m][k], acc[ai][bj][m][n], 0, 0, 0); __builtin_amdgcn_s_setprio(0); } while (0)
; #define PG8_WAIT_L(n) asm volatile("s_waitcnt lgkmcnt(" #n ")" ::: "memory")
; #define PG8_BAR __builtin_amdgcn_s_barrier()
; template <class Epi>
; __device__ __forceinline__ void gemm_phase(LAS unsigned char* lds, const Gemm g, const StaticOrder& S, const Epi& E) {
;     ...
;             PG8_BAR; PG8_WAIT_L(0); PG8_MMA(0, 1, At, B1); PG8_BAR;
	v_mfma_f32_16x16x32_bf16 v[120:123], v[212:215], v[180:183], v[120:123]
	v_mfma_f32_16x16x32_bf16 v[112:115], v[220:223], v[180:183], v[112:115]
	v_mfma_f32_16x16x32_bf16 v[104:107], v[212:215], v[188:191], v[104:107]
	v_mfma_f32_16x16x32_bf16 v[96:99], v[220:223], v[188:191], v[96:99]
	v_mfma_f32_16x16x32_bf16 v[88:91], v[212:215], v[196:199], v[88:91]
	v_mfma_f32_16x16x32_bf16 v[80:83], v[220:223], v[196:199], v[80:83]
	v_mfma_f32_16x16x32_bf16 v[72:75], v[212:215], v[204:207], v[72:75]
	v_mfma_f32_16x16x32_bf16 v[64:67], v[220:223], v[204:207], v[64:67]
	v_mfma_f32_16x16x32_bf16 v[120:123], v[216:219], v[184:187], v[120:123]
	v_mfma_f32_16x16x32_bf16 v[112:115], v[224:227], v[184:187], v[112:115]
	v_mfma_f32_16x16x32_bf16 v[104:107], v[216:219], v[192:195], v[104:107]
	v_mfma_f32_16x16x32_bf16 v[96:99], v[224:227], v[192:195], v[96:99]
	v_mfma_f32_16x16x32_bf16 v[88:91], v[216:219], v[200:203], v[88:91]
	v_mfma_f32_16x16x32_bf16 v[80:83], v[224:227], v[200:203], v[80:83]
	v_mfma_f32_16x16x32_bf16 v[72:75], v[216:219], v[208:211], v[72:75]
	v_mfma_f32_16x16x32_bf16 v[64:67], v[224:227], v[208:211], v[64:67]
	s_barrier
	s_setprio 0
	s_mov_b32 m0, s56
	v_lshl_add_u64 v[228:229], v[232:233], 0, s[4:5]


; #define PG8_STAGE(bufoff, gbase, voff) do { _Pragma("unroll") for (int _i = 0; _i < 2; ++_i) \
;         __builtin_amdgcn_global_load_lds((const unsigned*)((const char*)(gbase) + (voff)[_i]), (LAS unsigned*)(lds + (bufoff) + ldsw + _i * 8192), 16, 0, 0); } while (0)
; #define PG8_LDA(dst, b, h) do { _Pragma("unroll") for (int m = 0; m < 4; ++m) _Pragma("unroll") for (int k = 0; k < 2; ++k) dst[m][k] = *(const LAS bf16x8*)(lds + PG8_SA(b, h) + aoff + m * 2048 + k * 1024); } while (0)
; #define PG8_MMA(ai, bj, At, Bt) do { __builtin_amdgcn_s_setprio(1); _Pragma("unroll") for (int m = 0; m < 4; ++m) _Pragma("unroll") for (int n = 0; n < 2; ++n) _Pragma("unroll") for (int k = 0; k < 2; ++k) \
;         acc[ai][bj][m][n] = __builtin_amdgcn_mfma_f32_16x16x32_bf16(Bt[n][k], At[m][k], acc[ai][bj][m][n], 0, 0, 0); __builtin_amdgcn_s_setprio(0); } while (0)
; #define PG8_WAIT_L(n) asm volatile("s_waitcnt lgkmcnt(" #n ")" ::: "memory")
; #define PG8_BAR __builtin_amdgcn_s_barrier()
; #define PG8_SCHED __builtin_amdgcn_sched_barrier(0)
; template <class Epi>
; __device__ __forceinline__ void gemm_phase(LAS unsigned char* lds, const Gemm g, const StaticOrder& S, const Epi& E) {
;     ...
;             PG8_LDA(At, 1, 1); PG8_STAGE(PG8_SA(1, 0), a3, voffA);
;             PG8_BAR; PG8_WAIT_L(0); PG8_MMA(1, 0, At, B0); PG8_BAR; PG8_SCHED;
	ds_read_b128 v[180:183], v149 offset:49152
	ds_read_b128 v[184:187], v149 offset:50176
	ds_read_b128 v[188:191], v149 offset:51200
	ds_read_b128 v[192:195], v149 offset:52224
	ds_read_b128 v[196:199], v149 offset:53248
	ds_read_b128 v[200:203], v149 offset:54272
	ds_read_b128 v[204:207], v149 offset:55296
	ds_read_b128 v[208:211], v149 offset:56320
	global_load_lds_dwordx4 v[228:229], off
	v_lshl_add_u64 v[228:229], v[234:235], 0, s[4:5]
	s_mov_b32 m0, s57
	s_nop 0
	global_load_lds_dwordx4 v[228:229], off
	s_waitcnt lgkmcnt(0)
	s_setprio 1
	s_barrier


; #define PG8_MMA(ai, bj, At, Bt) do { __builtin_amdgcn_s_setprio(1); _Pragma("unroll") for (int m = 0; m < 4; ++m) _Pragma("unroll") for (int n = 0; n < 2; ++n) _Pragma("unroll") for (int k = 0; k < 2; ++k) \
;         acc[ai][bj][m][n] = __builtin_amdgcn_mfma_f32_16x16x32_bf16(Bt[n][k], At[m][k], acc[ai][bj][m][n], 0, 0, 0); __builtin_amdgcn_s_setprio(0); } while (0)
; #define PG8_WAIT_L(n) asm volatile("s_waitcnt lgkmcnt(" #n ")" ::: "memory")
; #define PG8_BAR __builtin_amdgcn_s_barrier()
; #define PG8_SCHED __builtin_amdgcn_sched_barrier(0)
; template <class Epi>
; __device__ __forceinline__ void gemm_phase(LAS unsigned char* lds, const Gemm g, const StaticOrder& S, const Epi& E) {
;     ...
;             PG8_BAR; PG8_WAIT_L(0); PG8_MMA(1, 0, At, B0); PG8_BAR; PG8_SCHED;
	v_mfma_f32_16x16x32_bf16 v[60:63], v[160:163], v[180:183], v[60:63]
	v_mfma_f32_16x16x32_bf16 v[52:55], v[170:173], v[180:183], v[52:55]
	v_mfma_f32_16x16x32_bf16 v[44:47], v[160:163], v[188:191], v[44:47]
	v_mfma_f32_16x16x32_bf16 v[36:39], v[170:173], v[188:191], v[36:39]
	v_mfma_f32_16x16x32_bf16 v[28:31], v[160:163], v[196:199], v[28:31]
	v_mfma_f32_16x16x32_bf16 v[20:23], v[170:173], v[196:199], v[20:23]
	v_mfma_f32_16x16x32_bf16 v[12:15], v[160:163], v[204:207], v[12:15]
	v_mfma_f32_16x16x32_bf16 v[4:7], v[170:173], v[204:207], v[4:7]
	v_mfma_f32_16x16x32_bf16 v[60:63], v[166:169], v[184:187], v[60:63]
	v_mfma_f32_16x16x32_bf16 v[52:55], v[174:177], v[184:187], v[52:55]
	v_mfma_f32_16x16x32_bf16 v[44:47], v[166:169], v[192:195], v[44:47]
	v_mfma_f32_16x16x32_bf16 v[36:39], v[174:177], v[192:195], v[36:39]
	v_mfma_f32_16x16x32_bf16 v[28:31], v[166:169], v[200:203], v[28:31]
	v_mfma_f32_16x16x32_bf16 v[20:23], v[174:177], v[200:203], v[20:23]
	v_mfma_f32_16x16x32_bf16 v[12:15], v[166:169], v[208:211], v[12:15]
	v_mfma_f32_16x16x32_bf16 v[4:7], v[174:177], v[208:211], v[4:7]
	s_barrier
	s_setprio 0

; #define PG8_STAGE(bufoff, gbase, voff) do { _Pragma("unroll") for (int _i = 0; _i < 2; ++_i) \
;         __builtin_amdgcn_global_load_lds((const unsigned*)((const char*)(gbase) + (voff)[_i]), (LAS unsigned*)(lds + (bufoff) + ldsw + _i * 8192), 16, 0, 0); } while (0)
; #define PG8_MMA(ai, bj, At, Bt) do { __builtin_amdgcn_s_setprio(1); _Pragma("unroll") for (int m = 0; m < 4; ++m) _Pragma("unroll") for (int n = 0; n < 2; ++n) _Pragma("unroll") for (int k = 0; k < 2; ++k) \
;         acc[ai][bj][m][n] = __builtin_amdgcn_mfma_f32_16x16x32_bf16(Bt[n][k], At[m][k], acc[ai][bj][m][n], 0, 0, 0); __builtin_amdgcn_s_setprio(0); } while (0)
; #define PG8_WAIT_V(n) asm volatile("s_waitcnt vmcnt(" #n ")" ::: "memory")
; #define PG8_BAR __builtin_amdgcn_s_barrier()
; template <class Epi>
; __device__ __forceinline__ void gemm_phase(LAS unsigned char* lds, const Gemm g, const StaticOrder& S, const Epi& E) {
;     ...
;             PG8_STAGE(PG8_SB(1, 1), b3 + hstep, voffB);
;             PG8_WAIT_V(6); PG8_BAR; PG8_MMA(1, 1, At, B1); PG8_BAR;
	s_add_u32 s18, s18, 0x80080
	s_addc_u32 s19, s19, 0
	s_add_i32 s20, s20, s31
	v_lshl_add_u64 v[160:161], s[18:19], 0, v[132:133]
	s_mov_b32 m0, s20
	s_nop 0
	global_load_lds_dwordx4 v[160:161], off
	v_lshl_add_u64 v[160:161], s[18:19], 0, v[128:129]
	s_add_i32 m0, s20, 0x2000
	s_nop 0
	global_load_lds_dwordx4 v[160:161], off
	s_waitcnt vmcnt(6)
	s_setprio 1
	s_barrier

; #define PG8_MMA(ai, bj, At, Bt) do { __builtin_amdgcn_s_setprio(1); _Pragma("unroll") for (int m = 0; m < 4; ++m) _Pragma("unroll") for (int n = 0; n < 2; ++n) _Pragma("unroll") for (int k = 0; k < 2; ++k) \
;         acc[ai][bj][m][n] = __builtin_amdgcn_mfma_f32_16x16x32_bf16(Bt[n][k], At[m][k], acc[ai][bj][m][n], 0, 0, 0); __builtin_amdgcn_s_setprio(0); } while (0)
; #define PG8_WAIT_V(n) asm volatile("s_waitcnt vmcnt(" #n ")" ::: "memory")
; #define PG8_BAR __builtin_amdgcn_s_barrier()
; template <class Epi>
; __device__ __forceinline__ void gemm_phase(LAS unsigned char* lds, const Gemm g, const StaticOrder& S, const Epi& E) {
;     ...
;         for (int t = 0; t < nt; t += 2) {
;     ...
;             PG8_WAIT_V(6); PG8_BAR; PG8_MMA(1, 1, At, B1); PG8_BAR;
	v_mfma_f32_16x16x32_bf16 v[56:59], v[212:215], v[180:183], v[56:59]
	v_mfma_f32_16x16x32_bf16 v[48:51], v[220:223], v[180:183], v[48:51]
	v_mfma_f32_16x16x32_bf16 v[40:43], v[212:215], v[188:191], v[40:43]
	v_mfma_f32_16x16x32_bf16 v[32:35], v[220:223], v[188:191], v[32:35]
	v_mfma_f32_16x16x32_bf16 v[24:27], v[212:215], v[196:199], v[24:27]
	v_mfma_f32_16x16x32_bf16 v[16:19], v[220:223], v[196:199], v[16:19]
	v_mfma_f32_16x16x32_bf16 v[8:11], v[212:215], v[204:207], v[8:11]
	v_mfma_f32_16x16x32_bf16 v[0:3], v[220:223], v[204:207], v[0:3]
	v_mfma_f32_16x16x32_bf16 v[56:59], v[216:219], v[184:187], v[56:59]
	v_mfma_f32_16x16x32_bf16 v[48:51], v[224:227], v[184:187], v[48:51]
	v_mfma_f32_16x16x32_bf16 v[40:43], v[216:219], v[192:195], v[40:43]
	v_mfma_f32_16x16x32_bf16 v[32:35], v[224:227], v[192:195], v[32:35]
	v_mfma_f32_16x16x32_bf16 v[24:27], v[216:219], v[200:203], v[24:27]
	v_mfma_f32_16x16x32_bf16 v[16:19], v[224:227], v[200:203], v[16:19]
	v_mfma_f32_16x16x32_bf16 v[8:11], v[216:219], v[208:211], v[8:11]
	v_mfma_f32_16x16x32_bf16 v[0:3], v[224:227], v[208:211], v[0:3]
	s_barrier
	s_setprio 0
	s_add_i32 s67, s67, 2
	s_add_u32 s16, s16, 0x100
	s_addc_u32 s17, s17, 0
	s_add_u32 s65, s65, 0x100
	s_addc_u32 s66, s66, 0
	s_cmp_gt_u32 s67, 29


; __device__ __forceinline__ float sigmoidf_(float x) { return __builtin_amdgcn_rcpf(1.0f + fexp(-x)); }
;     __device__ __forceinline__ void operator()(const f32x4 (&acc)[2][2][4][2], const Unit& u, int wr, int wc, int fr, int fq, const Pre& P) const {
;         const int row0 = ROW_X + u.pm * BM + wr * 64 + fr, col0 = u.pn * HALF + wc * 32 + 8 * fq;
; #pragma unroll
;         for (int ai = 0; ai < 2; ++ai)
; #pragma unroll
;             for (int m = 0; m < 4; ++m) { const int r = row0 + ai * HALF + m * 16; const float rs = __builtin_amdgcn_rsqf(P.rs[ai * 4 + m] * (1.0f / DM) + RMS_EPS);
;                 float y[8];
; #pragma unroll
;                 for (int n = 0; n < 2; ++n)
; #pragma unroll
;                     for (int j = 0; j < 4; ++j) { const float a = acc[ai][0][m][n][j] * rs, b = acc[ai][1][m][n][j] * rs; y[n * 4 + j] = a * b * sigmoidf_(a); }
;                 u32x4 w; w.x = cvtpk(y[0], y[1]); w.y = cvtpk(y[2], y[3]); w.z = cvtpk(y[4], y[5]); w.w = cvtpk(y[6], y[7]);
;                 *(u32x4*)(O + (size_t)r * FF + col0) = w; }
	s_cbranch_scc0 .LBB0_259
	s_waitcnt vmcnt(0)
	v_fmamk_f32 v159, v159, 0x3a000000, v151
	v_rsq_f32_e32 v166, v159
	v_lshl_or_b32 v162, s15, 7, v147
	v_lshl_add_u32 v160, s14, 8, v145
	v_ashrrev_i32_e32 v163, 31, v162
	v_pk_mul_f32 v[124:125], v[166:167], v[124:125] op_sel_hi:[0,1]
	v_pk_mul_f32 v[120:121], v[166:167], v[120:121] op_sel_hi:[0,1]
	v_mul_f32_e32 v159, 0xbfb8aa3b, v124
	v_pk_mul_f32 v[120:121], v[124:125], v[120:121]
	v_mul_f32_e32 v124, 0xbfb8aa3b, v125
	v_exp_f32_e32 v159, v159
	v_exp_f32_e32 v124, v124
	v_pk_mul_f32 v[122:123], v[166:167], v[122:123] op_sel_hi:[0,1]
	v_pk_mul_f32 v[116:117], v[166:167], v[116:117] op_sel_hi:[0,1]
	v_add_f32_e32 v159, 1.0, v159
	v_add_f32_e32 v124, 1.0, v124
	v_rcp_f32_e32 v168, v159
	v_rcp_f32_e32 v169, v124
	v_pk_mul_f32 v[124:125], v[166:167], v[126:127] op_sel_hi:[0,1]
	v_pk_mul_f32 v[122:123], v[124:125], v[122:123]
	v_pk_mul_f32 v[112:113], v[166:167], v[112:113] op_sel_hi:[0,1]
	v_pk_mul_f32 v[120:121], v[168:169], v[120:121]
	v_pk_mul_f32 v[112:113], v[116:117], v[112:113]
	v_cvt_pk_bf16_f32 v120, v120, v121
	v_mul_f32_e32 v121, 0xbfb8aa3b, v124
	v_exp_f32_e32 v121, v121
	v_pk_mul_f32 v[114:115], v[166:167], v[114:115] op_sel_hi:[0,1]
	s_and_b64 vcc, vcc, exec
	v_add_f32_e32 v121, 1.0, v121
	v_rcp_f32_e32 v126, v121
	v_mul_f32_e32 v121, 0xbfb8aa3b, v125
	v_exp_f32_e32 v121, v121
	s_nop 0
	v_add_f32_e32 v121, 1.0, v121
	v_rcp_f32_e32 v127, v121
	s_nop 0
	v_pk_mul_f32 v[122:123], v[126:127], v[122:123]
	s_nop 0
	v_cvt_pk_bf16_f32 v121, v122, v123
	v_mul_f32_e32 v122, 0xbfb8aa3b, v116
	v_mul_f32_e32 v116, 0xbfb8aa3b, v117
	v_exp_f32_e32 v122, v122
	v_exp_f32_e32 v116, v116
	v_add_f32_e32 v122, 1.0, v122
	v_add_f32_e32 v116, 1.0, v116
	v_rcp_f32_e32 v122, v122
	v_rcp_f32_e32 v123, v116
	s_nop 0
	v_pk_mul_f32 v[112:113], v[122:123], v[112:113]
	s_nop 0
	v_cvt_pk_bf16_f32 v122, v112, v113
	v_pk_mul_f32 v[112:113], v[166:167], v[118:119] op_sel_hi:[0,1]
	v_mul_f32_e32 v116, 0xbfb8aa3b, v112
	v_pk_mul_f32 v[114:115], v[112:113], v[114:115]
	v_mul_f32_e32 v112, 0xbfb8aa3b, v113
	v_exp_f32_e32 v116, v116
	v_exp_f32_e32 v112, v112
	v_add_f32_e32 v116, 1.0, v116
	v_add_f32_e32 v112, 1.0, v112
	v_rcp_f32_e32 v116, v116
	v_rcp_f32_e32 v117, v112
	s_nop 0
	v_pk_mul_f32 v[112:113], v[116:117], v[114:115]
	s_nop 0
	v_cvt_pk_bf16_f32 v123, v112, v113
	v_mov_b64_e32 v[112:113], s[0:1]
	v_mad_i64_i32 v[116:117], s[14:15], v160, s62, v[112:113]
	v_lshlrev_b64 v[114:115], 1, v[162:163]
	v_lshl_add_u64 v[116:117], v[116:117], 0, v[114:115]
	global_store_dwordx4 v[116:117], v[120:123], off
	v_fmamk_f32 v116, v158, 0x3a000000, v151
	v_rsq_f32_e32 v116, v116
	v_or_b32_e32 v117, 16, v160
	v_pk_mul_f32 v[108:109], v[116:117], v[108:109] op_sel_hi:[0,1]
	v_pk_mul_f32 v[104:105], v[116:117], v[104:105] op_sel_hi:[0,1]
	v_mul_f32_e32 v118, 0xbfb8aa3b, v108
	v_pk_mul_f32 v[104:105], v[108:109], v[104:105]
	v_mul_f32_e32 v108, 0xbfb8aa3b, v109
	v_exp_f32_e32 v118, v118
	v_exp_f32_e32 v108, v108
	v_pk_mul_f32 v[106:107], v[116:117], v[106:107] op_sel_hi:[0,1]
	v_pk_mul_f32 v[100:101], v[116:117], v[100:101] op_sel_hi:[0,1]
	v_add_f32_e32 v118, 1.0, v118
	v_add_f32_e32 v108, 1.0, v108
	v_rcp_f32_e32 v118, v118
	v_rcp_f32_e32 v119, v108
	v_pk_mul_f32 v[108:109], v[116:117], v[110:111] op_sel_hi:[0,1]
	v_pk_mul_f32 v[106:107], v[108:109], v[106:107]
	v_pk_mul_f32 v[96:97], v[116:117], v[96:97] op_sel_hi:[0,1]
	v_pk_mul_f32 v[104:105], v[118:119], v[104:105]
	v_pk_mul_f32 v[96:97], v[100:101], v[96:97]
	v_cvt_pk_bf16_f32 v104, v104, v105
	v_mul_f32_e32 v105, 0xbfb8aa3b, v108
	v_exp_f32_e32 v105, v105
	v_pk_mul_f32 v[98:99], v[116:117], v[98:99] op_sel_hi:[0,1]
	v_add_f32_e32 v105, 1.0, v105
	v_rcp_f32_e32 v110, v105
	v_mul_f32_e32 v105, 0xbfb8aa3b, v109
	v_exp_f32_e32 v105, v105
	s_nop 0
	v_add_f32_e32 v105, 1.0, v105
	v_rcp_f32_e32 v111, v105
	s_nop 0
	v_pk_mul_f32 v[106:107], v[110:111], v[106:107]
	s_nop 0
	v_cvt_pk_bf16_f32 v105, v106, v107
	v_mul_f32_e32 v106, 0xbfb8aa3b, v100
	v_mul_f32_e32 v100, 0xbfb8aa3b, v101
	v_exp_f32_e32 v106, v106
	v_exp_f32_e32 v100, v100
	v_add_f32_e32 v106, 1.0, v106
	v_add_f32_e32 v100, 1.0, v100
	v_rcp_f32_e32 v106, v106
	v_rcp_f32_e32 v107, v100
	s_nop 0
	v_pk_mul_f32 v[96:97], v[106:107], v[96:97]
	s_nop 0
	v_cvt_pk_bf16_f32 v106, v96, v97
	v_pk_mul_f32 v[96:97], v[116:117], v[102:103] op_sel_hi:[0,1]
	v_mul_f32_e32 v100, 0xbfb8aa3b, v96
	v_pk_mul_f32 v[98:99], v[96:97], v[98:99]
	v_mul_f32_e32 v96, 0xbfb8aa3b, v97
	v_exp_f32_e32 v100, v100
	v_exp_f32_e32 v96, v96
	v_add_f32_e32 v100, 1.0, v100
	v_add_f32_e32 v96, 1.0, v96
	v_rcp_f32_e32 v100, v100
	v_rcp_f32_e32 v101, v96
	s_nop 0
	v_pk_mul_f32 v[96:97], v[100:101], v[98:99]
	s_nop 0
	v_cvt_pk_bf16_f32 v107, v96, v97
	v_mad_i64_i32 v[96:97], s[14:15], v117, s62, v[112:113]
	v_lshl_add_u64 v[96:97], v[96:97], 0, v[114:115]
	global_store_dwordx4 v[96:97], v[104:107], off
	v_fmamk_f32 v96, v157, 0x3a000000, v151
	v_rsq_f32_e32 v96, v96
	v_or_b32_e32 v97, 32, v160
	v_pk_mul_f32 v[92:93], v[96:97], v[92:93] op_sel_hi:[0,1]
	v_pk_mul_f32 v[88:89], v[96:97], v[88:89] op_sel_hi:[0,1]
	v_mul_f32_e32 v98, 0xbfb8aa3b, v92
	v_pk_mul_f32 v[88:89], v[92:93], v[88:89]
	v_mul_f32_e32 v92, 0xbfb8aa3b, v93
	v_exp_f32_e32 v98, v98
	v_exp_f32_e32 v92, v92
	v_pk_mul_f32 v[90:91], v[96:97], v[90:91] op_sel_hi:[0,1]
	v_pk_mul_f32 v[84:85], v[96:97], v[84:85] op_sel_hi:[0,1]
	v_add_f32_e32 v98, 1.0, v98
	v_add_f32_e32 v92, 1.0, v92
	v_rcp_f32_e32 v98, v98
	v_rcp_f32_e32 v99, v92
	v_pk_mul_f32 v[92:93], v[96:97], v[94:95] op_sel_hi:[0,1]
	v_pk_mul_f32 v[90:91], v[92:93], v[90:91]
	v_pk_mul_f32 v[80:81], v[96:97], v[80:81] op_sel_hi:[0,1]
; __device__ __forceinline__ float sigmoidf_(float x) { return __builtin_amdgcn_rcpf(1.0f + fexp(-x)); }
;     __device__ __forceinline__ void operator()(const f32x4 (&acc)[2][2][4][2], const Unit& u, int wr, int wc, int fr, int fq, const Pre& P) const {
;     ...
;             for (int m = 0; m < 4; ++m) { const int r = row0 + ai * HALF + m * 16; const float rs = __builtin_amdgcn_rsqf(P.rs[ai * 4 + m] * (1.0f / DM) + RMS_EPS);
;                 float y[8];
; #pragma unroll
;                 for (int n = 0; n < 2; ++n)
; #pragma unroll
;                     for (int j = 0; j < 4; ++j) { const float a = acc[ai][0][m][n][j] * rs, b = acc[ai][1][m][n][j] * rs; y[n * 4 + j] = a * b * sigmoidf_(a); }
;                 u32x4 w; w.x = cvtpk(y[0], y[1]); w.y = cvtpk(y[2], y[3]); w.z = cvtpk(y[4], y[5]); w.w = cvtpk(y[6], y[7]);
;                 *(u32x4*)(O + (size_t)r * FF + col0) = w; }
	v_pk_mul_f32 v[88:89], v[98:99], v[88:89]
	v_pk_mul_f32 v[80:81], v[84:85], v[80:81]
	v_cvt_pk_bf16_f32 v88, v88, v89
	v_mul_f32_e32 v89, 0xbfb8aa3b, v92
	v_exp_f32_e32 v89, v89
	v_pk_mul_f32 v[82:83], v[96:97], v[82:83] op_sel_hi:[0,1]
	v_add_f32_e32 v89, 1.0, v89
	v_rcp_f32_e32 v94, v89
	v_mul_f32_e32 v89, 0xbfb8aa3b, v93
	v_exp_f32_e32 v89, v89
	s_nop 0
	v_add_f32_e32 v89, 1.0, v89
	v_rcp_f32_e32 v95, v89
	s_nop 0
	v_pk_mul_f32 v[90:91], v[94:95], v[90:91]
	s_nop 0
	v_cvt_pk_bf16_f32 v89, v90, v91
	v_mul_f32_e32 v90, 0xbfb8aa3b, v84
	v_mul_f32_e32 v84, 0xbfb8aa3b, v85
	v_exp_f32_e32 v90, v90
	v_exp_f32_e32 v84, v84
	v_add_f32_e32 v90, 1.0, v90
	v_add_f32_e32 v84, 1.0, v84
	v_rcp_f32_e32 v90, v90
	v_rcp_f32_e32 v91, v84
	s_nop 0
	v_pk_mul_f32 v[80:81], v[90:91], v[80:81]
	s_nop 0
	v_cvt_pk_bf16_f32 v90, v80, v81
	v_pk_mul_f32 v[80:81], v[96:97], v[86:87] op_sel_hi:[0,1]
	v_mul_f32_e32 v84, 0xbfb8aa3b, v80
	v_pk_mul_f32 v[82:83], v[80:81], v[82:83]
	v_mul_f32_e32 v80, 0xbfb8aa3b, v81
	v_exp_f32_e32 v84, v84
	v_exp_f32_e32 v80, v80
	v_add_f32_e32 v84, 1.0, v84
	v_add_f32_e32 v80, 1.0, v80
	v_rcp_f32_e32 v84, v84
	v_rcp_f32_e32 v85, v80
	s_nop 0
	v_pk_mul_f32 v[80:81], v[84:85], v[82:83]
	s_nop 0
	v_cvt_pk_bf16_f32 v91, v80, v81
	v_mad_i64_i32 v[80:81], s[14:15], v97, s62, v[112:113]
	v_lshl_add_u64 v[80:81], v[80:81], 0, v[114:115]
	global_store_dwordx4 v[80:81], v[88:91], off
	v_fmamk_f32 v80, v156, 0x3a000000, v151
	v_rsq_f32_e32 v80, v80
	v_or_b32_e32 v81, 48, v160
	v_pk_mul_f32 v[76:77], v[80:81], v[76:77] op_sel_hi:[0,1]
	v_pk_mul_f32 v[72:73], v[80:81], v[72:73] op_sel_hi:[0,1]
	v_mul_f32_e32 v82, 0xbfb8aa3b, v76
	v_pk_mul_f32 v[72:73], v[76:77], v[72:73]
	v_mul_f32_e32 v76, 0xbfb8aa3b, v77
	v_exp_f32_e32 v82, v82
	v_exp_f32_e32 v76, v76
	v_pk_mul_f32 v[74:75], v[80:81], v[74:75] op_sel_hi:[0,1]
	v_pk_mul_f32 v[68:69], v[80:81], v[68:69] op_sel_hi:[0,1]
	v_add_f32_e32 v82, 1.0, v82
	v_add_f32_e32 v76, 1.0, v76
	v_rcp_f32_e32 v82, v82
	v_rcp_f32_e32 v83, v76
	v_pk_mul_f32 v[76:77], v[80:81], v[78:79] op_sel_hi:[0,1]
	v_pk_mul_f32 v[74:75], v[76:77], v[74:75]
	v_pk_mul_f32 v[64:65], v[80:81], v[64:65] op_sel_hi:[0,1]
	v_pk_mul_f32 v[72:73], v[82:83], v[72:73]
	v_pk_mul_f32 v[64:65], v[68:69], v[64:65]
	v_cvt_pk_bf16_f32 v72, v72, v73
	v_mul_f32_e32 v73, 0xbfb8aa3b, v76
	v_exp_f32_e32 v73, v73
	v_pk_mul_f32 v[66:67], v[80:81], v[66:67] op_sel_hi:[0,1]
	v_add_f32_e32 v73, 1.0, v73
	v_rcp_f32_e32 v78, v73
	v_mul_f32_e32 v73, 0xbfb8aa3b, v77
	v_exp_f32_e32 v73, v73
	s_nop 0
	v_add_f32_e32 v73, 1.0, v73
	v_rcp_f32_e32 v79, v73
	s_nop 0
	v_pk_mul_f32 v[74:75], v[78:79], v[74:75]
	s_nop 0
	v_cvt_pk_bf16_f32 v73, v74, v75
	v_mul_f32_e32 v74, 0xbfb8aa3b, v68
	v_mul_f32_e32 v68, 0xbfb8aa3b, v69
	v_exp_f32_e32 v74, v74
	v_exp_f32_e32 v68, v68
	v_add_f32_e32 v74, 1.0, v74
	v_add_f32_e32 v68, 1.0, v68
	v_rcp_f32_e32 v74, v74
	v_rcp_f32_e32 v75, v68
	s_nop 0
	v_pk_mul_f32 v[64:65], v[74:75], v[64:65]
	s_nop 0
	v_cvt_pk_bf16_f32 v74, v64, v65
	v_pk_mul_f32 v[64:65], v[80:81], v[70:71] op_sel_hi:[0,1]
	v_mul_f32_e32 v68, 0xbfb8aa3b, v64
	v_pk_mul_f32 v[66:67], v[64:65], v[66:67]
	v_mul_f32_e32 v64, 0xbfb8aa3b, v65
	v_exp_f32_e32 v68, v68
	v_exp_f32_e32 v64, v64
	v_add_f32_e32 v68, 1.0, v68
	v_add_f32_e32 v64, 1.0, v64
	v_rcp_f32_e32 v68, v68
	v_rcp_f32_e32 v69, v64
	s_nop 0
	v_pk_mul_f32 v[64:65], v[68:69], v[66:67]
	s_nop 0
	v_cvt_pk_bf16_f32 v75, v64, v65
	v_mad_i64_i32 v[64:65], s[14:15], v81, s62, v[112:113]
	v_lshl_add_u64 v[64:65], v[64:65], 0, v[114:115]
	global_store_dwordx4 v[64:65], v[72:75], off
	v_fmamk_f32 v64, v155, 0x3a000000, v151
	v_rsq_f32_e32 v64, v64
	v_add_u32_e32 v65, 0x80, v160
	v_pk_mul_f32 v[60:61], v[64:65], v[60:61] op_sel_hi:[0,1]
	v_pk_mul_f32 v[56:57], v[64:65], v[56:57] op_sel_hi:[0,1]
	v_mul_f32_e32 v66, 0xbfb8aa3b, v60
	v_pk_mul_f32 v[56:57], v[60:61], v[56:57]
	v_mul_f32_e32 v60, 0xbfb8aa3b, v61
	v_exp_f32_e32 v66, v66
	v_exp_f32_e32 v60, v60
	v_pk_mul_f32 v[58:59], v[64:65], v[58:59] op_sel_hi:[0,1]
	v_pk_mul_f32 v[52:53], v[64:65], v[52:53] op_sel_hi:[0,1]
	v_add_f32_e32 v66, 1.0, v66
	v_add_f32_e32 v60, 1.0, v60
	v_rcp_f32_e32 v66, v66
	v_rcp_f32_e32 v67, v60
	v_pk_mul_f32 v[60:61], v[64:65], v[62:63] op_sel_hi:[0,1]
	v_pk_mul_f32 v[58:59], v[60:61], v[58:59]
	v_pk_mul_f32 v[48:49], v[64:65], v[48:49] op_sel_hi:[0,1]
	v_pk_mul_f32 v[56:57], v[66:67], v[56:57]
	v_pk_mul_f32 v[48:49], v[52:53], v[48:49]
	v_cvt_pk_bf16_f32 v56, v56, v57
	v_mul_f32_e32 v57, 0xbfb8aa3b, v60
	v_exp_f32_e32 v57, v57
	v_pk_mul_f32 v[50:51], v[64:65], v[50:51] op_sel_hi:[0,1]
	v_add_f32_e32 v57, 1.0, v57
	v_rcp_f32_e32 v62, v57
	v_mul_f32_e32 v57, 0xbfb8aa3b, v61
	v_exp_f32_e32 v57, v57
	s_nop 0
	v_add_f32_e32 v57, 1.0, v57
	v_rcp_f32_e32 v63, v57
	s_nop 0
	v_pk_mul_f32 v[58:59], v[62:63], v[58:59]
	s_nop 0
	v_cvt_pk_bf16_f32 v57, v58, v59
	v_mul_f32_e32 v58, 0xbfb8aa3b, v52
	v_mul_f32_e32 v52, 0xbfb8aa3b, v53
	v_exp_f32_e32 v58, v58
	v_exp_f32_e32 v52, v52
	v_add_f32_e32 v58, 1.0, v58
	v_add_f32_e32 v52, 1.0, v52
	v_rcp_f32_e32 v58, v58
	v_rcp_f32_e32 v59, v52
	s_nop 0
	v_pk_mul_f32 v[48:49], v[58:59], v[48:49]
	s_nop 0
	v_cvt_pk_bf16_f32 v58, v48, v49
	v_pk_mul_f32 v[48:49], v[64:65], v[54:55] op_sel_hi:[0,1]
	v_mul_f32_e32 v52, 0xbfb8aa3b, v48
	v_pk_mul_f32 v[50:51], v[48:49], v[50:51]
	v_mul_f32_e32 v48, 0xbfb8aa3b, v49
	v_exp_f32_e32 v52, v52
	v_exp_f32_e32 v48, v48
	v_add_f32_e32 v52, 1.0, v52
	v_add_f32_e32 v48, 1.0, v48
	v_rcp_f32_e32 v52, v52
	v_rcp_f32_e32 v53, v48
	s_nop 0
	v_pk_mul_f32 v[48:49], v[52:53], v[50:51]
	s_nop 0
	v_cvt_pk_bf16_f32 v59, v48, v49
	v_mad_i64_i32 v[48:49], s[14:15], v65, s62, v[112:113]
; __device__ __forceinline__ float sigmoidf_(float x) { return __builtin_amdgcn_rcpf(1.0f + fexp(-x)); }
; template <class Epi>
; __device__ __forceinline__ void gemm_phase(LAS unsigned char* lds, const Gemm g, const StaticOrder& S, const Epi& E) {
;     ...
;         if (!has_next) break;
;     __device__ __forceinline__ void operator()(const f32x4 (&acc)[2][2][4][2], const Unit& u, int wr, int wc, int fr, int fq, const Pre& P) const {
;     ...
;             for (int m = 0; m < 4; ++m) { const int r = row0 + ai * HALF + m * 16; const float rs = __builtin_amdgcn_rsqf(P.rs[ai * 4 + m] * (1.0f / DM) + RMS_EPS);
;                 float y[8];
; #pragma unroll
;                 for (int n = 0; n < 2; ++n)
; #pragma unroll
;                     for (int j = 0; j < 4; ++j) { const float a = acc[ai][0][m][n][j] * rs, b = acc[ai][1][m][n][j] * rs; y[n * 4 + j] = a * b * sigmoidf_(a); }
;                 u32x4 w; w.x = cvtpk(y[0], y[1]); w.y = cvtpk(y[2], y[3]); w.z = cvtpk(y[4], y[5]); w.w = cvtpk(y[6], y[7]);
;                 *(u32x4*)(O + (size_t)r * FF + col0) = w; }
	v_lshl_add_u64 v[48:49], v[48:49], 0, v[114:115]
	global_store_dwordx4 v[48:49], v[56:59], off
	v_fmamk_f32 v48, v154, 0x3a000000, v151
	v_rsq_f32_e32 v48, v48
	v_add_u32_e32 v49, 0x90, v160
	v_pk_mul_f32 v[44:45], v[48:49], v[44:45] op_sel_hi:[0,1]
	v_pk_mul_f32 v[40:41], v[48:49], v[40:41] op_sel_hi:[0,1]
	v_mul_f32_e32 v50, 0xbfb8aa3b, v44
	v_pk_mul_f32 v[40:41], v[44:45], v[40:41]
	v_mul_f32_e32 v44, 0xbfb8aa3b, v45
	v_exp_f32_e32 v50, v50
	v_exp_f32_e32 v44, v44
	v_pk_mul_f32 v[42:43], v[48:49], v[42:43] op_sel_hi:[0,1]
	v_pk_mul_f32 v[36:37], v[48:49], v[36:37] op_sel_hi:[0,1]
	v_add_f32_e32 v50, 1.0, v50
	v_add_f32_e32 v44, 1.0, v44
	v_rcp_f32_e32 v50, v50
	v_rcp_f32_e32 v51, v44
	v_pk_mul_f32 v[44:45], v[48:49], v[46:47] op_sel_hi:[0,1]
	v_pk_mul_f32 v[42:43], v[44:45], v[42:43]
	v_pk_mul_f32 v[32:33], v[48:49], v[32:33] op_sel_hi:[0,1]
	v_pk_mul_f32 v[40:41], v[50:51], v[40:41]
	v_pk_mul_f32 v[32:33], v[36:37], v[32:33]
	v_cvt_pk_bf16_f32 v40, v40, v41
	v_mul_f32_e32 v41, 0xbfb8aa3b, v44
	v_exp_f32_e32 v41, v41
	v_pk_mul_f32 v[34:35], v[48:49], v[34:35] op_sel_hi:[0,1]
	v_add_f32_e32 v41, 1.0, v41
	v_rcp_f32_e32 v46, v41
	v_mul_f32_e32 v41, 0xbfb8aa3b, v45
	v_exp_f32_e32 v41, v41
	s_nop 0
	v_add_f32_e32 v41, 1.0, v41
	v_rcp_f32_e32 v47, v41
	s_nop 0
	v_pk_mul_f32 v[42:43], v[46:47], v[42:43]
	s_nop 0
	v_cvt_pk_bf16_f32 v41, v42, v43
	v_mul_f32_e32 v42, 0xbfb8aa3b, v36
	v_mul_f32_e32 v36, 0xbfb8aa3b, v37
	v_exp_f32_e32 v42, v42
	v_exp_f32_e32 v36, v36
	v_add_f32_e32 v42, 1.0, v42
	v_add_f32_e32 v36, 1.0, v36
	v_rcp_f32_e32 v42, v42
	v_rcp_f32_e32 v43, v36
	s_nop 0
	v_pk_mul_f32 v[32:33], v[42:43], v[32:33]
	s_nop 0
	v_cvt_pk_bf16_f32 v42, v32, v33
	v_pk_mul_f32 v[32:33], v[48:49], v[38:39] op_sel_hi:[0,1]
	v_mul_f32_e32 v36, 0xbfb8aa3b, v32
	v_pk_mul_f32 v[34:35], v[32:33], v[34:35]
	v_mul_f32_e32 v32, 0xbfb8aa3b, v33
	v_exp_f32_e32 v36, v36
	v_exp_f32_e32 v32, v32
	v_add_f32_e32 v36, 1.0, v36
	v_add_f32_e32 v32, 1.0, v32
	v_rcp_f32_e32 v36, v36
	v_rcp_f32_e32 v37, v32
	s_nop 0
	v_pk_mul_f32 v[32:33], v[36:37], v[34:35]
	s_nop 0
	v_cvt_pk_bf16_f32 v43, v32, v33
	v_mad_i64_i32 v[32:33], s[14:15], v49, s62, v[112:113]
	v_lshl_add_u64 v[32:33], v[32:33], 0, v[114:115]
	global_store_dwordx4 v[32:33], v[40:43], off
	v_fmamk_f32 v32, v153, 0x3a000000, v151
	v_rsq_f32_e32 v32, v32
	v_add_u32_e32 v33, 0xa0, v160
	v_pk_mul_f32 v[28:29], v[32:33], v[28:29] op_sel_hi:[0,1]
	v_pk_mul_f32 v[24:25], v[32:33], v[24:25] op_sel_hi:[0,1]
	v_mul_f32_e32 v34, 0xbfb8aa3b, v28
	v_pk_mul_f32 v[24:25], v[28:29], v[24:25]
	v_mul_f32_e32 v28, 0xbfb8aa3b, v29
	v_exp_f32_e32 v34, v34
	v_exp_f32_e32 v28, v28
	v_pk_mul_f32 v[26:27], v[32:33], v[26:27] op_sel_hi:[0,1]
	v_pk_mul_f32 v[20:21], v[32:33], v[20:21] op_sel_hi:[0,1]
	v_add_f32_e32 v34, 1.0, v34
	v_add_f32_e32 v28, 1.0, v28
	v_rcp_f32_e32 v34, v34
	v_rcp_f32_e32 v35, v28
	v_pk_mul_f32 v[28:29], v[32:33], v[30:31] op_sel_hi:[0,1]
	v_pk_mul_f32 v[26:27], v[28:29], v[26:27]
	v_pk_mul_f32 v[16:17], v[32:33], v[16:17] op_sel_hi:[0,1]
	v_pk_mul_f32 v[24:25], v[34:35], v[24:25]
	v_pk_mul_f32 v[16:17], v[20:21], v[16:17]
	v_cvt_pk_bf16_f32 v24, v24, v25
	v_mul_f32_e32 v25, 0xbfb8aa3b, v28
	v_exp_f32_e32 v25, v25
	v_pk_mul_f32 v[18:19], v[32:33], v[18:19] op_sel_hi:[0,1]
	v_add_f32_e32 v25, 1.0, v25
	v_rcp_f32_e32 v30, v25
	v_mul_f32_e32 v25, 0xbfb8aa3b, v29
	v_exp_f32_e32 v25, v25
	s_nop 0
	v_add_f32_e32 v25, 1.0, v25
	v_rcp_f32_e32 v31, v25
	s_nop 0
	v_pk_mul_f32 v[26:27], v[30:31], v[26:27]
	s_nop 0
	v_cvt_pk_bf16_f32 v25, v26, v27
	v_mul_f32_e32 v26, 0xbfb8aa3b, v20
	v_mul_f32_e32 v20, 0xbfb8aa3b, v21
	v_exp_f32_e32 v26, v26
	v_exp_f32_e32 v20, v20
	v_add_f32_e32 v26, 1.0, v26
	v_add_f32_e32 v20, 1.0, v20
	v_rcp_f32_e32 v26, v26
	v_rcp_f32_e32 v27, v20
	s_nop 0
	v_pk_mul_f32 v[16:17], v[26:27], v[16:17]
	s_nop 0
	v_cvt_pk_bf16_f32 v26, v16, v17
	v_pk_mul_f32 v[16:17], v[32:33], v[22:23] op_sel_hi:[0,1]
	v_mul_f32_e32 v20, 0xbfb8aa3b, v16
	v_pk_mul_f32 v[18:19], v[16:17], v[18:19]
	v_mul_f32_e32 v16, 0xbfb8aa3b, v17
	v_exp_f32_e32 v20, v20
	v_exp_f32_e32 v16, v16
	v_add_f32_e32 v20, 1.0, v20
	v_add_f32_e32 v16, 1.0, v16
	v_rcp_f32_e32 v20, v20
	v_rcp_f32_e32 v21, v16
	s_nop 0
	v_pk_mul_f32 v[16:17], v[20:21], v[18:19]
	s_nop 0
	v_cvt_pk_bf16_f32 v27, v16, v17
	v_mad_i64_i32 v[16:17], s[14:15], v33, s62, v[112:113]
	v_lshl_add_u64 v[16:17], v[16:17], 0, v[114:115]
	global_store_dwordx4 v[16:17], v[24:27], off
	v_fmamk_f32 v16, v152, 0x3a000000, v151
	v_rsq_f32_e32 v16, v16
	v_add_u32_e32 v17, 0xb0, v160
	v_pk_mul_f32 v[12:13], v[16:17], v[12:13] op_sel_hi:[0,1]
	v_pk_mul_f32 v[8:9], v[16:17], v[8:9] op_sel_hi:[0,1]
	v_mul_f32_e32 v18, 0xbfb8aa3b, v12
	v_pk_mul_f32 v[8:9], v[12:13], v[8:9]
	v_mul_f32_e32 v12, 0xbfb8aa3b, v13
	v_exp_f32_e32 v18, v18
	v_exp_f32_e32 v12, v12
	v_pk_mul_f32 v[10:11], v[16:17], v[10:11] op_sel_hi:[0,1]
	v_pk_mul_f32 v[4:5], v[16:17], v[4:5] op_sel_hi:[0,1]
	v_add_f32_e32 v18, 1.0, v18
	v_add_f32_e32 v12, 1.0, v12
	v_rcp_f32_e32 v18, v18
	v_rcp_f32_e32 v19, v12
	v_pk_mul_f32 v[12:13], v[16:17], v[14:15] op_sel_hi:[0,1]
	v_pk_mul_f32 v[10:11], v[12:13], v[10:11]
	v_pk_mul_f32 v[0:1], v[16:17], v[0:1] op_sel_hi:[0,1]
	v_pk_mul_f32 v[8:9], v[18:19], v[8:9]
	v_pk_mul_f32 v[0:1], v[4:5], v[0:1]
	v_cvt_pk_bf16_f32 v8, v8, v9
	v_mul_f32_e32 v9, 0xbfb8aa3b, v12
	v_exp_f32_e32 v9, v9
	v_pk_mul_f32 v[2:3], v[16:17], v[2:3] op_sel_hi:[0,1]
	v_add_f32_e32 v9, 1.0, v9
	v_rcp_f32_e32 v14, v9
	v_mul_f32_e32 v9, 0xbfb8aa3b, v13
	v_exp_f32_e32 v9, v9
	s_nop 0
	v_add_f32_e32 v9, 1.0, v9
	v_rcp_f32_e32 v15, v9
	s_nop 0
	v_pk_mul_f32 v[10:11], v[14:15], v[10:11]
	s_nop 0
	v_cvt_pk_bf16_f32 v9, v10, v11
	v_mul_f32_e32 v10, 0xbfb8aa3b, v4
	v_mul_f32_e32 v4, 0xbfb8aa3b, v5
	v_exp_f32_e32 v10, v10
	v_exp_f32_e32 v4, v4
	v_add_f32_e32 v10, 1.0, v10
	v_add_f32_e32 v4, 1.0, v4
	v_rcp_f32_e32 v10, v10
	v_rcp_f32_e32 v11, v4
	s_nop 0
	v_pk_mul_f32 v[0:1], v[10:11], v[0:1]
	s_nop 0
	v_cvt_pk_bf16_f32 v10, v0, v1
	v_pk_mul_f32 v[0:1], v[16:17], v[6:7] op_sel_hi:[0,1]
	v_mul_f32_e32 v4, 0xbfb8aa3b, v0
	v_pk_mul_f32 v[2:3], v[0:1], v[2:3]
	v_mul_f32_e32 v0, 0xbfb8aa3b, v1
	v_exp_f32_e32 v4, v4
	v_exp_f32_e32 v0, v0
	v_add_f32_e32 v4, 1.0, v4
	v_add_f32_e32 v0, 1.0, v0
	v_rcp_f32_e32 v4, v4
	v_rcp_f32_e32 v5, v0
	s_nop 0
	v_pk_mul_f32 v[0:1], v[4:5], v[2:3]
	s_nop 0
	v_cvt_pk_bf16_f32 v11, v0, v1
	v_mad_i64_i32 v[0:1], s[14:15], v17, s62, v[112:113]
	v_lshl_add_u64 v[0:1], v[0:1], 0, v[114:115]
	s_mov_b64 s[14:15], -1
	global_store_dwordx4 v[0:1], v[8:11], off
	s_cbranch_vccz .LBB0_255
;     __device__ __forceinline__ Pre pre(const Unit& u, int wr, int fr) const { return load_rs(ssq, u.pm, wr, fr); }
;     __device__ __forceinline__ Pre pre(const Unit& u, int wr, int fr) const { return load_rs(ssq, u.pm, wr, fr); }
;     __device__ __forceinline__ Pre pre(const Unit& u, int wr, int fr) const { return load_rs(ssq, u.pm, wr, fr); }
; template <class Epi>
; __device__ __forceinline__ void gemm_phase(LAS unsigned char* lds, const Gemm g, const StaticOrder& S, const Epi& E) {
;     ...
;         pre = E.pre(nxt, wr, fr);
; __device__ __forceinline__ PreRs load_rs(const float* ssq, int pm, int wr, int fr) { PreRs p;
; #pragma unroll
;     for (int ai = 0; ai < 2; ++ai)
; #pragma unroll
;         for (int m = 0; m < 4; ++m) p.rs[ai * 4 + m] = ssq[ROW_X + pm * BM + ai * HALF + wr * 64 + m * 16 + fr];
;     return p; }
	v_lshl_add_u32 v0, s8, 8, v145
	v_ashrrev_i32_e32 v1, 31, v0
	v_lshl_add_u64 v[2:3], v[0:1], 2, s[2:3]
	v_add_u32_e32 v4, 0x80, v0
	v_add_u32_e32 v6, 0x90, v0
	v_add_u32_e32 v8, 0xa0, v0
	v_add_u32_e32 v0, 0xb0, v0
	v_ashrrev_i32_e32 v5, 31, v4
	v_ashrrev_i32_e32 v7, 31, v6
	v_ashrrev_i32_e32 v9, 31, v8
	v_ashrrev_i32_e32 v1, 31, v0
	v_lshl_add_u64 v[4:5], v[4:5], 2, s[2:3]
	v_lshl_add_u64 v[6:7], v[6:7], 2, s[2:3]
	v_lshl_add_u64 v[8:9], v[8:9], 2, s[2:3]
	v_lshl_add_u64 v[0:1], v[0:1], 2, s[2:3]
	global_load_dword v159, v[2:3], off
	global_load_dword v158, v[2:3], off offset:64
	global_load_dword v157, v[2:3], off offset:128
	global_load_dword v156, v[2:3], off offset:192
	global_load_dword v155, v[4:5], off
	global_load_dword v154, v[6:7], off
	global_load_dword v153, v[8:9], off
	global_load_dword v152, v[0:1], off
	s_mov_b64 s[14:15], 0
	s_branch .LBB0_255

; #define PG8_STAGE(bufoff, gbase, voff) do { _Pragma("unroll") for (int _i = 0; _i < 2; ++_i) \
;         __builtin_amdgcn_global_load_lds((const unsigned*)((const char*)(gbase) + (voff)[_i]), (LAS unsigned*)(lds + (bufoff) + ldsw + _i * 8192), 16, 0, 0); } while (0)
; #define PG8_LDA(dst, b, h) do { _Pragma("unroll") for (int m = 0; m < 4; ++m) _Pragma("unroll") for (int k = 0; k < 2; ++k) dst[m][k] = *(const LAS bf16x8*)(lds + PG8_SA(b, h) + aoff + m * 2048 + k * 1024); } while (0)
; #define PG8_LDB(dst, b, h) do { _Pragma("unroll") for (int n = 0; n < 2; ++n) _Pragma("unroll") for (int k = 0; k < 2; ++k) dst[n][k] = *(const LAS bf16x8*)(lds + PG8_SB(b, h) + boff + n * 2048 + k * 1024); } while (0)
; #define PG8_MMA(ai, bj, At, Bt) do { __builtin_amdgcn_s_setprio(1); _Pragma("unroll") for (int m = 0; m < 4; ++m) _Pragma("unroll") for (int n = 0; n < 2; ++n) _Pragma("unroll") for (int k = 0; k < 2; ++k) \
;         acc[ai][bj][m][n] = __builtin_amdgcn_mfma_f32_16x16x32_bf16(Bt[n][k], At[m][k], acc[ai][bj][m][n], 0, 0, 0); __builtin_amdgcn_s_setprio(0); } while (0)
; #define PG8_WAIT_L(n) asm volatile("s_waitcnt lgkmcnt(" #n ")" ::: "memory")
; #define PG8_BAR __builtin_amdgcn_s_barrier()
; #define PG8_SCHED __builtin_amdgcn_sched_barrier(0)
; template <class Epi>
; __device__ __forceinline__ void gemm_phase(LAS unsigned char* lds, const Gemm g, const StaticOrder& S, const Epi& E) {
;     ...
;             const bool last = (t == nt - 2);
;             const char* a1 = cA + (size_t)(t + 1) * kstep;
;             const char* a2 = last ? nA : cA + (size_t)(t + 2) * kstep; const char* b2 = last ? nB : cB + (size_t)(t + 2) * kstep;
;             const char* a3 = a2 + kstep; const char* b3 = b2 + kstep;
;             PG8_LDB(B0, 0, 0); PG8_SCHED; PG8_LDA(At, 0, 0); PG8_STAGE(PG8_SA(1, 1), a1 + hstep, voffA);
;             PG8_WAIT_L(8); PG8_BAR; PG8_WAIT_L(0); PG8_MMA(0, 0, At, B0); PG8_BAR; PG8_SCHED;
.LBB0_364:
	ds_read_b128 v[128:131], v161
	ds_read_b128 v[132:135], v161 offset:1024
	ds_read_b128 v[152:155], v161 offset:2048
	ds_read_b128 v[166:169], v161 offset:3072
	s_add_u32 s16, s14, 0xffea8080
	s_addc_u32 s17, s15, -1
	s_cmpk_eq_i32 s65, 0x52
	s_cselect_b32 s19, s1, s17
	s_cselect_b32 s18, s0, s16
	s_cselect_b32 s17, s7, s64
	s_cselect_b32 s16, s6, s63
	v_lshl_add_u64 v[156:157], s[14:15], 0, v[144:145]
	s_add_i32 m0, s30, 0xc000
	ds_read_b128 v[170:173], v162
	ds_read_b128 v[174:177], v162 offset:1024
	ds_read_b128 v[180:183], v162 offset:2048
	ds_read_b128 v[184:187], v162 offset:3072
	ds_read_b128 v[188:191], v162 offset:4096
	ds_read_b128 v[192:195], v162 offset:5120
	ds_read_b128 v[196:199], v162 offset:6144
	ds_read_b128 v[200:203], v162 offset:7168
	global_load_lds_dwordx4 v[156:157], off
	v_lshl_add_u64 v[156:157], s[14:15], 0, v[146:147]
	s_add_i32 m0, s30, 0xe000
	s_nop 0
	global_load_lds_dwordx4 v[156:157], off
	s_waitcnt lgkmcnt(8)
	s_setprio 1
	s_barrier
	s_waitcnt lgkmcnt(0)


; #define PG8_MMA(ai, bj, At, Bt) do { __builtin_amdgcn_s_setprio(1); _Pragma("unroll") for (int m = 0; m < 4; ++m) _Pragma("unroll") for (int n = 0; n < 2; ++n) _Pragma("unroll") for (int k = 0; k < 2; ++k) \
;         acc[ai][bj][m][n] = __builtin_amdgcn_mfma_f32_16x16x32_bf16(Bt[n][k], At[m][k], acc[ai][bj][m][n], 0, 0, 0); __builtin_amdgcn_s_setprio(0); } while (0)
; #define PG8_WAIT_L(n) asm volatile("s_waitcnt lgkmcnt(" #n ")" ::: "memory")
; #define PG8_BAR __builtin_amdgcn_s_barrier()
; #define PG8_SCHED __builtin_amdgcn_sched_barrier(0)
; template <class Epi>
; __device__ __forceinline__ void gemm_phase(LAS unsigned char* lds, const Gemm g, const StaticOrder& S, const Epi& E) {
;     ...
;             PG8_WAIT_L(8); PG8_BAR; PG8_WAIT_L(0); PG8_MMA(0, 0, At, B0); PG8_BAR; PG8_SCHED;
	v_mfma_f32_16x16x32_bf16 v[124:127], v[128:131], v[170:173], v[124:127]
	v_mfma_f32_16x16x32_bf16 v[120:123], v[152:155], v[170:173], v[120:123]
	v_mfma_f32_16x16x32_bf16 v[108:111], v[128:131], v[180:183], v[108:111]
	v_mfma_f32_16x16x32_bf16 v[104:107], v[152:155], v[180:183], v[104:107]
	v_mfma_f32_16x16x32_bf16 v[92:95], v[128:131], v[188:191], v[92:95]
	v_mfma_f32_16x16x32_bf16 v[88:91], v[152:155], v[188:191], v[88:91]
	v_mfma_f32_16x16x32_bf16 v[76:79], v[128:131], v[196:199], v[76:79]
	v_mfma_f32_16x16x32_bf16 v[72:75], v[152:155], v[196:199], v[72:75]
	v_mfma_f32_16x16x32_bf16 v[124:127], v[132:135], v[174:177], v[124:127]
	v_mfma_f32_16x16x32_bf16 v[120:123], v[166:169], v[174:177], v[120:123]
	v_mfma_f32_16x16x32_bf16 v[108:111], v[132:135], v[184:187], v[108:111]
	v_mfma_f32_16x16x32_bf16 v[104:107], v[166:169], v[184:187], v[104:107]
	v_mfma_f32_16x16x32_bf16 v[92:95], v[132:135], v[192:195], v[92:95]
	v_mfma_f32_16x16x32_bf16 v[88:91], v[166:169], v[192:195], v[88:91]
	v_mfma_f32_16x16x32_bf16 v[76:79], v[132:135], v[200:203], v[76:79]
	v_mfma_f32_16x16x32_bf16 v[72:75], v[166:169], v[200:203], v[72:75]
	s_barrier
	s_setprio 0

; #define PG8_STAGE(bufoff, gbase, voff) do { _Pragma("unroll") for (int _i = 0; _i < 2; ++_i) \
;         __builtin_amdgcn_global_load_lds((const unsigned*)((const char*)(gbase) + (voff)[_i]), (LAS unsigned*)(lds + (bufoff) + ldsw + _i * 8192), 16, 0, 0); } while (0)
; #define PG8_LDB(dst, b, h) do { _Pragma("unroll") for (int n = 0; n < 2; ++n) _Pragma("unroll") for (int k = 0; k < 2; ++k) dst[n][k] = *(const LAS bf16x8*)(lds + PG8_SB(b, h) + boff + n * 2048 + k * 1024); } while (0)
; #define PG8_MMA(ai, bj, At, Bt) do { __builtin_amdgcn_s_setprio(1); _Pragma("unroll") for (int m = 0; m < 4; ++m) _Pragma("unroll") for (int n = 0; n < 2; ++n) _Pragma("unroll") for (int k = 0; k < 2; ++k) \
;         acc[ai][bj][m][n] = __builtin_amdgcn_mfma_f32_16x16x32_bf16(Bt[n][k], At[m][k], acc[ai][bj][m][n], 0, 0, 0); __builtin_amdgcn_s_setprio(0); } while (0)
; #define PG8_WAIT_L(n) asm volatile("s_waitcnt lgkmcnt(" #n ")" ::: "memory")
; #define PG8_BAR __builtin_amdgcn_s_barrier()
; template <class Epi>
; __device__ __forceinline__ void gemm_phase(LAS unsigned char* lds, const Gemm g, const StaticOrder& S, const Epi& E) {
;     ...
;             PG8_LDB(B1, 0, 1); PG8_STAGE(PG8_SB(0, 0), b2, voffB);
;             PG8_BAR; PG8_WAIT_L(0); PG8_MMA(0, 1, At, B1); PG8_BAR;
	s_add_i32 s66, s57, s21
	v_lshl_add_u64 v[156:157], s[16:17], 0, v[138:139]
	s_mov_b32 m0, s66
	ds_read_b128 v[204:207], v163
	ds_read_b128 v[208:211], v163 offset:1024
	ds_read_b128 v[212:215], v163 offset:2048
	ds_read_b128 v[216:219], v163 offset:3072
	global_load_lds_dwordx4 v[156:157], off
	v_lshl_add_u64 v[220:221], s[16:17], 0, v[142:143]
	s_add_i32 m0, s66, 0x2000
	s_nop 0
	global_load_lds_dwordx4 v[220:221], off
	s_waitcnt lgkmcnt(0)
	s_setprio 1
	s_barrier


; #define PG8_MMA(ai, bj, At, Bt) do { __builtin_amdgcn_s_setprio(1); _Pragma("unroll") for (int m = 0; m < 4; ++m) _Pragma("unroll") for (int n = 0; n < 2; ++n) _Pragma("unroll") for (int k = 0; k < 2; ++k) \
;         acc[ai][bj][m][n] = __builtin_amdgcn_mfma_f32_16x16x32_bf16(Bt[n][k], At[m][k], acc[ai][bj][m][n], 0, 0, 0); __builtin_amdgcn_s_setprio(0); } while (0)
; #define PG8_WAIT_L(n) asm volatile("s_waitcnt lgkmcnt(" #n ")" ::: "memory")
; #define PG8_BAR __builtin_amdgcn_s_barrier()
; template <class Epi>
; __device__ __forceinline__ void gemm_phase(LAS unsigned char* lds, const Gemm g, const StaticOrder& S, const Epi& E) {
;     ...
;             PG8_BAR; PG8_WAIT_L(0); PG8_MMA(0, 1, At, B1); PG8_BAR;
	v_mfma_f32_16x16x32_bf16 v[116:119], v[204:207], v[170:173], v[116:119]
	v_mfma_f32_16x16x32_bf16 v[112:115], v[212:215], v[170:173], v[112:115]
	v_mfma_f32_16x16x32_bf16 v[100:103], v[204:207], v[180:183], v[100:103]
	v_mfma_f32_16x16x32_bf16 v[96:99], v[212:215], v[180:183], v[96:99]
	v_mfma_f32_16x16x32_bf16 v[84:87], v[204:207], v[188:191], v[84:87]
	v_mfma_f32_16x16x32_bf16 v[80:83], v[212:215], v[188:191], v[80:83]
	v_mfma_f32_16x16x32_bf16 v[68:71], v[204:207], v[196:199], v[68:71]
	v_mfma_f32_16x16x32_bf16 v[64:67], v[212:215], v[196:199], v[64:67]
	v_mfma_f32_16x16x32_bf16 v[116:119], v[208:211], v[174:177], v[116:119]
	v_mfma_f32_16x16x32_bf16 v[112:115], v[216:219], v[174:177], v[112:115]
	v_mfma_f32_16x16x32_bf16 v[100:103], v[208:211], v[184:187], v[100:103]
	v_mfma_f32_16x16x32_bf16 v[96:99], v[216:219], v[184:187], v[96:99]
	v_mfma_f32_16x16x32_bf16 v[84:87], v[208:211], v[192:195], v[84:87]
	v_mfma_f32_16x16x32_bf16 v[80:83], v[216:219], v[192:195], v[80:83]
	v_mfma_f32_16x16x32_bf16 v[68:71], v[208:211], v[200:203], v[68:71]
	v_mfma_f32_16x16x32_bf16 v[64:67], v[216:219], v[200:203], v[64:67]
	s_barrier
	s_setprio 0
	s_mov_b32 m0, s30
	v_lshl_add_u64 v[222:223], s[18:19], 0, v[136:137]


; #define PG8_STAGE(bufoff, gbase, voff) do { _Pragma("unroll") for (int _i = 0; _i < 2; ++_i) \
;         __builtin_amdgcn_global_load_lds((const unsigned*)((const char*)(gbase) + (voff)[_i]), (LAS unsigned*)(lds + (bufoff) + ldsw + _i * 8192), 16, 0, 0); } while (0)
; #define PG8_LDA(dst, b, h) do { _Pragma("unroll") for (int m = 0; m < 4; ++m) _Pragma("unroll") for (int k = 0; k < 2; ++k) dst[m][k] = *(const LAS bf16x8*)(lds + PG8_SA(b, h) + aoff + m * 2048 + k * 1024); } while (0)
; #define PG8_MMA(ai, bj, At, Bt) do { __builtin_amdgcn_s_setprio(1); _Pragma("unroll") for (int m = 0; m < 4; ++m) _Pragma("unroll") for (int n = 0; n < 2; ++n) _Pragma("unroll") for (int k = 0; k < 2; ++k) \
;         acc[ai][bj][m][n] = __builtin_amdgcn_mfma_f32_16x16x32_bf16(Bt[n][k], At[m][k], acc[ai][bj][m][n], 0, 0, 0); __builtin_amdgcn_s_setprio(0); } while (0)
; #define PG8_WAIT_L(n) asm volatile("s_waitcnt lgkmcnt(" #n ")" ::: "memory")
; #define PG8_BAR __builtin_amdgcn_s_barrier()
; #define PG8_SCHED __builtin_amdgcn_sched_barrier(0)
; template <class Epi>
; __device__ __forceinline__ void gemm_phase(LAS unsigned char* lds, const Gemm g, const StaticOrder& S, const Epi& E) {
;     ...
;             PG8_LDA(At, 0, 1); PG8_STAGE(PG8_SA(0, 0), a2, voffA);
;             PG8_BAR; PG8_WAIT_L(0); PG8_MMA(1, 0, At, B0); PG8_BAR; PG8_SCHED;
	ds_read_b128 v[170:173], v162 offset:16384
	ds_read_b128 v[174:177], v162 offset:17408
	ds_read_b128 v[180:183], v162 offset:18432
	ds_read_b128 v[184:187], v162 offset:19456
	ds_read_b128 v[188:191], v162 offset:20480
	ds_read_b128 v[192:195], v162 offset:21504
	ds_read_b128 v[196:199], v162 offset:22528
	ds_read_b128 v[200:203], v162 offset:23552
	global_load_lds_dwordx4 v[222:223], off
	v_lshl_add_u64 v[224:225], s[18:19], 0, v[140:141]
	s_mov_b32 m0, s31
	s_nop 0
	global_load_lds_dwordx4 v[224:225], off
	s_waitcnt lgkmcnt(0)
	s_setprio 1
	s_barrier


; #define PG8_MMA(ai, bj, At, Bt) do { __builtin_amdgcn_s_setprio(1); _Pragma("unroll") for (int m = 0; m < 4; ++m) _Pragma("unroll") for (int n = 0; n < 2; ++n) _Pragma("unroll") for (int k = 0; k < 2; ++k) \
;         acc[ai][bj][m][n] = __builtin_amdgcn_mfma_f32_16x16x32_bf16(Bt[n][k], At[m][k], acc[ai][bj][m][n], 0, 0, 0); __builtin_amdgcn_s_setprio(0); } while (0)
; #define PG8_WAIT_L(n) asm volatile("s_waitcnt lgkmcnt(" #n ")" ::: "memory")
; #define PG8_BAR __builtin_amdgcn_s_barrier()
; #define PG8_SCHED __builtin_amdgcn_sched_barrier(0)
; template <class Epi>
; __device__ __forceinline__ void gemm_phase(LAS unsigned char* lds, const Gemm g, const StaticOrder& S, const Epi& E) {
;     ...
;             PG8_BAR; PG8_WAIT_L(0); PG8_MMA(1, 0, At, B0); PG8_BAR; PG8_SCHED;
	v_mfma_f32_16x16x32_bf16 v[60:63], v[128:131], v[170:173], v[60:63]
	v_mfma_f32_16x16x32_bf16 v[56:59], v[152:155], v[170:173], v[56:59]
	v_mfma_f32_16x16x32_bf16 v[44:47], v[128:131], v[180:183], v[44:47]
	v_mfma_f32_16x16x32_bf16 v[40:43], v[152:155], v[180:183], v[40:43]
	v_mfma_f32_16x16x32_bf16 v[28:31], v[128:131], v[188:191], v[28:31]
	v_mfma_f32_16x16x32_bf16 v[24:27], v[152:155], v[188:191], v[24:27]
	v_mfma_f32_16x16x32_bf16 v[12:15], v[128:131], v[196:199], v[12:15]
	v_mfma_f32_16x16x32_bf16 v[8:11], v[152:155], v[196:199], v[8:11]
	v_mfma_f32_16x16x32_bf16 v[60:63], v[132:135], v[174:177], v[60:63]
	v_mfma_f32_16x16x32_bf16 v[56:59], v[166:169], v[174:177], v[56:59]
	v_mfma_f32_16x16x32_bf16 v[44:47], v[132:135], v[184:187], v[44:47]
	v_mfma_f32_16x16x32_bf16 v[40:43], v[166:169], v[184:187], v[40:43]
	v_mfma_f32_16x16x32_bf16 v[28:31], v[132:135], v[192:195], v[28:31]
	v_mfma_f32_16x16x32_bf16 v[24:27], v[166:169], v[192:195], v[24:27]
	v_mfma_f32_16x16x32_bf16 v[12:15], v[132:135], v[200:203], v[12:15]
	v_mfma_f32_16x16x32_bf16 v[8:11], v[166:169], v[200:203], v[8:11]
	s_barrier
	s_setprio 0

; #define PG8_STAGE(bufoff, gbase, voff) do { _Pragma("unroll") for (int _i = 0; _i < 2; ++_i) \
;         __builtin_amdgcn_global_load_lds((const unsigned*)((const char*)(gbase) + (voff)[_i]), (LAS unsigned*)(lds + (bufoff) + ldsw + _i * 8192), 16, 0, 0); } while (0)
; #define PG8_MMA(ai, bj, At, Bt) do { __builtin_amdgcn_s_setprio(1); _Pragma("unroll") for (int m = 0; m < 4; ++m) _Pragma("unroll") for (int n = 0; n < 2; ++n) _Pragma("unroll") for (int k = 0; k < 2; ++k) \
;         acc[ai][bj][m][n] = __builtin_amdgcn_mfma_f32_16x16x32_bf16(Bt[n][k], At[m][k], acc[ai][bj][m][n], 0, 0, 0); __builtin_amdgcn_s_setprio(0); } while (0)
; #define PG8_WAIT_V(n) asm volatile("s_waitcnt vmcnt(" #n ")" ::: "memory")
; #define PG8_BAR __builtin_amdgcn_s_barrier()
; template <class Epi>
; __device__ __forceinline__ void gemm_phase(LAS unsigned char* lds, const Gemm g, const StaticOrder& S, const Epi& E) {
;     ...
;             PG8_STAGE(PG8_SB(0, 1), b2 + hstep, voffB);
;             PG8_WAIT_V(6); PG8_BAR; PG8_MMA(1, 1, At, B1); PG8_BAR;
	s_add_u32 s66, s16, 0x158000
	s_addc_u32 s67, s17, 0
	s_add_i32 s68, s58, s21
	v_lshl_add_u64 v[128:129], s[66:67], 0, v[138:139]
	s_mov_b32 m0, s68
	s_nop 0
	global_load_lds_dwordx4 v[128:129], off
	v_lshl_add_u64 v[128:129], s[66:67], 0, v[142:143]
	s_add_i32 m0, s68, 0x2000
	s_nop 0
	global_load_lds_dwordx4 v[128:129], off
	s_waitcnt vmcnt(6)
	s_setprio 1
	s_barrier

; #define PG8_MMA(ai, bj, At, Bt) do { __builtin_amdgcn_s_setprio(1); _Pragma("unroll") for (int m = 0; m < 4; ++m) _Pragma("unroll") for (int n = 0; n < 2; ++n) _Pragma("unroll") for (int k = 0; k < 2; ++k) \
;         acc[ai][bj][m][n] = __builtin_amdgcn_mfma_f32_16x16x32_bf16(Bt[n][k], At[m][k], acc[ai][bj][m][n], 0, 0, 0); __builtin_amdgcn_s_setprio(0); } while (0)
; #define PG8_WAIT_V(n) asm volatile("s_waitcnt vmcnt(" #n ")" ::: "memory")
; #define PG8_BAR __builtin_amdgcn_s_barrier()
; template <class Epi>
; __device__ __forceinline__ void gemm_phase(LAS unsigned char* lds, const Gemm g, const StaticOrder& S, const Epi& E) {
;     ...
;             PG8_WAIT_V(6); PG8_BAR; PG8_MMA(1, 1, At, B1); PG8_BAR;
	v_mfma_f32_16x16x32_bf16 v[52:55], v[204:207], v[170:173], v[52:55]
	v_mfma_f32_16x16x32_bf16 v[48:51], v[212:215], v[170:173], v[48:51]
	v_mfma_f32_16x16x32_bf16 v[36:39], v[204:207], v[180:183], v[36:39]
	v_mfma_f32_16x16x32_bf16 v[32:35], v[212:215], v[180:183], v[32:35]
	v_mfma_f32_16x16x32_bf16 v[20:23], v[204:207], v[188:191], v[20:23]
	v_mfma_f32_16x16x32_bf16 v[16:19], v[212:215], v[188:191], v[16:19]
	v_mfma_f32_16x16x32_bf16 v[4:7], v[204:207], v[196:199], v[4:7]
	v_mfma_f32_16x16x32_bf16 v[0:3], v[212:215], v[196:199], v[0:3]
	v_mfma_f32_16x16x32_bf16 v[52:55], v[208:211], v[174:177], v[52:55]
	v_mfma_f32_16x16x32_bf16 v[48:51], v[216:219], v[174:177], v[48:51]
	v_mfma_f32_16x16x32_bf16 v[36:39], v[208:211], v[184:187], v[36:39]
	v_mfma_f32_16x16x32_bf16 v[32:35], v[216:219], v[184:187], v[32:35]
	v_mfma_f32_16x16x32_bf16 v[20:23], v[208:211], v[192:195], v[20:23]
	v_mfma_f32_16x16x32_bf16 v[16:19], v[216:219], v[192:195], v[16:19]
	v_mfma_f32_16x16x32_bf16 v[4:7], v[208:211], v[200:203], v[4:7]
	v_mfma_f32_16x16x32_bf16 v[0:3], v[216:219], v[200:203], v[0:3]
	s_barrier
	s_setprio 0
	s_add_i32 s66, 0, 0x18000
	v_add_u32_e32 v166, s66, v158


; #define PG8_STAGE(bufoff, gbase, voff) do { _Pragma("unroll") for (int _i = 0; _i < 2; ++_i) \
;         __builtin_amdgcn_global_load_lds((const unsigned*)((const char*)(gbase) + (voff)[_i]), (LAS unsigned*)(lds + (bufoff) + ldsw + _i * 8192), 16, 0, 0); } while (0)
; #define PG8_LDA(dst, b, h) do { _Pragma("unroll") for (int m = 0; m < 4; ++m) _Pragma("unroll") for (int k = 0; k < 2; ++k) dst[m][k] = *(const LAS bf16x8*)(lds + PG8_SA(b, h) + aoff + m * 2048 + k * 1024); } while (0)
; #define PG8_LDB(dst, b, h) do { _Pragma("unroll") for (int n = 0; n < 2; ++n) _Pragma("unroll") for (int k = 0; k < 2; ++k) dst[n][k] = *(const LAS bf16x8*)(lds + PG8_SB(b, h) + boff + n * 2048 + k * 1024); } while (0)
; #define PG8_MMA(ai, bj, At, Bt) do { __builtin_amdgcn_s_setprio(1); _Pragma("unroll") for (int m = 0; m < 4; ++m) _Pragma("unroll") for (int n = 0; n < 2; ++n) _Pragma("unroll") for (int k = 0; k < 2; ++k) \
;         acc[ai][bj][m][n] = __builtin_amdgcn_mfma_f32_16x16x32_bf16(Bt[n][k], At[m][k], acc[ai][bj][m][n], 0, 0, 0); __builtin_amdgcn_s_setprio(0); } while (0)
; #define PG8_WAIT_L(n) asm volatile("s_waitcnt lgkmcnt(" #n ")" ::: "memory")
; #define PG8_BAR __builtin_amdgcn_s_barrier()
; #define PG8_SCHED __builtin_amdgcn_sched_barrier(0)
; template <class Epi>
; __device__ __forceinline__ void gemm_phase(LAS unsigned char* lds, const Gemm g, const StaticOrder& S, const Epi& E) {
;     ...
;             PG8_LDB(B0, 1, 0); PG8_SCHED; PG8_LDA(At, 1, 0); PG8_STAGE(PG8_SA(0, 1), a2 + hstep, voffA);
;             PG8_WAIT_L(8); PG8_BAR; PG8_WAIT_L(0); PG8_MMA(0, 0, At, B0); PG8_BAR; PG8_SCHED;
	ds_read_b128 v[128:131], v166
	ds_read_b128 v[132:135], v166 offset:1024
	ds_read_b128 v[152:155], v166 offset:2048
	ds_read_b128 v[166:169], v166 offset:3072
	s_add_u32 s18, s18, 0x158000
	s_addc_u32 s19, s19, 0
	s_mov_b32 m0, s33
	v_lshl_add_u64 v[204:205], s[18:19], 0, v[136:137]
	ds_read_b128 v[170:173], v162 offset:32768
	ds_read_b128 v[174:177], v162 offset:33792
	ds_read_b128 v[180:183], v162 offset:34816
	ds_read_b128 v[184:187], v162 offset:35840
	ds_read_b128 v[188:191], v162 offset:36864
	ds_read_b128 v[192:195], v162 offset:37888
	ds_read_b128 v[196:199], v162 offset:38912
	ds_read_b128 v[200:203], v162 offset:39936
	global_load_lds_dwordx4 v[204:205], off
	v_lshl_add_u64 v[204:205], s[18:19], 0, v[140:141]
	s_mov_b32 m0, s34
	s_nop 0
	global_load_lds_dwordx4 v[204:205], off
	s_waitcnt lgkmcnt(8)
	s_setprio 1
	s_barrier
	s_waitcnt lgkmcnt(0)


; #define PG8_MMA(ai, bj, At, Bt) do { __builtin_amdgcn_s_setprio(1); _Pragma("unroll") for (int m = 0; m < 4; ++m) _Pragma("unroll") for (int n = 0; n < 2; ++n) _Pragma("unroll") for (int k = 0; k < 2; ++k) \
;         acc[ai][bj][m][n] = __builtin_amdgcn_mfma_f32_16x16x32_bf16(Bt[n][k], At[m][k], acc[ai][bj][m][n], 0, 0, 0); __builtin_amdgcn_s_setprio(0); } while (0)
; #define PG8_WAIT_L(n) asm volatile("s_waitcnt lgkmcnt(" #n ")" ::: "memory")
; #define PG8_BAR __builtin_amdgcn_s_barrier()
; #define PG8_SCHED __builtin_amdgcn_sched_barrier(0)
; template <class Epi>
; __device__ __forceinline__ void gemm_phase(LAS unsigned char* lds, const Gemm g, const StaticOrder& S, const Epi& E) {
;     ...
;             PG8_WAIT_L(8); PG8_BAR; PG8_WAIT_L(0); PG8_MMA(0, 0, At, B0); PG8_BAR; PG8_SCHED;
	v_mfma_f32_16x16x32_bf16 v[124:127], v[128:131], v[170:173], v[124:127]
	v_mfma_f32_16x16x32_bf16 v[120:123], v[152:155], v[170:173], v[120:123]
	v_mfma_f32_16x16x32_bf16 v[108:111], v[128:131], v[180:183], v[108:111]
	v_mfma_f32_16x16x32_bf16 v[104:107], v[152:155], v[180:183], v[104:107]
	v_mfma_f32_16x16x32_bf16 v[92:95], v[128:131], v[188:191], v[92:95]
	v_mfma_f32_16x16x32_bf16 v[88:91], v[152:155], v[188:191], v[88:91]
	v_mfma_f32_16x16x32_bf16 v[76:79], v[128:131], v[196:199], v[76:79]
	v_mfma_f32_16x16x32_bf16 v[72:75], v[152:155], v[196:199], v[72:75]
	v_mfma_f32_16x16x32_bf16 v[124:127], v[132:135], v[174:177], v[124:127]
	v_mfma_f32_16x16x32_bf16 v[120:123], v[166:169], v[174:177], v[120:123]
	v_mfma_f32_16x16x32_bf16 v[108:111], v[132:135], v[184:187], v[108:111]
	v_mfma_f32_16x16x32_bf16 v[104:107], v[166:169], v[184:187], v[104:107]
	v_mfma_f32_16x16x32_bf16 v[92:95], v[132:135], v[192:195], v[92:95]
	v_mfma_f32_16x16x32_bf16 v[88:91], v[166:169], v[192:195], v[88:91]
	v_mfma_f32_16x16x32_bf16 v[76:79], v[132:135], v[200:203], v[76:79]
	v_mfma_f32_16x16x32_bf16 v[72:75], v[166:169], v[200:203], v[72:75]
	s_barrier
	s_setprio 0

; #define PG8_STAGE(bufoff, gbase, voff) do { _Pragma("unroll") for (int _i = 0; _i < 2; ++_i) \
;         __builtin_amdgcn_global_load_lds((const unsigned*)((const char*)(gbase) + (voff)[_i]), (LAS unsigned*)(lds + (bufoff) + ldsw + _i * 8192), 16, 0, 0); } while (0)
; #define PG8_LDB(dst, b, h) do { _Pragma("unroll") for (int n = 0; n < 2; ++n) _Pragma("unroll") for (int k = 0; k < 2; ++k) dst[n][k] = *(const LAS bf16x8*)(lds + PG8_SB(b, h) + boff + n * 2048 + k * 1024); } while (0)
; #define PG8_MMA(ai, bj, At, Bt) do { __builtin_amdgcn_s_setprio(1); _Pragma("unroll") for (int m = 0; m < 4; ++m) _Pragma("unroll") for (int n = 0; n < 2; ++n) _Pragma("unroll") for (int k = 0; k < 2; ++k) \
;         acc[ai][bj][m][n] = __builtin_amdgcn_mfma_f32_16x16x32_bf16(Bt[n][k], At[m][k], acc[ai][bj][m][n], 0, 0, 0); __builtin_amdgcn_s_setprio(0); } while (0)
; #define PG8_WAIT_L(n) asm volatile("s_waitcnt lgkmcnt(" #n ")" ::: "memory")
; #define PG8_BAR __builtin_amdgcn_s_barrier()
; template <class Epi>
; __device__ __forceinline__ void gemm_phase(LAS unsigned char* lds, const Gemm g, const StaticOrder& S, const Epi& E) {
;     ...
;             PG8_LDB(B1, 1, 1); PG8_STAGE(PG8_SB(1, 0), b3, voffB);
;             PG8_BAR; PG8_WAIT_L(0); PG8_MMA(0, 1, At, B1); PG8_BAR;
	s_add_i32 s18, 0, 0x1c000
	s_add_i32 s19, s66, s21
	v_add_u32_e32 v179, s18, v158
	v_lshl_add_u64 v[156:157], v[156:157], 0, s[12:13]
	s_mov_b32 m0, s19
	ds_read_b128 v[204:207], v179
	ds_read_b128 v[208:211], v179 offset:1024
	ds_read_b128 v[212:215], v179 offset:2048
	ds_read_b128 v[216:219], v179 offset:3072
	global_load_lds_dwordx4 v[156:157], off
	v_lshl_add_u64 v[156:157], v[220:221], 0, s[12:13]
	s_add_i32 m0, s19, 0x2000
	s_nop 0
	global_load_lds_dwordx4 v[156:157], off
	s_waitcnt lgkmcnt(0)
	s_setprio 1
	s_barrier


; #define PG8_MMA(ai, bj, At, Bt) do { __builtin_amdgcn_s_setprio(1); _Pragma("unroll") for (int m = 0; m < 4; ++m) _Pragma("unroll") for (int n = 0; n < 2; ++n) _Pragma("unroll") for (int k = 0; k < 2; ++k) \
;         acc[ai][bj][m][n] = __builtin_amdgcn_mfma_f32_16x16x32_bf16(Bt[n][k], At[m][k], acc[ai][bj][m][n], 0, 0, 0); __builtin_amdgcn_s_setprio(0); } while (0)
; #define PG8_WAIT_L(n) asm volatile("s_waitcnt lgkmcnt(" #n ")" ::: "memory")
; #define PG8_BAR __builtin_amdgcn_s_barrier()
; template <class Epi>
; __device__ __forceinline__ void gemm_phase(LAS unsigned char* lds, const Gemm g, const StaticOrder& S, const Epi& E) {
;     ...
;             PG8_BAR; PG8_WAIT_L(0); PG8_MMA(0, 1, At, B1); PG8_BAR;
	v_mfma_f32_16x16x32_bf16 v[116:119], v[204:207], v[170:173], v[116:119]
	v_mfma_f32_16x16x32_bf16 v[112:115], v[212:215], v[170:173], v[112:115]
	v_mfma_f32_16x16x32_bf16 v[100:103], v[204:207], v[180:183], v[100:103]
	v_mfma_f32_16x16x32_bf16 v[96:99], v[212:215], v[180:183], v[96:99]
	v_mfma_f32_16x16x32_bf16 v[84:87], v[204:207], v[188:191], v[84:87]
	v_mfma_f32_16x16x32_bf16 v[80:83], v[212:215], v[188:191], v[80:83]
	v_mfma_f32_16x16x32_bf16 v[68:71], v[204:207], v[196:199], v[68:71]
	v_mfma_f32_16x16x32_bf16 v[64:67], v[212:215], v[196:199], v[64:67]
	v_mfma_f32_16x16x32_bf16 v[116:119], v[208:211], v[174:177], v[116:119]
	v_mfma_f32_16x16x32_bf16 v[112:115], v[216:219], v[174:177], v[112:115]
	v_mfma_f32_16x16x32_bf16 v[100:103], v[208:211], v[184:187], v[100:103]
	v_mfma_f32_16x16x32_bf16 v[96:99], v[216:219], v[184:187], v[96:99]
	v_mfma_f32_16x16x32_bf16 v[84:87], v[208:211], v[192:195], v[84:87]
	v_mfma_f32_16x16x32_bf16 v[80:83], v[216:219], v[192:195], v[80:83]
	v_mfma_f32_16x16x32_bf16 v[68:71], v[208:211], v[200:203], v[68:71]
	v_mfma_f32_16x16x32_bf16 v[64:67], v[216:219], v[200:203], v[64:67]
	s_barrier
	s_setprio 0
	s_mov_b32 m0, s38
	v_lshl_add_u64 v[156:157], v[222:223], 0, s[12:13]


; #define PG8_STAGE(bufoff, gbase, voff) do { _Pragma("unroll") for (int _i = 0; _i < 2; ++_i) \
;         __builtin_amdgcn_global_load_lds((const unsigned*)((const char*)(gbase) + (voff)[_i]), (LAS unsigned*)(lds + (bufoff) + ldsw + _i * 8192), 16, 0, 0); } while (0)
; #define PG8_LDA(dst, b, h) do { _Pragma("unroll") for (int m = 0; m < 4; ++m) _Pragma("unroll") for (int k = 0; k < 2; ++k) dst[m][k] = *(const LAS bf16x8*)(lds + PG8_SA(b, h) + aoff + m * 2048 + k * 1024); } while (0)
; #define PG8_MMA(ai, bj, At, Bt) do { __builtin_amdgcn_s_setprio(1); _Pragma("unroll") for (int m = 0; m < 4; ++m) _Pragma("unroll") for (int n = 0; n < 2; ++n) _Pragma("unroll") for (int k = 0; k < 2; ++k) \
;         acc[ai][bj][m][n] = __builtin_amdgcn_mfma_f32_16x16x32_bf16(Bt[n][k], At[m][k], acc[ai][bj][m][n], 0, 0, 0); __builtin_amdgcn_s_setprio(0); } while (0)
; #define PG8_WAIT_L(n) asm volatile("s_waitcnt lgkmcnt(" #n ")" ::: "memory")
; #define PG8_BAR __builtin_amdgcn_s_barrier()
; #define PG8_SCHED __builtin_amdgcn_sched_barrier(0)
; template <class Epi>
; __device__ __forceinline__ void gemm_phase(LAS unsigned char* lds, const Gemm g, const StaticOrder& S, const Epi& E) {
;     ...
;             PG8_LDA(At, 1, 1); PG8_STAGE(PG8_SA(1, 0), a3, voffA);
;             PG8_BAR; PG8_WAIT_L(0); PG8_MMA(1, 0, At, B0); PG8_BAR; PG8_SCHED;
	ds_read_b128 v[170:173], v162 offset:49152
	ds_read_b128 v[174:177], v162 offset:50176
	ds_read_b128 v[180:183], v162 offset:51200
	ds_read_b128 v[184:187], v162 offset:52224
	ds_read_b128 v[188:191], v162 offset:53248
	ds_read_b128 v[192:195], v162 offset:54272
	ds_read_b128 v[196:199], v162 offset:55296
	ds_read_b128 v[200:203], v162 offset:56320
	global_load_lds_dwordx4 v[156:157], off
	v_lshl_add_u64 v[156:157], v[224:225], 0, s[12:13]
	s_mov_b32 m0, s39
	s_nop 0
	global_load_lds_dwordx4 v[156:157], off
	s_waitcnt lgkmcnt(0)
	s_setprio 1
	s_barrier


; #define PG8_MMA(ai, bj, At, Bt) do { __builtin_amdgcn_s_setprio(1); _Pragma("unroll") for (int m = 0; m < 4; ++m) _Pragma("unroll") for (int n = 0; n < 2; ++n) _Pragma("unroll") for (int k = 0; k < 2; ++k) \
;         acc[ai][bj][m][n] = __builtin_amdgcn_mfma_f32_16x16x32_bf16(Bt[n][k], At[m][k], acc[ai][bj][m][n], 0, 0, 0); __builtin_amdgcn_s_setprio(0); } while (0)
; #define PG8_WAIT_L(n) asm volatile("s_waitcnt lgkmcnt(" #n ")" ::: "memory")
; #define PG8_BAR __builtin_amdgcn_s_barrier()
; #define PG8_SCHED __builtin_amdgcn_sched_barrier(0)
; template <class Epi>
; __device__ __forceinline__ void gemm_phase(LAS unsigned char* lds, const Gemm g, const StaticOrder& S, const Epi& E) {
;     ...
;             PG8_BAR; PG8_WAIT_L(0); PG8_MMA(1, 0, At, B0); PG8_BAR; PG8_SCHED;
	v_mfma_f32_16x16x32_bf16 v[60:63], v[128:131], v[170:173], v[60:63]
	v_mfma_f32_16x16x32_bf16 v[56:59], v[152:155], v[170:173], v[56:59]
	v_mfma_f32_16x16x32_bf16 v[44:47], v[128:131], v[180:183], v[44:47]
	v_mfma_f32_16x16x32_bf16 v[40:43], v[152:155], v[180:183], v[40:43]
	v_mfma_f32_16x16x32_bf16 v[28:31], v[128:131], v[188:191], v[28:31]
	v_mfma_f32_16x16x32_bf16 v[24:27], v[152:155], v[188:191], v[24:27]
	v_mfma_f32_16x16x32_bf16 v[12:15], v[128:131], v[196:199], v[12:15]
	v_mfma_f32_16x16x32_bf16 v[8:11], v[152:155], v[196:199], v[8:11]
	v_mfma_f32_16x16x32_bf16 v[60:63], v[132:135], v[174:177], v[60:63]
	v_mfma_f32_16x16x32_bf16 v[56:59], v[166:169], v[174:177], v[56:59]
	v_mfma_f32_16x16x32_bf16 v[44:47], v[132:135], v[184:187], v[44:47]
	v_mfma_f32_16x16x32_bf16 v[40:43], v[166:169], v[184:187], v[40:43]
	v_mfma_f32_16x16x32_bf16 v[28:31], v[132:135], v[192:195], v[28:31]
	v_mfma_f32_16x16x32_bf16 v[24:27], v[166:169], v[192:195], v[24:27]
	v_mfma_f32_16x16x32_bf16 v[12:15], v[132:135], v[200:203], v[12:15]
	v_mfma_f32_16x16x32_bf16 v[8:11], v[166:169], v[200:203], v[8:11]
	s_barrier
	s_setprio 0

; #define PG8_STAGE(bufoff, gbase, voff) do { _Pragma("unroll") for (int _i = 0; _i < 2; ++_i) \
;         __builtin_amdgcn_global_load_lds((const unsigned*)((const char*)(gbase) + (voff)[_i]), (LAS unsigned*)(lds + (bufoff) + ldsw + _i * 8192), 16, 0, 0); } while (0)
; #define PG8_MMA(ai, bj, At, Bt) do { __builtin_amdgcn_s_setprio(1); _Pragma("unroll") for (int m = 0; m < 4; ++m) _Pragma("unroll") for (int n = 0; n < 2; ++n) _Pragma("unroll") for (int k = 0; k < 2; ++k) \
;         acc[ai][bj][m][n] = __builtin_amdgcn_mfma_f32_16x16x32_bf16(Bt[n][k], At[m][k], acc[ai][bj][m][n], 0, 0, 0); __builtin_amdgcn_s_setprio(0); } while (0)
; #define PG8_WAIT_V(n) asm volatile("s_waitcnt vmcnt(" #n ")" ::: "memory")
; #define PG8_BAR __builtin_amdgcn_s_barrier()
; template <class Epi>
; __device__ __forceinline__ void gemm_phase(LAS unsigned char* lds, const Gemm g, const StaticOrder& S, const Epi& E) {
;     ...
;             PG8_STAGE(PG8_SB(1, 1), b3 + hstep, voffB);
;             PG8_WAIT_V(6); PG8_BAR; PG8_MMA(1, 1, At, B1); PG8_BAR;
	s_add_u32 s16, s16, 0x158080
	s_addc_u32 s17, s17, 0
	s_add_i32 s18, s18, s21
	v_lshl_add_u64 v[128:129], s[16:17], 0, v[138:139]
	s_mov_b32 m0, s18
	s_nop 0
	global_load_lds_dwordx4 v[128:129], off
	v_lshl_add_u64 v[128:129], s[16:17], 0, v[142:143]
	s_add_i32 m0, s18, 0x2000
	s_nop 0
	global_load_lds_dwordx4 v[128:129], off
	s_waitcnt vmcnt(6)
	s_setprio 1
	s_barrier

; #define PG8_MMA(ai, bj, At, Bt) do { __builtin_amdgcn_s_setprio(1); _Pragma("unroll") for (int m = 0; m < 4; ++m) _Pragma("unroll") for (int n = 0; n < 2; ++n) _Pragma("unroll") for (int k = 0; k < 2; ++k) \
;         acc[ai][bj][m][n] = __builtin_amdgcn_mfma_f32_16x16x32_bf16(Bt[n][k], At[m][k], acc[ai][bj][m][n], 0, 0, 0); __builtin_amdgcn_s_setprio(0); } while (0)
; #define PG8_WAIT_V(n) asm volatile("s_waitcnt vmcnt(" #n ")" ::: "memory")
; #define PG8_BAR __builtin_amdgcn_s_barrier()
; template <class Epi>
; __device__ __forceinline__ void gemm_phase(LAS unsigned char* lds, const Gemm g, const StaticOrder& S, const Epi& E) {
;     ...
;         for (int t = 0; t < nt; t += 2) {
;     ...
;             PG8_WAIT_V(6); PG8_BAR; PG8_MMA(1, 1, At, B1); PG8_BAR;
	v_mfma_f32_16x16x32_bf16 v[52:55], v[204:207], v[170:173], v[52:55]
	v_mfma_f32_16x16x32_bf16 v[48:51], v[212:215], v[170:173], v[48:51]
	v_mfma_f32_16x16x32_bf16 v[36:39], v[204:207], v[180:183], v[36:39]
	v_mfma_f32_16x16x32_bf16 v[32:35], v[212:215], v[180:183], v[32:35]
	v_mfma_f32_16x16x32_bf16 v[20:23], v[204:207], v[188:191], v[20:23]
	v_mfma_f32_16x16x32_bf16 v[16:19], v[212:215], v[188:191], v[16:19]
	v_mfma_f32_16x16x32_bf16 v[4:7], v[204:207], v[196:199], v[4:7]
	v_mfma_f32_16x16x32_bf16 v[0:3], v[212:215], v[196:199], v[0:3]
	v_mfma_f32_16x16x32_bf16 v[52:55], v[208:211], v[174:177], v[52:55]
	v_mfma_f32_16x16x32_bf16 v[48:51], v[216:219], v[174:177], v[48:51]
	v_mfma_f32_16x16x32_bf16 v[36:39], v[208:211], v[184:187], v[36:39]
	v_mfma_f32_16x16x32_bf16 v[32:35], v[216:219], v[184:187], v[32:35]
	v_mfma_f32_16x16x32_bf16 v[20:23], v[208:211], v[192:195], v[20:23]
	v_mfma_f32_16x16x32_bf16 v[16:19], v[216:219], v[192:195], v[16:19]
	v_mfma_f32_16x16x32_bf16 v[4:7], v[208:211], v[200:203], v[4:7]
	v_mfma_f32_16x16x32_bf16 v[0:3], v[216:219], v[200:203], v[0:3]
	s_barrier
	s_setprio 0
	s_add_i32 s65, s65, 2
	s_add_u32 s14, s14, 0x100
	s_addc_u32 s15, s15, 0
	s_add_u32 s63, s63, 0x100
	s_addc_u32 s64, s64, 0
	s_cmpk_gt_u32 s65, 0x53


; __device__ __forceinline__ float bflo(unsigned w) { return __uint_as_float(w << 16); }
; __device__ __forceinline__ float bfhi(unsigned w) { return __uint_as_float(w & 0xffff0000u); }
; #define ER_LOAD(g_, set_) do { const size_t off_ = (size_t)(row0 + ((g_) >> 2) * HALF + ((g_) & 3) * 16) * DM + col0; \
;         hv[set_][0] = *(const u32x4*)(HB + off_); hv[set_][1] = *(const u32x4*)(HB + off_ + HALF); } while (0)
;     __device__ __forceinline__ void operator()(const f32x4 (&acc)[2][2][4][2], const Unit& u, int wr, int wc, int fr, int fq, const Pre&) const {
;         const int row0 = ROW_X + u.pm * BM + wr * 64 + fr, col0 = u.pn * BM + wc * 32 + 8 * fq;
;         u32x4 hv[2][2]; float sprev = 0.f;
;     ...
;         ER_LOAD(0, 0);
; #pragma unroll
;         for (int g = 0; g < 8; ++g) { const int ai = g >> 2, m = g & 3; const int r = row0 + ai * HALF + m * 16; const size_t off = (size_t)r * DM + col0; float s = 0.f;
;             if (g + 1 < 8) ER_LOAD(g + 1, (g + 1) & 1);
; #pragma unroll
;             for (int bj = 0; bj < 2; ++bj) { const u32x4 w = hv[g & 1][bj];
;                 const f32x4 h0 = {bflo(w.x), bfhi(w.x), bflo(w.y), bfhi(w.y)}, h1 = {bflo(w.z), bfhi(w.z), bflo(w.w), bfhi(w.w)};
;                 const f32x4 o0 = h0 + acc[ai][bj][m][0] * alpha, o1 = h1 + acc[ai][bj][m][1] * alpha;
;                 if (FINAL) { float* op = OUT + (size_t)(r - ROW_X) * DM + col0 + bj * HALF; *(f32x4*)op = o0; *(f32x4*)(op + 4) = o1; }
;                 else { u32x4 q; q.x = cvtpk(o0[0], o0[1]); q.y = cvtpk(o0[2], o0[3]); q.z = cvtpk(o1[0], o1[1]); q.w = cvtpk(o1[2], o1[3]); *(u32x4*)(HB + off + bj * HALF) = q;
;                        s += ((o0[0] * o0[0] + o0[1] * o0[1]) + (o0[2] * o0[2] + o0[3] * o0[3])) + ((o1[0] * o1[0] + o1[1] * o1[1]) + (o1[2] * o1[2] + o1[3] * o1[3])); } }
;             if (!FINAL) { if (g > 0) { float t = sprev; t += __shfl_xor(t, 16); t += __shfl_xor(t, 32);
;                     if (fq == 0) __hip_atomic_fetch_add(ssq_out + row0 + ((g - 1) >> 2) * HALF + ((g - 1) & 3) * 16, t, __ATOMIC_RELAXED, __HIP_MEMORY_SCOPE_AGENT); }
;                 sprev = s; } }
	s_cbranch_scc0 .LBB0_364
	v_lshl_add_u32 v154, s61, 8, v159
	v_lshl_or_b32 v152, s62, 8, v160
	v_ashrrev_i32_e32 v155, 31, v154
	v_ashrrev_i32_e32 v153, 31, v152
	v_lshlrev_b64 v[128:129], 12, v[154:155]
	v_lshl_add_u64 v[128:129], s[8:9], 0, v[128:129]
	v_lshlrev_b64 v[130:131], 1, v[152:153]
	v_lshl_add_u64 v[184:185], v[128:129], 0, v[130:131]
	v_or_b32_e32 v128, 16, v154
	v_ashrrev_i32_e32 v129, 31, v128
	global_load_dwordx4 v[166:169], v[184:185], off
	global_load_dwordx4 v[170:173], v[184:185], off offset:256
	v_lshlrev_b64 v[128:129], 12, v[128:129]
	v_lshl_add_u64 v[128:129], s[8:9], 0, v[128:129]
	v_lshl_add_u64 v[186:187], v[128:129], 0, v[130:131]
	global_load_dwordx4 v[174:177], v[186:187], off
	global_load_dwordx4 v[180:183], v[186:187], off offset:256
	v_or_b32_e32 v128, 32, v154
	v_ashrrev_i32_e32 v129, 31, v128
	v_lshlrev_b64 v[128:129], 12, v[128:129]
	v_lshl_add_u64 v[128:129], s[8:9], 0, v[128:129]
	v_lshl_add_u64 v[156:157], v[128:129], 0, v[130:131]
	global_load_dwordx4 v[132:135], v[156:157], off
	global_load_dwordx4 v[128:131], v[156:157], off offset:256
	s_waitcnt vmcnt(0)
	v_lshlrev_b32_e32 v188, 16, v166
	v_and_b32_e32 v189, 0xffff0000, v166
	v_lshlrev_b32_e32 v166, 16, v167
	v_and_b32_e32 v167, 0xffff0000, v167
	v_lshlrev_b32_e32 v190, 16, v168
	v_and_b32_e32 v191, 0xffff0000, v168
	v_lshlrev_b32_e32 v168, 16, v169
	v_and_b32_e32 v169, 0xffff0000, v169
	v_lshlrev_b32_e32 v192, 16, v170
	v_and_b32_e32 v193, 0xffff0000, v170
	v_lshlrev_b32_e32 v170, 16, v171
	v_and_b32_e32 v171, 0xffff0000, v171
	v_lshlrev_b32_e32 v194, 16, v172
	v_and_b32_e32 v195, 0xffff0000, v172
	v_lshlrev_b32_e32 v172, 16, v173
	v_and_b32_e32 v173, 0xffff0000, v173
	v_pk_fma_f32 v[126:127], v[126:127], 0.5, v[166:167] op_sel_hi:[1,0,1]
	v_pk_fma_f32 v[124:125], v[124:125], 0.5, v[188:189] op_sel_hi:[1,0,1]
	v_pk_fma_f32 v[122:123], v[122:123], 0.5, v[168:169] op_sel_hi:[1,0,1]
	v_pk_fma_f32 v[166:167], v[120:121], 0.5, v[190:191] op_sel_hi:[1,0,1]
	v_pk_fma_f32 v[168:169], v[118:119], 0.5, v[170:171] op_sel_hi:[1,0,1]
	v_pk_fma_f32 v[170:171], v[116:117], 0.5, v[192:193] op_sel_hi:[1,0,1]
	v_pk_fma_f32 v[172:173], v[114:115], 0.5, v[172:173] op_sel_hi:[1,0,1]
	v_pk_fma_f32 v[188:189], v[112:113], 0.5, v[194:195] op_sel_hi:[1,0,1]
	v_cvt_pk_bf16_f32 v114, v124, v125
	v_cvt_pk_bf16_f32 v115, v126, v127
	v_cvt_pk_bf16_f32 v116, v166, v167
	v_cvt_pk_bf16_f32 v117, v122, v123
	v_mul_f32_e32 v125, v125, v125
	v_mul_f32_e32 v127, v127, v127
	v_mul_f32_e32 v167, v167, v167
	v_mul_f32_e32 v123, v123, v123
	v_cvt_pk_bf16_f32 v118, v170, v171
	v_cvt_pk_bf16_f32 v119, v168, v169
	v_cvt_pk_bf16_f32 v121, v172, v173
	v_mul_f32_e32 v171, v171, v171
	v_mul_f32_e32 v169, v169, v169
	v_mul_f32_e32 v179, v189, v189
	v_mul_f32_e32 v173, v173, v173
	v_lshlrev_b32_e32 v112, 16, v174
	v_and_b32_e32 v113, 0xffff0000, v174
	v_lshlrev_b32_e32 v190, 16, v176
	v_and_b32_e32 v191, 0xffff0000, v176
	v_lshlrev_b32_e32 v176, 16, v177
	v_and_b32_e32 v177, 0xffff0000, v177
	v_fmac_f32_e32 v125, v124, v124
	v_fmac_f32_e32 v127, v126, v126
	v_fmac_f32_e32 v167, v166, v166
	v_fmac_f32_e32 v123, v122, v122
	v_fmac_f32_e32 v171, v170, v170
	v_fmac_f32_e32 v169, v168, v168
	v_fmac_f32_e32 v179, v188, v188
	v_fmac_f32_e32 v173, v172, v172
	v_lshlrev_b32_e32 v174, 16, v175
	v_and_b32_e32 v175, 0xffff0000, v175
	v_pk_fma_f32 v[112:113], v[108:109], 0.5, v[112:113] op_sel_hi:[1,0,1]
	v_pk_fma_f32 v[108:109], v[106:107], 0.5, v[176:177] op_sel_hi:[1,0,1]
	global_store_dwordx4 v[184:185], v[114:117], off
	v_add_f32_e32 v106, v125, v127
	v_add_f32_e32 v107, v167, v123
	v_add_f32_e32 v114, v171, v169
	v_add_f32_e32 v115, v179, v173
	v_pk_fma_f32 v[110:111], v[110:111], 0.5, v[174:175] op_sel_hi:[1,0,1]
	v_add_f32_e32 v106, v106, v107
	v_add_f32_e32 v107, v114, v115
	v_pk_fma_f32 v[114:115], v[104:105], 0.5, v[190:191] op_sel_hi:[1,0,1]
	v_add_f32_e32 v125, v106, v107
	v_cvt_pk_bf16_f32 v104, v112, v113
	v_cvt_pk_bf16_f32 v105, v110, v111
	v_cvt_pk_bf16_f32 v106, v114, v115
	v_cvt_pk_bf16_f32 v107, v108, v109
	v_cvt_pk_bf16_f32 v120, v188, v189
	global_store_dwordx4 v[186:187], v[104:107], off
	global_store_dwordx4 v[184:185], v[118:121], off offset:256
	v_lshlrev_b32_e32 v122, 16, v182
	v_lshlrev_b32_e32 v104, 16, v180
	v_and_b32_e32 v105, 0xffff0000, v180
	v_pk_fma_f32 v[118:119], v[100:101], 0.5, v[104:105] op_sel_hi:[1,0,1]
	v_and_b32_e32 v101, 64, v165
	v_xor_b32_e32 v100, 16, v165
	v_add_u32_e32 v101, 64, v101
	v_cmp_lt_i32_e32 vcc, v100, v101
	v_and_b32_e32 v123, 0xffff0000, v182
	v_pk_fma_f32 v[122:123], v[96:97], 0.5, v[122:123] op_sel_hi:[1,0,1]
	v_cndmask_b32_e32 v100, v165, v100, vcc
	v_lshlrev_b32_e32 v124, 2, v100
	ds_bpermute_b32 v100, v124, v125
	v_xor_b32_e32 v97, 32, v165
	v_cmp_lt_i32_e32 vcc, v97, v101
	v_lshlrev_b32_e32 v106, 16, v181
	v_and_b32_e32 v107, 0xffff0000, v181
	v_cndmask_b32_e32 v97, v165, v97, vcc
	s_waitcnt lgkmcnt(0)
	v_add_f32_e32 v96, v125, v100
	v_lshlrev_b32_e32 v125, 2, v97
	ds_bpermute_b32 v97, v125, v96
	v_lshlrev_b32_e32 v120, 16, v183
	v_and_b32_e32 v121, 0xffff0000, v183
	v_pk_fma_f32 v[116:117], v[102:103], 0.5, v[106:107] op_sel_hi:[1,0,1]
	v_pk_fma_f32 v[120:121], v[98:99], 0.5, v[120:121] op_sel_hi:[1,0,1]
	v_cvt_pk_bf16_f32 v98, v118, v119
	v_cvt_pk_bf16_f32 v99, v116, v117
	v_cvt_pk_bf16_f32 v100, v122, v123
	v_cvt_pk_bf16_f32 v101, v120, v121
	v_lshl_add_u64 v[104:105], v[154:155], 2, s[10:11]
	global_store_dwordx4 v[186:187], v[98:101], off offset:256
	s_and_saveexec_b64 s[14:15], s[2:3]
	s_cbranch_execz .LBB0_367
	s_waitcnt lgkmcnt(0)
	v_add_f32_e32 v96, v96, v97
	global_atomic_add_f32 v[104:105], v96, off

; #define PG8_STAGE(bufoff, gbase, voff) do { _Pragma("unroll") for (int _i = 0; _i < 2; ++_i) \
;         __builtin_amdgcn_global_load_lds((const unsigned*)((const char*)(gbase) + (voff)[_i]), (LAS unsigned*)(lds + (bufoff) + ldsw + _i * 8192), 16, 0, 0); } while (0)
; #define PG8_LDA(dst, b, h) do { _Pragma("unroll") for (int m = 0; m < 4; ++m) _Pragma("unroll") for (int k = 0; k < 2; ++k) dst[m][k] = *(const LAS bf16x8*)(lds + PG8_SA(b, h) + aoff + m * 2048 + k * 1024); } while (0)
; #define PG8_LDB(dst, b, h) do { _Pragma("unroll") for (int n = 0; n < 2; ++n) _Pragma("unroll") for (int k = 0; k < 2; ++k) dst[n][k] = *(const LAS bf16x8*)(lds + PG8_SB(b, h) + boff + n * 2048 + k * 1024); } while (0)
; #define PG8_MMA(ai, bj, At, Bt) do { __builtin_amdgcn_s_setprio(1); _Pragma("unroll") for (int m = 0; m < 4; ++m) _Pragma("unroll") for (int n = 0; n < 2; ++n) _Pragma("unroll") for (int k = 0; k < 2; ++k) \
;         acc[ai][bj][m][n] = __builtin_amdgcn_mfma_f32_16x16x32_bf16(Bt[n][k], At[m][k], acc[ai][bj][m][n], 0, 0, 0); __builtin_amdgcn_s_setprio(0); } while (0)
; #define PG8_WAIT_L(n) asm volatile("s_waitcnt lgkmcnt(" #n ")" ::: "memory")
; #define PG8_BAR __builtin_amdgcn_s_barrier()
; #define PG8_SCHED __builtin_amdgcn_sched_barrier(0)
; template <class Epi>
; __device__ __forceinline__ void gemm_phase(LAS unsigned char* lds, const Gemm g, const StaticOrder& S, const Epi& E) {
;     ...
;             const bool last = (t == nt - 2);
;             const char* a1 = cA + (size_t)(t + 1) * kstep;
;             const char* a2 = last ? nA : cA + (size_t)(t + 2) * kstep; const char* b2 = last ? nB : cB + (size_t)(t + 2) * kstep;
;             const char* a3 = a2 + kstep; const char* b3 = b2 + kstep;
;             PG8_LDB(B0, 0, 0); PG8_SCHED; PG8_LDA(At, 0, 0); PG8_STAGE(PG8_SA(1, 1), a1 + hstep, voffA);
;             PG8_WAIT_L(8); PG8_BAR; PG8_WAIT_L(0); PG8_MMA(0, 0, At, B0); PG8_BAR; PG8_SCHED;
.LBB0_691:
	ds_read_b128 v[150:153], v167
	ds_read_b128 v[154:157], v167 offset:1024
	ds_read_b128 v[158:161], v167 offset:2048
	ds_read_b128 v[180:183], v167 offset:3072
	s_add_u32 s8, s6, 0xfff80080
	s_addc_u32 s9, s7, -1
	s_cmp_eq_u32 s63, 28
	s_cselect_b32 s11, s1, s9
	s_cselect_b32 s10, s5, s8
	s_cselect_b32 s9, s12, s61
	s_cselect_b32 s8, s13, s33
	v_lshl_add_u64 v[162:163], s[6:7], 0, v[140:141]
	s_add_i32 m0, s74, 0xc000
	ds_read_b128 v[184:187], v168
	ds_read_b128 v[188:191], v168 offset:1024
	ds_read_b128 v[192:195], v168 offset:2048
	ds_read_b128 v[196:199], v168 offset:3072
	ds_read_b128 v[200:203], v168 offset:4096
	ds_read_b128 v[204:207], v168 offset:5120
	ds_read_b128 v[208:211], v168 offset:6144
	ds_read_b128 v[212:215], v168 offset:7168
	global_load_lds_dwordx4 v[162:163], off
	v_lshl_add_u64 v[162:163], s[6:7], 0, v[142:143]
	s_add_i32 m0, s74, 0xe000
	s_nop 0
	global_load_lds_dwordx4 v[162:163], off
	s_waitcnt lgkmcnt(8)
	s_setprio 1
	s_barrier
	s_waitcnt lgkmcnt(0)


; #define PG8_MMA(ai, bj, At, Bt) do { __builtin_amdgcn_s_setprio(1); _Pragma("unroll") for (int m = 0; m < 4; ++m) _Pragma("unroll") for (int n = 0; n < 2; ++n) _Pragma("unroll") for (int k = 0; k < 2; ++k) \
;         acc[ai][bj][m][n] = __builtin_amdgcn_mfma_f32_16x16x32_bf16(Bt[n][k], At[m][k], acc[ai][bj][m][n], 0, 0, 0); __builtin_amdgcn_s_setprio(0); } while (0)
; #define PG8_WAIT_L(n) asm volatile("s_waitcnt lgkmcnt(" #n ")" ::: "memory")
; #define PG8_BAR __builtin_amdgcn_s_barrier()
; #define PG8_SCHED __builtin_amdgcn_sched_barrier(0)
; template <class Epi>
; __device__ __forceinline__ void gemm_phase(LAS unsigned char* lds, const Gemm g, const StaticOrder& S, const Epi& E) {
;     ...
;             PG8_WAIT_L(8); PG8_BAR; PG8_WAIT_L(0); PG8_MMA(0, 0, At, B0); PG8_BAR; PG8_SCHED;
	v_mfma_f32_16x16x32_bf16 v[124:127], v[150:153], v[184:187], v[124:127]
	v_mfma_f32_16x16x32_bf16 v[120:123], v[158:161], v[184:187], v[120:123]
	v_mfma_f32_16x16x32_bf16 v[108:111], v[150:153], v[192:195], v[108:111]
	v_mfma_f32_16x16x32_bf16 v[104:107], v[158:161], v[192:195], v[104:107]
	v_mfma_f32_16x16x32_bf16 v[92:95], v[150:153], v[200:203], v[92:95]
	v_mfma_f32_16x16x32_bf16 v[88:91], v[158:161], v[200:203], v[88:91]
	v_mfma_f32_16x16x32_bf16 v[76:79], v[150:153], v[208:211], v[76:79]
	v_mfma_f32_16x16x32_bf16 v[72:75], v[158:161], v[208:211], v[72:75]
	v_mfma_f32_16x16x32_bf16 v[124:127], v[154:157], v[188:191], v[124:127]
	v_mfma_f32_16x16x32_bf16 v[120:123], v[180:183], v[188:191], v[120:123]
	v_mfma_f32_16x16x32_bf16 v[108:111], v[154:157], v[196:199], v[108:111]
	v_mfma_f32_16x16x32_bf16 v[104:107], v[180:183], v[196:199], v[104:107]
	v_mfma_f32_16x16x32_bf16 v[92:95], v[154:157], v[204:207], v[92:95]
	v_mfma_f32_16x16x32_bf16 v[88:91], v[180:183], v[204:207], v[88:91]
	v_mfma_f32_16x16x32_bf16 v[76:79], v[154:157], v[212:215], v[76:79]
	v_mfma_f32_16x16x32_bf16 v[72:75], v[180:183], v[212:215], v[72:75]
	s_barrier
	s_setprio 0

; #define PG8_STAGE(bufoff, gbase, voff) do { _Pragma("unroll") for (int _i = 0; _i < 2; ++_i) \
;         __builtin_amdgcn_global_load_lds((const unsigned*)((const char*)(gbase) + (voff)[_i]), (LAS unsigned*)(lds + (bufoff) + ldsw + _i * 8192), 16, 0, 0); } while (0)
; #define PG8_LDB(dst, b, h) do { _Pragma("unroll") for (int n = 0; n < 2; ++n) _Pragma("unroll") for (int k = 0; k < 2; ++k) dst[n][k] = *(const LAS bf16x8*)(lds + PG8_SB(b, h) + boff + n * 2048 + k * 1024); } while (0)
; #define PG8_MMA(ai, bj, At, Bt) do { __builtin_amdgcn_s_setprio(1); _Pragma("unroll") for (int m = 0; m < 4; ++m) _Pragma("unroll") for (int n = 0; n < 2; ++n) _Pragma("unroll") for (int k = 0; k < 2; ++k) \
;         acc[ai][bj][m][n] = __builtin_amdgcn_mfma_f32_16x16x32_bf16(Bt[n][k], At[m][k], acc[ai][bj][m][n], 0, 0, 0); __builtin_amdgcn_s_setprio(0); } while (0)
; #define PG8_WAIT_L(n) asm volatile("s_waitcnt lgkmcnt(" #n ")" ::: "memory")
; #define PG8_BAR __builtin_amdgcn_s_barrier()
; template <class Epi>
; __device__ __forceinline__ void gemm_phase(LAS unsigned char* lds, const Gemm g, const StaticOrder& S, const Epi& E) {
;     ...
;             PG8_LDB(B1, 0, 1); PG8_STAGE(PG8_SB(0, 0), b2, voffB);
;             PG8_BAR; PG8_WAIT_L(0); PG8_MMA(0, 1, At, B1); PG8_BAR;
	s_add_i32 s89, s84, s69
	v_lshl_add_u64 v[162:163], s[8:9], 0, v[130:131]
	s_mov_b32 m0, s89
	ds_read_b128 v[216:219], v169
	ds_read_b128 v[220:223], v169 offset:1024
	ds_read_b128 v[224:227], v169 offset:2048
	ds_read_b128 v[228:231], v169 offset:3072
	global_load_lds_dwordx4 v[162:163], off
	v_lshl_add_u64 v[232:233], s[8:9], 0, v[134:135]
	s_add_i32 m0, s89, 0x2000
	s_nop 0
	global_load_lds_dwordx4 v[232:233], off
	s_waitcnt lgkmcnt(0)
	s_setprio 1
	s_barrier


; #define PG8_MMA(ai, bj, At, Bt) do { __builtin_amdgcn_s_setprio(1); _Pragma("unroll") for (int m = 0; m < 4; ++m) _Pragma("unroll") for (int n = 0; n < 2; ++n) _Pragma("unroll") for (int k = 0; k < 2; ++k) \
;         acc[ai][bj][m][n] = __builtin_amdgcn_mfma_f32_16x16x32_bf16(Bt[n][k], At[m][k], acc[ai][bj][m][n], 0, 0, 0); __builtin_amdgcn_s_setprio(0); } while (0)
; #define PG8_WAIT_L(n) asm volatile("s_waitcnt lgkmcnt(" #n ")" ::: "memory")
; #define PG8_BAR __builtin_amdgcn_s_barrier()
; template <class Epi>
; __device__ __forceinline__ void gemm_phase(LAS unsigned char* lds, const Gemm g, const StaticOrder& S, const Epi& E) {
;     ...
;             PG8_BAR; PG8_WAIT_L(0); PG8_MMA(0, 1, At, B1); PG8_BAR;
	v_mfma_f32_16x16x32_bf16 v[116:119], v[216:219], v[184:187], v[116:119]
	v_mfma_f32_16x16x32_bf16 v[112:115], v[224:227], v[184:187], v[112:115]
	v_mfma_f32_16x16x32_bf16 v[100:103], v[216:219], v[192:195], v[100:103]
	v_mfma_f32_16x16x32_bf16 v[96:99], v[224:227], v[192:195], v[96:99]
	v_mfma_f32_16x16x32_bf16 v[84:87], v[216:219], v[200:203], v[84:87]
	v_mfma_f32_16x16x32_bf16 v[80:83], v[224:227], v[200:203], v[80:83]
	v_mfma_f32_16x16x32_bf16 v[68:71], v[216:219], v[208:211], v[68:71]
	v_mfma_f32_16x16x32_bf16 v[64:67], v[224:227], v[208:211], v[64:67]
	v_mfma_f32_16x16x32_bf16 v[116:119], v[220:223], v[188:191], v[116:119]
	v_mfma_f32_16x16x32_bf16 v[112:115], v[228:231], v[188:191], v[112:115]
	v_mfma_f32_16x16x32_bf16 v[100:103], v[220:223], v[196:199], v[100:103]
	v_mfma_f32_16x16x32_bf16 v[96:99], v[228:231], v[196:199], v[96:99]
	v_mfma_f32_16x16x32_bf16 v[84:87], v[220:223], v[204:207], v[84:87]
	v_mfma_f32_16x16x32_bf16 v[80:83], v[228:231], v[204:207], v[80:83]
	v_mfma_f32_16x16x32_bf16 v[68:71], v[220:223], v[212:215], v[68:71]
	v_mfma_f32_16x16x32_bf16 v[64:67], v[228:231], v[212:215], v[64:67]
	s_barrier
	s_setprio 0
	s_mov_b32 m0, s74
	v_lshl_add_u64 v[234:235], s[10:11], 0, v[128:129]


; #define PG8_STAGE(bufoff, gbase, voff) do { _Pragma("unroll") for (int _i = 0; _i < 2; ++_i) \
;         __builtin_amdgcn_global_load_lds((const unsigned*)((const char*)(gbase) + (voff)[_i]), (LAS unsigned*)(lds + (bufoff) + ldsw + _i * 8192), 16, 0, 0); } while (0)
; #define PG8_LDA(dst, b, h) do { _Pragma("unroll") for (int m = 0; m < 4; ++m) _Pragma("unroll") for (int k = 0; k < 2; ++k) dst[m][k] = *(const LAS bf16x8*)(lds + PG8_SA(b, h) + aoff + m * 2048 + k * 1024); } while (0)
; #define PG8_MMA(ai, bj, At, Bt) do { __builtin_amdgcn_s_setprio(1); _Pragma("unroll") for (int m = 0; m < 4; ++m) _Pragma("unroll") for (int n = 0; n < 2; ++n) _Pragma("unroll") for (int k = 0; k < 2; ++k) \
;         acc[ai][bj][m][n] = __builtin_amdgcn_mfma_f32_16x16x32_bf16(Bt[n][k], At[m][k], acc[ai][bj][m][n], 0, 0, 0); __builtin_amdgcn_s_setprio(0); } while (0)
; #define PG8_WAIT_L(n) asm volatile("s_waitcnt lgkmcnt(" #n ")" ::: "memory")
; #define PG8_BAR __builtin_amdgcn_s_barrier()
; #define PG8_SCHED __builtin_amdgcn_sched_barrier(0)
; template <class Epi>
; __device__ __forceinline__ void gemm_phase(LAS unsigned char* lds, const Gemm g, const StaticOrder& S, const Epi& E) {
;     ...
;             PG8_LDA(At, 0, 1); PG8_STAGE(PG8_SA(0, 0), a2, voffA);
;             PG8_BAR; PG8_WAIT_L(0); PG8_MMA(1, 0, At, B0); PG8_BAR; PG8_SCHED;
	ds_read_b128 v[184:187], v168 offset:16384
	ds_read_b128 v[188:191], v168 offset:17408
	ds_read_b128 v[192:195], v168 offset:18432
	ds_read_b128 v[196:199], v168 offset:19456
	ds_read_b128 v[200:203], v168 offset:20480
	ds_read_b128 v[204:207], v168 offset:21504
	ds_read_b128 v[208:211], v168 offset:22528
	ds_read_b128 v[212:215], v168 offset:23552
	global_load_lds_dwordx4 v[234:235], off
	v_lshl_add_u64 v[236:237], s[10:11], 0, v[132:133]
	s_mov_b32 m0, s75
	s_nop 0
	global_load_lds_dwordx4 v[236:237], off
	s_waitcnt lgkmcnt(0)
	s_setprio 1
	s_barrier


; #define PG8_MMA(ai, bj, At, Bt) do { __builtin_amdgcn_s_setprio(1); _Pragma("unroll") for (int m = 0; m < 4; ++m) _Pragma("unroll") for (int n = 0; n < 2; ++n) _Pragma("unroll") for (int k = 0; k < 2; ++k) \
;         acc[ai][bj][m][n] = __builtin_amdgcn_mfma_f32_16x16x32_bf16(Bt[n][k], At[m][k], acc[ai][bj][m][n], 0, 0, 0); __builtin_amdgcn_s_setprio(0); } while (0)
; #define PG8_WAIT_L(n) asm volatile("s_waitcnt lgkmcnt(" #n ")" ::: "memory")
; #define PG8_BAR __builtin_amdgcn_s_barrier()
; #define PG8_SCHED __builtin_amdgcn_sched_barrier(0)
; template <class Epi>
; __device__ __forceinline__ void gemm_phase(LAS unsigned char* lds, const Gemm g, const StaticOrder& S, const Epi& E) {
;     ...
;             PG8_BAR; PG8_WAIT_L(0); PG8_MMA(1, 0, At, B0); PG8_BAR; PG8_SCHED;
	v_mfma_f32_16x16x32_bf16 v[60:63], v[150:153], v[184:187], v[60:63]
	v_mfma_f32_16x16x32_bf16 v[56:59], v[158:161], v[184:187], v[56:59]
	v_mfma_f32_16x16x32_bf16 v[44:47], v[150:153], v[192:195], v[44:47]
	v_mfma_f32_16x16x32_bf16 v[40:43], v[158:161], v[192:195], v[40:43]
	v_mfma_f32_16x16x32_bf16 v[28:31], v[150:153], v[200:203], v[28:31]
	v_mfma_f32_16x16x32_bf16 v[24:27], v[158:161], v[200:203], v[24:27]
	v_mfma_f32_16x16x32_bf16 v[12:15], v[150:153], v[208:211], v[12:15]
	v_mfma_f32_16x16x32_bf16 v[8:11], v[158:161], v[208:211], v[8:11]
	v_mfma_f32_16x16x32_bf16 v[60:63], v[154:157], v[188:191], v[60:63]
	v_mfma_f32_16x16x32_bf16 v[56:59], v[180:183], v[188:191], v[56:59]
	v_mfma_f32_16x16x32_bf16 v[44:47], v[154:157], v[196:199], v[44:47]
	v_mfma_f32_16x16x32_bf16 v[40:43], v[180:183], v[196:199], v[40:43]
	v_mfma_f32_16x16x32_bf16 v[28:31], v[154:157], v[204:207], v[28:31]
	v_mfma_f32_16x16x32_bf16 v[24:27], v[180:183], v[204:207], v[24:27]
	v_mfma_f32_16x16x32_bf16 v[12:15], v[154:157], v[212:215], v[12:15]
	v_mfma_f32_16x16x32_bf16 v[8:11], v[180:183], v[212:215], v[8:11]
	s_barrier
	s_setprio 0

; #define PG8_STAGE(bufoff, gbase, voff) do { _Pragma("unroll") for (int _i = 0; _i < 2; ++_i) \
;         __builtin_amdgcn_global_load_lds((const unsigned*)((const char*)(gbase) + (voff)[_i]), (LAS unsigned*)(lds + (bufoff) + ldsw + _i * 8192), 16, 0, 0); } while (0)
; #define PG8_MMA(ai, bj, At, Bt) do { __builtin_amdgcn_s_setprio(1); _Pragma("unroll") for (int m = 0; m < 4; ++m) _Pragma("unroll") for (int n = 0; n < 2; ++n) _Pragma("unroll") for (int k = 0; k < 2; ++k) \
;         acc[ai][bj][m][n] = __builtin_amdgcn_mfma_f32_16x16x32_bf16(Bt[n][k], At[m][k], acc[ai][bj][m][n], 0, 0, 0); __builtin_amdgcn_s_setprio(0); } while (0)
; #define PG8_WAIT_V(n) asm volatile("s_waitcnt vmcnt(" #n ")" ::: "memory")
; #define PG8_BAR __builtin_amdgcn_s_barrier()
; template <class Epi>
; __device__ __forceinline__ void gemm_phase(LAS unsigned char* lds, const Gemm g, const StaticOrder& S, const Epi& E) {
;     ...
;             PG8_STAGE(PG8_SB(0, 1), b2 + hstep, voffB);
;             PG8_WAIT_V(6); PG8_BAR; PG8_MMA(1, 1, At, B1); PG8_BAR;
	s_add_u32 s90, s8, 0x80000
	s_addc_u32 s91, s9, 0
	s_add_i32 s89, s85, s69
	v_lshl_add_u64 v[150:151], s[90:91], 0, v[130:131]
	s_mov_b32 m0, s89
	s_nop 0
	global_load_lds_dwordx4 v[150:151], off
	v_lshl_add_u64 v[150:151], s[90:91], 0, v[134:135]
	s_add_i32 m0, s89, 0x2000
	s_nop 0
	global_load_lds_dwordx4 v[150:151], off
	s_waitcnt vmcnt(6)
	s_setprio 1
	s_barrier

; #define PG8_MMA(ai, bj, At, Bt) do { __builtin_amdgcn_s_setprio(1); _Pragma("unroll") for (int m = 0; m < 4; ++m) _Pragma("unroll") for (int n = 0; n < 2; ++n) _Pragma("unroll") for (int k = 0; k < 2; ++k) \
;         acc[ai][bj][m][n] = __builtin_amdgcn_mfma_f32_16x16x32_bf16(Bt[n][k], At[m][k], acc[ai][bj][m][n], 0, 0, 0); __builtin_amdgcn_s_setprio(0); } while (0)
; #define PG8_WAIT_V(n) asm volatile("s_waitcnt vmcnt(" #n ")" ::: "memory")
; #define PG8_BAR __builtin_amdgcn_s_barrier()
; template <class Epi>
; __device__ __forceinline__ void gemm_phase(LAS unsigned char* lds, const Gemm g, const StaticOrder& S, const Epi& E) {
;     ...
;             PG8_WAIT_V(6); PG8_BAR; PG8_MMA(1, 1, At, B1); PG8_BAR;
	v_mfma_f32_16x16x32_bf16 v[52:55], v[216:219], v[184:187], v[52:55]
	v_mfma_f32_16x16x32_bf16 v[48:51], v[224:227], v[184:187], v[48:51]
	v_mfma_f32_16x16x32_bf16 v[36:39], v[216:219], v[192:195], v[36:39]
	v_mfma_f32_16x16x32_bf16 v[32:35], v[224:227], v[192:195], v[32:35]
	v_mfma_f32_16x16x32_bf16 v[20:23], v[216:219], v[200:203], v[20:23]
	v_mfma_f32_16x16x32_bf16 v[16:19], v[224:227], v[200:203], v[16:19]
	v_mfma_f32_16x16x32_bf16 v[4:7], v[216:219], v[208:211], v[4:7]
	v_mfma_f32_16x16x32_bf16 v[0:3], v[224:227], v[208:211], v[0:3]
	v_mfma_f32_16x16x32_bf16 v[52:55], v[220:223], v[188:191], v[52:55]
	v_mfma_f32_16x16x32_bf16 v[48:51], v[228:231], v[188:191], v[48:51]
	v_mfma_f32_16x16x32_bf16 v[36:39], v[220:223], v[196:199], v[36:39]
	v_mfma_f32_16x16x32_bf16 v[32:35], v[228:231], v[196:199], v[32:35]
	v_mfma_f32_16x16x32_bf16 v[20:23], v[220:223], v[204:207], v[20:23]
	v_mfma_f32_16x16x32_bf16 v[16:19], v[228:231], v[204:207], v[16:19]
	v_mfma_f32_16x16x32_bf16 v[4:7], v[220:223], v[212:215], v[4:7]
	v_mfma_f32_16x16x32_bf16 v[0:3], v[228:231], v[212:215], v[0:3]
	s_barrier
	s_setprio 0
	s_add_i32 s89, 0, 0x18000
	v_add_u32_e32 v138, s89, v165


; #define PG8_STAGE(bufoff, gbase, voff) do { _Pragma("unroll") for (int _i = 0; _i < 2; ++_i) \
;         __builtin_amdgcn_global_load_lds((const unsigned*)((const char*)(gbase) + (voff)[_i]), (LAS unsigned*)(lds + (bufoff) + ldsw + _i * 8192), 16, 0, 0); } while (0)
; #define PG8_LDA(dst, b, h) do { _Pragma("unroll") for (int m = 0; m < 4; ++m) _Pragma("unroll") for (int k = 0; k < 2; ++k) dst[m][k] = *(const LAS bf16x8*)(lds + PG8_SA(b, h) + aoff + m * 2048 + k * 1024); } while (0)
; #define PG8_LDB(dst, b, h) do { _Pragma("unroll") for (int n = 0; n < 2; ++n) _Pragma("unroll") for (int k = 0; k < 2; ++k) dst[n][k] = *(const LAS bf16x8*)(lds + PG8_SB(b, h) + boff + n * 2048 + k * 1024); } while (0)
; #define PG8_MMA(ai, bj, At, Bt) do { __builtin_amdgcn_s_setprio(1); _Pragma("unroll") for (int m = 0; m < 4; ++m) _Pragma("unroll") for (int n = 0; n < 2; ++n) _Pragma("unroll") for (int k = 0; k < 2; ++k) \
;         acc[ai][bj][m][n] = __builtin_amdgcn_mfma_f32_16x16x32_bf16(Bt[n][k], At[m][k], acc[ai][bj][m][n], 0, 0, 0); __builtin_amdgcn_s_setprio(0); } while (0)
; #define PG8_WAIT_L(n) asm volatile("s_waitcnt lgkmcnt(" #n ")" ::: "memory")
; #define PG8_BAR __builtin_amdgcn_s_barrier()
; #define PG8_SCHED __builtin_amdgcn_sched_barrier(0)
; template <class Epi>
; __device__ __forceinline__ void gemm_phase(LAS unsigned char* lds, const Gemm g, const StaticOrder& S, const Epi& E) {
;     ...
;             PG8_LDB(B0, 1, 0); PG8_SCHED; PG8_LDA(At, 1, 0); PG8_STAGE(PG8_SA(0, 1), a2 + hstep, voffA);
;             PG8_WAIT_L(8); PG8_BAR; PG8_WAIT_L(0); PG8_MMA(0, 0, At, B0); PG8_BAR; PG8_SCHED;
	ds_read_b128 v[150:153], v138
	ds_read_b128 v[154:157], v138 offset:1024
	ds_read_b128 v[158:161], v138 offset:2048
	ds_read_b128 v[180:183], v138 offset:3072
	s_add_u32 s10, s10, 0x80000
	s_addc_u32 s11, s11, 0
	s_mov_b32 m0, s76
	v_lshl_add_u64 v[216:217], s[10:11], 0, v[128:129]
	ds_read_b128 v[184:187], v168 offset:32768
	ds_read_b128 v[188:191], v168 offset:33792
	ds_read_b128 v[192:195], v168 offset:34816
	ds_read_b128 v[196:199], v168 offset:35840
	ds_read_b128 v[200:203], v168 offset:36864
	ds_read_b128 v[204:207], v168 offset:37888
	ds_read_b128 v[208:211], v168 offset:38912
	ds_read_b128 v[212:215], v168 offset:39936
	global_load_lds_dwordx4 v[216:217], off
	v_lshl_add_u64 v[216:217], s[10:11], 0, v[132:133]
	s_mov_b32 m0, s77
	s_nop 0
	global_load_lds_dwordx4 v[216:217], off
	s_waitcnt lgkmcnt(8)
	s_setprio 1
	s_barrier
	s_waitcnt lgkmcnt(0)


; #define PG8_MMA(ai, bj, At, Bt) do { __builtin_amdgcn_s_setprio(1); _Pragma("unroll") for (int m = 0; m < 4; ++m) _Pragma("unroll") for (int n = 0; n < 2; ++n) _Pragma("unroll") for (int k = 0; k < 2; ++k) \
;         acc[ai][bj][m][n] = __builtin_amdgcn_mfma_f32_16x16x32_bf16(Bt[n][k], At[m][k], acc[ai][bj][m][n], 0, 0, 0); __builtin_amdgcn_s_setprio(0); } while (0)
; #define PG8_WAIT_L(n) asm volatile("s_waitcnt lgkmcnt(" #n ")" ::: "memory")
; #define PG8_BAR __builtin_amdgcn_s_barrier()
; #define PG8_SCHED __builtin_amdgcn_sched_barrier(0)
; template <class Epi>
; __device__ __forceinline__ void gemm_phase(LAS unsigned char* lds, const Gemm g, const StaticOrder& S, const Epi& E) {
;     ...
;             PG8_WAIT_L(8); PG8_BAR; PG8_WAIT_L(0); PG8_MMA(0, 0, At, B0); PG8_BAR; PG8_SCHED;
	v_mfma_f32_16x16x32_bf16 v[124:127], v[150:153], v[184:187], v[124:127]
	v_mfma_f32_16x16x32_bf16 v[120:123], v[158:161], v[184:187], v[120:123]
	v_mfma_f32_16x16x32_bf16 v[108:111], v[150:153], v[192:195], v[108:111]
	v_mfma_f32_16x16x32_bf16 v[104:107], v[158:161], v[192:195], v[104:107]
	v_mfma_f32_16x16x32_bf16 v[92:95], v[150:153], v[200:203], v[92:95]
	v_mfma_f32_16x16x32_bf16 v[88:91], v[158:161], v[200:203], v[88:91]
	v_mfma_f32_16x16x32_bf16 v[76:79], v[150:153], v[208:211], v[76:79]
	v_mfma_f32_16x16x32_bf16 v[72:75], v[158:161], v[208:211], v[72:75]
	v_mfma_f32_16x16x32_bf16 v[124:127], v[154:157], v[188:191], v[124:127]
	v_mfma_f32_16x16x32_bf16 v[120:123], v[180:183], v[188:191], v[120:123]
	v_mfma_f32_16x16x32_bf16 v[108:111], v[154:157], v[196:199], v[108:111]
	v_mfma_f32_16x16x32_bf16 v[104:107], v[180:183], v[196:199], v[104:107]
	v_mfma_f32_16x16x32_bf16 v[92:95], v[154:157], v[204:207], v[92:95]
	v_mfma_f32_16x16x32_bf16 v[88:91], v[180:183], v[204:207], v[88:91]
	v_mfma_f32_16x16x32_bf16 v[76:79], v[154:157], v[212:215], v[76:79]
	v_mfma_f32_16x16x32_bf16 v[72:75], v[180:183], v[212:215], v[72:75]
	s_barrier
	s_setprio 0

; #define PG8_STAGE(bufoff, gbase, voff) do { _Pragma("unroll") for (int _i = 0; _i < 2; ++_i) \
;         __builtin_amdgcn_global_load_lds((const unsigned*)((const char*)(gbase) + (voff)[_i]), (LAS unsigned*)(lds + (bufoff) + ldsw + _i * 8192), 16, 0, 0); } while (0)
; #define PG8_LDB(dst, b, h) do { _Pragma("unroll") for (int n = 0; n < 2; ++n) _Pragma("unroll") for (int k = 0; k < 2; ++k) dst[n][k] = *(const LAS bf16x8*)(lds + PG8_SB(b, h) + boff + n * 2048 + k * 1024); } while (0)
; #define PG8_MMA(ai, bj, At, Bt) do { __builtin_amdgcn_s_setprio(1); _Pragma("unroll") for (int m = 0; m < 4; ++m) _Pragma("unroll") for (int n = 0; n < 2; ++n) _Pragma("unroll") for (int k = 0; k < 2; ++k) \
;         acc[ai][bj][m][n] = __builtin_amdgcn_mfma_f32_16x16x32_bf16(Bt[n][k], At[m][k], acc[ai][bj][m][n], 0, 0, 0); __builtin_amdgcn_s_setprio(0); } while (0)
; #define PG8_WAIT_L(n) asm volatile("s_waitcnt lgkmcnt(" #n ")" ::: "memory")
; #define PG8_BAR __builtin_amdgcn_s_barrier()
; template <class Epi>
; __device__ __forceinline__ void gemm_phase(LAS unsigned char* lds, const Gemm g, const StaticOrder& S, const Epi& E) {
;     ...
;             PG8_LDB(B1, 1, 1); PG8_STAGE(PG8_SB(1, 0), b3, voffB);
;             PG8_BAR; PG8_WAIT_L(0); PG8_MMA(0, 1, At, B1); PG8_BAR;
	s_add_i32 s10, 0, 0x1c000
	s_add_i32 s11, s89, s69
	v_add_u32_e32 v138, s10, v165
	v_lshl_add_u64 v[162:163], v[162:163], 0, s[34:35]
	s_mov_b32 m0, s11
	ds_read_b128 v[216:219], v138
	ds_read_b128 v[220:223], v138 offset:1024
	ds_read_b128 v[224:227], v138 offset:2048
	ds_read_b128 v[228:231], v138 offset:3072
	global_load_lds_dwordx4 v[162:163], off
	v_lshl_add_u64 v[162:163], v[232:233], 0, s[34:35]
	s_add_i32 m0, s11, 0x2000
	s_nop 0
	global_load_lds_dwordx4 v[162:163], off
	s_waitcnt lgkmcnt(0)
	s_setprio 1
	s_barrier


; #define PG8_MMA(ai, bj, At, Bt) do { __builtin_amdgcn_s_setprio(1); _Pragma("unroll") for (int m = 0; m < 4; ++m) _Pragma("unroll") for (int n = 0; n < 2; ++n) _Pragma("unroll") for (int k = 0; k < 2; ++k) \
;         acc[ai][bj][m][n] = __builtin_amdgcn_mfma_f32_16x16x32_bf16(Bt[n][k], At[m][k], acc[ai][bj][m][n], 0, 0, 0); __builtin_amdgcn_s_setprio(0); } while (0)
; #define PG8_WAIT_L(n) asm volatile("s_waitcnt lgkmcnt(" #n ")" ::: "memory")
; #define PG8_BAR __builtin_amdgcn_s_barrier()
; template <class Epi>
; __device__ __forceinline__ void gemm_phase(LAS unsigned char* lds, const Gemm g, const StaticOrder& S, const Epi& E) {
;     ...
;             PG8_BAR; PG8_WAIT_L(0); PG8_MMA(0, 1, At, B1); PG8_BAR;
	v_mfma_f32_16x16x32_bf16 v[116:119], v[216:219], v[184:187], v[116:119]
	v_mfma_f32_16x16x32_bf16 v[112:115], v[224:227], v[184:187], v[112:115]
	v_mfma_f32_16x16x32_bf16 v[100:103], v[216:219], v[192:195], v[100:103]
	v_mfma_f32_16x16x32_bf16 v[96:99], v[224:227], v[192:195], v[96:99]
	v_mfma_f32_16x16x32_bf16 v[84:87], v[216:219], v[200:203], v[84:87]
	v_mfma_f32_16x16x32_bf16 v[80:83], v[224:227], v[200:203], v[80:83]
	v_mfma_f32_16x16x32_bf16 v[68:71], v[216:219], v[208:211], v[68:71]
	v_mfma_f32_16x16x32_bf16 v[64:67], v[224:227], v[208:211], v[64:67]
	v_mfma_f32_16x16x32_bf16 v[116:119], v[220:223], v[188:191], v[116:119]
	v_mfma_f32_16x16x32_bf16 v[112:115], v[228:231], v[188:191], v[112:115]
	v_mfma_f32_16x16x32_bf16 v[100:103], v[220:223], v[196:199], v[100:103]
	v_mfma_f32_16x16x32_bf16 v[96:99], v[228:231], v[196:199], v[96:99]
	v_mfma_f32_16x16x32_bf16 v[84:87], v[220:223], v[204:207], v[84:87]
	v_mfma_f32_16x16x32_bf16 v[80:83], v[228:231], v[204:207], v[80:83]
	v_mfma_f32_16x16x32_bf16 v[68:71], v[220:223], v[212:215], v[68:71]
	v_mfma_f32_16x16x32_bf16 v[64:67], v[228:231], v[212:215], v[64:67]
	s_barrier
	s_setprio 0
	s_mov_b32 m0, s79
	v_lshl_add_u64 v[162:163], v[234:235], 0, s[34:35]


; #define PG8_STAGE(bufoff, gbase, voff) do { _Pragma("unroll") for (int _i = 0; _i < 2; ++_i) \
;         __builtin_amdgcn_global_load_lds((const unsigned*)((const char*)(gbase) + (voff)[_i]), (LAS unsigned*)(lds + (bufoff) + ldsw + _i * 8192), 16, 0, 0); } while (0)
; #define PG8_LDA(dst, b, h) do { _Pragma("unroll") for (int m = 0; m < 4; ++m) _Pragma("unroll") for (int k = 0; k < 2; ++k) dst[m][k] = *(const LAS bf16x8*)(lds + PG8_SA(b, h) + aoff + m * 2048 + k * 1024); } while (0)
; #define PG8_MMA(ai, bj, At, Bt) do { __builtin_amdgcn_s_setprio(1); _Pragma("unroll") for (int m = 0; m < 4; ++m) _Pragma("unroll") for (int n = 0; n < 2; ++n) _Pragma("unroll") for (int k = 0; k < 2; ++k) \
;         acc[ai][bj][m][n] = __builtin_amdgcn_mfma_f32_16x16x32_bf16(Bt[n][k], At[m][k], acc[ai][bj][m][n], 0, 0, 0); __builtin_amdgcn_s_setprio(0); } while (0)
; #define PG8_WAIT_L(n) asm volatile("s_waitcnt lgkmcnt(" #n ")" ::: "memory")
; #define PG8_BAR __builtin_amdgcn_s_barrier()
; #define PG8_SCHED __builtin_amdgcn_sched_barrier(0)
; template <class Epi>
; __device__ __forceinline__ void gemm_phase(LAS unsigned char* lds, const Gemm g, const StaticOrder& S, const Epi& E) {
;     ...
;             PG8_LDA(At, 1, 1); PG8_STAGE(PG8_SA(1, 0), a3, voffA);
;             PG8_BAR; PG8_WAIT_L(0); PG8_MMA(1, 0, At, B0); PG8_BAR; PG8_SCHED;
	ds_read_b128 v[184:187], v168 offset:49152
	ds_read_b128 v[188:191], v168 offset:50176
	ds_read_b128 v[192:195], v168 offset:51200
	ds_read_b128 v[196:199], v168 offset:52224
	ds_read_b128 v[200:203], v168 offset:53248
	ds_read_b128 v[204:207], v168 offset:54272
	ds_read_b128 v[208:211], v168 offset:55296
	ds_read_b128 v[212:215], v168 offset:56320
	global_load_lds_dwordx4 v[162:163], off
	v_lshl_add_u64 v[162:163], v[236:237], 0, s[34:35]
	s_mov_b32 m0, s80
	s_nop 0
	global_load_lds_dwordx4 v[162:163], off
	s_waitcnt lgkmcnt(0)
	s_setprio 1
	s_barrier


; #define PG8_MMA(ai, bj, At, Bt) do { __builtin_amdgcn_s_setprio(1); _Pragma("unroll") for (int m = 0; m < 4; ++m) _Pragma("unroll") for (int n = 0; n < 2; ++n) _Pragma("unroll") for (int k = 0; k < 2; ++k) \
;         acc[ai][bj][m][n] = __builtin_amdgcn_mfma_f32_16x16x32_bf16(Bt[n][k], At[m][k], acc[ai][bj][m][n], 0, 0, 0); __builtin_amdgcn_s_setprio(0); } while (0)
; #define PG8_WAIT_L(n) asm volatile("s_waitcnt lgkmcnt(" #n ")" ::: "memory")
; #define PG8_BAR __builtin_amdgcn_s_barrier()
; #define PG8_SCHED __builtin_amdgcn_sched_barrier(0)
; template <class Epi>
; __device__ __forceinline__ void gemm_phase(LAS unsigned char* lds, const Gemm g, const StaticOrder& S, const Epi& E) {
;     ...
;             PG8_BAR; PG8_WAIT_L(0); PG8_MMA(1, 0, At, B0); PG8_BAR; PG8_SCHED;
	v_mfma_f32_16x16x32_bf16 v[60:63], v[150:153], v[184:187], v[60:63]
	v_mfma_f32_16x16x32_bf16 v[56:59], v[158:161], v[184:187], v[56:59]
	v_mfma_f32_16x16x32_bf16 v[44:47], v[150:153], v[192:195], v[44:47]
	v_mfma_f32_16x16x32_bf16 v[40:43], v[158:161], v[192:195], v[40:43]
	v_mfma_f32_16x16x32_bf16 v[28:31], v[150:153], v[200:203], v[28:31]
	v_mfma_f32_16x16x32_bf16 v[24:27], v[158:161], v[200:203], v[24:27]
	v_mfma_f32_16x16x32_bf16 v[12:15], v[150:153], v[208:211], v[12:15]
	v_mfma_f32_16x16x32_bf16 v[8:11], v[158:161], v[208:211], v[8:11]
	v_mfma_f32_16x16x32_bf16 v[60:63], v[154:157], v[188:191], v[60:63]
	v_mfma_f32_16x16x32_bf16 v[56:59], v[180:183], v[188:191], v[56:59]
	v_mfma_f32_16x16x32_bf16 v[44:47], v[154:157], v[196:199], v[44:47]
	v_mfma_f32_16x16x32_bf16 v[40:43], v[180:183], v[196:199], v[40:43]
	v_mfma_f32_16x16x32_bf16 v[28:31], v[154:157], v[204:207], v[28:31]
	v_mfma_f32_16x16x32_bf16 v[24:27], v[180:183], v[204:207], v[24:27]
	v_mfma_f32_16x16x32_bf16 v[12:15], v[154:157], v[212:215], v[12:15]
	v_mfma_f32_16x16x32_bf16 v[8:11], v[180:183], v[212:215], v[8:11]
	s_barrier
	s_setprio 0

; #define PG8_STAGE(bufoff, gbase, voff) do { _Pragma("unroll") for (int _i = 0; _i < 2; ++_i) \
;         __builtin_amdgcn_global_load_lds((const unsigned*)((const char*)(gbase) + (voff)[_i]), (LAS unsigned*)(lds + (bufoff) + ldsw + _i * 8192), 16, 0, 0); } while (0)
; #define PG8_MMA(ai, bj, At, Bt) do { __builtin_amdgcn_s_setprio(1); _Pragma("unroll") for (int m = 0; m < 4; ++m) _Pragma("unroll") for (int n = 0; n < 2; ++n) _Pragma("unroll") for (int k = 0; k < 2; ++k) \
;         acc[ai][bj][m][n] = __builtin_amdgcn_mfma_f32_16x16x32_bf16(Bt[n][k], At[m][k], acc[ai][bj][m][n], 0, 0, 0); __builtin_amdgcn_s_setprio(0); } while (0)
; #define PG8_WAIT_V(n) asm volatile("s_waitcnt vmcnt(" #n ")" ::: "memory")
; #define PG8_BAR __builtin_amdgcn_s_barrier()
; template <class Epi>
; __device__ __forceinline__ void gemm_phase(LAS unsigned char* lds, const Gemm g, const StaticOrder& S, const Epi& E) {
;     ...
;             PG8_STAGE(PG8_SB(1, 1), b3 + hstep, voffB);
;             PG8_WAIT_V(6); PG8_BAR; PG8_MMA(1, 1, At, B1); PG8_BAR;
	s_add_u32 s8, s8, 0x80080
	s_addc_u32 s9, s9, 0
	s_add_i32 s10, s10, s69
	v_lshl_add_u64 v[150:151], s[8:9], 0, v[130:131]
	s_mov_b32 m0, s10
	s_nop 0
	global_load_lds_dwordx4 v[150:151], off
	v_lshl_add_u64 v[150:151], s[8:9], 0, v[134:135]
	s_add_i32 m0, s10, 0x2000
	s_nop 0
	global_load_lds_dwordx4 v[150:151], off
	s_waitcnt vmcnt(6)
	s_setprio 1
	s_barrier

; #define PG8_MMA(ai, bj, At, Bt) do { __builtin_amdgcn_s_setprio(1); _Pragma("unroll") for (int m = 0; m < 4; ++m) _Pragma("unroll") for (int n = 0; n < 2; ++n) _Pragma("unroll") for (int k = 0; k < 2; ++k) \
;         acc[ai][bj][m][n] = __builtin_amdgcn_mfma_f32_16x16x32_bf16(Bt[n][k], At[m][k], acc[ai][bj][m][n], 0, 0, 0); __builtin_amdgcn_s_setprio(0); } while (0)
; #define PG8_WAIT_V(n) asm volatile("s_waitcnt vmcnt(" #n ")" ::: "memory")
; #define PG8_BAR __builtin_amdgcn_s_barrier()
; template <class Epi>
; __device__ __forceinline__ void gemm_phase(LAS unsigned char* lds, const Gemm g, const StaticOrder& S, const Epi& E) {
;     ...
;         for (int t = 0; t < nt; t += 2) {
;     ...
;             PG8_WAIT_V(6); PG8_BAR; PG8_MMA(1, 1, At, B1); PG8_BAR;
	v_mfma_f32_16x16x32_bf16 v[52:55], v[216:219], v[184:187], v[52:55]
	v_mfma_f32_16x16x32_bf16 v[48:51], v[224:227], v[184:187], v[48:51]
	v_mfma_f32_16x16x32_bf16 v[36:39], v[216:219], v[192:195], v[36:39]
	v_mfma_f32_16x16x32_bf16 v[32:35], v[224:227], v[192:195], v[32:35]
	v_mfma_f32_16x16x32_bf16 v[20:23], v[216:219], v[200:203], v[20:23]
	v_mfma_f32_16x16x32_bf16 v[16:19], v[224:227], v[200:203], v[16:19]
	v_mfma_f32_16x16x32_bf16 v[4:7], v[216:219], v[208:211], v[4:7]
	v_mfma_f32_16x16x32_bf16 v[0:3], v[224:227], v[208:211], v[0:3]
	v_mfma_f32_16x16x32_bf16 v[52:55], v[220:223], v[188:191], v[52:55]
	v_mfma_f32_16x16x32_bf16 v[48:51], v[228:231], v[188:191], v[48:51]
	v_mfma_f32_16x16x32_bf16 v[36:39], v[220:223], v[196:199], v[36:39]
	v_mfma_f32_16x16x32_bf16 v[32:35], v[228:231], v[196:199], v[32:35]
	v_mfma_f32_16x16x32_bf16 v[20:23], v[220:223], v[204:207], v[20:23]
	v_mfma_f32_16x16x32_bf16 v[16:19], v[228:231], v[204:207], v[16:19]
	v_mfma_f32_16x16x32_bf16 v[4:7], v[220:223], v[212:215], v[4:7]
	v_mfma_f32_16x16x32_bf16 v[0:3], v[228:231], v[212:215], v[0:3]
	s_barrier
	s_setprio 0
	s_add_i32 s63, s63, 2
	s_add_u32 s6, s6, 0x100
	s_addc_u32 s7, s7, 0
	s_add_u32 s33, s33, 0x100
	s_addc_u32 s61, s61, 0
	s_cmp_gt_u32 s63, 29


; __device__ __forceinline__ float sigmoidf_(float x) { return __builtin_amdgcn_rcpf(1.0f + fexp(-x)); }
;     __device__ __forceinline__ void operator()(const f32x4 (&acc)[2][2][4][2], const Unit& u, int wr, int wc, int fr, int fq, const Pre& P) const {
;         const int sec = u.pn >> 3, row0 = ROW_X + u.pm * BM + wr * 64 + fr, colb = (u.pn & 7) * BM + wc * 32 + 8 * fq;
; #pragma unroll
;         for (int ai = 0; ai < 2; ++ai)
; #pragma unroll
;             for (int m = 0; m < 4; ++m) { const int r = row0 + ai * HALF + m * 16; const float rs = __builtin_amdgcn_rsqf(P.rs[ai * 4 + m] * (1.0f / DM) + RMS_EPS);
; #pragma unroll
;                 for (int bj = 0; bj < 2; ++bj) { const int c = colb + bj * HALF; const size_t off = (size_t)r * DM + c; float x[8], y[8];
; #pragma unroll
;                     for (int n = 0; n < 2; ++n)
; #pragma unroll
;                         for (int j = 0; j < 4; ++j) x[n * 4 + j] = acc[ai][bj][m][n][j] * rs;
;                     bf16_t* dst;
;                     if (sec == 0) { dst = QB;
; #pragma unroll
;                         for (int j = 0; j < 8; ++j) y[j] = x[j] * sigmoidf_(x[j]); }
;                     else if (sec == 1) { dst = KB; const f32x4 l0 = *(const f32x4*)(LBv + c), l1 = *(const f32x4*)(LBv + c + 4); float lf[8];
; #pragma unroll
;                         for (int j = 0; j < 8; ++j) { const float lb = j < 4 ? l0[j] : l1[j - 4]; const float fg = lb + (1.0f - lb) * sigmoidf_(x[j]); y[j] = 1.0f - fg; lf[j] = __logf(fg); }
	s_cbranch_scc0 .LBB0_691
	v_fmamk_f32 v149, v149, 0x3a000000, v170
	s_lshl_b32 s1, s0, 8
	v_rsq_f32_e32 v152, v149
	s_ashr_i32 s61, s0, 3
	v_lshl_add_u32 v148, s4, 8, v137
	s_and_b32 s1, s1, 0x700
	s_cmp_gt_u32 s0, 7
	v_ashrrev_i32_e32 v149, 31, v148
	v_or_b32_e32 v138, s1, v166
	v_lshlrev_b32_e32 v254, 2, v138
	global_load_dwordx4 v[238:241], v254, s[24:25]
	global_load_dwordx4 v[242:245], v254, s[24:25] offset:16
	global_load_dwordx4 v[246:249], v254, s[24:25] offset:512
	global_load_dwordx4 v[250:253], v254, s[24:25] offset:528
	s_cselect_b64 s[12:13], -1, 0
	v_lshlrev_b64 v[150:151], 11, v[148:149]
	v_pk_mul_f32 v[124:125], v[152:153], v[124:125] op_sel_hi:[0,1]
	v_pk_mul_f32 v[126:127], v[152:153], v[126:127] op_sel_hi:[0,1]
	v_pk_mul_f32 v[154:155], v[152:153], v[120:121] op_sel_hi:[0,1]
	v_pk_mul_f32 v[122:123], v[152:153], v[122:123] op_sel_hi:[0,1]
	v_or_b32_e32 v120, v150, v138
	v_mov_b32_e32 v121, v151
	s_mov_b64 s[0:1], -1
	s_and_b64 vcc, exec, s[12:13]
	s_cbranch_vccz .LBB0_704
	s_mov_b64 s[6:7], -1
	s_mov_b64 s[0:1], 0
	s_cmp_lt_i32 s61, 2
	s_mov_b64 s[4:5], 0
	s_cbranch_scc1 .LBB0_699
	s_cmp_eq_u32 s61, 2
	s_mov_b64 s[4:5], -1
	s_cbranch_scc0 .LBB0_696
	s_mov_b64 s[4:5], 0
	v_mov_b32_e32 v161, v123
	v_mov_b32_e32 v160, v122
	v_mov_b32_e32 v163, v155
	v_mov_b32_e32 v162, v154
	v_mov_b32_e32 v157, v127
	v_mov_b32_e32 v156, v126
	v_mov_b32_e32 v159, v125
	v_mov_b32_e32 v158, v124

; #define PG8_STAGE(bufoff, gbase, voff) do { _Pragma("unroll") for (int _i = 0; _i < 2; ++_i) \
;         __builtin_amdgcn_global_load_lds((const unsigned*)((const char*)(gbase) + (voff)[_i]), (LAS unsigned*)(lds + (bufoff) + ldsw + _i * 8192), 16, 0, 0); } while (0)
; #define PG8_LDA(dst, b, h) do { _Pragma("unroll") for (int m = 0; m < 4; ++m) _Pragma("unroll") for (int k = 0; k < 2; ++k) dst[m][k] = *(const LAS bf16x8*)(lds + PG8_SA(b, h) + aoff + m * 2048 + k * 1024); } while (0)
; #define PG8_LDB(dst, b, h) do { _Pragma("unroll") for (int n = 0; n < 2; ++n) _Pragma("unroll") for (int k = 0; k < 2; ++k) dst[n][k] = *(const LAS bf16x8*)(lds + PG8_SB(b, h) + boff + n * 2048 + k * 1024); } while (0)
; #define PG8_MMA(ai, bj, At, Bt) do { __builtin_amdgcn_s_setprio(1); _Pragma("unroll") for (int m = 0; m < 4; ++m) _Pragma("unroll") for (int n = 0; n < 2; ++n) _Pragma("unroll") for (int k = 0; k < 2; ++k) \
;         acc[ai][bj][m][n] = __builtin_amdgcn_mfma_f32_16x16x32_bf16(Bt[n][k], At[m][k], acc[ai][bj][m][n], 0, 0, 0); __builtin_amdgcn_s_setprio(0); } while (0)
; #define PG8_WAIT_L(n) asm volatile("s_waitcnt lgkmcnt(" #n ")" ::: "memory")
; #define PG8_BAR __builtin_amdgcn_s_barrier()
; #define PG8_SCHED __builtin_amdgcn_sched_barrier(0)
; template <class Epi>
; __device__ __forceinline__ void gemm_phase(LAS unsigned char* lds, const Gemm g, const StaticOrder& S, const Epi& E) {
;     ...
;             const bool last = (t == nt - 2);
;             const char* a1 = cA + (size_t)(t + 1) * kstep;
;             const char* a2 = last ? nA : cA + (size_t)(t + 2) * kstep; const char* b2 = last ? nB : cB + (size_t)(t + 2) * kstep;
;             const char* a3 = a2 + kstep; const char* b3 = b2 + kstep;
;             PG8_LDB(B0, 0, 0); PG8_SCHED; PG8_LDA(At, 0, 0); PG8_STAGE(PG8_SA(1, 1), a1 + hstep, voffA);
;             PG8_WAIT_L(8); PG8_BAR; PG8_WAIT_L(0); PG8_MMA(0, 0, At, B0); PG8_BAR; PG8_SCHED;
.LBB0_1220:
	ds_read_b128 v[128:131], v162
	ds_read_b128 v[132:135], v162 offset:1024
	ds_read_b128 v[154:157], v162 offset:2048
	ds_read_b128 v[168:171], v162 offset:3072
	s_add_u32 s24, s22, 0xfff80080
	s_addc_u32 s25, s23, -1
	s_cmp_eq_u32 s67, 28
	s_cselect_b32 s31, s13, s25
	s_cselect_b32 s30, s19, s24
	s_cselect_b32 s25, s11, s66
	s_cselect_b32 s24, s64, s65
	v_lshl_add_u64 v[158:159], s[22:23], 0, v[146:147]
	s_add_i32 m0, s21, 0xc000
	ds_read_b128 v[172:175], v163
	ds_read_b128 v[180:183], v163 offset:1024
	ds_read_b128 v[184:187], v163 offset:2048
	ds_read_b128 v[188:191], v163 offset:3072
	ds_read_b128 v[192:195], v163 offset:4096
	ds_read_b128 v[196:199], v163 offset:5120
	ds_read_b128 v[200:203], v163 offset:6144
	ds_read_b128 v[204:207], v163 offset:7168
	global_load_lds_dwordx4 v[158:159], off
	v_lshl_add_u64 v[158:159], s[22:23], 0, v[148:149]
	s_add_i32 m0, s21, 0xe000
	s_nop 0
	global_load_lds_dwordx4 v[158:159], off
	s_waitcnt lgkmcnt(8)
	s_setprio 1
	s_barrier
	s_waitcnt lgkmcnt(0)


; #define PG8_MMA(ai, bj, At, Bt) do { __builtin_amdgcn_s_setprio(1); _Pragma("unroll") for (int m = 0; m < 4; ++m) _Pragma("unroll") for (int n = 0; n < 2; ++n) _Pragma("unroll") for (int k = 0; k < 2; ++k) \
;         acc[ai][bj][m][n] = __builtin_amdgcn_mfma_f32_16x16x32_bf16(Bt[n][k], At[m][k], acc[ai][bj][m][n], 0, 0, 0); __builtin_amdgcn_s_setprio(0); } while (0)
; #define PG8_WAIT_L(n) asm volatile("s_waitcnt lgkmcnt(" #n ")" ::: "memory")
; #define PG8_BAR __builtin_amdgcn_s_barrier()
; #define PG8_SCHED __builtin_amdgcn_sched_barrier(0)
; template <class Epi>
; __device__ __forceinline__ void gemm_phase(LAS unsigned char* lds, const Gemm g, const StaticOrder& S, const Epi& E) {
;     ...
;             PG8_WAIT_L(8); PG8_BAR; PG8_WAIT_L(0); PG8_MMA(0, 0, At, B0); PG8_BAR; PG8_SCHED;
	v_mfma_f32_16x16x32_bf16 v[124:127], v[128:131], v[172:175], v[124:127]
	v_mfma_f32_16x16x32_bf16 v[120:123], v[154:157], v[172:175], v[120:123]
	v_mfma_f32_16x16x32_bf16 v[108:111], v[128:131], v[184:187], v[108:111]
	v_mfma_f32_16x16x32_bf16 v[104:107], v[154:157], v[184:187], v[104:107]
	v_mfma_f32_16x16x32_bf16 v[92:95], v[128:131], v[192:195], v[92:95]
	v_mfma_f32_16x16x32_bf16 v[88:91], v[154:157], v[192:195], v[88:91]
	v_mfma_f32_16x16x32_bf16 v[76:79], v[128:131], v[200:203], v[76:79]
	v_mfma_f32_16x16x32_bf16 v[72:75], v[154:157], v[200:203], v[72:75]
	v_mfma_f32_16x16x32_bf16 v[124:127], v[132:135], v[180:183], v[124:127]
	v_mfma_f32_16x16x32_bf16 v[120:123], v[168:171], v[180:183], v[120:123]
	v_mfma_f32_16x16x32_bf16 v[108:111], v[132:135], v[188:191], v[108:111]
	v_mfma_f32_16x16x32_bf16 v[104:107], v[168:171], v[188:191], v[104:107]
	v_mfma_f32_16x16x32_bf16 v[92:95], v[132:135], v[196:199], v[92:95]
	v_mfma_f32_16x16x32_bf16 v[88:91], v[168:171], v[196:199], v[88:91]
	v_mfma_f32_16x16x32_bf16 v[76:79], v[132:135], v[204:207], v[76:79]
	v_mfma_f32_16x16x32_bf16 v[72:75], v[168:171], v[204:207], v[72:75]
	s_barrier
	s_setprio 0

; #define PG8_STAGE(bufoff, gbase, voff) do { _Pragma("unroll") for (int _i = 0; _i < 2; ++_i) \
;         __builtin_amdgcn_global_load_lds((const unsigned*)((const char*)(gbase) + (voff)[_i]), (LAS unsigned*)(lds + (bufoff) + ldsw + _i * 8192), 16, 0, 0); } while (0)
; #define PG8_LDB(dst, b, h) do { _Pragma("unroll") for (int n = 0; n < 2; ++n) _Pragma("unroll") for (int k = 0; k < 2; ++k) dst[n][k] = *(const LAS bf16x8*)(lds + PG8_SB(b, h) + boff + n * 2048 + k * 1024); } while (0)
; #define PG8_MMA(ai, bj, At, Bt) do { __builtin_amdgcn_s_setprio(1); _Pragma("unroll") for (int m = 0; m < 4; ++m) _Pragma("unroll") for (int n = 0; n < 2; ++n) _Pragma("unroll") for (int k = 0; k < 2; ++k) \
;         acc[ai][bj][m][n] = __builtin_amdgcn_mfma_f32_16x16x32_bf16(Bt[n][k], At[m][k], acc[ai][bj][m][n], 0, 0, 0); __builtin_amdgcn_s_setprio(0); } while (0)
; #define PG8_WAIT_L(n) asm volatile("s_waitcnt lgkmcnt(" #n ")" ::: "memory")
; #define PG8_BAR __builtin_amdgcn_s_barrier()
; template <class Epi>
; __device__ __forceinline__ void gemm_phase(LAS unsigned char* lds, const Gemm g, const StaticOrder& S, const Epi& E) {
;     ...
;             PG8_LDB(B1, 0, 1); PG8_STAGE(PG8_SB(0, 0), b2, voffB);
;             PG8_BAR; PG8_WAIT_L(0); PG8_MMA(0, 1, At, B1); PG8_BAR;
	s_add_i32 s68, s62, s36
	v_lshl_add_u64 v[158:159], s[24:25], 0, v[140:141]
	s_mov_b32 m0, s68
	ds_read_b128 v[208:211], v165
	ds_read_b128 v[212:215], v165 offset:1024
	ds_read_b128 v[216:219], v165 offset:2048
	ds_read_b128 v[220:223], v165 offset:3072
	global_load_lds_dwordx4 v[158:159], off
	v_lshl_add_u64 v[176:177], s[24:25], 0, v[144:145]
	s_add_i32 m0, s68, 0x2000
	s_nop 0
	global_load_lds_dwordx4 v[176:177], off
	s_waitcnt lgkmcnt(0)
	s_setprio 1
	s_barrier


; #define PG8_MMA(ai, bj, At, Bt) do { __builtin_amdgcn_s_setprio(1); _Pragma("unroll") for (int m = 0; m < 4; ++m) _Pragma("unroll") for (int n = 0; n < 2; ++n) _Pragma("unroll") for (int k = 0; k < 2; ++k) \
;         acc[ai][bj][m][n] = __builtin_amdgcn_mfma_f32_16x16x32_bf16(Bt[n][k], At[m][k], acc[ai][bj][m][n], 0, 0, 0); __builtin_amdgcn_s_setprio(0); } while (0)
; #define PG8_WAIT_L(n) asm volatile("s_waitcnt lgkmcnt(" #n ")" ::: "memory")
; #define PG8_BAR __builtin_amdgcn_s_barrier()
; template <class Epi>
; __device__ __forceinline__ void gemm_phase(LAS unsigned char* lds, const Gemm g, const StaticOrder& S, const Epi& E) {
;     ...
;             PG8_BAR; PG8_WAIT_L(0); PG8_MMA(0, 1, At, B1); PG8_BAR;
	v_mfma_f32_16x16x32_bf16 v[116:119], v[208:211], v[172:175], v[116:119]
	v_mfma_f32_16x16x32_bf16 v[112:115], v[216:219], v[172:175], v[112:115]
	v_mfma_f32_16x16x32_bf16 v[100:103], v[208:211], v[184:187], v[100:103]
	v_mfma_f32_16x16x32_bf16 v[96:99], v[216:219], v[184:187], v[96:99]
	v_mfma_f32_16x16x32_bf16 v[84:87], v[208:211], v[192:195], v[84:87]
	v_mfma_f32_16x16x32_bf16 v[80:83], v[216:219], v[192:195], v[80:83]
	v_mfma_f32_16x16x32_bf16 v[68:71], v[208:211], v[200:203], v[68:71]
	v_mfma_f32_16x16x32_bf16 v[64:67], v[216:219], v[200:203], v[64:67]
	v_mfma_f32_16x16x32_bf16 v[116:119], v[212:215], v[180:183], v[116:119]
	v_mfma_f32_16x16x32_bf16 v[112:115], v[220:223], v[180:183], v[112:115]
	v_mfma_f32_16x16x32_bf16 v[100:103], v[212:215], v[188:191], v[100:103]
	v_mfma_f32_16x16x32_bf16 v[96:99], v[220:223], v[188:191], v[96:99]
	v_mfma_f32_16x16x32_bf16 v[84:87], v[212:215], v[196:199], v[84:87]
	v_mfma_f32_16x16x32_bf16 v[80:83], v[220:223], v[196:199], v[80:83]
	v_mfma_f32_16x16x32_bf16 v[68:71], v[212:215], v[204:207], v[68:71]
	v_mfma_f32_16x16x32_bf16 v[64:67], v[220:223], v[204:207], v[64:67]
	s_barrier
	s_setprio 0
	s_mov_b32 m0, s21
	v_lshl_add_u64 v[224:225], s[30:31], 0, v[138:139]


; #define PG8_STAGE(bufoff, gbase, voff) do { _Pragma("unroll") for (int _i = 0; _i < 2; ++_i) \
;         __builtin_amdgcn_global_load_lds((const unsigned*)((const char*)(gbase) + (voff)[_i]), (LAS unsigned*)(lds + (bufoff) + ldsw + _i * 8192), 16, 0, 0); } while (0)
; #define PG8_LDA(dst, b, h) do { _Pragma("unroll") for (int m = 0; m < 4; ++m) _Pragma("unroll") for (int k = 0; k < 2; ++k) dst[m][k] = *(const LAS bf16x8*)(lds + PG8_SA(b, h) + aoff + m * 2048 + k * 1024); } while (0)
; #define PG8_MMA(ai, bj, At, Bt) do { __builtin_amdgcn_s_setprio(1); _Pragma("unroll") for (int m = 0; m < 4; ++m) _Pragma("unroll") for (int n = 0; n < 2; ++n) _Pragma("unroll") for (int k = 0; k < 2; ++k) \
;         acc[ai][bj][m][n] = __builtin_amdgcn_mfma_f32_16x16x32_bf16(Bt[n][k], At[m][k], acc[ai][bj][m][n], 0, 0, 0); __builtin_amdgcn_s_setprio(0); } while (0)
; #define PG8_WAIT_L(n) asm volatile("s_waitcnt lgkmcnt(" #n ")" ::: "memory")
; #define PG8_BAR __builtin_amdgcn_s_barrier()
; #define PG8_SCHED __builtin_amdgcn_sched_barrier(0)
; template <class Epi>
; __device__ __forceinline__ void gemm_phase(LAS unsigned char* lds, const Gemm g, const StaticOrder& S, const Epi& E) {
;     ...
;             PG8_LDA(At, 0, 1); PG8_STAGE(PG8_SA(0, 0), a2, voffA);
;             PG8_BAR; PG8_WAIT_L(0); PG8_MMA(1, 0, At, B0); PG8_BAR; PG8_SCHED;
	ds_read_b128 v[172:175], v163 offset:16384
	ds_read_b128 v[180:183], v163 offset:17408
	ds_read_b128 v[184:187], v163 offset:18432
	ds_read_b128 v[188:191], v163 offset:19456
	ds_read_b128 v[192:195], v163 offset:20480
	ds_read_b128 v[196:199], v163 offset:21504
	ds_read_b128 v[200:203], v163 offset:22528
	ds_read_b128 v[204:207], v163 offset:23552
	global_load_lds_dwordx4 v[224:225], off
	v_lshl_add_u64 v[226:227], s[30:31], 0, v[142:143]
	s_mov_b32 m0, s39
	s_nop 0
	global_load_lds_dwordx4 v[226:227], off
	s_waitcnt lgkmcnt(0)
	s_setprio 1
	s_barrier


; #define PG8_MMA(ai, bj, At, Bt) do { __builtin_amdgcn_s_setprio(1); _Pragma("unroll") for (int m = 0; m < 4; ++m) _Pragma("unroll") for (int n = 0; n < 2; ++n) _Pragma("unroll") for (int k = 0; k < 2; ++k) \
;         acc[ai][bj][m][n] = __builtin_amdgcn_mfma_f32_16x16x32_bf16(Bt[n][k], At[m][k], acc[ai][bj][m][n], 0, 0, 0); __builtin_amdgcn_s_setprio(0); } while (0)
; #define PG8_WAIT_L(n) asm volatile("s_waitcnt lgkmcnt(" #n ")" ::: "memory")
; #define PG8_BAR __builtin_amdgcn_s_barrier()
; #define PG8_SCHED __builtin_amdgcn_sched_barrier(0)
; template <class Epi>
; __device__ __forceinline__ void gemm_phase(LAS unsigned char* lds, const Gemm g, const StaticOrder& S, const Epi& E) {
;     ...
;             PG8_BAR; PG8_WAIT_L(0); PG8_MMA(1, 0, At, B0); PG8_BAR; PG8_SCHED;
	v_mfma_f32_16x16x32_bf16 v[60:63], v[128:131], v[172:175], v[60:63]
	v_mfma_f32_16x16x32_bf16 v[56:59], v[154:157], v[172:175], v[56:59]
	v_mfma_f32_16x16x32_bf16 v[44:47], v[128:131], v[184:187], v[44:47]
	v_mfma_f32_16x16x32_bf16 v[40:43], v[154:157], v[184:187], v[40:43]
	v_mfma_f32_16x16x32_bf16 v[28:31], v[128:131], v[192:195], v[28:31]
	v_mfma_f32_16x16x32_bf16 v[24:27], v[154:157], v[192:195], v[24:27]
	v_mfma_f32_16x16x32_bf16 v[12:15], v[128:131], v[200:203], v[12:15]
	v_mfma_f32_16x16x32_bf16 v[8:11], v[154:157], v[200:203], v[8:11]
	v_mfma_f32_16x16x32_bf16 v[60:63], v[132:135], v[180:183], v[60:63]
	v_mfma_f32_16x16x32_bf16 v[56:59], v[168:171], v[180:183], v[56:59]
	v_mfma_f32_16x16x32_bf16 v[44:47], v[132:135], v[188:191], v[44:47]
	v_mfma_f32_16x16x32_bf16 v[40:43], v[168:171], v[188:191], v[40:43]
	v_mfma_f32_16x16x32_bf16 v[28:31], v[132:135], v[196:199], v[28:31]
	v_mfma_f32_16x16x32_bf16 v[24:27], v[168:171], v[196:199], v[24:27]
	v_mfma_f32_16x16x32_bf16 v[12:15], v[132:135], v[204:207], v[12:15]
	v_mfma_f32_16x16x32_bf16 v[8:11], v[168:171], v[204:207], v[8:11]
	s_barrier
	s_setprio 0

; #define PG8_STAGE(bufoff, gbase, voff) do { _Pragma("unroll") for (int _i = 0; _i < 2; ++_i) \
;         __builtin_amdgcn_global_load_lds((const unsigned*)((const char*)(gbase) + (voff)[_i]), (LAS unsigned*)(lds + (bufoff) + ldsw + _i * 8192), 16, 0, 0); } while (0)
; #define PG8_MMA(ai, bj, At, Bt) do { __builtin_amdgcn_s_setprio(1); _Pragma("unroll") for (int m = 0; m < 4; ++m) _Pragma("unroll") for (int n = 0; n < 2; ++n) _Pragma("unroll") for (int k = 0; k < 2; ++k) \
;         acc[ai][bj][m][n] = __builtin_amdgcn_mfma_f32_16x16x32_bf16(Bt[n][k], At[m][k], acc[ai][bj][m][n], 0, 0, 0); __builtin_amdgcn_s_setprio(0); } while (0)
; #define PG8_WAIT_V(n) asm volatile("s_waitcnt vmcnt(" #n ")" ::: "memory")
; #define PG8_BAR __builtin_amdgcn_s_barrier()
; template <class Epi>
; __device__ __forceinline__ void gemm_phase(LAS unsigned char* lds, const Gemm g, const StaticOrder& S, const Epi& E) {
;     ...
;             PG8_STAGE(PG8_SB(0, 1), b2 + hstep, voffB);
;             PG8_WAIT_V(6); PG8_BAR; PG8_MMA(1, 1, At, B1); PG8_BAR;
	s_add_u32 s68, s24, 0x80000
	s_addc_u32 s69, s25, 0
	s_add_i32 s70, s63, s36
	v_lshl_add_u64 v[128:129], s[68:69], 0, v[140:141]
	s_mov_b32 m0, s70
	s_nop 0
	global_load_lds_dwordx4 v[128:129], off
	v_lshl_add_u64 v[128:129], s[68:69], 0, v[144:145]
	s_add_i32 m0, s70, 0x2000
	s_nop 0
	global_load_lds_dwordx4 v[128:129], off
	s_waitcnt vmcnt(6)
	s_setprio 1
	s_barrier

; #define PG8_MMA(ai, bj, At, Bt) do { __builtin_amdgcn_s_setprio(1); _Pragma("unroll") for (int m = 0; m < 4; ++m) _Pragma("unroll") for (int n = 0; n < 2; ++n) _Pragma("unroll") for (int k = 0; k < 2; ++k) \
;         acc[ai][bj][m][n] = __builtin_amdgcn_mfma_f32_16x16x32_bf16(Bt[n][k], At[m][k], acc[ai][bj][m][n], 0, 0, 0); __builtin_amdgcn_s_setprio(0); } while (0)
; #define PG8_WAIT_V(n) asm volatile("s_waitcnt vmcnt(" #n ")" ::: "memory")
; #define PG8_BAR __builtin_amdgcn_s_barrier()
; template <class Epi>
; __device__ __forceinline__ void gemm_phase(LAS unsigned char* lds, const Gemm g, const StaticOrder& S, const Epi& E) {
;     ...
;             PG8_WAIT_V(6); PG8_BAR; PG8_MMA(1, 1, At, B1); PG8_BAR;
	v_mfma_f32_16x16x32_bf16 v[52:55], v[208:211], v[172:175], v[52:55]
	v_mfma_f32_16x16x32_bf16 v[48:51], v[216:219], v[172:175], v[48:51]
	v_mfma_f32_16x16x32_bf16 v[36:39], v[208:211], v[184:187], v[36:39]
	v_mfma_f32_16x16x32_bf16 v[32:35], v[216:219], v[184:187], v[32:35]
	v_mfma_f32_16x16x32_bf16 v[20:23], v[208:211], v[192:195], v[20:23]
	v_mfma_f32_16x16x32_bf16 v[16:19], v[216:219], v[192:195], v[16:19]
	v_mfma_f32_16x16x32_bf16 v[4:7], v[208:211], v[200:203], v[4:7]
	v_mfma_f32_16x16x32_bf16 v[0:3], v[216:219], v[200:203], v[0:3]
	v_mfma_f32_16x16x32_bf16 v[52:55], v[212:215], v[180:183], v[52:55]
	v_mfma_f32_16x16x32_bf16 v[48:51], v[220:223], v[180:183], v[48:51]
	v_mfma_f32_16x16x32_bf16 v[36:39], v[212:215], v[188:191], v[36:39]
	v_mfma_f32_16x16x32_bf16 v[32:35], v[220:223], v[188:191], v[32:35]
	v_mfma_f32_16x16x32_bf16 v[20:23], v[212:215], v[196:199], v[20:23]
	v_mfma_f32_16x16x32_bf16 v[16:19], v[220:223], v[196:199], v[16:19]
	v_mfma_f32_16x16x32_bf16 v[4:7], v[212:215], v[204:207], v[4:7]
	v_mfma_f32_16x16x32_bf16 v[0:3], v[220:223], v[204:207], v[0:3]
	s_barrier
	s_setprio 0
	s_add_i32 s68, 0, 0x18000
	v_add_u32_e32 v167, s68, v137


; #define PG8_STAGE(bufoff, gbase, voff) do { _Pragma("unroll") for (int _i = 0; _i < 2; ++_i) \
;         __builtin_amdgcn_global_load_lds((const unsigned*)((const char*)(gbase) + (voff)[_i]), (LAS unsigned*)(lds + (bufoff) + ldsw + _i * 8192), 16, 0, 0); } while (0)
; #define PG8_LDA(dst, b, h) do { _Pragma("unroll") for (int m = 0; m < 4; ++m) _Pragma("unroll") for (int k = 0; k < 2; ++k) dst[m][k] = *(const LAS bf16x8*)(lds + PG8_SA(b, h) + aoff + m * 2048 + k * 1024); } while (0)
; #define PG8_LDB(dst, b, h) do { _Pragma("unroll") for (int n = 0; n < 2; ++n) _Pragma("unroll") for (int k = 0; k < 2; ++k) dst[n][k] = *(const LAS bf16x8*)(lds + PG8_SB(b, h) + boff + n * 2048 + k * 1024); } while (0)
; #define PG8_MMA(ai, bj, At, Bt) do { __builtin_amdgcn_s_setprio(1); _Pragma("unroll") for (int m = 0; m < 4; ++m) _Pragma("unroll") for (int n = 0; n < 2; ++n) _Pragma("unroll") for (int k = 0; k < 2; ++k) \
;         acc[ai][bj][m][n] = __builtin_amdgcn_mfma_f32_16x16x32_bf16(Bt[n][k], At[m][k], acc[ai][bj][m][n], 0, 0, 0); __builtin_amdgcn_s_setprio(0); } while (0)
; #define PG8_WAIT_L(n) asm volatile("s_waitcnt lgkmcnt(" #n ")" ::: "memory")
; #define PG8_BAR __builtin_amdgcn_s_barrier()
; #define PG8_SCHED __builtin_amdgcn_sched_barrier(0)
; template <class Epi>
; __device__ __forceinline__ void gemm_phase(LAS unsigned char* lds, const Gemm g, const StaticOrder& S, const Epi& E) {
;     ...
;             PG8_LDB(B0, 1, 0); PG8_SCHED; PG8_LDA(At, 1, 0); PG8_STAGE(PG8_SA(0, 1), a2 + hstep, voffA);
;             PG8_WAIT_L(8); PG8_BAR; PG8_WAIT_L(0); PG8_MMA(0, 0, At, B0); PG8_BAR; PG8_SCHED;
	ds_read_b128 v[128:131], v167
	ds_read_b128 v[132:135], v167 offset:1024
	ds_read_b128 v[154:157], v167 offset:2048
	ds_read_b128 v[168:171], v167 offset:3072
	s_add_u32 s30, s30, 0x80000
	s_addc_u32 s31, s31, 0
	s_mov_b32 m0, s42
	v_lshl_add_u64 v[208:209], s[30:31], 0, v[138:139]
	ds_read_b128 v[172:175], v163 offset:32768
	ds_read_b128 v[180:183], v163 offset:33792
	ds_read_b128 v[184:187], v163 offset:34816
	ds_read_b128 v[188:191], v163 offset:35840
	ds_read_b128 v[192:195], v163 offset:36864
	ds_read_b128 v[196:199], v163 offset:37888
	ds_read_b128 v[200:203], v163 offset:38912
	ds_read_b128 v[204:207], v163 offset:39936
	global_load_lds_dwordx4 v[208:209], off
	v_lshl_add_u64 v[208:209], s[30:31], 0, v[142:143]
	s_mov_b32 m0, s43
	s_nop 0
	global_load_lds_dwordx4 v[208:209], off
	s_waitcnt lgkmcnt(8)
	s_setprio 1
	s_barrier
	s_waitcnt lgkmcnt(0)


; #define PG8_MMA(ai, bj, At, Bt) do { __builtin_amdgcn_s_setprio(1); _Pragma("unroll") for (int m = 0; m < 4; ++m) _Pragma("unroll") for (int n = 0; n < 2; ++n) _Pragma("unroll") for (int k = 0; k < 2; ++k) \
;         acc[ai][bj][m][n] = __builtin_amdgcn_mfma_f32_16x16x32_bf16(Bt[n][k], At[m][k], acc[ai][bj][m][n], 0, 0, 0); __builtin_amdgcn_s_setprio(0); } while (0)
; #define PG8_WAIT_L(n) asm volatile("s_waitcnt lgkmcnt(" #n ")" ::: "memory")
; #define PG8_BAR __builtin_amdgcn_s_barrier()
; #define PG8_SCHED __builtin_amdgcn_sched_barrier(0)
; template <class Epi>
; __device__ __forceinline__ void gemm_phase(LAS unsigned char* lds, const Gemm g, const StaticOrder& S, const Epi& E) {
;     ...
;             PG8_WAIT_L(8); PG8_BAR; PG8_WAIT_L(0); PG8_MMA(0, 0, At, B0); PG8_BAR; PG8_SCHED;
	v_mfma_f32_16x16x32_bf16 v[124:127], v[128:131], v[172:175], v[124:127]
	v_mfma_f32_16x16x32_bf16 v[120:123], v[154:157], v[172:175], v[120:123]
	v_mfma_f32_16x16x32_bf16 v[108:111], v[128:131], v[184:187], v[108:111]
	v_mfma_f32_16x16x32_bf16 v[104:107], v[154:157], v[184:187], v[104:107]
	v_mfma_f32_16x16x32_bf16 v[92:95], v[128:131], v[192:195], v[92:95]
	v_mfma_f32_16x16x32_bf16 v[88:91], v[154:157], v[192:195], v[88:91]
	v_mfma_f32_16x16x32_bf16 v[76:79], v[128:131], v[200:203], v[76:79]
	v_mfma_f32_16x16x32_bf16 v[72:75], v[154:157], v[200:203], v[72:75]
	v_mfma_f32_16x16x32_bf16 v[124:127], v[132:135], v[180:183], v[124:127]
	v_mfma_f32_16x16x32_bf16 v[120:123], v[168:171], v[180:183], v[120:123]
	v_mfma_f32_16x16x32_bf16 v[108:111], v[132:135], v[188:191], v[108:111]
	v_mfma_f32_16x16x32_bf16 v[104:107], v[168:171], v[188:191], v[104:107]
	v_mfma_f32_16x16x32_bf16 v[92:95], v[132:135], v[196:199], v[92:95]
	v_mfma_f32_16x16x32_bf16 v[88:91], v[168:171], v[196:199], v[88:91]
	v_mfma_f32_16x16x32_bf16 v[76:79], v[132:135], v[204:207], v[76:79]
	v_mfma_f32_16x16x32_bf16 v[72:75], v[168:171], v[204:207], v[72:75]
	s_barrier
	s_setprio 0

; #define PG8_STAGE(bufoff, gbase, voff) do { _Pragma("unroll") for (int _i = 0; _i < 2; ++_i) \
;         __builtin_amdgcn_global_load_lds((const unsigned*)((const char*)(gbase) + (voff)[_i]), (LAS unsigned*)(lds + (bufoff) + ldsw + _i * 8192), 16, 0, 0); } while (0)
; #define PG8_LDB(dst, b, h) do { _Pragma("unroll") for (int n = 0; n < 2; ++n) _Pragma("unroll") for (int k = 0; k < 2; ++k) dst[n][k] = *(const LAS bf16x8*)(lds + PG8_SB(b, h) + boff + n * 2048 + k * 1024); } while (0)
; #define PG8_MMA(ai, bj, At, Bt) do { __builtin_amdgcn_s_setprio(1); _Pragma("unroll") for (int m = 0; m < 4; ++m) _Pragma("unroll") for (int n = 0; n < 2; ++n) _Pragma("unroll") for (int k = 0; k < 2; ++k) \
;         acc[ai][bj][m][n] = __builtin_amdgcn_mfma_f32_16x16x32_bf16(Bt[n][k], At[m][k], acc[ai][bj][m][n], 0, 0, 0); __builtin_amdgcn_s_setprio(0); } while (0)
; #define PG8_WAIT_L(n) asm volatile("s_waitcnt lgkmcnt(" #n ")" ::: "memory")
; #define PG8_BAR __builtin_amdgcn_s_barrier()
; template <class Epi>
; __device__ __forceinline__ void gemm_phase(LAS unsigned char* lds, const Gemm g, const StaticOrder& S, const Epi& E) {
;     ...
;             PG8_LDB(B1, 1, 1); PG8_STAGE(PG8_SB(1, 0), b3, voffB);
;             PG8_BAR; PG8_WAIT_L(0); PG8_MMA(0, 1, At, B1); PG8_BAR;
	s_add_i32 s30, 0, 0x1c000
	s_add_i32 s31, s68, s36
	v_add_u32_e32 v167, s30, v137
	v_lshl_add_u64 v[158:159], v[158:159], 0, s[8:9]
	s_mov_b32 m0, s31
	ds_read_b128 v[208:211], v167
	ds_read_b128 v[212:215], v167 offset:1024
	ds_read_b128 v[216:219], v167 offset:2048
	ds_read_b128 v[220:223], v167 offset:3072
	global_load_lds_dwordx4 v[158:159], off
	v_lshl_add_u64 v[158:159], v[176:177], 0, s[8:9]
	s_add_i32 m0, s31, 0x2000
	s_nop 0
	global_load_lds_dwordx4 v[158:159], off
	s_waitcnt lgkmcnt(0)
	s_setprio 1
	s_barrier


; #define PG8_MMA(ai, bj, At, Bt) do { __builtin_amdgcn_s_setprio(1); _Pragma("unroll") for (int m = 0; m < 4; ++m) _Pragma("unroll") for (int n = 0; n < 2; ++n) _Pragma("unroll") for (int k = 0; k < 2; ++k) \
;         acc[ai][bj][m][n] = __builtin_amdgcn_mfma_f32_16x16x32_bf16(Bt[n][k], At[m][k], acc[ai][bj][m][n], 0, 0, 0); __builtin_amdgcn_s_setprio(0); } while (0)
; #define PG8_WAIT_L(n) asm volatile("s_waitcnt lgkmcnt(" #n ")" ::: "memory")
; #define PG8_BAR __builtin_amdgcn_s_barrier()
; template <class Epi>
; __device__ __forceinline__ void gemm_phase(LAS unsigned char* lds, const Gemm g, const StaticOrder& S, const Epi& E) {
;     ...
;             PG8_BAR; PG8_WAIT_L(0); PG8_MMA(0, 1, At, B1); PG8_BAR;
	v_mfma_f32_16x16x32_bf16 v[116:119], v[208:211], v[172:175], v[116:119]
	v_mfma_f32_16x16x32_bf16 v[112:115], v[216:219], v[172:175], v[112:115]
	v_mfma_f32_16x16x32_bf16 v[100:103], v[208:211], v[184:187], v[100:103]
	v_mfma_f32_16x16x32_bf16 v[96:99], v[216:219], v[184:187], v[96:99]
	v_mfma_f32_16x16x32_bf16 v[84:87], v[208:211], v[192:195], v[84:87]
	v_mfma_f32_16x16x32_bf16 v[80:83], v[216:219], v[192:195], v[80:83]
	v_mfma_f32_16x16x32_bf16 v[68:71], v[208:211], v[200:203], v[68:71]
	v_mfma_f32_16x16x32_bf16 v[64:67], v[216:219], v[200:203], v[64:67]
	v_mfma_f32_16x16x32_bf16 v[116:119], v[212:215], v[180:183], v[116:119]
	v_mfma_f32_16x16x32_bf16 v[112:115], v[220:223], v[180:183], v[112:115]
	v_mfma_f32_16x16x32_bf16 v[100:103], v[212:215], v[188:191], v[100:103]
	v_mfma_f32_16x16x32_bf16 v[96:99], v[220:223], v[188:191], v[96:99]
	v_mfma_f32_16x16x32_bf16 v[84:87], v[212:215], v[196:199], v[84:87]
	v_mfma_f32_16x16x32_bf16 v[80:83], v[220:223], v[196:199], v[80:83]
	v_mfma_f32_16x16x32_bf16 v[68:71], v[212:215], v[204:207], v[68:71]
	v_mfma_f32_16x16x32_bf16 v[64:67], v[220:223], v[204:207], v[64:67]
	s_barrier
	s_setprio 0
	s_mov_b32 m0, s57
	v_lshl_add_u64 v[158:159], v[224:225], 0, s[8:9]


; #define PG8_STAGE(bufoff, gbase, voff) do { _Pragma("unroll") for (int _i = 0; _i < 2; ++_i) \
;         __builtin_amdgcn_global_load_lds((const unsigned*)((const char*)(gbase) + (voff)[_i]), (LAS unsigned*)(lds + (bufoff) + ldsw + _i * 8192), 16, 0, 0); } while (0)
; #define PG8_LDA(dst, b, h) do { _Pragma("unroll") for (int m = 0; m < 4; ++m) _Pragma("unroll") for (int k = 0; k < 2; ++k) dst[m][k] = *(const LAS bf16x8*)(lds + PG8_SA(b, h) + aoff + m * 2048 + k * 1024); } while (0)
; #define PG8_MMA(ai, bj, At, Bt) do { __builtin_amdgcn_s_setprio(1); _Pragma("unroll") for (int m = 0; m < 4; ++m) _Pragma("unroll") for (int n = 0; n < 2; ++n) _Pragma("unroll") for (int k = 0; k < 2; ++k) \
;         acc[ai][bj][m][n] = __builtin_amdgcn_mfma_f32_16x16x32_bf16(Bt[n][k], At[m][k], acc[ai][bj][m][n], 0, 0, 0); __builtin_amdgcn_s_setprio(0); } while (0)
; #define PG8_WAIT_L(n) asm volatile("s_waitcnt lgkmcnt(" #n ")" ::: "memory")
; #define PG8_BAR __builtin_amdgcn_s_barrier()
; #define PG8_SCHED __builtin_amdgcn_sched_barrier(0)
; template <class Epi>
; __device__ __forceinline__ void gemm_phase(LAS unsigned char* lds, const Gemm g, const StaticOrder& S, const Epi& E) {
;     ...
;             PG8_LDA(At, 1, 1); PG8_STAGE(PG8_SA(1, 0), a3, voffA);
;             PG8_BAR; PG8_WAIT_L(0); PG8_MMA(1, 0, At, B0); PG8_BAR; PG8_SCHED;
	ds_read_b128 v[172:175], v163 offset:49152
	ds_read_b128 v[180:183], v163 offset:50176
	ds_read_b128 v[184:187], v163 offset:51200
	ds_read_b128 v[188:191], v163 offset:52224
	ds_read_b128 v[192:195], v163 offset:53248
	ds_read_b128 v[196:199], v163 offset:54272
	ds_read_b128 v[200:203], v163 offset:55296
	ds_read_b128 v[204:207], v163 offset:56320
	global_load_lds_dwordx4 v[158:159], off
	v_lshl_add_u64 v[158:159], v[226:227], 0, s[8:9]
	s_mov_b32 m0, s58
	s_nop 0
	global_load_lds_dwordx4 v[158:159], off
	s_waitcnt lgkmcnt(0)
	s_setprio 1
	s_barrier


; #define PG8_MMA(ai, bj, At, Bt) do { __builtin_amdgcn_s_setprio(1); _Pragma("unroll") for (int m = 0; m < 4; ++m) _Pragma("unroll") for (int n = 0; n < 2; ++n) _Pragma("unroll") for (int k = 0; k < 2; ++k) \
;         acc[ai][bj][m][n] = __builtin_amdgcn_mfma_f32_16x16x32_bf16(Bt[n][k], At[m][k], acc[ai][bj][m][n], 0, 0, 0); __builtin_amdgcn_s_setprio(0); } while (0)
; #define PG8_WAIT_L(n) asm volatile("s_waitcnt lgkmcnt(" #n ")" ::: "memory")
; #define PG8_BAR __builtin_amdgcn_s_barrier()
; #define PG8_SCHED __builtin_amdgcn_sched_barrier(0)
; template <class Epi>
; __device__ __forceinline__ void gemm_phase(LAS unsigned char* lds, const Gemm g, const StaticOrder& S, const Epi& E) {
;     ...
;             PG8_BAR; PG8_WAIT_L(0); PG8_MMA(1, 0, At, B0); PG8_BAR; PG8_SCHED;
	v_mfma_f32_16x16x32_bf16 v[60:63], v[128:131], v[172:175], v[60:63]
	v_mfma_f32_16x16x32_bf16 v[56:59], v[154:157], v[172:175], v[56:59]
	v_mfma_f32_16x16x32_bf16 v[44:47], v[128:131], v[184:187], v[44:47]
	v_mfma_f32_16x16x32_bf16 v[40:43], v[154:157], v[184:187], v[40:43]
	v_mfma_f32_16x16x32_bf16 v[28:31], v[128:131], v[192:195], v[28:31]
	v_mfma_f32_16x16x32_bf16 v[24:27], v[154:157], v[192:195], v[24:27]
	v_mfma_f32_16x16x32_bf16 v[12:15], v[128:131], v[200:203], v[12:15]
	v_mfma_f32_16x16x32_bf16 v[8:11], v[154:157], v[200:203], v[8:11]
	v_mfma_f32_16x16x32_bf16 v[60:63], v[132:135], v[180:183], v[60:63]
	v_mfma_f32_16x16x32_bf16 v[56:59], v[168:171], v[180:183], v[56:59]
	v_mfma_f32_16x16x32_bf16 v[44:47], v[132:135], v[188:191], v[44:47]
	v_mfma_f32_16x16x32_bf16 v[40:43], v[168:171], v[188:191], v[40:43]
	v_mfma_f32_16x16x32_bf16 v[28:31], v[132:135], v[196:199], v[28:31]
	v_mfma_f32_16x16x32_bf16 v[24:27], v[168:171], v[196:199], v[24:27]
	v_mfma_f32_16x16x32_bf16 v[12:15], v[132:135], v[204:207], v[12:15]
	v_mfma_f32_16x16x32_bf16 v[8:11], v[168:171], v[204:207], v[8:11]
	s_barrier
	s_setprio 0

; #define PG8_STAGE(bufoff, gbase, voff) do { _Pragma("unroll") for (int _i = 0; _i < 2; ++_i) \
;         __builtin_amdgcn_global_load_lds((const unsigned*)((const char*)(gbase) + (voff)[_i]), (LAS unsigned*)(lds + (bufoff) + ldsw + _i * 8192), 16, 0, 0); } while (0)
; #define PG8_MMA(ai, bj, At, Bt) do { __builtin_amdgcn_s_setprio(1); _Pragma("unroll") for (int m = 0; m < 4; ++m) _Pragma("unroll") for (int n = 0; n < 2; ++n) _Pragma("unroll") for (int k = 0; k < 2; ++k) \
;         acc[ai][bj][m][n] = __builtin_amdgcn_mfma_f32_16x16x32_bf16(Bt[n][k], At[m][k], acc[ai][bj][m][n], 0, 0, 0); __builtin_amdgcn_s_setprio(0); } while (0)
; #define PG8_WAIT_V(n) asm volatile("s_waitcnt vmcnt(" #n ")" ::: "memory")
; #define PG8_BAR __builtin_amdgcn_s_barrier()
; template <class Epi>
; __device__ __forceinline__ void gemm_phase(LAS unsigned char* lds, const Gemm g, const StaticOrder& S, const Epi& E) {
;     ...
;             PG8_STAGE(PG8_SB(1, 1), b3 + hstep, voffB);
;             PG8_WAIT_V(6); PG8_BAR; PG8_MMA(1, 1, At, B1); PG8_BAR;
	s_add_u32 s24, s24, 0x80080
	s_addc_u32 s25, s25, 0
	s_add_i32 s30, s30, s36
	v_lshl_add_u64 v[128:129], s[24:25], 0, v[140:141]
	s_mov_b32 m0, s30
	s_nop 0
	global_load_lds_dwordx4 v[128:129], off
	v_lshl_add_u64 v[128:129], s[24:25], 0, v[144:145]
	s_add_i32 m0, s30, 0x2000
	s_nop 0
	global_load_lds_dwordx4 v[128:129], off
	s_waitcnt vmcnt(6)
	s_setprio 1
	s_barrier

; #define PG8_MMA(ai, bj, At, Bt) do { __builtin_amdgcn_s_setprio(1); _Pragma("unroll") for (int m = 0; m < 4; ++m) _Pragma("unroll") for (int n = 0; n < 2; ++n) _Pragma("unroll") for (int k = 0; k < 2; ++k) \
;         acc[ai][bj][m][n] = __builtin_amdgcn_mfma_f32_16x16x32_bf16(Bt[n][k], At[m][k], acc[ai][bj][m][n], 0, 0, 0); __builtin_amdgcn_s_setprio(0); } while (0)
; #define PG8_WAIT_V(n) asm volatile("s_waitcnt vmcnt(" #n ")" ::: "memory")
; #define PG8_BAR __builtin_amdgcn_s_barrier()
; template <class Epi>
; __device__ __forceinline__ void gemm_phase(LAS unsigned char* lds, const Gemm g, const StaticOrder& S, const Epi& E) {
;     ...
;             PG8_WAIT_V(6); PG8_BAR; PG8_MMA(1, 1, At, B1); PG8_BAR;
	v_mfma_f32_16x16x32_bf16 v[52:55], v[208:211], v[172:175], v[52:55]
	v_mfma_f32_16x16x32_bf16 v[48:51], v[216:219], v[172:175], v[48:51]
	v_mfma_f32_16x16x32_bf16 v[36:39], v[208:211], v[184:187], v[36:39]
	v_mfma_f32_16x16x32_bf16 v[32:35], v[216:219], v[184:187], v[32:35]
	v_mfma_f32_16x16x32_bf16 v[20:23], v[208:211], v[192:195], v[20:23]
	v_mfma_f32_16x16x32_bf16 v[16:19], v[216:219], v[192:195], v[16:19]
	v_mfma_f32_16x16x32_bf16 v[4:7], v[208:211], v[200:203], v[4:7]
	v_mfma_f32_16x16x32_bf16 v[0:3], v[216:219], v[200:203], v[0:3]
	v_mfma_f32_16x16x32_bf16 v[52:55], v[212:215], v[180:183], v[52:55]
	v_mfma_f32_16x16x32_bf16 v[48:51], v[220:223], v[180:183], v[48:51]
	v_mfma_f32_16x16x32_bf16 v[36:39], v[212:215], v[188:191], v[36:39]
	v_mfma_f32_16x16x32_bf16 v[32:35], v[220:223], v[188:191], v[32:35]
	v_mfma_f32_16x16x32_bf16 v[20:23], v[212:215], v[196:199], v[20:23]
	v_mfma_f32_16x16x32_bf16 v[16:19], v[220:223], v[196:199], v[16:19]
	v_mfma_f32_16x16x32_bf16 v[4:7], v[212:215], v[204:207], v[4:7]
	v_mfma_f32_16x16x32_bf16 v[0:3], v[220:223], v[204:207], v[0:3]
	s_barrier
	s_setprio 0
	s_add_i32 s67, s67, 2
	s_add_u32 s22, s22, 0x100
	s_addc_u32 s23, s23, 0
	s_add_u32 s65, s65, 0x100
	s_addc_u32 s66, s66, 0
	s_cmp_gt_u32 s67, 29


; __device__ __forceinline__ float bflo(unsigned w) { return __uint_as_float(w << 16); }
; __device__ __forceinline__ float bfhi(unsigned w) { return __uint_as_float(w & 0xffff0000u); }
; #define ER_LOAD(g_, set_) do { const size_t off_ = (size_t)(row0 + ((g_) >> 2) * HALF + ((g_) & 3) * 16) * DM + col0; \
;         hv[set_][0] = *(const u32x4*)(HB + off_); hv[set_][1] = *(const u32x4*)(HB + off_ + HALF); } while (0)
;     __device__ __forceinline__ void operator()(const f32x4 (&acc)[2][2][4][2], const Unit& u, int wr, int wc, int fr, int fq, const Pre&) const {
;         const int row0 = ROW_X + u.pm * BM + wr * 64 + fr, col0 = u.pn * BM + wc * 32 + 8 * fq;
;         u32x4 hv[2][2]; float sprev = 0.f;
;     ...
;         ER_LOAD(0, 0);
; #pragma unroll
;         for (int g = 0; g < 8; ++g) { const int ai = g >> 2, m = g & 3; const int r = row0 + ai * HALF + m * 16; const size_t off = (size_t)r * DM + col0; float s = 0.f;
;             if (g + 1 < 8) ER_LOAD(g + 1, (g + 1) & 1);
; #pragma unroll
;             for (int bj = 0; bj < 2; ++bj) { const u32x4 w = hv[g & 1][bj];
;                 const f32x4 h0 = {bflo(w.x), bfhi(w.x), bflo(w.y), bfhi(w.y)}, h1 = {bflo(w.z), bfhi(w.z), bflo(w.w), bfhi(w.w)};
;                 const f32x4 o0 = h0 + acc[ai][bj][m][0] * alpha, o1 = h1 + acc[ai][bj][m][1] * alpha;
;                 if (FINAL) { float* op = OUT + (size_t)(r - ROW_X) * DM + col0 + bj * HALF; *(f32x4*)op = o0; *(f32x4*)(op + 4) = o1; }
;                 else { u32x4 q; q.x = cvtpk(o0[0], o0[1]); q.y = cvtpk(o0[2], o0[3]); q.z = cvtpk(o1[0], o1[1]); q.w = cvtpk(o1[2], o1[3]); *(u32x4*)(HB + off + bj * HALF) = q;
;                        s += ((o0[0] * o0[0] + o0[1] * o0[1]) + (o0[2] * o0[2] + o0[3] * o0[3])) + ((o1[0] * o1[0] + o1[1] * o1[1]) + (o1[2] * o1[2] + o1[3] * o1[3])); } }
;             if (!FINAL) { if (g > 0) { float t = sprev; t += __shfl_xor(t, 16); t += __shfl_xor(t, 32);
;                     if (fq == 0) __hip_atomic_fetch_add(ssq_out + row0 + ((g - 1) >> 2) * HALF + ((g - 1) & 3) * 16, t, __ATOMIC_RELAXED, __HIP_MEMORY_SCOPE_AGENT); }
;                 sprev = s; } }
;     ...
;         if (!FINAL) { float t = sprev; t += __shfl_xor(t, 16); t += __shfl_xor(t, 32);
;             if (fq == 0) __hip_atomic_fetch_add(ssq_out + row0 + HALF + 48, t, __ATOMIC_RELAXED, __HIP_MEMORY_SCOPE_AGENT); }
	s_cbranch_scc0 .LBB0_1220
	v_lshl_add_u32 v156, s18, 8, v160
	v_lshl_or_b32 v154, s20, 8, v161
	v_ashrrev_i32_e32 v157, 31, v156
	v_ashrrev_i32_e32 v155, 31, v154
	v_lshlrev_b64 v[128:129], 12, v[156:157]
	v_lshl_add_u64 v[128:129], s[0:1], 0, v[128:129]
	v_lshlrev_b64 v[130:131], 1, v[154:155]
	v_lshl_add_u64 v[176:177], v[128:129], 0, v[130:131]
	v_or_b32_e32 v128, 16, v156
	v_ashrrev_i32_e32 v129, 31, v128
	global_load_dwordx4 v[168:171], v[176:177], off
	global_load_dwordx4 v[172:175], v[176:177], off offset:256
	v_lshlrev_b64 v[128:129], 12, v[128:129]
	v_lshl_add_u64 v[128:129], s[0:1], 0, v[128:129]
	v_lshl_add_u64 v[188:189], v[128:129], 0, v[130:131]
	global_load_dwordx4 v[180:183], v[188:189], off
	global_load_dwordx4 v[184:187], v[188:189], off offset:256
	v_or_b32_e32 v128, 32, v156
	v_ashrrev_i32_e32 v129, 31, v128
	v_lshlrev_b64 v[128:129], 12, v[128:129]
	v_lshl_add_u64 v[128:129], s[0:1], 0, v[128:129]
	v_lshl_add_u64 v[158:159], v[128:129], 0, v[130:131]
	global_load_dwordx4 v[132:135], v[158:159], off
	global_load_dwordx4 v[128:131], v[158:159], off offset:256
	s_waitcnt vmcnt(0)
	v_lshlrev_b32_e32 v190, 16, v168
	v_and_b32_e32 v191, 0xffff0000, v168
	v_lshlrev_b32_e32 v168, 16, v169
	v_and_b32_e32 v169, 0xffff0000, v169
	v_lshlrev_b32_e32 v192, 16, v170
	v_and_b32_e32 v193, 0xffff0000, v170
	v_lshlrev_b32_e32 v170, 16, v171
	v_and_b32_e32 v171, 0xffff0000, v171
	v_lshlrev_b32_e32 v194, 16, v172
	v_and_b32_e32 v195, 0xffff0000, v172
	v_lshlrev_b32_e32 v172, 16, v173
	v_and_b32_e32 v173, 0xffff0000, v173
	v_lshlrev_b32_e32 v196, 16, v174
	v_and_b32_e32 v197, 0xffff0000, v174
	v_lshlrev_b32_e32 v174, 16, v175
	v_and_b32_e32 v175, 0xffff0000, v175
	v_pk_add_f32 v[126:127], v[126:127], v[168:169]
	v_pk_add_f32 v[124:125], v[124:125], v[190:191]
	v_pk_add_f32 v[122:123], v[122:123], v[170:171]
	v_pk_add_f32 v[168:169], v[120:121], v[192:193]
	v_pk_add_f32 v[170:171], v[118:119], v[172:173]
	v_pk_add_f32 v[172:173], v[116:117], v[194:195]
	v_pk_add_f32 v[174:175], v[114:115], v[174:175]
	v_pk_add_f32 v[190:191], v[112:113], v[196:197]
	v_cvt_pk_bf16_f32 v114, v124, v125
	v_cvt_pk_bf16_f32 v115, v126, v127
	v_cvt_pk_bf16_f32 v116, v168, v169
	v_cvt_pk_bf16_f32 v117, v122, v123
	v_mul_f32_e32 v125, v125, v125
	v_mul_f32_e32 v127, v127, v127
	v_mul_f32_e32 v167, v169, v169
	v_mul_f32_e32 v123, v123, v123
	v_cvt_pk_bf16_f32 v118, v172, v173
	v_cvt_pk_bf16_f32 v119, v170, v171
	v_cvt_pk_bf16_f32 v121, v174, v175
	v_mul_f32_e32 v169, v173, v173
	v_mul_f32_e32 v171, v171, v171
	v_mul_f32_e32 v173, v191, v191
	v_mul_f32_e32 v175, v175, v175
	v_lshlrev_b32_e32 v112, 16, v180
	v_and_b32_e32 v113, 0xffff0000, v180
	v_lshlrev_b32_e32 v192, 16, v182
	v_and_b32_e32 v193, 0xffff0000, v182
	v_lshlrev_b32_e32 v182, 16, v183
	v_and_b32_e32 v183, 0xffff0000, v183
	v_fmac_f32_e32 v125, v124, v124
	v_fmac_f32_e32 v127, v126, v126
	v_fmac_f32_e32 v167, v168, v168
	v_fmac_f32_e32 v123, v122, v122
	v_fmac_f32_e32 v169, v172, v172
	v_fmac_f32_e32 v171, v170, v170
	v_fmac_f32_e32 v173, v190, v190
	v_fmac_f32_e32 v175, v174, v174
	v_lshlrev_b32_e32 v180, 16, v181
	v_and_b32_e32 v181, 0xffff0000, v181
	v_pk_add_f32 v[112:113], v[108:109], v[112:113]
	v_pk_add_f32 v[108:109], v[106:107], v[182:183]
	global_store_dwordx4 v[176:177], v[114:117], off
	v_add_f32_e32 v106, v125, v127
	v_add_f32_e32 v107, v167, v123
	v_add_f32_e32 v114, v169, v171
	v_add_f32_e32 v115, v173, v175
	v_pk_add_f32 v[110:111], v[110:111], v[180:181]
	v_add_f32_e32 v106, v106, v107
	v_add_f32_e32 v107, v114, v115
	v_pk_add_f32 v[114:115], v[104:105], v[192:193]
	v_add_f32_e32 v125, v106, v107
	v_cvt_pk_bf16_f32 v104, v112, v113
	v_cvt_pk_bf16_f32 v105, v110, v111
	v_cvt_pk_bf16_f32 v106, v114, v115
	v_cvt_pk_bf16_f32 v107, v108, v109
	v_cvt_pk_bf16_f32 v120, v190, v191
	global_store_dwordx4 v[188:189], v[104:107], off
	global_store_dwordx4 v[176:177], v[118:121], off offset:256
	v_lshlrev_b32_e32 v122, 16, v186
	v_lshlrev_b32_e32 v104, 16, v184
	v_and_b32_e32 v105, 0xffff0000, v184
	v_pk_add_f32 v[118:119], v[100:101], v[104:105]
	v_and_b32_e32 v101, 64, v166
	v_xor_b32_e32 v100, 16, v166
	v_add_u32_e32 v101, 64, v101
	v_cmp_lt_i32_e32 vcc, v100, v101
	v_and_b32_e32 v123, 0xffff0000, v186
	v_pk_add_f32 v[122:123], v[96:97], v[122:123]
	v_cndmask_b32_e32 v100, v166, v100, vcc
	v_lshlrev_b32_e32 v124, 2, v100
	ds_bpermute_b32 v100, v124, v125
	v_xor_b32_e32 v97, 32, v166
	v_cmp_lt_i32_e32 vcc, v97, v101
	v_lshlrev_b32_e32 v106, 16, v185
	v_and_b32_e32 v107, 0xffff0000, v185
	v_cndmask_b32_e32 v97, v166, v97, vcc
	s_waitcnt lgkmcnt(0)
	v_add_f32_e32 v96, v125, v100
	v_lshlrev_b32_e32 v125, 2, v97
	ds_bpermute_b32 v97, v125, v96
	v_lshlrev_b32_e32 v120, 16, v187
	v_and_b32_e32 v121, 0xffff0000, v187
	v_pk_add_f32 v[116:117], v[102:103], v[106:107]
	v_pk_add_f32 v[120:121], v[98:99], v[120:121]
	v_cvt_pk_bf16_f32 v98, v118, v119
	v_cvt_pk_bf16_f32 v99, v116, v117
	v_cvt_pk_bf16_f32 v100, v122, v123
	v_cvt_pk_bf16_f32 v101, v120, v121
	v_lshl_add_u64 v[104:105], v[156:157], 2, s[6:7]
	global_store_dwordx4 v[188:189], v[98:101], off offset:256
	s_and_saveexec_b64 s[18:19], s[2:3]
	s_cbranch_execz .LBB0_1223
	s_waitcnt lgkmcnt(0)
	v_add_f32_e32 v96, v96, v97
	global_atomic_add_f32 v[104:105], v96, off

; #define PG8_STAGE(bufoff, gbase, voff) do { _Pragma("unroll") for (int _i = 0; _i < 2; ++_i) \
;         __builtin_amdgcn_global_load_lds((const unsigned*)((const char*)(gbase) + (voff)[_i]), (LAS unsigned*)(lds + (bufoff) + ldsw + _i * 8192), 16, 0, 0); } while (0)
; #define PG8_LDA(dst, b, h) do { _Pragma("unroll") for (int m = 0; m < 4; ++m) _Pragma("unroll") for (int k = 0; k < 2; ++k) dst[m][k] = *(const LAS bf16x8*)(lds + PG8_SA(b, h) + aoff + m * 2048 + k * 1024); } while (0)
; #define PG8_LDB(dst, b, h) do { _Pragma("unroll") for (int n = 0; n < 2; ++n) _Pragma("unroll") for (int k = 0; k < 2; ++k) dst[n][k] = *(const LAS bf16x8*)(lds + PG8_SB(b, h) + boff + n * 2048 + k * 1024); } while (0)
; #define PG8_MMA(ai, bj, At, Bt) do { __builtin_amdgcn_s_setprio(1); _Pragma("unroll") for (int m = 0; m < 4; ++m) _Pragma("unroll") for (int n = 0; n < 2; ++n) _Pragma("unroll") for (int k = 0; k < 2; ++k) \
;         acc[ai][bj][m][n] = __builtin_amdgcn_mfma_f32_16x16x32_bf16(Bt[n][k], At[m][k], acc[ai][bj][m][n], 0, 0, 0); __builtin_amdgcn_s_setprio(0); } while (0)
; #define PG8_WAIT_L(n) asm volatile("s_waitcnt lgkmcnt(" #n ")" ::: "memory")
; #define PG8_BAR __builtin_amdgcn_s_barrier()
; #define PG8_SCHED __builtin_amdgcn_sched_barrier(0)
; template <class Epi>
; __device__ __forceinline__ void gemm_phase(LAS unsigned char* lds, const Gemm g, const StaticOrder& S, const Epi& E) {
;     ...
;             const bool last = (t == nt - 2);
;             const char* a1 = cA + (size_t)(t + 1) * kstep;
;             const char* a2 = last ? nA : cA + (size_t)(t + 2) * kstep; const char* b2 = last ? nB : cB + (size_t)(t + 2) * kstep;
;             const char* a3 = a2 + kstep; const char* b3 = b2 + kstep;
;             PG8_LDB(B0, 0, 0); PG8_SCHED; PG8_LDA(At, 0, 0); PG8_STAGE(PG8_SA(1, 1), a1 + hstep, voffA);
;             PG8_WAIT_L(8); PG8_BAR; PG8_WAIT_L(0); PG8_MMA(0, 0, At, B0); PG8_BAR; PG8_SCHED;
.LBB0_1306:
	ds_read_b128 v[166:169], v149
	ds_read_b128 v[170:173], v149 offset:1024
	ds_read_b128 v[174:177], v149 offset:2048
	ds_read_b128 v[180:183], v149 offset:3072
	s_add_u32 s18, s16, 0xfff80080
	s_addc_u32 s19, s17, -1
	s_cmp_eq_u32 s65, 28
	s_cselect_b32 s21, s9, s19
	s_cselect_b32 s20, s61, s18
	s_cselect_b32 s19, s7, s64
	s_cselect_b32 s18, s62, s63
	v_lshl_add_u64 v[162:163], s[16:17], 0, v[138:139]
	s_add_i32 m0, s35, 0xc000
	ds_read_b128 v[184:187], v150
	ds_read_b128 v[188:191], v150 offset:1024
	ds_read_b128 v[192:195], v150 offset:2048
	ds_read_b128 v[196:199], v150 offset:3072
	ds_read_b128 v[200:203], v150 offset:4096
	ds_read_b128 v[204:207], v150 offset:5120
	ds_read_b128 v[208:211], v150 offset:6144
	ds_read_b128 v[212:215], v150 offset:7168
	global_load_lds_dwordx4 v[162:163], off
	v_lshl_add_u64 v[162:163], s[16:17], 0, v[140:141]
	s_add_i32 m0, s35, 0xe000
	s_nop 0
	global_load_lds_dwordx4 v[162:163], off
	s_waitcnt lgkmcnt(8)
	s_setprio 1
	s_barrier
	s_waitcnt lgkmcnt(0)


; #define PG8_MMA(ai, bj, At, Bt) do { __builtin_amdgcn_s_setprio(1); _Pragma("unroll") for (int m = 0; m < 4; ++m) _Pragma("unroll") for (int n = 0; n < 2; ++n) _Pragma("unroll") for (int k = 0; k < 2; ++k) \
;         acc[ai][bj][m][n] = __builtin_amdgcn_mfma_f32_16x16x32_bf16(Bt[n][k], At[m][k], acc[ai][bj][m][n], 0, 0, 0); __builtin_amdgcn_s_setprio(0); } while (0)
; #define PG8_WAIT_L(n) asm volatile("s_waitcnt lgkmcnt(" #n ")" ::: "memory")
; #define PG8_BAR __builtin_amdgcn_s_barrier()
; #define PG8_SCHED __builtin_amdgcn_sched_barrier(0)
; template <class Epi>
; __device__ __forceinline__ void gemm_phase(LAS unsigned char* lds, const Gemm g, const StaticOrder& S, const Epi& E) {
;     ...
;             PG8_WAIT_L(8); PG8_BAR; PG8_WAIT_L(0); PG8_MMA(0, 0, At, B0); PG8_BAR; PG8_SCHED;
	v_mfma_f32_16x16x32_bf16 v[124:127], v[166:169], v[184:187], v[124:127]
	v_mfma_f32_16x16x32_bf16 v[116:119], v[174:177], v[184:187], v[116:119]
	v_mfma_f32_16x16x32_bf16 v[108:111], v[166:169], v[192:195], v[108:111]
	v_mfma_f32_16x16x32_bf16 v[100:103], v[174:177], v[192:195], v[100:103]
	v_mfma_f32_16x16x32_bf16 v[92:95], v[166:169], v[200:203], v[92:95]
	v_mfma_f32_16x16x32_bf16 v[84:87], v[174:177], v[200:203], v[84:87]
	v_mfma_f32_16x16x32_bf16 v[76:79], v[166:169], v[208:211], v[76:79]
	v_mfma_f32_16x16x32_bf16 v[68:71], v[174:177], v[208:211], v[68:71]
	v_mfma_f32_16x16x32_bf16 v[124:127], v[170:173], v[188:191], v[124:127]
	v_mfma_f32_16x16x32_bf16 v[116:119], v[180:183], v[188:191], v[116:119]
	v_mfma_f32_16x16x32_bf16 v[108:111], v[170:173], v[196:199], v[108:111]
	v_mfma_f32_16x16x32_bf16 v[100:103], v[180:183], v[196:199], v[100:103]
	v_mfma_f32_16x16x32_bf16 v[92:95], v[170:173], v[204:207], v[92:95]
	v_mfma_f32_16x16x32_bf16 v[84:87], v[180:183], v[204:207], v[84:87]
	v_mfma_f32_16x16x32_bf16 v[76:79], v[170:173], v[212:215], v[76:79]
	v_mfma_f32_16x16x32_bf16 v[68:71], v[180:183], v[212:215], v[68:71]
	s_barrier
	s_setprio 0

; #define PG8_STAGE(bufoff, gbase, voff) do { _Pragma("unroll") for (int _i = 0; _i < 2; ++_i) \
;         __builtin_amdgcn_global_load_lds((const unsigned*)((const char*)(gbase) + (voff)[_i]), (LAS unsigned*)(lds + (bufoff) + ldsw + _i * 8192), 16, 0, 0); } while (0)
; #define PG8_LDB(dst, b, h) do { _Pragma("unroll") for (int n = 0; n < 2; ++n) _Pragma("unroll") for (int k = 0; k < 2; ++k) dst[n][k] = *(const LAS bf16x8*)(lds + PG8_SB(b, h) + boff + n * 2048 + k * 1024); } while (0)
; #define PG8_MMA(ai, bj, At, Bt) do { __builtin_amdgcn_s_setprio(1); _Pragma("unroll") for (int m = 0; m < 4; ++m) _Pragma("unroll") for (int n = 0; n < 2; ++n) _Pragma("unroll") for (int k = 0; k < 2; ++k) \
;         acc[ai][bj][m][n] = __builtin_amdgcn_mfma_f32_16x16x32_bf16(Bt[n][k], At[m][k], acc[ai][bj][m][n], 0, 0, 0); __builtin_amdgcn_s_setprio(0); } while (0)
; #define PG8_WAIT_L(n) asm volatile("s_waitcnt lgkmcnt(" #n ")" ::: "memory")
; #define PG8_BAR __builtin_amdgcn_s_barrier()
; template <class Epi>
; __device__ __forceinline__ void gemm_phase(LAS unsigned char* lds, const Gemm g, const StaticOrder& S, const Epi& E) {
;     ...
;             PG8_LDB(B1, 0, 1); PG8_STAGE(PG8_SB(0, 0), b2, voffB);
;             PG8_BAR; PG8_WAIT_L(0); PG8_MMA(0, 1, At, B1); PG8_BAR;
	s_add_i32 s66, s58, s31
	v_lshl_add_u64 v[162:163], s[18:19], 0, v[132:133]
	s_mov_b32 m0, s66
	ds_read_b128 v[216:219], v152
	ds_read_b128 v[220:223], v152 offset:1024
	ds_read_b128 v[224:227], v152 offset:2048
	ds_read_b128 v[228:231], v152 offset:3072
	global_load_lds_dwordx4 v[162:163], off
	v_lshl_add_u64 v[232:233], s[18:19], 0, v[128:129]
	s_add_i32 m0, s66, 0x2000
	s_nop 0
	global_load_lds_dwordx4 v[232:233], off
	s_waitcnt lgkmcnt(0)
	s_setprio 1
	s_barrier


; #define PG8_MMA(ai, bj, At, Bt) do { __builtin_amdgcn_s_setprio(1); _Pragma("unroll") for (int m = 0; m < 4; ++m) _Pragma("unroll") for (int n = 0; n < 2; ++n) _Pragma("unroll") for (int k = 0; k < 2; ++k) \
;         acc[ai][bj][m][n] = __builtin_amdgcn_mfma_f32_16x16x32_bf16(Bt[n][k], At[m][k], acc[ai][bj][m][n], 0, 0, 0); __builtin_amdgcn_s_setprio(0); } while (0)
; #define PG8_WAIT_L(n) asm volatile("s_waitcnt lgkmcnt(" #n ")" ::: "memory")
; #define PG8_BAR __builtin_amdgcn_s_barrier()
; template <class Epi>
; __device__ __forceinline__ void gemm_phase(LAS unsigned char* lds, const Gemm g, const StaticOrder& S, const Epi& E) {
;     ...
;             PG8_BAR; PG8_WAIT_L(0); PG8_MMA(0, 1, At, B1); PG8_BAR;
	v_mfma_f32_16x16x32_bf16 v[120:123], v[216:219], v[184:187], v[120:123]
	v_mfma_f32_16x16x32_bf16 v[112:115], v[224:227], v[184:187], v[112:115]
	v_mfma_f32_16x16x32_bf16 v[104:107], v[216:219], v[192:195], v[104:107]
	v_mfma_f32_16x16x32_bf16 v[96:99], v[224:227], v[192:195], v[96:99]
	v_mfma_f32_16x16x32_bf16 v[88:91], v[216:219], v[200:203], v[88:91]
	v_mfma_f32_16x16x32_bf16 v[80:83], v[224:227], v[200:203], v[80:83]
	v_mfma_f32_16x16x32_bf16 v[72:75], v[216:219], v[208:211], v[72:75]
	v_mfma_f32_16x16x32_bf16 v[64:67], v[224:227], v[208:211], v[64:67]
	v_mfma_f32_16x16x32_bf16 v[120:123], v[220:223], v[188:191], v[120:123]
	v_mfma_f32_16x16x32_bf16 v[112:115], v[228:231], v[188:191], v[112:115]
	v_mfma_f32_16x16x32_bf16 v[104:107], v[220:223], v[196:199], v[104:107]
	v_mfma_f32_16x16x32_bf16 v[96:99], v[228:231], v[196:199], v[96:99]
	v_mfma_f32_16x16x32_bf16 v[88:91], v[220:223], v[204:207], v[88:91]
	v_mfma_f32_16x16x32_bf16 v[80:83], v[228:231], v[204:207], v[80:83]
	v_mfma_f32_16x16x32_bf16 v[72:75], v[220:223], v[212:215], v[72:75]
	v_mfma_f32_16x16x32_bf16 v[64:67], v[228:231], v[212:215], v[64:67]
	s_barrier
	s_setprio 0
	s_mov_b32 m0, s35
	v_lshl_add_u64 v[234:235], s[20:21], 0, v[134:135]


; #define PG8_STAGE(bufoff, gbase, voff) do { _Pragma("unroll") for (int _i = 0; _i < 2; ++_i) \
;         __builtin_amdgcn_global_load_lds((const unsigned*)((const char*)(gbase) + (voff)[_i]), (LAS unsigned*)(lds + (bufoff) + ldsw + _i * 8192), 16, 0, 0); } while (0)
; #define PG8_LDA(dst, b, h) do { _Pragma("unroll") for (int m = 0; m < 4; ++m) _Pragma("unroll") for (int k = 0; k < 2; ++k) dst[m][k] = *(const LAS bf16x8*)(lds + PG8_SA(b, h) + aoff + m * 2048 + k * 1024); } while (0)
; #define PG8_MMA(ai, bj, At, Bt) do { __builtin_amdgcn_s_setprio(1); _Pragma("unroll") for (int m = 0; m < 4; ++m) _Pragma("unroll") for (int n = 0; n < 2; ++n) _Pragma("unroll") for (int k = 0; k < 2; ++k) \
;         acc[ai][bj][m][n] = __builtin_amdgcn_mfma_f32_16x16x32_bf16(Bt[n][k], At[m][k], acc[ai][bj][m][n], 0, 0, 0); __builtin_amdgcn_s_setprio(0); } while (0)
; #define PG8_WAIT_L(n) asm volatile("s_waitcnt lgkmcnt(" #n ")" ::: "memory")
; #define PG8_BAR __builtin_amdgcn_s_barrier()
; #define PG8_SCHED __builtin_amdgcn_sched_barrier(0)
; template <class Epi>
; __device__ __forceinline__ void gemm_phase(LAS unsigned char* lds, const Gemm g, const StaticOrder& S, const Epi& E) {
;     ...
;             PG8_LDA(At, 0, 1); PG8_STAGE(PG8_SA(0, 0), a2, voffA);
;             PG8_BAR; PG8_WAIT_L(0); PG8_MMA(1, 0, At, B0); PG8_BAR; PG8_SCHED;
	ds_read_b128 v[184:187], v150 offset:16384
	ds_read_b128 v[188:191], v150 offset:17408
	ds_read_b128 v[192:195], v150 offset:18432
	ds_read_b128 v[196:199], v150 offset:19456
	ds_read_b128 v[200:203], v150 offset:20480
	ds_read_b128 v[204:207], v150 offset:21504
	ds_read_b128 v[208:211], v150 offset:22528
	ds_read_b128 v[212:215], v150 offset:23552
	global_load_lds_dwordx4 v[234:235], off
	v_lshl_add_u64 v[236:237], s[20:21], 0, v[130:131]
	s_mov_b32 m0, s36
	s_nop 0
	global_load_lds_dwordx4 v[236:237], off
	s_waitcnt lgkmcnt(0)
	s_setprio 1
	s_barrier


; #define PG8_MMA(ai, bj, At, Bt) do { __builtin_amdgcn_s_setprio(1); _Pragma("unroll") for (int m = 0; m < 4; ++m) _Pragma("unroll") for (int n = 0; n < 2; ++n) _Pragma("unroll") for (int k = 0; k < 2; ++k) \
;         acc[ai][bj][m][n] = __builtin_amdgcn_mfma_f32_16x16x32_bf16(Bt[n][k], At[m][k], acc[ai][bj][m][n], 0, 0, 0); __builtin_amdgcn_s_setprio(0); } while (0)
; #define PG8_WAIT_L(n) asm volatile("s_waitcnt lgkmcnt(" #n ")" ::: "memory")
; #define PG8_BAR __builtin_amdgcn_s_barrier()
; #define PG8_SCHED __builtin_amdgcn_sched_barrier(0)
; template <class Epi>
; __device__ __forceinline__ void gemm_phase(LAS unsigned char* lds, const Gemm g, const StaticOrder& S, const Epi& E) {
;     ...
;             PG8_BAR; PG8_WAIT_L(0); PG8_MMA(1, 0, At, B0); PG8_BAR; PG8_SCHED;
	v_mfma_f32_16x16x32_bf16 v[60:63], v[166:169], v[184:187], v[60:63]
	v_mfma_f32_16x16x32_bf16 v[52:55], v[174:177], v[184:187], v[52:55]
	v_mfma_f32_16x16x32_bf16 v[44:47], v[166:169], v[192:195], v[44:47]
	v_mfma_f32_16x16x32_bf16 v[36:39], v[174:177], v[192:195], v[36:39]
	v_mfma_f32_16x16x32_bf16 v[28:31], v[166:169], v[200:203], v[28:31]
	v_mfma_f32_16x16x32_bf16 v[20:23], v[174:177], v[200:203], v[20:23]
	v_mfma_f32_16x16x32_bf16 v[12:15], v[166:169], v[208:211], v[12:15]
	v_mfma_f32_16x16x32_bf16 v[4:7], v[174:177], v[208:211], v[4:7]
	v_mfma_f32_16x16x32_bf16 v[60:63], v[170:173], v[188:191], v[60:63]
	v_mfma_f32_16x16x32_bf16 v[52:55], v[180:183], v[188:191], v[52:55]
	v_mfma_f32_16x16x32_bf16 v[44:47], v[170:173], v[196:199], v[44:47]
	v_mfma_f32_16x16x32_bf16 v[36:39], v[180:183], v[196:199], v[36:39]
	v_mfma_f32_16x16x32_bf16 v[28:31], v[170:173], v[204:207], v[28:31]
	v_mfma_f32_16x16x32_bf16 v[20:23], v[180:183], v[204:207], v[20:23]
	v_mfma_f32_16x16x32_bf16 v[12:15], v[170:173], v[212:215], v[12:15]
	v_mfma_f32_16x16x32_bf16 v[4:7], v[180:183], v[212:215], v[4:7]
	s_barrier
	s_setprio 0

; #define PG8_STAGE(bufoff, gbase, voff) do { _Pragma("unroll") for (int _i = 0; _i < 2; ++_i) \
;         __builtin_amdgcn_global_load_lds((const unsigned*)((const char*)(gbase) + (voff)[_i]), (LAS unsigned*)(lds + (bufoff) + ldsw + _i * 8192), 16, 0, 0); } while (0)
; #define PG8_MMA(ai, bj, At, Bt) do { __builtin_amdgcn_s_setprio(1); _Pragma("unroll") for (int m = 0; m < 4; ++m) _Pragma("unroll") for (int n = 0; n < 2; ++n) _Pragma("unroll") for (int k = 0; k < 2; ++k) \
;         acc[ai][bj][m][n] = __builtin_amdgcn_mfma_f32_16x16x32_bf16(Bt[n][k], At[m][k], acc[ai][bj][m][n], 0, 0, 0); __builtin_amdgcn_s_setprio(0); } while (0)
; #define PG8_WAIT_V(n) asm volatile("s_waitcnt vmcnt(" #n ")" ::: "memory")
; #define PG8_BAR __builtin_amdgcn_s_barrier()
; template <class Epi>
; __device__ __forceinline__ void gemm_phase(LAS unsigned char* lds, const Gemm g, const StaticOrder& S, const Epi& E) {
;     ...
;             PG8_STAGE(PG8_SB(0, 1), b2 + hstep, voffB);
;             PG8_WAIT_V(6); PG8_BAR; PG8_MMA(1, 1, At, B1); PG8_BAR;
	s_add_u32 s66, s18, 0x80000
	s_addc_u32 s67, s19, 0
	s_add_i32 s68, s59, s31
	v_lshl_add_u64 v[166:167], s[66:67], 0, v[132:133]
	s_mov_b32 m0, s68
	s_nop 0
	global_load_lds_dwordx4 v[166:167], off
	v_lshl_add_u64 v[166:167], s[66:67], 0, v[128:129]
	s_add_i32 m0, s68, 0x2000
	s_nop 0
	global_load_lds_dwordx4 v[166:167], off
	s_waitcnt vmcnt(6)
	s_setprio 1
	s_barrier

; #define PG8_MMA(ai, bj, At, Bt) do { __builtin_amdgcn_s_setprio(1); _Pragma("unroll") for (int m = 0; m < 4; ++m) _Pragma("unroll") for (int n = 0; n < 2; ++n) _Pragma("unroll") for (int k = 0; k < 2; ++k) \
;         acc[ai][bj][m][n] = __builtin_amdgcn_mfma_f32_16x16x32_bf16(Bt[n][k], At[m][k], acc[ai][bj][m][n], 0, 0, 0); __builtin_amdgcn_s_setprio(0); } while (0)
; #define PG8_WAIT_V(n) asm volatile("s_waitcnt vmcnt(" #n ")" ::: "memory")
; #define PG8_BAR __builtin_amdgcn_s_barrier()
; template <class Epi>
; __device__ __forceinline__ void gemm_phase(LAS unsigned char* lds, const Gemm g, const StaticOrder& S, const Epi& E) {
;     ...
;             PG8_WAIT_V(6); PG8_BAR; PG8_MMA(1, 1, At, B1); PG8_BAR;
	v_mfma_f32_16x16x32_bf16 v[56:59], v[216:219], v[184:187], v[56:59]
	v_mfma_f32_16x16x32_bf16 v[48:51], v[224:227], v[184:187], v[48:51]
	v_mfma_f32_16x16x32_bf16 v[40:43], v[216:219], v[192:195], v[40:43]
	v_mfma_f32_16x16x32_bf16 v[32:35], v[224:227], v[192:195], v[32:35]
	v_mfma_f32_16x16x32_bf16 v[24:27], v[216:219], v[200:203], v[24:27]
	v_mfma_f32_16x16x32_bf16 v[16:19], v[224:227], v[200:203], v[16:19]
	v_mfma_f32_16x16x32_bf16 v[8:11], v[216:219], v[208:211], v[8:11]
	v_mfma_f32_16x16x32_bf16 v[0:3], v[224:227], v[208:211], v[0:3]
	v_mfma_f32_16x16x32_bf16 v[56:59], v[220:223], v[188:191], v[56:59]
	v_mfma_f32_16x16x32_bf16 v[48:51], v[228:231], v[188:191], v[48:51]
	v_mfma_f32_16x16x32_bf16 v[40:43], v[220:223], v[196:199], v[40:43]
	v_mfma_f32_16x16x32_bf16 v[32:35], v[228:231], v[196:199], v[32:35]
	v_mfma_f32_16x16x32_bf16 v[24:27], v[220:223], v[204:207], v[24:27]
	v_mfma_f32_16x16x32_bf16 v[16:19], v[228:231], v[204:207], v[16:19]
	v_mfma_f32_16x16x32_bf16 v[8:11], v[220:223], v[212:215], v[8:11]
	v_mfma_f32_16x16x32_bf16 v[0:3], v[228:231], v[212:215], v[0:3]
	s_barrier
	s_setprio 0
	s_add_i32 s66, 0, 0x18000
	v_add_u32_e32 v161, s66, v147


; #define PG8_STAGE(bufoff, gbase, voff) do { _Pragma("unroll") for (int _i = 0; _i < 2; ++_i) \
;         __builtin_amdgcn_global_load_lds((const unsigned*)((const char*)(gbase) + (voff)[_i]), (LAS unsigned*)(lds + (bufoff) + ldsw + _i * 8192), 16, 0, 0); } while (0)
; #define PG8_LDA(dst, b, h) do { _Pragma("unroll") for (int m = 0; m < 4; ++m) _Pragma("unroll") for (int k = 0; k < 2; ++k) dst[m][k] = *(const LAS bf16x8*)(lds + PG8_SA(b, h) + aoff + m * 2048 + k * 1024); } while (0)
; #define PG8_LDB(dst, b, h) do { _Pragma("unroll") for (int n = 0; n < 2; ++n) _Pragma("unroll") for (int k = 0; k < 2; ++k) dst[n][k] = *(const LAS bf16x8*)(lds + PG8_SB(b, h) + boff + n * 2048 + k * 1024); } while (0)
; #define PG8_MMA(ai, bj, At, Bt) do { __builtin_amdgcn_s_setprio(1); _Pragma("unroll") for (int m = 0; m < 4; ++m) _Pragma("unroll") for (int n = 0; n < 2; ++n) _Pragma("unroll") for (int k = 0; k < 2; ++k) \
;         acc[ai][bj][m][n] = __builtin_amdgcn_mfma_f32_16x16x32_bf16(Bt[n][k], At[m][k], acc[ai][bj][m][n], 0, 0, 0); __builtin_amdgcn_s_setprio(0); } while (0)
; #define PG8_WAIT_L(n) asm volatile("s_waitcnt lgkmcnt(" #n ")" ::: "memory")
; #define PG8_BAR __builtin_amdgcn_s_barrier()
; #define PG8_SCHED __builtin_amdgcn_sched_barrier(0)
; template <class Epi>
; __device__ __forceinline__ void gemm_phase(LAS unsigned char* lds, const Gemm g, const StaticOrder& S, const Epi& E) {
;     ...
;             PG8_LDB(B0, 1, 0); PG8_SCHED; PG8_LDA(At, 1, 0); PG8_STAGE(PG8_SA(0, 1), a2 + hstep, voffA);
;             PG8_WAIT_L(8); PG8_BAR; PG8_WAIT_L(0); PG8_MMA(0, 0, At, B0); PG8_BAR; PG8_SCHED;
	ds_read_b128 v[166:169], v161
	ds_read_b128 v[170:173], v161 offset:1024
	ds_read_b128 v[174:177], v161 offset:2048
	ds_read_b128 v[180:183], v161 offset:3072
	s_add_u32 s20, s20, 0x80000
	s_addc_u32 s21, s21, 0
	s_mov_b32 m0, s37
	v_lshl_add_u64 v[216:217], s[20:21], 0, v[134:135]
	ds_read_b128 v[184:187], v150 offset:32768
	ds_read_b128 v[188:191], v150 offset:33792
	ds_read_b128 v[192:195], v150 offset:34816
	ds_read_b128 v[196:199], v150 offset:35840
	ds_read_b128 v[200:203], v150 offset:36864
	ds_read_b128 v[204:207], v150 offset:37888
	ds_read_b128 v[208:211], v150 offset:38912
	ds_read_b128 v[212:215], v150 offset:39936
	global_load_lds_dwordx4 v[216:217], off
	v_lshl_add_u64 v[216:217], s[20:21], 0, v[130:131]
	s_mov_b32 m0, s38
	s_nop 0
	global_load_lds_dwordx4 v[216:217], off
	s_waitcnt lgkmcnt(8)
	s_setprio 1
	s_barrier
	s_waitcnt lgkmcnt(0)


; #define PG8_MMA(ai, bj, At, Bt) do { __builtin_amdgcn_s_setprio(1); _Pragma("unroll") for (int m = 0; m < 4; ++m) _Pragma("unroll") for (int n = 0; n < 2; ++n) _Pragma("unroll") for (int k = 0; k < 2; ++k) \
;         acc[ai][bj][m][n] = __builtin_amdgcn_mfma_f32_16x16x32_bf16(Bt[n][k], At[m][k], acc[ai][bj][m][n], 0, 0, 0); __builtin_amdgcn_s_setprio(0); } while (0)
; #define PG8_WAIT_L(n) asm volatile("s_waitcnt lgkmcnt(" #n ")" ::: "memory")
; #define PG8_BAR __builtin_amdgcn_s_barrier()
; #define PG8_SCHED __builtin_amdgcn_sched_barrier(0)
; template <class Epi>
; __device__ __forceinline__ void gemm_phase(LAS unsigned char* lds, const Gemm g, const StaticOrder& S, const Epi& E) {
;     ...
;             PG8_WAIT_L(8); PG8_BAR; PG8_WAIT_L(0); PG8_MMA(0, 0, At, B0); PG8_BAR; PG8_SCHED;
	v_mfma_f32_16x16x32_bf16 v[124:127], v[166:169], v[184:187], v[124:127]
	v_mfma_f32_16x16x32_bf16 v[116:119], v[174:177], v[184:187], v[116:119]
	v_mfma_f32_16x16x32_bf16 v[108:111], v[166:169], v[192:195], v[108:111]
	v_mfma_f32_16x16x32_bf16 v[100:103], v[174:177], v[192:195], v[100:103]
	v_mfma_f32_16x16x32_bf16 v[92:95], v[166:169], v[200:203], v[92:95]
	v_mfma_f32_16x16x32_bf16 v[84:87], v[174:177], v[200:203], v[84:87]
	v_mfma_f32_16x16x32_bf16 v[76:79], v[166:169], v[208:211], v[76:79]
	v_mfma_f32_16x16x32_bf16 v[68:71], v[174:177], v[208:211], v[68:71]
	v_mfma_f32_16x16x32_bf16 v[124:127], v[170:173], v[188:191], v[124:127]
	v_mfma_f32_16x16x32_bf16 v[116:119], v[180:183], v[188:191], v[116:119]
	v_mfma_f32_16x16x32_bf16 v[108:111], v[170:173], v[196:199], v[108:111]
	v_mfma_f32_16x16x32_bf16 v[100:103], v[180:183], v[196:199], v[100:103]
	v_mfma_f32_16x16x32_bf16 v[92:95], v[170:173], v[204:207], v[92:95]
	v_mfma_f32_16x16x32_bf16 v[84:87], v[180:183], v[204:207], v[84:87]
	v_mfma_f32_16x16x32_bf16 v[76:79], v[170:173], v[212:215], v[76:79]
	v_mfma_f32_16x16x32_bf16 v[68:71], v[180:183], v[212:215], v[68:71]
	s_barrier
	s_setprio 0

; #define PG8_STAGE(bufoff, gbase, voff) do { _Pragma("unroll") for (int _i = 0; _i < 2; ++_i) \
;         __builtin_amdgcn_global_load_lds((const unsigned*)((const char*)(gbase) + (voff)[_i]), (LAS unsigned*)(lds + (bufoff) + ldsw + _i * 8192), 16, 0, 0); } while (0)
; #define PG8_LDB(dst, b, h) do { _Pragma("unroll") for (int n = 0; n < 2; ++n) _Pragma("unroll") for (int k = 0; k < 2; ++k) dst[n][k] = *(const LAS bf16x8*)(lds + PG8_SB(b, h) + boff + n * 2048 + k * 1024); } while (0)
; #define PG8_MMA(ai, bj, At, Bt) do { __builtin_amdgcn_s_setprio(1); _Pragma("unroll") for (int m = 0; m < 4; ++m) _Pragma("unroll") for (int n = 0; n < 2; ++n) _Pragma("unroll") for (int k = 0; k < 2; ++k) \
;         acc[ai][bj][m][n] = __builtin_amdgcn_mfma_f32_16x16x32_bf16(Bt[n][k], At[m][k], acc[ai][bj][m][n], 0, 0, 0); __builtin_amdgcn_s_setprio(0); } while (0)
; #define PG8_WAIT_L(n) asm volatile("s_waitcnt lgkmcnt(" #n ")" ::: "memory")
; #define PG8_BAR __builtin_amdgcn_s_barrier()
; template <class Epi>
; __device__ __forceinline__ void gemm_phase(LAS unsigned char* lds, const Gemm g, const StaticOrder& S, const Epi& E) {
;     ...
;             PG8_LDB(B1, 1, 1); PG8_STAGE(PG8_SB(1, 0), b3, voffB);
;             PG8_BAR; PG8_WAIT_L(0); PG8_MMA(0, 1, At, B1); PG8_BAR;
	s_add_i32 s20, 0, 0x1c000
	s_add_i32 s21, s66, s31
	v_add_u32_e32 v161, s20, v147
	v_lshl_add_u64 v[162:163], v[162:163], 0, s[4:5]
	s_mov_b32 m0, s21
	ds_read_b128 v[216:219], v161
	ds_read_b128 v[220:223], v161 offset:1024
	ds_read_b128 v[224:227], v161 offset:2048
	ds_read_b128 v[228:231], v161 offset:3072
	global_load_lds_dwordx4 v[162:163], off
	v_lshl_add_u64 v[162:163], v[232:233], 0, s[4:5]
	s_add_i32 m0, s21, 0x2000
	s_nop 0
	global_load_lds_dwordx4 v[162:163], off
	s_waitcnt lgkmcnt(0)
	s_setprio 1
	s_barrier


; #define PG8_MMA(ai, bj, At, Bt) do { __builtin_amdgcn_s_setprio(1); _Pragma("unroll") for (int m = 0; m < 4; ++m) _Pragma("unroll") for (int n = 0; n < 2; ++n) _Pragma("unroll") for (int k = 0; k < 2; ++k) \
;         acc[ai][bj][m][n] = __builtin_amdgcn_mfma_f32_16x16x32_bf16(Bt[n][k], At[m][k], acc[ai][bj][m][n], 0, 0, 0); __builtin_amdgcn_s_setprio(0); } while (0)
; #define PG8_WAIT_L(n) asm volatile("s_waitcnt lgkmcnt(" #n ")" ::: "memory")
; #define PG8_BAR __builtin_amdgcn_s_barrier()
; template <class Epi>
; __device__ __forceinline__ void gemm_phase(LAS unsigned char* lds, const Gemm g, const StaticOrder& S, const Epi& E) {
;     ...
;             PG8_BAR; PG8_WAIT_L(0); PG8_MMA(0, 1, At, B1); PG8_BAR;
	v_mfma_f32_16x16x32_bf16 v[120:123], v[216:219], v[184:187], v[120:123]
	v_mfma_f32_16x16x32_bf16 v[112:115], v[224:227], v[184:187], v[112:115]
	v_mfma_f32_16x16x32_bf16 v[104:107], v[216:219], v[192:195], v[104:107]
	v_mfma_f32_16x16x32_bf16 v[96:99], v[224:227], v[192:195], v[96:99]
	v_mfma_f32_16x16x32_bf16 v[88:91], v[216:219], v[200:203], v[88:91]
	v_mfma_f32_16x16x32_bf16 v[80:83], v[224:227], v[200:203], v[80:83]
	v_mfma_f32_16x16x32_bf16 v[72:75], v[216:219], v[208:211], v[72:75]
	v_mfma_f32_16x16x32_bf16 v[64:67], v[224:227], v[208:211], v[64:67]
	v_mfma_f32_16x16x32_bf16 v[120:123], v[220:223], v[188:191], v[120:123]
	v_mfma_f32_16x16x32_bf16 v[112:115], v[228:231], v[188:191], v[112:115]
	v_mfma_f32_16x16x32_bf16 v[104:107], v[220:223], v[196:199], v[104:107]
	v_mfma_f32_16x16x32_bf16 v[96:99], v[228:231], v[196:199], v[96:99]
	v_mfma_f32_16x16x32_bf16 v[88:91], v[220:223], v[204:207], v[88:91]
	v_mfma_f32_16x16x32_bf16 v[80:83], v[228:231], v[204:207], v[80:83]
	v_mfma_f32_16x16x32_bf16 v[72:75], v[220:223], v[212:215], v[72:75]
	v_mfma_f32_16x16x32_bf16 v[64:67], v[228:231], v[212:215], v[64:67]
	s_barrier
	s_setprio 0
	s_mov_b32 m0, s42
	v_lshl_add_u64 v[162:163], v[234:235], 0, s[4:5]


; #define PG8_STAGE(bufoff, gbase, voff) do { _Pragma("unroll") for (int _i = 0; _i < 2; ++_i) \
;         __builtin_amdgcn_global_load_lds((const unsigned*)((const char*)(gbase) + (voff)[_i]), (LAS unsigned*)(lds + (bufoff) + ldsw + _i * 8192), 16, 0, 0); } while (0)
; #define PG8_LDA(dst, b, h) do { _Pragma("unroll") for (int m = 0; m < 4; ++m) _Pragma("unroll") for (int k = 0; k < 2; ++k) dst[m][k] = *(const LAS bf16x8*)(lds + PG8_SA(b, h) + aoff + m * 2048 + k * 1024); } while (0)
; #define PG8_MMA(ai, bj, At, Bt) do { __builtin_amdgcn_s_setprio(1); _Pragma("unroll") for (int m = 0; m < 4; ++m) _Pragma("unroll") for (int n = 0; n < 2; ++n) _Pragma("unroll") for (int k = 0; k < 2; ++k) \
;         acc[ai][bj][m][n] = __builtin_amdgcn_mfma_f32_16x16x32_bf16(Bt[n][k], At[m][k], acc[ai][bj][m][n], 0, 0, 0); __builtin_amdgcn_s_setprio(0); } while (0)
; #define PG8_WAIT_L(n) asm volatile("s_waitcnt lgkmcnt(" #n ")" ::: "memory")
; #define PG8_BAR __builtin_amdgcn_s_barrier()
; #define PG8_SCHED __builtin_amdgcn_sched_barrier(0)
; template <class Epi>
; __device__ __forceinline__ void gemm_phase(LAS unsigned char* lds, const Gemm g, const StaticOrder& S, const Epi& E) {
;     ...
;             PG8_LDA(At, 1, 1); PG8_STAGE(PG8_SA(1, 0), a3, voffA);
;             PG8_BAR; PG8_WAIT_L(0); PG8_MMA(1, 0, At, B0); PG8_BAR; PG8_SCHED;
	ds_read_b128 v[184:187], v150 offset:49152
	ds_read_b128 v[188:191], v150 offset:50176
	ds_read_b128 v[192:195], v150 offset:51200
	ds_read_b128 v[196:199], v150 offset:52224
	ds_read_b128 v[200:203], v150 offset:53248
	ds_read_b128 v[204:207], v150 offset:54272
	ds_read_b128 v[208:211], v150 offset:55296
	ds_read_b128 v[212:215], v150 offset:56320
	global_load_lds_dwordx4 v[162:163], off
	v_lshl_add_u64 v[162:163], v[236:237], 0, s[4:5]
	s_mov_b32 m0, s43
	s_nop 0
	global_load_lds_dwordx4 v[162:163], off
	s_waitcnt lgkmcnt(0)
	s_setprio 1
	s_barrier


; #define PG8_MMA(ai, bj, At, Bt) do { __builtin_amdgcn_s_setprio(1); _Pragma("unroll") for (int m = 0; m < 4; ++m) _Pragma("unroll") for (int n = 0; n < 2; ++n) _Pragma("unroll") for (int k = 0; k < 2; ++k) \
;         acc[ai][bj][m][n] = __builtin_amdgcn_mfma_f32_16x16x32_bf16(Bt[n][k], At[m][k], acc[ai][bj][m][n], 0, 0, 0); __builtin_amdgcn_s_setprio(0); } while (0)
; #define PG8_WAIT_L(n) asm volatile("s_waitcnt lgkmcnt(" #n ")" ::: "memory")
; #define PG8_BAR __builtin_amdgcn_s_barrier()
; #define PG8_SCHED __builtin_amdgcn_sched_barrier(0)
; template <class Epi>
; __device__ __forceinline__ void gemm_phase(LAS unsigned char* lds, const Gemm g, const StaticOrder& S, const Epi& E) {
;     ...
;             PG8_BAR; PG8_WAIT_L(0); PG8_MMA(1, 0, At, B0); PG8_BAR; PG8_SCHED;
	v_mfma_f32_16x16x32_bf16 v[60:63], v[166:169], v[184:187], v[60:63]
	v_mfma_f32_16x16x32_bf16 v[52:55], v[174:177], v[184:187], v[52:55]
	v_mfma_f32_16x16x32_bf16 v[44:47], v[166:169], v[192:195], v[44:47]
	v_mfma_f32_16x16x32_bf16 v[36:39], v[174:177], v[192:195], v[36:39]
	v_mfma_f32_16x16x32_bf16 v[28:31], v[166:169], v[200:203], v[28:31]
	v_mfma_f32_16x16x32_bf16 v[20:23], v[174:177], v[200:203], v[20:23]
	v_mfma_f32_16x16x32_bf16 v[12:15], v[166:169], v[208:211], v[12:15]
	v_mfma_f32_16x16x32_bf16 v[4:7], v[174:177], v[208:211], v[4:7]
	v_mfma_f32_16x16x32_bf16 v[60:63], v[170:173], v[188:191], v[60:63]
	v_mfma_f32_16x16x32_bf16 v[52:55], v[180:183], v[188:191], v[52:55]
	v_mfma_f32_16x16x32_bf16 v[44:47], v[170:173], v[196:199], v[44:47]
	v_mfma_f32_16x16x32_bf16 v[36:39], v[180:183], v[196:199], v[36:39]
	v_mfma_f32_16x16x32_bf16 v[28:31], v[170:173], v[204:207], v[28:31]
	v_mfma_f32_16x16x32_bf16 v[20:23], v[180:183], v[204:207], v[20:23]
	v_mfma_f32_16x16x32_bf16 v[12:15], v[170:173], v[212:215], v[12:15]
	v_mfma_f32_16x16x32_bf16 v[4:7], v[180:183], v[212:215], v[4:7]
	s_barrier
	s_setprio 0

; #define PG8_STAGE(bufoff, gbase, voff) do { _Pragma("unroll") for (int _i = 0; _i < 2; ++_i) \
;         __builtin_amdgcn_global_load_lds((const unsigned*)((const char*)(gbase) + (voff)[_i]), (LAS unsigned*)(lds + (bufoff) + ldsw + _i * 8192), 16, 0, 0); } while (0)
; #define PG8_MMA(ai, bj, At, Bt) do { __builtin_amdgcn_s_setprio(1); _Pragma("unroll") for (int m = 0; m < 4; ++m) _Pragma("unroll") for (int n = 0; n < 2; ++n) _Pragma("unroll") for (int k = 0; k < 2; ++k) \
;         acc[ai][bj][m][n] = __builtin_amdgcn_mfma_f32_16x16x32_bf16(Bt[n][k], At[m][k], acc[ai][bj][m][n], 0, 0, 0); __builtin_amdgcn_s_setprio(0); } while (0)
; #define PG8_WAIT_V(n) asm volatile("s_waitcnt vmcnt(" #n ")" ::: "memory")
; #define PG8_BAR __builtin_amdgcn_s_barrier()
; template <class Epi>
; __device__ __forceinline__ void gemm_phase(LAS unsigned char* lds, const Gemm g, const StaticOrder& S, const Epi& E) {
;     ...
;             PG8_STAGE(PG8_SB(1, 1), b3 + hstep, voffB);
;             PG8_WAIT_V(6); PG8_BAR; PG8_MMA(1, 1, At, B1); PG8_BAR;
	s_add_u32 s18, s18, 0x80080
	s_addc_u32 s19, s19, 0
	s_add_i32 s20, s20, s31
	v_lshl_add_u64 v[162:163], s[18:19], 0, v[132:133]
	s_mov_b32 m0, s20
	s_nop 0
	global_load_lds_dwordx4 v[162:163], off
	v_lshl_add_u64 v[162:163], s[18:19], 0, v[128:129]
	s_add_i32 m0, s20, 0x2000
	s_nop 0
	global_load_lds_dwordx4 v[162:163], off
	s_waitcnt vmcnt(6)
	s_setprio 1
	s_barrier

; #define PG8_MMA(ai, bj, At, Bt) do { __builtin_amdgcn_s_setprio(1); _Pragma("unroll") for (int m = 0; m < 4; ++m) _Pragma("unroll") for (int n = 0; n < 2; ++n) _Pragma("unroll") for (int k = 0; k < 2; ++k) \
;         acc[ai][bj][m][n] = __builtin_amdgcn_mfma_f32_16x16x32_bf16(Bt[n][k], At[m][k], acc[ai][bj][m][n], 0, 0, 0); __builtin_amdgcn_s_setprio(0); } while (0)
; #define PG8_WAIT_V(n) asm volatile("s_waitcnt vmcnt(" #n ")" ::: "memory")
; #define PG8_BAR __builtin_amdgcn_s_barrier()
; template <class Epi>
; __device__ __forceinline__ void gemm_phase(LAS unsigned char* lds, const Gemm g, const StaticOrder& S, const Epi& E) {
;     ...
;             PG8_WAIT_V(6); PG8_BAR; PG8_MMA(1, 1, At, B1); PG8_BAR;
	v_mfma_f32_16x16x32_bf16 v[56:59], v[216:219], v[184:187], v[56:59]
	v_mfma_f32_16x16x32_bf16 v[48:51], v[224:227], v[184:187], v[48:51]
	v_mfma_f32_16x16x32_bf16 v[40:43], v[216:219], v[192:195], v[40:43]
	v_mfma_f32_16x16x32_bf16 v[32:35], v[224:227], v[192:195], v[32:35]
	v_mfma_f32_16x16x32_bf16 v[24:27], v[216:219], v[200:203], v[24:27]
	v_mfma_f32_16x16x32_bf16 v[16:19], v[224:227], v[200:203], v[16:19]
	v_mfma_f32_16x16x32_bf16 v[8:11], v[216:219], v[208:211], v[8:11]
	v_mfma_f32_16x16x32_bf16 v[0:3], v[224:227], v[208:211], v[0:3]
	v_mfma_f32_16x16x32_bf16 v[56:59], v[220:223], v[188:191], v[56:59]
	v_mfma_f32_16x16x32_bf16 v[48:51], v[228:231], v[188:191], v[48:51]
	v_mfma_f32_16x16x32_bf16 v[40:43], v[220:223], v[196:199], v[40:43]
	v_mfma_f32_16x16x32_bf16 v[32:35], v[228:231], v[196:199], v[32:35]
	v_mfma_f32_16x16x32_bf16 v[24:27], v[220:223], v[204:207], v[24:27]
	v_mfma_f32_16x16x32_bf16 v[16:19], v[228:231], v[204:207], v[16:19]
	v_mfma_f32_16x16x32_bf16 v[8:11], v[220:223], v[212:215], v[8:11]
	v_mfma_f32_16x16x32_bf16 v[0:3], v[228:231], v[212:215], v[0:3]
	s_barrier
	s_setprio 0
	s_add_i32 s65, s65, 2
	s_add_u32 s16, s16, 0x100
	s_addc_u32 s17, s17, 0
	s_add_u32 s63, s63, 0x100
	s_addc_u32 s64, s64, 0
	s_cmp_gt_u32 s65, 29


; __device__ __forceinline__ float sigmoidf_(float x) { return __builtin_amdgcn_rcpf(1.0f + fexp(-x)); }
;     __device__ __forceinline__ void operator()(const f32x4 (&acc)[2][2][4][2], const Unit& u, int wr, int wc, int fr, int fq, const Pre& P) const {
;         const int row0 = ROW_X + u.pm * BM + wr * 64 + fr, col0 = u.pn * HALF + wc * 32 + 8 * fq;
; #pragma unroll
;         for (int ai = 0; ai < 2; ++ai)
; #pragma unroll
;             for (int m = 0; m < 4; ++m) { const int r = row0 + ai * HALF + m * 16; const float rs = __builtin_amdgcn_rsqf(P.rs[ai * 4 + m] * (1.0f / DM) + RMS_EPS);
;                 float y[8];
; #pragma unroll
;                 for (int n = 0; n < 2; ++n)
; #pragma unroll
;                     for (int j = 0; j < 4; ++j) { const float a = acc[ai][0][m][n][j] * rs, b = acc[ai][1][m][n][j] * rs; y[n * 4 + j] = a * b * sigmoidf_(a); }
;                 u32x4 w; w.x = cvtpk(y[0], y[1]); w.y = cvtpk(y[2], y[3]); w.z = cvtpk(y[4], y[5]); w.w = cvtpk(y[6], y[7]);
;                 *(u32x4*)(O + (size_t)r * FF + col0) = w; }
	s_cbranch_scc0 .LBB0_1306
	s_waitcnt vmcnt(0)
	v_fmamk_f32 v160, v160, 0x3a000000, v153
	v_rsq_f32_e32 v160, v160
	v_lshl_or_b32 v166, s15, 7, v148
	v_ashrrev_i32_e32 v167, 31, v166
	s_and_b64 vcc, vcc, exec
	v_pk_mul_f32 v[162:163], v[160:161], v[124:125] op_sel_hi:[0,1]
	v_mul_f32_e32 v124, 0xbfb8aa3b, v162
	v_mul_f32_e32 v125, 0xbfb8aa3b, v163
	v_exp_f32_e32 v161, v124
	v_exp_f32_e32 v125, v125
	v_lshl_add_u32 v124, s14, 8, v146
	v_add_f32_e32 v161, 1.0, v161
	v_add_f32_e32 v125, 1.0, v125
	v_rcp_f32_e32 v168, v161
	v_rcp_f32_e32 v169, v125
	v_pk_mul_f32 v[120:121], v[160:161], v[120:121] op_sel_hi:[0,1]
	v_pk_mul_f32 v[120:121], v[162:163], v[120:121]
	v_pk_mul_f32 v[126:127], v[160:161], v[126:127] op_sel_hi:[0,1]
	v_pk_mul_f32 v[120:121], v[168:169], v[120:121]
	v_mul_f32_e32 v125, 0xbfb8aa3b, v126
	v_cvt_pk_bf16_f32 v120, v120, v121
	v_mul_f32_e32 v121, 0xbfb8aa3b, v127
	v_exp_f32_e32 v125, v125
	v_exp_f32_e32 v121, v121
	v_pk_mul_f32 v[122:123], v[160:161], v[122:123] op_sel_hi:[0,1]
	v_pk_mul_f32 v[116:117], v[160:161], v[116:117] op_sel_hi:[0,1]
	v_add_f32_e32 v125, 1.0, v125
	v_add_f32_e32 v121, 1.0, v121
	v_rcp_f32_e32 v162, v125
	v_rcp_f32_e32 v163, v121
	v_pk_mul_f32 v[122:123], v[126:127], v[122:123]
	v_mul_f32_e32 v121, 0xbfb8aa3b, v116
	v_exp_f32_e32 v125, v121
	v_pk_mul_f32 v[122:123], v[162:163], v[122:123]
	v_pk_mul_f32 v[112:113], v[160:161], v[112:113] op_sel_hi:[0,1]
	v_cvt_pk_bf16_f32 v121, v122, v123
	v_mul_f32_e32 v123, 0xbfb8aa3b, v117
	v_exp_f32_e32 v123, v123
	v_add_f32_e32 v122, 1.0, v125
	v_pk_mul_f32 v[112:113], v[116:117], v[112:113]
	v_rcp_f32_e32 v122, v122
	v_add_f32_e32 v116, 1.0, v123
	v_rcp_f32_e32 v123, v116
	v_pk_mul_f32 v[116:117], v[160:161], v[118:119] op_sel_hi:[0,1]
	v_mul_f32_e32 v118, 0xbfb8aa3b, v116
	v_mul_f32_e32 v119, 0xbfb8aa3b, v117
	v_exp_f32_e32 v118, v118
	v_exp_f32_e32 v119, v119
	v_pk_mul_f32 v[112:113], v[122:123], v[112:113]
	v_add_f32_e32 v118, 1.0, v118
	v_cvt_pk_bf16_f32 v122, v112, v113
	v_pk_mul_f32 v[112:113], v[160:161], v[114:115] op_sel_hi:[0,1]
	v_fmamk_f32 v114, v159, 0x3a000000, v153
	v_pk_mul_f32 v[112:113], v[116:117], v[112:113]
	v_rsq_f32_e32 v116, v114
	v_add_f32_e32 v119, 1.0, v119
	v_rcp_f32_e32 v118, v118
	v_rcp_f32_e32 v119, v119
	v_pk_mul_f32 v[108:109], v[116:117], v[108:109] op_sel_hi:[0,1]
	v_mul_f32_e32 v117, 0xbfb8aa3b, v108
	v_exp_f32_e32 v117, v117
	v_mul_f32_e32 v125, 0xbfb8aa3b, v109
	v_pk_mul_f32 v[112:113], v[118:119], v[112:113]
	v_exp_f32_e32 v125, v125
	v_cvt_pk_bf16_f32 v123, v112, v113
	v_mov_b64_e32 v[112:113], s[0:1]
	v_mad_i64_i32 v[118:119], s[14:15], v124, s60, v[112:113]
	v_lshlrev_b64 v[114:115], 1, v[166:167]
	v_lshl_add_u64 v[118:119], v[118:119], 0, v[114:115]
	v_add_f32_e32 v117, 1.0, v117
	global_store_dwordx4 v[118:119], v[120:123], off
	v_rcp_f32_e32 v118, v117
	v_add_f32_e32 v117, 1.0, v125
	v_rcp_f32_e32 v119, v117
	v_or_b32_e32 v117, 16, v124
	v_pk_mul_f32 v[104:105], v[116:117], v[104:105] op_sel_hi:[0,1]
	v_pk_mul_f32 v[104:105], v[108:109], v[104:105]
	v_pk_mul_f32 v[108:109], v[116:117], v[110:111] op_sel_hi:[0,1]
	v_pk_mul_f32 v[104:105], v[118:119], v[104:105]
	v_mul_f32_e32 v110, 0xbfb8aa3b, v108
	v_cvt_pk_bf16_f32 v104, v104, v105
	v_mul_f32_e32 v105, 0xbfb8aa3b, v109
	v_exp_f32_e32 v110, v110
	v_exp_f32_e32 v105, v105
	v_pk_mul_f32 v[106:107], v[116:117], v[106:107] op_sel_hi:[0,1]
	v_pk_mul_f32 v[100:101], v[116:117], v[100:101] op_sel_hi:[0,1]
	v_add_f32_e32 v110, 1.0, v110
	v_add_f32_e32 v105, 1.0, v105
	v_rcp_f32_e32 v110, v110
	v_rcp_f32_e32 v111, v105
	v_pk_mul_f32 v[106:107], v[108:109], v[106:107]
	v_mul_f32_e32 v105, 0xbfb8aa3b, v100
	v_exp_f32_e32 v118, v105
	v_pk_mul_f32 v[106:107], v[110:111], v[106:107]
	v_pk_mul_f32 v[96:97], v[116:117], v[96:97] op_sel_hi:[0,1]
	v_cvt_pk_bf16_f32 v105, v106, v107
	v_mul_f32_e32 v107, 0xbfb8aa3b, v101
	v_exp_f32_e32 v107, v107
	v_pk_mul_f32 v[96:97], v[100:101], v[96:97]
	v_add_f32_e32 v106, 1.0, v118
	v_rcp_f32_e32 v106, v106
	v_add_f32_e32 v100, 1.0, v107
	v_rcp_f32_e32 v107, v100
	v_pk_mul_f32 v[100:101], v[116:117], v[102:103] op_sel_hi:[0,1]
	v_mul_f32_e32 v102, 0xbfb8aa3b, v100
	v_mul_f32_e32 v103, 0xbfb8aa3b, v101
	v_exp_f32_e32 v102, v102
	v_exp_f32_e32 v103, v103
	v_pk_mul_f32 v[96:97], v[106:107], v[96:97]
	v_add_f32_e32 v102, 1.0, v102
	v_add_f32_e32 v103, 1.0, v103
	v_rcp_f32_e32 v102, v102
	v_rcp_f32_e32 v103, v103
	v_cvt_pk_bf16_f32 v106, v96, v97
	v_pk_mul_f32 v[96:97], v[116:117], v[98:99] op_sel_hi:[0,1]
	v_pk_mul_f32 v[96:97], v[100:101], v[96:97]
	v_mad_i64_i32 v[98:99], s[14:15], v117, s60, v[112:113]
	v_pk_mul_f32 v[96:97], v[102:103], v[96:97]
	v_lshl_add_u64 v[98:99], v[98:99], 0, v[114:115]
	v_cvt_pk_bf16_f32 v107, v96, v97
	v_fmamk_f32 v96, v158, 0x3a000000, v153
	v_rsq_f32_e32 v96, v96
	global_store_dwordx4 v[98:99], v[104:107], off
	v_pk_mul_f32 v[92:93], v[96:97], v[92:93] op_sel_hi:[0,1]
	v_mul_f32_e32 v97, 0xbfb8aa3b, v92
	v_exp_f32_e32 v97, v97
	v_mul_f32_e32 v100, 0xbfb8aa3b, v93
	v_exp_f32_e32 v100, v100
	v_add_f32_e32 v97, 1.0, v97
	v_rcp_f32_e32 v98, v97
	v_add_f32_e32 v97, 1.0, v100
	v_rcp_f32_e32 v99, v97
	v_or_b32_e32 v97, 32, v124
	v_pk_mul_f32 v[88:89], v[96:97], v[88:89] op_sel_hi:[0,1]
	v_pk_mul_f32 v[88:89], v[92:93], v[88:89]
	v_pk_mul_f32 v[92:93], v[96:97], v[94:95] op_sel_hi:[0,1]
	v_pk_mul_f32 v[88:89], v[98:99], v[88:89]
	v_mul_f32_e32 v94, 0xbfb8aa3b, v92
	v_cvt_pk_bf16_f32 v88, v88, v89
	v_mul_f32_e32 v89, 0xbfb8aa3b, v93
	v_exp_f32_e32 v94, v94
	v_exp_f32_e32 v89, v89
	v_pk_mul_f32 v[90:91], v[96:97], v[90:91] op_sel_hi:[0,1]
	v_pk_mul_f32 v[84:85], v[96:97], v[84:85] op_sel_hi:[0,1]
	v_add_f32_e32 v94, 1.0, v94
; __device__ __forceinline__ float sigmoidf_(float x) { return __builtin_amdgcn_rcpf(1.0f + fexp(-x)); }
;     __device__ __forceinline__ void operator()(const f32x4 (&acc)[2][2][4][2], const Unit& u, int wr, int wc, int fr, int fq, const Pre& P) const {
;         const int row0 = ROW_X + u.pm * BM + wr * 64 + fr, col0 = u.pn * HALF + wc * 32 + 8 * fq;
; #pragma unroll
;         for (int ai = 0; ai < 2; ++ai)
; #pragma unroll
;             for (int m = 0; m < 4; ++m) { const int r = row0 + ai * HALF + m * 16; const float rs = __builtin_amdgcn_rsqf(P.rs[ai * 4 + m] * (1.0f / DM) + RMS_EPS);
;                 float y[8];
; #pragma unroll
;                 for (int n = 0; n < 2; ++n)
; #pragma unroll
;                     for (int j = 0; j < 4; ++j) { const float a = acc[ai][0][m][n][j] * rs, b = acc[ai][1][m][n][j] * rs; y[n * 4 + j] = a * b * sigmoidf_(a); }
;                 u32x4 w; w.x = cvtpk(y[0], y[1]); w.y = cvtpk(y[2], y[3]); w.z = cvtpk(y[4], y[5]); w.w = cvtpk(y[6], y[7]);
;                 *(u32x4*)(O + (size_t)r * FF + col0) = w; }
	v_add_f32_e32 v89, 1.0, v89
	v_rcp_f32_e32 v94, v94
	v_rcp_f32_e32 v95, v89
	v_pk_mul_f32 v[90:91], v[92:93], v[90:91]
	v_mul_f32_e32 v89, 0xbfb8aa3b, v84
	v_exp_f32_e32 v98, v89
	v_pk_mul_f32 v[90:91], v[94:95], v[90:91]
	v_pk_mul_f32 v[80:81], v[96:97], v[80:81] op_sel_hi:[0,1]
	v_cvt_pk_bf16_f32 v89, v90, v91
	v_mul_f32_e32 v91, 0xbfb8aa3b, v85
	v_exp_f32_e32 v91, v91
	v_pk_mul_f32 v[80:81], v[84:85], v[80:81]
	v_add_f32_e32 v90, 1.0, v98
	v_rcp_f32_e32 v90, v90
	v_add_f32_e32 v84, 1.0, v91
	v_rcp_f32_e32 v91, v84
	v_pk_mul_f32 v[84:85], v[96:97], v[86:87] op_sel_hi:[0,1]
	v_mul_f32_e32 v86, 0xbfb8aa3b, v84
	v_mul_f32_e32 v87, 0xbfb8aa3b, v85
	v_exp_f32_e32 v86, v86
	v_exp_f32_e32 v87, v87
	v_pk_mul_f32 v[80:81], v[90:91], v[80:81]
	v_add_f32_e32 v86, 1.0, v86
	v_add_f32_e32 v87, 1.0, v87
	v_rcp_f32_e32 v86, v86
	v_rcp_f32_e32 v87, v87
	v_cvt_pk_bf16_f32 v90, v80, v81
	v_pk_mul_f32 v[80:81], v[96:97], v[82:83] op_sel_hi:[0,1]
	v_pk_mul_f32 v[80:81], v[84:85], v[80:81]
	v_mad_i64_i32 v[82:83], s[14:15], v97, s60, v[112:113]
	v_pk_mul_f32 v[80:81], v[86:87], v[80:81]
	v_lshl_add_u64 v[82:83], v[82:83], 0, v[114:115]
	v_cvt_pk_bf16_f32 v91, v80, v81
	v_fmamk_f32 v80, v157, 0x3a000000, v153
	v_rsq_f32_e32 v80, v80
	global_store_dwordx4 v[82:83], v[88:91], off
	v_pk_mul_f32 v[76:77], v[80:81], v[76:77] op_sel_hi:[0,1]
	v_mul_f32_e32 v81, 0xbfb8aa3b, v76
	v_exp_f32_e32 v81, v81
	v_mul_f32_e32 v84, 0xbfb8aa3b, v77
	v_exp_f32_e32 v84, v84
	v_add_f32_e32 v81, 1.0, v81
	v_rcp_f32_e32 v82, v81
	v_add_f32_e32 v81, 1.0, v84
	v_rcp_f32_e32 v83, v81
	v_or_b32_e32 v81, 48, v124
	v_pk_mul_f32 v[72:73], v[80:81], v[72:73] op_sel_hi:[0,1]
	v_pk_mul_f32 v[72:73], v[76:77], v[72:73]
	v_pk_mul_f32 v[76:77], v[80:81], v[78:79] op_sel_hi:[0,1]
	v_pk_mul_f32 v[72:73], v[82:83], v[72:73]
	v_mul_f32_e32 v78, 0xbfb8aa3b, v76
	v_cvt_pk_bf16_f32 v72, v72, v73
	v_mul_f32_e32 v73, 0xbfb8aa3b, v77
	v_exp_f32_e32 v78, v78
	v_exp_f32_e32 v73, v73
	v_pk_mul_f32 v[74:75], v[80:81], v[74:75] op_sel_hi:[0,1]
	v_pk_mul_f32 v[68:69], v[80:81], v[68:69] op_sel_hi:[0,1]
	v_add_f32_e32 v78, 1.0, v78
	v_add_f32_e32 v73, 1.0, v73
	v_rcp_f32_e32 v78, v78
	v_rcp_f32_e32 v79, v73
	v_pk_mul_f32 v[74:75], v[76:77], v[74:75]
	v_mul_f32_e32 v73, 0xbfb8aa3b, v68
	v_exp_f32_e32 v82, v73
	v_pk_mul_f32 v[74:75], v[78:79], v[74:75]
	v_pk_mul_f32 v[64:65], v[80:81], v[64:65] op_sel_hi:[0,1]
	v_cvt_pk_bf16_f32 v73, v74, v75
	v_mul_f32_e32 v75, 0xbfb8aa3b, v69
	v_exp_f32_e32 v75, v75
	v_pk_mul_f32 v[64:65], v[68:69], v[64:65]
	v_add_f32_e32 v74, 1.0, v82
	v_rcp_f32_e32 v74, v74
	v_add_f32_e32 v68, 1.0, v75
	v_rcp_f32_e32 v75, v68
	v_pk_mul_f32 v[68:69], v[80:81], v[70:71] op_sel_hi:[0,1]
	v_mul_f32_e32 v70, 0xbfb8aa3b, v68
	v_mul_f32_e32 v71, 0xbfb8aa3b, v69
	v_exp_f32_e32 v70, v70
	v_exp_f32_e32 v71, v71
	v_pk_mul_f32 v[64:65], v[74:75], v[64:65]
	v_add_f32_e32 v70, 1.0, v70
	v_add_f32_e32 v71, 1.0, v71
	v_rcp_f32_e32 v70, v70
	v_rcp_f32_e32 v71, v71
	v_cvt_pk_bf16_f32 v74, v64, v65
	v_pk_mul_f32 v[64:65], v[80:81], v[66:67] op_sel_hi:[0,1]
	v_pk_mul_f32 v[64:65], v[68:69], v[64:65]
	v_mad_i64_i32 v[66:67], s[14:15], v81, s60, v[112:113]
	v_pk_mul_f32 v[64:65], v[70:71], v[64:65]
	v_lshl_add_u64 v[66:67], v[66:67], 0, v[114:115]
	v_cvt_pk_bf16_f32 v75, v64, v65
	v_fmamk_f32 v64, v156, 0x3a000000, v153
	v_rsq_f32_e32 v64, v64
	global_store_dwordx4 v[66:67], v[72:75], off
	v_pk_mul_f32 v[60:61], v[64:65], v[60:61] op_sel_hi:[0,1]
	v_mul_f32_e32 v65, 0xbfb8aa3b, v60
	v_exp_f32_e32 v65, v65
	v_mul_f32_e32 v68, 0xbfb8aa3b, v61
	v_exp_f32_e32 v68, v68
	v_add_f32_e32 v65, 1.0, v65
	v_rcp_f32_e32 v66, v65
	v_add_f32_e32 v65, 1.0, v68
	v_rcp_f32_e32 v67, v65
	v_add_u32_e32 v65, 0x80, v124
	v_pk_mul_f32 v[56:57], v[64:65], v[56:57] op_sel_hi:[0,1]
	v_pk_mul_f32 v[56:57], v[60:61], v[56:57]
	v_pk_mul_f32 v[60:61], v[64:65], v[62:63] op_sel_hi:[0,1]
	v_pk_mul_f32 v[56:57], v[66:67], v[56:57]
	v_mul_f32_e32 v62, 0xbfb8aa3b, v60
	v_cvt_pk_bf16_f32 v56, v56, v57
	v_mul_f32_e32 v57, 0xbfb8aa3b, v61
	v_exp_f32_e32 v62, v62
	v_exp_f32_e32 v57, v57
	v_pk_mul_f32 v[58:59], v[64:65], v[58:59] op_sel_hi:[0,1]
	v_pk_mul_f32 v[52:53], v[64:65], v[52:53] op_sel_hi:[0,1]
	v_add_f32_e32 v62, 1.0, v62
	v_add_f32_e32 v57, 1.0, v57
	v_rcp_f32_e32 v62, v62
	v_rcp_f32_e32 v63, v57
	v_pk_mul_f32 v[58:59], v[60:61], v[58:59]
	v_mul_f32_e32 v57, 0xbfb8aa3b, v52
	v_exp_f32_e32 v66, v57
	v_pk_mul_f32 v[58:59], v[62:63], v[58:59]
	v_pk_mul_f32 v[48:49], v[64:65], v[48:49] op_sel_hi:[0,1]
	v_cvt_pk_bf16_f32 v57, v58, v59
	v_mul_f32_e32 v59, 0xbfb8aa3b, v53
	v_exp_f32_e32 v59, v59
	v_pk_mul_f32 v[48:49], v[52:53], v[48:49]
	v_add_f32_e32 v58, 1.0, v66
	v_rcp_f32_e32 v58, v58
	v_add_f32_e32 v52, 1.0, v59
	v_rcp_f32_e32 v59, v52
	v_pk_mul_f32 v[52:53], v[64:65], v[54:55] op_sel_hi:[0,1]
	v_mul_f32_e32 v54, 0xbfb8aa3b, v52
	v_mul_f32_e32 v55, 0xbfb8aa3b, v53
	v_exp_f32_e32 v54, v54
	v_exp_f32_e32 v55, v55
	v_pk_mul_f32 v[48:49], v[58:59], v[48:49]
	v_add_f32_e32 v54, 1.0, v54
	v_add_f32_e32 v55, 1.0, v55
	v_rcp_f32_e32 v54, v54
	v_rcp_f32_e32 v55, v55
	v_cvt_pk_bf16_f32 v58, v48, v49
	v_pk_mul_f32 v[48:49], v[64:65], v[50:51] op_sel_hi:[0,1]
	v_pk_mul_f32 v[48:49], v[52:53], v[48:49]
	v_mad_i64_i32 v[50:51], s[14:15], v65, s60, v[112:113]
	v_pk_mul_f32 v[48:49], v[54:55], v[48:49]
	v_lshl_add_u64 v[50:51], v[50:51], 0, v[114:115]
	v_cvt_pk_bf16_f32 v59, v48, v49
	v_fmamk_f32 v48, v155, 0x3a000000, v153
	v_rsq_f32_e32 v48, v48
	global_store_dwordx4 v[50:51], v[56:59], off
	v_pk_mul_f32 v[44:45], v[48:49], v[44:45] op_sel_hi:[0,1]
	v_mul_f32_e32 v49, 0xbfb8aa3b, v44
	v_exp_f32_e32 v49, v49
	v_mul_f32_e32 v52, 0xbfb8aa3b, v45
; __device__ __forceinline__ float sigmoidf_(float x) { return __builtin_amdgcn_rcpf(1.0f + fexp(-x)); }
; __device__ __forceinline__ PreRs load_rs(const float* ssq, int pm, int wr, int fr) { PreRs p;
; #pragma unroll
;     for (int ai = 0; ai < 2; ++ai)
; #pragma unroll
;         for (int m = 0; m < 4; ++m) p.rs[ai * 4 + m] = ssq[ROW_X + pm * BM + ai * HALF + wr * 64 + m * 16 + fr];
;     return p; }
;     __device__ __forceinline__ void operator()(const f32x4 (&acc)[2][2][4][2], const Unit& u, int wr, int wc, int fr, int fq, const Pre& P) const {
;         const int row0 = ROW_X + u.pm * BM + wr * 64 + fr, col0 = u.pn * HALF + wc * 32 + 8 * fq;
; #pragma unroll
;         for (int ai = 0; ai < 2; ++ai)
; #pragma unroll
;             for (int m = 0; m < 4; ++m) { const int r = row0 + ai * HALF + m * 16; const float rs = __builtin_amdgcn_rsqf(P.rs[ai * 4 + m] * (1.0f / DM) + RMS_EPS);
;                 float y[8];
; #pragma unroll
;                 for (int n = 0; n < 2; ++n)
; #pragma unroll
;                     for (int j = 0; j < 4; ++j) { const float a = acc[ai][0][m][n][j] * rs, b = acc[ai][1][m][n][j] * rs; y[n * 4 + j] = a * b * sigmoidf_(a); }
;                 u32x4 w; w.x = cvtpk(y[0], y[1]); w.y = cvtpk(y[2], y[3]); w.z = cvtpk(y[4], y[5]); w.w = cvtpk(y[6], y[7]);
;                 *(u32x4*)(O + (size_t)r * FF + col0) = w; }
	v_exp_f32_e32 v52, v52
	v_add_f32_e32 v49, 1.0, v49
	v_rcp_f32_e32 v50, v49
	v_add_f32_e32 v49, 1.0, v52
	v_rcp_f32_e32 v51, v49
	v_add_u32_e32 v49, 0x90, v124
	v_pk_mul_f32 v[40:41], v[48:49], v[40:41] op_sel_hi:[0,1]
	v_pk_mul_f32 v[40:41], v[44:45], v[40:41]
	v_pk_mul_f32 v[44:45], v[48:49], v[46:47] op_sel_hi:[0,1]
	v_pk_mul_f32 v[40:41], v[50:51], v[40:41]
	v_mul_f32_e32 v46, 0xbfb8aa3b, v44
	v_cvt_pk_bf16_f32 v40, v40, v41
	v_mul_f32_e32 v41, 0xbfb8aa3b, v45
	v_exp_f32_e32 v46, v46
	v_exp_f32_e32 v41, v41
	v_pk_mul_f32 v[42:43], v[48:49], v[42:43] op_sel_hi:[0,1]
	v_pk_mul_f32 v[36:37], v[48:49], v[36:37] op_sel_hi:[0,1]
	v_add_f32_e32 v46, 1.0, v46
	v_add_f32_e32 v41, 1.0, v41
	v_rcp_f32_e32 v46, v46
	v_rcp_f32_e32 v47, v41
	v_pk_mul_f32 v[42:43], v[44:45], v[42:43]
	v_mul_f32_e32 v41, 0xbfb8aa3b, v36
	v_exp_f32_e32 v50, v41
	v_pk_mul_f32 v[42:43], v[46:47], v[42:43]
	v_pk_mul_f32 v[32:33], v[48:49], v[32:33] op_sel_hi:[0,1]
	v_cvt_pk_bf16_f32 v41, v42, v43
	v_mul_f32_e32 v43, 0xbfb8aa3b, v37
	v_exp_f32_e32 v43, v43
	v_pk_mul_f32 v[32:33], v[36:37], v[32:33]
	v_add_f32_e32 v42, 1.0, v50
	v_rcp_f32_e32 v42, v42
	v_add_f32_e32 v36, 1.0, v43
	v_rcp_f32_e32 v43, v36
	v_pk_mul_f32 v[36:37], v[48:49], v[38:39] op_sel_hi:[0,1]
	v_mul_f32_e32 v38, 0xbfb8aa3b, v36
	v_mul_f32_e32 v39, 0xbfb8aa3b, v37
	v_exp_f32_e32 v38, v38
	v_exp_f32_e32 v39, v39
	v_pk_mul_f32 v[32:33], v[42:43], v[32:33]
	v_add_f32_e32 v38, 1.0, v38
	v_add_f32_e32 v39, 1.0, v39
	v_rcp_f32_e32 v38, v38
	v_rcp_f32_e32 v39, v39
	v_cvt_pk_bf16_f32 v42, v32, v33
	v_pk_mul_f32 v[32:33], v[48:49], v[34:35] op_sel_hi:[0,1]
	v_pk_mul_f32 v[32:33], v[36:37], v[32:33]
	v_mad_i64_i32 v[34:35], s[14:15], v49, s60, v[112:113]
	v_pk_mul_f32 v[32:33], v[38:39], v[32:33]
	v_lshl_add_u64 v[34:35], v[34:35], 0, v[114:115]
	v_cvt_pk_bf16_f32 v43, v32, v33
	v_fmamk_f32 v32, v154, 0x3a000000, v153
	v_rsq_f32_e32 v32, v32
	global_store_dwordx4 v[34:35], v[40:43], off
	v_pk_mul_f32 v[28:29], v[32:33], v[28:29] op_sel_hi:[0,1]
	v_mul_f32_e32 v33, 0xbfb8aa3b, v28
	v_exp_f32_e32 v33, v33
	v_mul_f32_e32 v36, 0xbfb8aa3b, v29
	v_exp_f32_e32 v36, v36
	v_add_f32_e32 v33, 1.0, v33
	v_rcp_f32_e32 v34, v33
	v_add_f32_e32 v33, 1.0, v36
	v_rcp_f32_e32 v35, v33
	v_add_u32_e32 v33, 0xa0, v124
	v_pk_mul_f32 v[24:25], v[32:33], v[24:25] op_sel_hi:[0,1]
	v_pk_mul_f32 v[24:25], v[28:29], v[24:25]
	v_pk_mul_f32 v[28:29], v[32:33], v[30:31] op_sel_hi:[0,1]
	v_pk_mul_f32 v[24:25], v[34:35], v[24:25]
	v_mul_f32_e32 v30, 0xbfb8aa3b, v28
	v_cvt_pk_bf16_f32 v24, v24, v25
	v_mul_f32_e32 v25, 0xbfb8aa3b, v29
	v_exp_f32_e32 v30, v30
	v_exp_f32_e32 v25, v25
	v_pk_mul_f32 v[26:27], v[32:33], v[26:27] op_sel_hi:[0,1]
	v_pk_mul_f32 v[20:21], v[32:33], v[20:21] op_sel_hi:[0,1]
	v_add_f32_e32 v30, 1.0, v30
	v_add_f32_e32 v25, 1.0, v25
	v_rcp_f32_e32 v30, v30
	v_rcp_f32_e32 v31, v25
	v_pk_mul_f32 v[26:27], v[28:29], v[26:27]
	v_mul_f32_e32 v25, 0xbfb8aa3b, v20
	v_exp_f32_e32 v34, v25
	v_pk_mul_f32 v[26:27], v[30:31], v[26:27]
	v_pk_mul_f32 v[16:17], v[32:33], v[16:17] op_sel_hi:[0,1]
	v_cvt_pk_bf16_f32 v25, v26, v27
	v_mul_f32_e32 v27, 0xbfb8aa3b, v21
	v_exp_f32_e32 v27, v27
	v_pk_mul_f32 v[16:17], v[20:21], v[16:17]
	v_add_f32_e32 v26, 1.0, v34
	v_rcp_f32_e32 v26, v26
	v_add_f32_e32 v20, 1.0, v27
	v_rcp_f32_e32 v27, v20
	v_pk_mul_f32 v[20:21], v[32:33], v[22:23] op_sel_hi:[0,1]
	v_mul_f32_e32 v22, 0xbfb8aa3b, v20
	v_mul_f32_e32 v23, 0xbfb8aa3b, v21
	v_exp_f32_e32 v22, v22
	v_exp_f32_e32 v23, v23
	v_pk_mul_f32 v[16:17], v[26:27], v[16:17]
	v_add_f32_e32 v22, 1.0, v22
	v_add_f32_e32 v23, 1.0, v23
	v_rcp_f32_e32 v22, v22
	v_rcp_f32_e32 v23, v23
	v_cvt_pk_bf16_f32 v26, v16, v17
	v_pk_mul_f32 v[16:17], v[32:33], v[18:19] op_sel_hi:[0,1]
	v_pk_mul_f32 v[16:17], v[20:21], v[16:17]
	v_mad_i64_i32 v[18:19], s[14:15], v33, s60, v[112:113]
	v_pk_mul_f32 v[16:17], v[22:23], v[16:17]
	v_lshl_add_u64 v[18:19], v[18:19], 0, v[114:115]
	v_cvt_pk_bf16_f32 v27, v16, v17
	v_fmamk_f32 v16, v151, 0x3a000000, v153
	v_rsq_f32_e32 v16, v16
	global_store_dwordx4 v[18:19], v[24:27], off
	v_pk_mul_f32 v[12:13], v[16:17], v[12:13] op_sel_hi:[0,1]
	v_mul_f32_e32 v17, 0xbfb8aa3b, v12
	v_exp_f32_e32 v17, v17
	v_mul_f32_e32 v20, 0xbfb8aa3b, v13
	v_exp_f32_e32 v20, v20
	v_add_f32_e32 v17, 1.0, v17
	v_rcp_f32_e32 v18, v17
	v_add_f32_e32 v17, 1.0, v20
	v_rcp_f32_e32 v19, v17
	v_add_u32_e32 v17, 0xb0, v124
	v_pk_mul_f32 v[8:9], v[16:17], v[8:9] op_sel_hi:[0,1]
	v_pk_mul_f32 v[8:9], v[12:13], v[8:9]
	v_pk_mul_f32 v[12:13], v[16:17], v[14:15] op_sel_hi:[0,1]
	v_pk_mul_f32 v[8:9], v[18:19], v[8:9]
	v_mul_f32_e32 v14, 0xbfb8aa3b, v12
	v_cvt_pk_bf16_f32 v8, v8, v9
	v_mul_f32_e32 v9, 0xbfb8aa3b, v13
	v_exp_f32_e32 v14, v14
	v_exp_f32_e32 v9, v9
	v_pk_mul_f32 v[10:11], v[16:17], v[10:11] op_sel_hi:[0,1]
	v_pk_mul_f32 v[4:5], v[16:17], v[4:5] op_sel_hi:[0,1]
	v_add_f32_e32 v14, 1.0, v14
	v_add_f32_e32 v9, 1.0, v9
	v_rcp_f32_e32 v14, v14
	v_rcp_f32_e32 v15, v9
	v_pk_mul_f32 v[10:11], v[12:13], v[10:11]
	v_mul_f32_e32 v9, 0xbfb8aa3b, v4
	v_exp_f32_e32 v18, v9
	v_pk_mul_f32 v[10:11], v[14:15], v[10:11]
	v_pk_mul_f32 v[0:1], v[16:17], v[0:1] op_sel_hi:[0,1]
	v_cvt_pk_bf16_f32 v9, v10, v11
	v_mul_f32_e32 v11, 0xbfb8aa3b, v5
	v_exp_f32_e32 v11, v11
	v_pk_mul_f32 v[0:1], v[4:5], v[0:1]
	v_add_f32_e32 v10, 1.0, v18
	v_rcp_f32_e32 v10, v10
	v_add_f32_e32 v4, 1.0, v11
	v_rcp_f32_e32 v11, v4
	v_pk_mul_f32 v[4:5], v[16:17], v[6:7] op_sel_hi:[0,1]
	v_mul_f32_e32 v6, 0xbfb8aa3b, v4
	v_mul_f32_e32 v7, 0xbfb8aa3b, v5
	v_exp_f32_e32 v6, v6
	v_exp_f32_e32 v7, v7
	v_pk_mul_f32 v[0:1], v[10:11], v[0:1]
	v_add_f32_e32 v6, 1.0, v6
	v_add_f32_e32 v7, 1.0, v7
	v_rcp_f32_e32 v6, v6
	v_rcp_f32_e32 v7, v7
	v_cvt_pk_bf16_f32 v10, v0, v1
	v_pk_mul_f32 v[0:1], v[16:17], v[2:3] op_sel_hi:[0,1]
	v_pk_mul_f32 v[0:1], v[4:5], v[0:1]
	s_nop 0
	v_pk_mul_f32 v[0:1], v[6:7], v[0:1]
	s_nop 0
	v_cvt_pk_bf16_f32 v11, v0, v1
	v_mad_i64_i32 v[0:1], s[14:15], v17, s60, v[112:113]
	v_lshl_add_u64 v[0:1], v[0:1], 0, v[114:115]
	s_mov_b64 s[14:15], -1
	global_store_dwordx4 v[0:1], v[8:11], off
	s_cbranch_vccz .LBB0_1302
	v_lshl_add_u32 v0, s8, 8, v146
	v_ashrrev_i32_e32 v1, 31, v0
	v_lshl_add_u64 v[2:3], v[0:1], 2, s[2:3]
	v_add_u32_e32 v4, 0x80, v0
	v_add_u32_e32 v6, 0x90, v0
	v_add_u32_e32 v8, 0xa0, v0
	v_add_u32_e32 v0, 0xb0, v0
	v_ashrrev_i32_e32 v5, 31, v4
	v_ashrrev_i32_e32 v7, 31, v6
	v_ashrrev_i32_e32 v9, 31, v8
	v_ashrrev_i32_e32 v1, 31, v0
	v_lshl_add_u64 v[4:5], v[4:5], 2, s[2:3]
	v_lshl_add_u64 v[6:7], v[6:7], 2, s[2:3]
	v_lshl_add_u64 v[8:9], v[8:9], 2, s[2:3]
	v_lshl_add_u64 v[0:1], v[0:1], 2, s[2:3]
	global_load_dword v160, v[2:3], off
	global_load_dword v159, v[2:3], off offset:64
	global_load_dword v158, v[2:3], off offset:128
	global_load_dword v157, v[2:3], off offset:192
	global_load_dword v156, v[4:5], off
	global_load_dword v155, v[6:7], off
	global_load_dword v154, v[8:9], off
	global_load_dword v151, v[0:1], off
	s_mov_b64 s[14:15], 0
	s_branch .LBB0_1302

; #define PG8_STAGE(bufoff, gbase, voff) do { _Pragma("unroll") for (int _i = 0; _i < 2; ++_i) \
;         __builtin_amdgcn_global_load_lds((const unsigned*)((const char*)(gbase) + (voff)[_i]), (LAS unsigned*)(lds + (bufoff) + ldsw + _i * 8192), 16, 0, 0); } while (0)
; #define PG8_LDA(dst, b, h) do { _Pragma("unroll") for (int m = 0; m < 4; ++m) _Pragma("unroll") for (int k = 0; k < 2; ++k) dst[m][k] = *(const LAS bf16x8*)(lds + PG8_SA(b, h) + aoff + m * 2048 + k * 1024); } while (0)
; #define PG8_LDB(dst, b, h) do { _Pragma("unroll") for (int n = 0; n < 2; ++n) _Pragma("unroll") for (int k = 0; k < 2; ++k) dst[n][k] = *(const LAS bf16x8*)(lds + PG8_SB(b, h) + boff + n * 2048 + k * 1024); } while (0)
; #define PG8_MMA(ai, bj, At, Bt) do { __builtin_amdgcn_s_setprio(1); _Pragma("unroll") for (int m = 0; m < 4; ++m) _Pragma("unroll") for (int n = 0; n < 2; ++n) _Pragma("unroll") for (int k = 0; k < 2; ++k) \
;         acc[ai][bj][m][n] = __builtin_amdgcn_mfma_f32_16x16x32_bf16(Bt[n][k], At[m][k], acc[ai][bj][m][n], 0, 0, 0); __builtin_amdgcn_s_setprio(0); } while (0)
; #define PG8_WAIT_L(n) asm volatile("s_waitcnt lgkmcnt(" #n ")" ::: "memory")
; #define PG8_BAR __builtin_amdgcn_s_barrier()
; #define PG8_SCHED __builtin_amdgcn_sched_barrier(0)
; template <class Epi>
; __device__ __forceinline__ void gemm_phase(LAS unsigned char* lds, const Gemm g, const StaticOrder& S, const Epi& E) {
;     ...
;             const bool last = (t == nt - 2);
;             const char* a1 = cA + (size_t)(t + 1) * kstep;
;             const char* a2 = last ? nA : cA + (size_t)(t + 2) * kstep; const char* b2 = last ? nB : cB + (size_t)(t + 2) * kstep;
;             const char* a3 = a2 + kstep; const char* b3 = b2 + kstep;
;             PG8_LDB(B0, 0, 0); PG8_SCHED; PG8_LDA(At, 0, 0); PG8_STAGE(PG8_SA(1, 1), a1 + hstep, voffA);
;             PG8_WAIT_L(8); PG8_BAR; PG8_WAIT_L(0); PG8_MMA(0, 0, At, B0); PG8_BAR; PG8_SCHED;
.LBB0_1411:
	ds_read_b128 v[128:131], v162
	ds_read_b128 v[132:135], v162 offset:1024
	ds_read_b128 v[154:157], v162 offset:2048
	ds_read_b128 v[168:171], v162 offset:3072
	s_add_u32 s16, s14, 0xffea8080
	s_addc_u32 s17, s15, -1
	s_cmpk_eq_i32 s63, 0x52
	s_cselect_b32 s19, s1, s17
	s_cselect_b32 s18, s0, s16
	s_cselect_b32 s17, s7, s62
	s_cselect_b32 s16, s6, s61
	v_lshl_add_u64 v[158:159], s[14:15], 0, v[146:147]
	s_add_i32 m0, s30, 0xc000
	ds_read_b128 v[172:175], v163
	ds_read_b128 v[180:183], v163 offset:1024
	ds_read_b128 v[184:187], v163 offset:2048
	ds_read_b128 v[188:191], v163 offset:3072
	ds_read_b128 v[192:195], v163 offset:4096
	ds_read_b128 v[196:199], v163 offset:5120
	ds_read_b128 v[200:203], v163 offset:6144
	ds_read_b128 v[204:207], v163 offset:7168
	global_load_lds_dwordx4 v[158:159], off
	v_lshl_add_u64 v[158:159], s[14:15], 0, v[148:149]
	s_add_i32 m0, s30, 0xe000
	s_nop 0
	global_load_lds_dwordx4 v[158:159], off
	s_waitcnt lgkmcnt(8)
	s_setprio 1
	s_barrier
	s_waitcnt lgkmcnt(0)


; #define PG8_MMA(ai, bj, At, Bt) do { __builtin_amdgcn_s_setprio(1); _Pragma("unroll") for (int m = 0; m < 4; ++m) _Pragma("unroll") for (int n = 0; n < 2; ++n) _Pragma("unroll") for (int k = 0; k < 2; ++k) \
;         acc[ai][bj][m][n] = __builtin_amdgcn_mfma_f32_16x16x32_bf16(Bt[n][k], At[m][k], acc[ai][bj][m][n], 0, 0, 0); __builtin_amdgcn_s_setprio(0); } while (0)
; #define PG8_WAIT_L(n) asm volatile("s_waitcnt lgkmcnt(" #n ")" ::: "memory")
; #define PG8_BAR __builtin_amdgcn_s_barrier()
; #define PG8_SCHED __builtin_amdgcn_sched_barrier(0)
; template <class Epi>
; __device__ __forceinline__ void gemm_phase(LAS unsigned char* lds, const Gemm g, const StaticOrder& S, const Epi& E) {
;     ...
;             PG8_WAIT_L(8); PG8_BAR; PG8_WAIT_L(0); PG8_MMA(0, 0, At, B0); PG8_BAR; PG8_SCHED;
	v_mfma_f32_16x16x32_bf16 v[124:127], v[128:131], v[172:175], v[124:127]
	v_mfma_f32_16x16x32_bf16 v[120:123], v[154:157], v[172:175], v[120:123]
	v_mfma_f32_16x16x32_bf16 v[108:111], v[128:131], v[184:187], v[108:111]
	v_mfma_f32_16x16x32_bf16 v[104:107], v[154:157], v[184:187], v[104:107]
	v_mfma_f32_16x16x32_bf16 v[92:95], v[128:131], v[192:195], v[92:95]
	v_mfma_f32_16x16x32_bf16 v[88:91], v[154:157], v[192:195], v[88:91]
	v_mfma_f32_16x16x32_bf16 v[76:79], v[128:131], v[200:203], v[76:79]
	v_mfma_f32_16x16x32_bf16 v[72:75], v[154:157], v[200:203], v[72:75]
	v_mfma_f32_16x16x32_bf16 v[124:127], v[132:135], v[180:183], v[124:127]
	v_mfma_f32_16x16x32_bf16 v[120:123], v[168:171], v[180:183], v[120:123]
	v_mfma_f32_16x16x32_bf16 v[108:111], v[132:135], v[188:191], v[108:111]
	v_mfma_f32_16x16x32_bf16 v[104:107], v[168:171], v[188:191], v[104:107]
	v_mfma_f32_16x16x32_bf16 v[92:95], v[132:135], v[196:199], v[92:95]
	v_mfma_f32_16x16x32_bf16 v[88:91], v[168:171], v[196:199], v[88:91]
	v_mfma_f32_16x16x32_bf16 v[76:79], v[132:135], v[204:207], v[76:79]
	v_mfma_f32_16x16x32_bf16 v[72:75], v[168:171], v[204:207], v[72:75]
	s_barrier
	s_setprio 0

; #define PG8_STAGE(bufoff, gbase, voff) do { _Pragma("unroll") for (int _i = 0; _i < 2; ++_i) \
;         __builtin_amdgcn_global_load_lds((const unsigned*)((const char*)(gbase) + (voff)[_i]), (LAS unsigned*)(lds + (bufoff) + ldsw + _i * 8192), 16, 0, 0); } while (0)
; #define PG8_LDB(dst, b, h) do { _Pragma("unroll") for (int n = 0; n < 2; ++n) _Pragma("unroll") for (int k = 0; k < 2; ++k) dst[n][k] = *(const LAS bf16x8*)(lds + PG8_SB(b, h) + boff + n * 2048 + k * 1024); } while (0)
; #define PG8_MMA(ai, bj, At, Bt) do { __builtin_amdgcn_s_setprio(1); _Pragma("unroll") for (int m = 0; m < 4; ++m) _Pragma("unroll") for (int n = 0; n < 2; ++n) _Pragma("unroll") for (int k = 0; k < 2; ++k) \
;         acc[ai][bj][m][n] = __builtin_amdgcn_mfma_f32_16x16x32_bf16(Bt[n][k], At[m][k], acc[ai][bj][m][n], 0, 0, 0); __builtin_amdgcn_s_setprio(0); } while (0)
; #define PG8_WAIT_L(n) asm volatile("s_waitcnt lgkmcnt(" #n ")" ::: "memory")
; #define PG8_BAR __builtin_amdgcn_s_barrier()
; template <class Epi>
; __device__ __forceinline__ void gemm_phase(LAS unsigned char* lds, const Gemm g, const StaticOrder& S, const Epi& E) {
;     ...
;             PG8_LDB(B1, 0, 1); PG8_STAGE(PG8_SB(0, 0), b2, voffB);
;             PG8_BAR; PG8_WAIT_L(0); PG8_MMA(0, 1, At, B1); PG8_BAR;
	s_add_i32 s64, s43, s21
	v_lshl_add_u64 v[158:159], s[16:17], 0, v[140:141]
	s_mov_b32 m0, s64
	ds_read_b128 v[208:211], v165
	ds_read_b128 v[212:215], v165 offset:1024
	ds_read_b128 v[216:219], v165 offset:2048
	ds_read_b128 v[220:223], v165 offset:3072
	global_load_lds_dwordx4 v[158:159], off
	v_lshl_add_u64 v[176:177], s[16:17], 0, v[144:145]
	s_add_i32 m0, s64, 0x2000
	s_nop 0
	global_load_lds_dwordx4 v[176:177], off
	s_waitcnt lgkmcnt(0)
	s_setprio 1
	s_barrier


; #define PG8_MMA(ai, bj, At, Bt) do { __builtin_amdgcn_s_setprio(1); _Pragma("unroll") for (int m = 0; m < 4; ++m) _Pragma("unroll") for (int n = 0; n < 2; ++n) _Pragma("unroll") for (int k = 0; k < 2; ++k) \
;         acc[ai][bj][m][n] = __builtin_amdgcn_mfma_f32_16x16x32_bf16(Bt[n][k], At[m][k], acc[ai][bj][m][n], 0, 0, 0); __builtin_amdgcn_s_setprio(0); } while (0)
; #define PG8_WAIT_L(n) asm volatile("s_waitcnt lgkmcnt(" #n ")" ::: "memory")
; #define PG8_BAR __builtin_amdgcn_s_barrier()
; template <class Epi>
; __device__ __forceinline__ void gemm_phase(LAS unsigned char* lds, const Gemm g, const StaticOrder& S, const Epi& E) {
;     ...
;             PG8_BAR; PG8_WAIT_L(0); PG8_MMA(0, 1, At, B1); PG8_BAR;
	v_mfma_f32_16x16x32_bf16 v[116:119], v[208:211], v[172:175], v[116:119]
	v_mfma_f32_16x16x32_bf16 v[112:115], v[216:219], v[172:175], v[112:115]
	v_mfma_f32_16x16x32_bf16 v[100:103], v[208:211], v[184:187], v[100:103]
	v_mfma_f32_16x16x32_bf16 v[96:99], v[216:219], v[184:187], v[96:99]
	v_mfma_f32_16x16x32_bf16 v[84:87], v[208:211], v[192:195], v[84:87]
	v_mfma_f32_16x16x32_bf16 v[80:83], v[216:219], v[192:195], v[80:83]
	v_mfma_f32_16x16x32_bf16 v[68:71], v[208:211], v[200:203], v[68:71]
	v_mfma_f32_16x16x32_bf16 v[64:67], v[216:219], v[200:203], v[64:67]
	v_mfma_f32_16x16x32_bf16 v[116:119], v[212:215], v[180:183], v[116:119]
	v_mfma_f32_16x16x32_bf16 v[112:115], v[220:223], v[180:183], v[112:115]
	v_mfma_f32_16x16x32_bf16 v[100:103], v[212:215], v[188:191], v[100:103]
	v_mfma_f32_16x16x32_bf16 v[96:99], v[220:223], v[188:191], v[96:99]
	v_mfma_f32_16x16x32_bf16 v[84:87], v[212:215], v[196:199], v[84:87]
	v_mfma_f32_16x16x32_bf16 v[80:83], v[220:223], v[196:199], v[80:83]
	v_mfma_f32_16x16x32_bf16 v[68:71], v[212:215], v[204:207], v[68:71]
	v_mfma_f32_16x16x32_bf16 v[64:67], v[220:223], v[204:207], v[64:67]
	s_barrier
	s_setprio 0
	s_mov_b32 m0, s30
	v_lshl_add_u64 v[224:225], s[18:19], 0, v[138:139]


; #define PG8_STAGE(bufoff, gbase, voff) do { _Pragma("unroll") for (int _i = 0; _i < 2; ++_i) \
;         __builtin_amdgcn_global_load_lds((const unsigned*)((const char*)(gbase) + (voff)[_i]), (LAS unsigned*)(lds + (bufoff) + ldsw + _i * 8192), 16, 0, 0); } while (0)
; #define PG8_LDA(dst, b, h) do { _Pragma("unroll") for (int m = 0; m < 4; ++m) _Pragma("unroll") for (int k = 0; k < 2; ++k) dst[m][k] = *(const LAS bf16x8*)(lds + PG8_SA(b, h) + aoff + m * 2048 + k * 1024); } while (0)
; #define PG8_MMA(ai, bj, At, Bt) do { __builtin_amdgcn_s_setprio(1); _Pragma("unroll") for (int m = 0; m < 4; ++m) _Pragma("unroll") for (int n = 0; n < 2; ++n) _Pragma("unroll") for (int k = 0; k < 2; ++k) \
;         acc[ai][bj][m][n] = __builtin_amdgcn_mfma_f32_16x16x32_bf16(Bt[n][k], At[m][k], acc[ai][bj][m][n], 0, 0, 0); __builtin_amdgcn_s_setprio(0); } while (0)
; #define PG8_WAIT_L(n) asm volatile("s_waitcnt lgkmcnt(" #n ")" ::: "memory")
; #define PG8_BAR __builtin_amdgcn_s_barrier()
; #define PG8_SCHED __builtin_amdgcn_sched_barrier(0)
; template <class Epi>
; __device__ __forceinline__ void gemm_phase(LAS unsigned char* lds, const Gemm g, const StaticOrder& S, const Epi& E) {
;     ...
;             PG8_LDA(At, 0, 1); PG8_STAGE(PG8_SA(0, 0), a2, voffA);
;             PG8_BAR; PG8_WAIT_L(0); PG8_MMA(1, 0, At, B0); PG8_BAR; PG8_SCHED;
	ds_read_b128 v[172:175], v163 offset:16384
	ds_read_b128 v[180:183], v163 offset:17408
	ds_read_b128 v[184:187], v163 offset:18432
	ds_read_b128 v[188:191], v163 offset:19456
	ds_read_b128 v[192:195], v163 offset:20480
	ds_read_b128 v[196:199], v163 offset:21504
	ds_read_b128 v[200:203], v163 offset:22528
	ds_read_b128 v[204:207], v163 offset:23552
	global_load_lds_dwordx4 v[224:225], off
	v_lshl_add_u64 v[226:227], s[18:19], 0, v[142:143]
	s_mov_b32 m0, s31
	s_nop 0
	global_load_lds_dwordx4 v[226:227], off
	s_waitcnt lgkmcnt(0)
	s_setprio 1
	s_barrier


; #define PG8_MMA(ai, bj, At, Bt) do { __builtin_amdgcn_s_setprio(1); _Pragma("unroll") for (int m = 0; m < 4; ++m) _Pragma("unroll") for (int n = 0; n < 2; ++n) _Pragma("unroll") for (int k = 0; k < 2; ++k) \
;         acc[ai][bj][m][n] = __builtin_amdgcn_mfma_f32_16x16x32_bf16(Bt[n][k], At[m][k], acc[ai][bj][m][n], 0, 0, 0); __builtin_amdgcn_s_setprio(0); } while (0)
; #define PG8_WAIT_L(n) asm volatile("s_waitcnt lgkmcnt(" #n ")" ::: "memory")
; #define PG8_BAR __builtin_amdgcn_s_barrier()
; #define PG8_SCHED __builtin_amdgcn_sched_barrier(0)
; template <class Epi>
; __device__ __forceinline__ void gemm_phase(LAS unsigned char* lds, const Gemm g, const StaticOrder& S, const Epi& E) {
;     ...
;             PG8_BAR; PG8_WAIT_L(0); PG8_MMA(1, 0, At, B0); PG8_BAR; PG8_SCHED;
	v_mfma_f32_16x16x32_bf16 v[60:63], v[128:131], v[172:175], v[60:63]
	v_mfma_f32_16x16x32_bf16 v[56:59], v[154:157], v[172:175], v[56:59]
	v_mfma_f32_16x16x32_bf16 v[44:47], v[128:131], v[184:187], v[44:47]
	v_mfma_f32_16x16x32_bf16 v[40:43], v[154:157], v[184:187], v[40:43]
	v_mfma_f32_16x16x32_bf16 v[28:31], v[128:131], v[192:195], v[28:31]
	v_mfma_f32_16x16x32_bf16 v[24:27], v[154:157], v[192:195], v[24:27]
	v_mfma_f32_16x16x32_bf16 v[12:15], v[128:131], v[200:203], v[12:15]
	v_mfma_f32_16x16x32_bf16 v[8:11], v[154:157], v[200:203], v[8:11]
	v_mfma_f32_16x16x32_bf16 v[60:63], v[132:135], v[180:183], v[60:63]
	v_mfma_f32_16x16x32_bf16 v[56:59], v[168:171], v[180:183], v[56:59]
	v_mfma_f32_16x16x32_bf16 v[44:47], v[132:135], v[188:191], v[44:47]
	v_mfma_f32_16x16x32_bf16 v[40:43], v[168:171], v[188:191], v[40:43]
	v_mfma_f32_16x16x32_bf16 v[28:31], v[132:135], v[196:199], v[28:31]
	v_mfma_f32_16x16x32_bf16 v[24:27], v[168:171], v[196:199], v[24:27]
	v_mfma_f32_16x16x32_bf16 v[12:15], v[132:135], v[204:207], v[12:15]
	v_mfma_f32_16x16x32_bf16 v[8:11], v[168:171], v[204:207], v[8:11]
	s_barrier
	s_setprio 0

; #define PG8_STAGE(bufoff, gbase, voff) do { _Pragma("unroll") for (int _i = 0; _i < 2; ++_i) \
;         __builtin_amdgcn_global_load_lds((const unsigned*)((const char*)(gbase) + (voff)[_i]), (LAS unsigned*)(lds + (bufoff) + ldsw + _i * 8192), 16, 0, 0); } while (0)
; #define PG8_MMA(ai, bj, At, Bt) do { __builtin_amdgcn_s_setprio(1); _Pragma("unroll") for (int m = 0; m < 4; ++m) _Pragma("unroll") for (int n = 0; n < 2; ++n) _Pragma("unroll") for (int k = 0; k < 2; ++k) \
;         acc[ai][bj][m][n] = __builtin_amdgcn_mfma_f32_16x16x32_bf16(Bt[n][k], At[m][k], acc[ai][bj][m][n], 0, 0, 0); __builtin_amdgcn_s_setprio(0); } while (0)
; #define PG8_WAIT_V(n) asm volatile("s_waitcnt vmcnt(" #n ")" ::: "memory")
; #define PG8_BAR __builtin_amdgcn_s_barrier()
; template <class Epi>
; __device__ __forceinline__ void gemm_phase(LAS unsigned char* lds, const Gemm g, const StaticOrder& S, const Epi& E) {
;     ...
;             PG8_STAGE(PG8_SB(0, 1), b2 + hstep, voffB);
;             PG8_WAIT_V(6); PG8_BAR; PG8_MMA(1, 1, At, B1); PG8_BAR;
	s_add_u32 s64, s16, 0x158000
	s_addc_u32 s65, s17, 0
	s_add_i32 s66, s56, s21
	v_lshl_add_u64 v[128:129], s[64:65], 0, v[140:141]
	s_mov_b32 m0, s66
	s_nop 0
	global_load_lds_dwordx4 v[128:129], off
	v_lshl_add_u64 v[128:129], s[64:65], 0, v[144:145]
	s_add_i32 m0, s66, 0x2000
	s_nop 0
	global_load_lds_dwordx4 v[128:129], off
	s_waitcnt vmcnt(6)
	s_setprio 1
	s_barrier

; #define PG8_MMA(ai, bj, At, Bt) do { __builtin_amdgcn_s_setprio(1); _Pragma("unroll") for (int m = 0; m < 4; ++m) _Pragma("unroll") for (int n = 0; n < 2; ++n) _Pragma("unroll") for (int k = 0; k < 2; ++k) \
;         acc[ai][bj][m][n] = __builtin_amdgcn_mfma_f32_16x16x32_bf16(Bt[n][k], At[m][k], acc[ai][bj][m][n], 0, 0, 0); __builtin_amdgcn_s_setprio(0); } while (0)
; #define PG8_WAIT_V(n) asm volatile("s_waitcnt vmcnt(" #n ")" ::: "memory")
; #define PG8_BAR __builtin_amdgcn_s_barrier()
; template <class Epi>
; __device__ __forceinline__ void gemm_phase(LAS unsigned char* lds, const Gemm g, const StaticOrder& S, const Epi& E) {
;     ...
;             PG8_WAIT_V(6); PG8_BAR; PG8_MMA(1, 1, At, B1); PG8_BAR;
	v_mfma_f32_16x16x32_bf16 v[52:55], v[208:211], v[172:175], v[52:55]
	v_mfma_f32_16x16x32_bf16 v[48:51], v[216:219], v[172:175], v[48:51]
	v_mfma_f32_16x16x32_bf16 v[36:39], v[208:211], v[184:187], v[36:39]
	v_mfma_f32_16x16x32_bf16 v[32:35], v[216:219], v[184:187], v[32:35]
	v_mfma_f32_16x16x32_bf16 v[20:23], v[208:211], v[192:195], v[20:23]
	v_mfma_f32_16x16x32_bf16 v[16:19], v[216:219], v[192:195], v[16:19]
	v_mfma_f32_16x16x32_bf16 v[4:7], v[208:211], v[200:203], v[4:7]
	v_mfma_f32_16x16x32_bf16 v[0:3], v[216:219], v[200:203], v[0:3]
	v_mfma_f32_16x16x32_bf16 v[52:55], v[212:215], v[180:183], v[52:55]
	v_mfma_f32_16x16x32_bf16 v[48:51], v[220:223], v[180:183], v[48:51]
	v_mfma_f32_16x16x32_bf16 v[36:39], v[212:215], v[188:191], v[36:39]
	v_mfma_f32_16x16x32_bf16 v[32:35], v[220:223], v[188:191], v[32:35]
	v_mfma_f32_16x16x32_bf16 v[20:23], v[212:215], v[196:199], v[20:23]
	v_mfma_f32_16x16x32_bf16 v[16:19], v[220:223], v[196:199], v[16:19]
	v_mfma_f32_16x16x32_bf16 v[4:7], v[212:215], v[204:207], v[4:7]
	v_mfma_f32_16x16x32_bf16 v[0:3], v[220:223], v[204:207], v[0:3]
	s_barrier
	s_setprio 0
	s_add_i32 s64, 0, 0x18000
	v_add_u32_e32 v167, s64, v137


; #define PG8_STAGE(bufoff, gbase, voff) do { _Pragma("unroll") for (int _i = 0; _i < 2; ++_i) \
;         __builtin_amdgcn_global_load_lds((const unsigned*)((const char*)(gbase) + (voff)[_i]), (LAS unsigned*)(lds + (bufoff) + ldsw + _i * 8192), 16, 0, 0); } while (0)
; #define PG8_LDA(dst, b, h) do { _Pragma("unroll") for (int m = 0; m < 4; ++m) _Pragma("unroll") for (int k = 0; k < 2; ++k) dst[m][k] = *(const LAS bf16x8*)(lds + PG8_SA(b, h) + aoff + m * 2048 + k * 1024); } while (0)
; #define PG8_LDB(dst, b, h) do { _Pragma("unroll") for (int n = 0; n < 2; ++n) _Pragma("unroll") for (int k = 0; k < 2; ++k) dst[n][k] = *(const LAS bf16x8*)(lds + PG8_SB(b, h) + boff + n * 2048 + k * 1024); } while (0)
; #define PG8_MMA(ai, bj, At, Bt) do { __builtin_amdgcn_s_setprio(1); _Pragma("unroll") for (int m = 0; m < 4; ++m) _Pragma("unroll") for (int n = 0; n < 2; ++n) _Pragma("unroll") for (int k = 0; k < 2; ++k) \
;         acc[ai][bj][m][n] = __builtin_amdgcn_mfma_f32_16x16x32_bf16(Bt[n][k], At[m][k], acc[ai][bj][m][n], 0, 0, 0); __builtin_amdgcn_s_setprio(0); } while (0)
; #define PG8_WAIT_L(n) asm volatile("s_waitcnt lgkmcnt(" #n ")" ::: "memory")
; #define PG8_BAR __builtin_amdgcn_s_barrier()
; #define PG8_SCHED __builtin_amdgcn_sched_barrier(0)
; template <class Epi>
; __device__ __forceinline__ void gemm_phase(LAS unsigned char* lds, const Gemm g, const StaticOrder& S, const Epi& E) {
;     ...
;             PG8_LDB(B0, 1, 0); PG8_SCHED; PG8_LDA(At, 1, 0); PG8_STAGE(PG8_SA(0, 1), a2 + hstep, voffA);
;             PG8_WAIT_L(8); PG8_BAR; PG8_WAIT_L(0); PG8_MMA(0, 0, At, B0); PG8_BAR; PG8_SCHED;
	ds_read_b128 v[128:131], v167
	ds_read_b128 v[132:135], v167 offset:1024
	ds_read_b128 v[154:157], v167 offset:2048
	ds_read_b128 v[168:171], v167 offset:3072
	s_add_u32 s18, s18, 0x158000
	s_addc_u32 s19, s19, 0
	s_mov_b32 m0, s33
	v_lshl_add_u64 v[208:209], s[18:19], 0, v[138:139]
	ds_read_b128 v[172:175], v163 offset:32768
	ds_read_b128 v[180:183], v163 offset:33792
	ds_read_b128 v[184:187], v163 offset:34816
	ds_read_b128 v[188:191], v163 offset:35840
	ds_read_b128 v[192:195], v163 offset:36864
	ds_read_b128 v[196:199], v163 offset:37888
	ds_read_b128 v[200:203], v163 offset:38912
	ds_read_b128 v[204:207], v163 offset:39936
	global_load_lds_dwordx4 v[208:209], off
	v_lshl_add_u64 v[208:209], s[18:19], 0, v[142:143]
	s_mov_b32 m0, s34
	s_nop 0
	global_load_lds_dwordx4 v[208:209], off
	s_waitcnt lgkmcnt(8)
	s_setprio 1
	s_barrier
	s_waitcnt lgkmcnt(0)


; #define PG8_MMA(ai, bj, At, Bt) do { __builtin_amdgcn_s_setprio(1); _Pragma("unroll") for (int m = 0; m < 4; ++m) _Pragma("unroll") for (int n = 0; n < 2; ++n) _Pragma("unroll") for (int k = 0; k < 2; ++k) \
;         acc[ai][bj][m][n] = __builtin_amdgcn_mfma_f32_16x16x32_bf16(Bt[n][k], At[m][k], acc[ai][bj][m][n], 0, 0, 0); __builtin_amdgcn_s_setprio(0); } while (0)
; #define PG8_WAIT_L(n) asm volatile("s_waitcnt lgkmcnt(" #n ")" ::: "memory")
; #define PG8_BAR __builtin_amdgcn_s_barrier()
; #define PG8_SCHED __builtin_amdgcn_sched_barrier(0)
; template <class Epi>
; __device__ __forceinline__ void gemm_phase(LAS unsigned char* lds, const Gemm g, const StaticOrder& S, const Epi& E) {
;     ...
;             PG8_WAIT_L(8); PG8_BAR; PG8_WAIT_L(0); PG8_MMA(0, 0, At, B0); PG8_BAR; PG8_SCHED;
	v_mfma_f32_16x16x32_bf16 v[124:127], v[128:131], v[172:175], v[124:127]
	v_mfma_f32_16x16x32_bf16 v[120:123], v[154:157], v[172:175], v[120:123]
	v_mfma_f32_16x16x32_bf16 v[108:111], v[128:131], v[184:187], v[108:111]
	v_mfma_f32_16x16x32_bf16 v[104:107], v[154:157], v[184:187], v[104:107]
	v_mfma_f32_16x16x32_bf16 v[92:95], v[128:131], v[192:195], v[92:95]
	v_mfma_f32_16x16x32_bf16 v[88:91], v[154:157], v[192:195], v[88:91]
	v_mfma_f32_16x16x32_bf16 v[76:79], v[128:131], v[200:203], v[76:79]
	v_mfma_f32_16x16x32_bf16 v[72:75], v[154:157], v[200:203], v[72:75]
	v_mfma_f32_16x16x32_bf16 v[124:127], v[132:135], v[180:183], v[124:127]
	v_mfma_f32_16x16x32_bf16 v[120:123], v[168:171], v[180:183], v[120:123]
	v_mfma_f32_16x16x32_bf16 v[108:111], v[132:135], v[188:191], v[108:111]
	v_mfma_f32_16x16x32_bf16 v[104:107], v[168:171], v[188:191], v[104:107]
	v_mfma_f32_16x16x32_bf16 v[92:95], v[132:135], v[196:199], v[92:95]
	v_mfma_f32_16x16x32_bf16 v[88:91], v[168:171], v[196:199], v[88:91]
	v_mfma_f32_16x16x32_bf16 v[76:79], v[132:135], v[204:207], v[76:79]
	v_mfma_f32_16x16x32_bf16 v[72:75], v[168:171], v[204:207], v[72:75]
	s_barrier
	s_setprio 0

; #define PG8_STAGE(bufoff, gbase, voff) do { _Pragma("unroll") for (int _i = 0; _i < 2; ++_i) \
;         __builtin_amdgcn_global_load_lds((const unsigned*)((const char*)(gbase) + (voff)[_i]), (LAS unsigned*)(lds + (bufoff) + ldsw + _i * 8192), 16, 0, 0); } while (0)
; #define PG8_LDB(dst, b, h) do { _Pragma("unroll") for (int n = 0; n < 2; ++n) _Pragma("unroll") for (int k = 0; k < 2; ++k) dst[n][k] = *(const LAS bf16x8*)(lds + PG8_SB(b, h) + boff + n * 2048 + k * 1024); } while (0)
; #define PG8_MMA(ai, bj, At, Bt) do { __builtin_amdgcn_s_setprio(1); _Pragma("unroll") for (int m = 0; m < 4; ++m) _Pragma("unroll") for (int n = 0; n < 2; ++n) _Pragma("unroll") for (int k = 0; k < 2; ++k) \
;         acc[ai][bj][m][n] = __builtin_amdgcn_mfma_f32_16x16x32_bf16(Bt[n][k], At[m][k], acc[ai][bj][m][n], 0, 0, 0); __builtin_amdgcn_s_setprio(0); } while (0)
; #define PG8_WAIT_L(n) asm volatile("s_waitcnt lgkmcnt(" #n ")" ::: "memory")
; #define PG8_BAR __builtin_amdgcn_s_barrier()
; template <class Epi>
; __device__ __forceinline__ void gemm_phase(LAS unsigned char* lds, const Gemm g, const StaticOrder& S, const Epi& E) {
;     ...
;             PG8_LDB(B1, 1, 1); PG8_STAGE(PG8_SB(1, 0), b3, voffB);
;             PG8_BAR; PG8_WAIT_L(0); PG8_MMA(0, 1, At, B1); PG8_BAR;
	s_add_i32 s18, 0, 0x1c000
	s_add_i32 s19, s64, s21
	v_add_u32_e32 v167, s18, v137
	v_lshl_add_u64 v[158:159], v[158:159], 0, s[12:13]
	s_mov_b32 m0, s19
	ds_read_b128 v[208:211], v167
	ds_read_b128 v[212:215], v167 offset:1024
	ds_read_b128 v[216:219], v167 offset:2048
	ds_read_b128 v[220:223], v167 offset:3072
	global_load_lds_dwordx4 v[158:159], off
	v_lshl_add_u64 v[158:159], v[176:177], 0, s[12:13]
	s_add_i32 m0, s19, 0x2000
	s_nop 0
	global_load_lds_dwordx4 v[158:159], off
	s_waitcnt lgkmcnt(0)
	s_setprio 1
	s_barrier


; #define PG8_MMA(ai, bj, At, Bt) do { __builtin_amdgcn_s_setprio(1); _Pragma("unroll") for (int m = 0; m < 4; ++m) _Pragma("unroll") for (int n = 0; n < 2; ++n) _Pragma("unroll") for (int k = 0; k < 2; ++k) \
;         acc[ai][bj][m][n] = __builtin_amdgcn_mfma_f32_16x16x32_bf16(Bt[n][k], At[m][k], acc[ai][bj][m][n], 0, 0, 0); __builtin_amdgcn_s_setprio(0); } while (0)
; #define PG8_WAIT_L(n) asm volatile("s_waitcnt lgkmcnt(" #n ")" ::: "memory")
; #define PG8_BAR __builtin_amdgcn_s_barrier()
; template <class Epi>
; __device__ __forceinline__ void gemm_phase(LAS unsigned char* lds, const Gemm g, const StaticOrder& S, const Epi& E) {
;     ...
;             PG8_BAR; PG8_WAIT_L(0); PG8_MMA(0, 1, At, B1); PG8_BAR;
	v_mfma_f32_16x16x32_bf16 v[116:119], v[208:211], v[172:175], v[116:119]
	v_mfma_f32_16x16x32_bf16 v[112:115], v[216:219], v[172:175], v[112:115]
	v_mfma_f32_16x16x32_bf16 v[100:103], v[208:211], v[184:187], v[100:103]
	v_mfma_f32_16x16x32_bf16 v[96:99], v[216:219], v[184:187], v[96:99]
	v_mfma_f32_16x16x32_bf16 v[84:87], v[208:211], v[192:195], v[84:87]
	v_mfma_f32_16x16x32_bf16 v[80:83], v[216:219], v[192:195], v[80:83]
	v_mfma_f32_16x16x32_bf16 v[68:71], v[208:211], v[200:203], v[68:71]
	v_mfma_f32_16x16x32_bf16 v[64:67], v[216:219], v[200:203], v[64:67]
	v_mfma_f32_16x16x32_bf16 v[116:119], v[212:215], v[180:183], v[116:119]
	v_mfma_f32_16x16x32_bf16 v[112:115], v[220:223], v[180:183], v[112:115]
	v_mfma_f32_16x16x32_bf16 v[100:103], v[212:215], v[188:191], v[100:103]
	v_mfma_f32_16x16x32_bf16 v[96:99], v[220:223], v[188:191], v[96:99]
	v_mfma_f32_16x16x32_bf16 v[84:87], v[212:215], v[196:199], v[84:87]
	v_mfma_f32_16x16x32_bf16 v[80:83], v[220:223], v[196:199], v[80:83]
	v_mfma_f32_16x16x32_bf16 v[68:71], v[212:215], v[204:207], v[68:71]
	v_mfma_f32_16x16x32_bf16 v[64:67], v[220:223], v[204:207], v[64:67]
	s_barrier
	s_setprio 0
	s_mov_b32 m0, s36
	v_lshl_add_u64 v[158:159], v[224:225], 0, s[12:13]


; #define PG8_STAGE(bufoff, gbase, voff) do { _Pragma("unroll") for (int _i = 0; _i < 2; ++_i) \
;         __builtin_amdgcn_global_load_lds((const unsigned*)((const char*)(gbase) + (voff)[_i]), (LAS unsigned*)(lds + (bufoff) + ldsw + _i * 8192), 16, 0, 0); } while (0)
; #define PG8_LDA(dst, b, h) do { _Pragma("unroll") for (int m = 0; m < 4; ++m) _Pragma("unroll") for (int k = 0; k < 2; ++k) dst[m][k] = *(const LAS bf16x8*)(lds + PG8_SA(b, h) + aoff + m * 2048 + k * 1024); } while (0)
; #define PG8_MMA(ai, bj, At, Bt) do { __builtin_amdgcn_s_setprio(1); _Pragma("unroll") for (int m = 0; m < 4; ++m) _Pragma("unroll") for (int n = 0; n < 2; ++n) _Pragma("unroll") for (int k = 0; k < 2; ++k) \
;         acc[ai][bj][m][n] = __builtin_amdgcn_mfma_f32_16x16x32_bf16(Bt[n][k], At[m][k], acc[ai][bj][m][n], 0, 0, 0); __builtin_amdgcn_s_setprio(0); } while (0)
; #define PG8_WAIT_L(n) asm volatile("s_waitcnt lgkmcnt(" #n ")" ::: "memory")
; #define PG8_BAR __builtin_amdgcn_s_barrier()
; #define PG8_SCHED __builtin_amdgcn_sched_barrier(0)
; template <class Epi>
; __device__ __forceinline__ void gemm_phase(LAS unsigned char* lds, const Gemm g, const StaticOrder& S, const Epi& E) {
;     ...
;             PG8_LDA(At, 1, 1); PG8_STAGE(PG8_SA(1, 0), a3, voffA);
;             PG8_BAR; PG8_WAIT_L(0); PG8_MMA(1, 0, At, B0); PG8_BAR; PG8_SCHED;
	ds_read_b128 v[172:175], v163 offset:49152
	ds_read_b128 v[180:183], v163 offset:50176
	ds_read_b128 v[184:187], v163 offset:51200
	ds_read_b128 v[188:191], v163 offset:52224
	ds_read_b128 v[192:195], v163 offset:53248
	ds_read_b128 v[196:199], v163 offset:54272
	ds_read_b128 v[200:203], v163 offset:55296
	ds_read_b128 v[204:207], v163 offset:56320
	global_load_lds_dwordx4 v[158:159], off
	v_lshl_add_u64 v[158:159], v[226:227], 0, s[12:13]
	s_mov_b32 m0, s37
	s_nop 0
	global_load_lds_dwordx4 v[158:159], off
	s_waitcnt lgkmcnt(0)
	s_setprio 1
	s_barrier


; #define PG8_MMA(ai, bj, At, Bt) do { __builtin_amdgcn_s_setprio(1); _Pragma("unroll") for (int m = 0; m < 4; ++m) _Pragma("unroll") for (int n = 0; n < 2; ++n) _Pragma("unroll") for (int k = 0; k < 2; ++k) \
;         acc[ai][bj][m][n] = __builtin_amdgcn_mfma_f32_16x16x32_bf16(Bt[n][k], At[m][k], acc[ai][bj][m][n], 0, 0, 0); __builtin_amdgcn_s_setprio(0); } while (0)
; #define PG8_WAIT_L(n) asm volatile("s_waitcnt lgkmcnt(" #n ")" ::: "memory")
; #define PG8_BAR __builtin_amdgcn_s_barrier()
; #define PG8_SCHED __builtin_amdgcn_sched_barrier(0)
; template <class Epi>
; __device__ __forceinline__ void gemm_phase(LAS unsigned char* lds, const Gemm g, const StaticOrder& S, const Epi& E) {
;     ...
;             PG8_BAR; PG8_WAIT_L(0); PG8_MMA(1, 0, At, B0); PG8_BAR; PG8_SCHED;
	v_mfma_f32_16x16x32_bf16 v[60:63], v[128:131], v[172:175], v[60:63]
	v_mfma_f32_16x16x32_bf16 v[56:59], v[154:157], v[172:175], v[56:59]
	v_mfma_f32_16x16x32_bf16 v[44:47], v[128:131], v[184:187], v[44:47]
	v_mfma_f32_16x16x32_bf16 v[40:43], v[154:157], v[184:187], v[40:43]
	v_mfma_f32_16x16x32_bf16 v[28:31], v[128:131], v[192:195], v[28:31]
	v_mfma_f32_16x16x32_bf16 v[24:27], v[154:157], v[192:195], v[24:27]
	v_mfma_f32_16x16x32_bf16 v[12:15], v[128:131], v[200:203], v[12:15]
	v_mfma_f32_16x16x32_bf16 v[8:11], v[154:157], v[200:203], v[8:11]
	v_mfma_f32_16x16x32_bf16 v[60:63], v[132:135], v[180:183], v[60:63]
	v_mfma_f32_16x16x32_bf16 v[56:59], v[168:171], v[180:183], v[56:59]
	v_mfma_f32_16x16x32_bf16 v[44:47], v[132:135], v[188:191], v[44:47]
	v_mfma_f32_16x16x32_bf16 v[40:43], v[168:171], v[188:191], v[40:43]
	v_mfma_f32_16x16x32_bf16 v[28:31], v[132:135], v[196:199], v[28:31]
	v_mfma_f32_16x16x32_bf16 v[24:27], v[168:171], v[196:199], v[24:27]
	v_mfma_f32_16x16x32_bf16 v[12:15], v[132:135], v[204:207], v[12:15]
	v_mfma_f32_16x16x32_bf16 v[8:11], v[168:171], v[204:207], v[8:11]
	s_barrier
	s_setprio 0

; #define PG8_STAGE(bufoff, gbase, voff) do { _Pragma("unroll") for (int _i = 0; _i < 2; ++_i) \
;         __builtin_amdgcn_global_load_lds((const unsigned*)((const char*)(gbase) + (voff)[_i]), (LAS unsigned*)(lds + (bufoff) + ldsw + _i * 8192), 16, 0, 0); } while (0)
; #define PG8_MMA(ai, bj, At, Bt) do { __builtin_amdgcn_s_setprio(1); _Pragma("unroll") for (int m = 0; m < 4; ++m) _Pragma("unroll") for (int n = 0; n < 2; ++n) _Pragma("unroll") for (int k = 0; k < 2; ++k) \
;         acc[ai][bj][m][n] = __builtin_amdgcn_mfma_f32_16x16x32_bf16(Bt[n][k], At[m][k], acc[ai][bj][m][n], 0, 0, 0); __builtin_amdgcn_s_setprio(0); } while (0)
; #define PG8_WAIT_V(n) asm volatile("s_waitcnt vmcnt(" #n ")" ::: "memory")
; #define PG8_BAR __builtin_amdgcn_s_barrier()
; template <class Epi>
; __device__ __forceinline__ void gemm_phase(LAS unsigned char* lds, const Gemm g, const StaticOrder& S, const Epi& E) {
;     ...
;             PG8_STAGE(PG8_SB(1, 1), b3 + hstep, voffB);
;             PG8_WAIT_V(6); PG8_BAR; PG8_MMA(1, 1, At, B1); PG8_BAR;
	s_add_u32 s16, s16, 0x158080
	s_addc_u32 s17, s17, 0
	s_add_i32 s18, s18, s21
	v_lshl_add_u64 v[128:129], s[16:17], 0, v[140:141]
	s_mov_b32 m0, s18
	s_nop 0
	global_load_lds_dwordx4 v[128:129], off
	v_lshl_add_u64 v[128:129], s[16:17], 0, v[144:145]
	s_add_i32 m0, s18, 0x2000
	s_nop 0
	global_load_lds_dwordx4 v[128:129], off
	s_waitcnt vmcnt(6)
	s_setprio 1
	s_barrier

; #define PG8_MMA(ai, bj, At, Bt) do { __builtin_amdgcn_s_setprio(1); _Pragma("unroll") for (int m = 0; m < 4; ++m) _Pragma("unroll") for (int n = 0; n < 2; ++n) _Pragma("unroll") for (int k = 0; k < 2; ++k) \
;         acc[ai][bj][m][n] = __builtin_amdgcn_mfma_f32_16x16x32_bf16(Bt[n][k], At[m][k], acc[ai][bj][m][n], 0, 0, 0); __builtin_amdgcn_s_setprio(0); } while (0)
; #define PG8_WAIT_V(n) asm volatile("s_waitcnt vmcnt(" #n ")" ::: "memory")
; #define PG8_BAR __builtin_amdgcn_s_barrier()
; template <class Epi>
; __device__ __forceinline__ void gemm_phase(LAS unsigned char* lds, const Gemm g, const StaticOrder& S, const Epi& E) {
;     ...
;             PG8_WAIT_V(6); PG8_BAR; PG8_MMA(1, 1, At, B1); PG8_BAR;
	v_mfma_f32_16x16x32_bf16 v[52:55], v[208:211], v[172:175], v[52:55]
	v_mfma_f32_16x16x32_bf16 v[48:51], v[216:219], v[172:175], v[48:51]
	v_mfma_f32_16x16x32_bf16 v[36:39], v[208:211], v[184:187], v[36:39]
	v_mfma_f32_16x16x32_bf16 v[32:35], v[216:219], v[184:187], v[32:35]
	v_mfma_f32_16x16x32_bf16 v[20:23], v[208:211], v[192:195], v[20:23]
	v_mfma_f32_16x16x32_bf16 v[16:19], v[216:219], v[192:195], v[16:19]
	v_mfma_f32_16x16x32_bf16 v[4:7], v[208:211], v[200:203], v[4:7]
	v_mfma_f32_16x16x32_bf16 v[0:3], v[216:219], v[200:203], v[0:3]
	v_mfma_f32_16x16x32_bf16 v[52:55], v[212:215], v[180:183], v[52:55]
	v_mfma_f32_16x16x32_bf16 v[48:51], v[220:223], v[180:183], v[48:51]
	v_mfma_f32_16x16x32_bf16 v[36:39], v[212:215], v[188:191], v[36:39]
	v_mfma_f32_16x16x32_bf16 v[32:35], v[220:223], v[188:191], v[32:35]
	v_mfma_f32_16x16x32_bf16 v[20:23], v[212:215], v[196:199], v[20:23]
	v_mfma_f32_16x16x32_bf16 v[16:19], v[220:223], v[196:199], v[16:19]
	v_mfma_f32_16x16x32_bf16 v[4:7], v[212:215], v[204:207], v[4:7]
	v_mfma_f32_16x16x32_bf16 v[0:3], v[220:223], v[204:207], v[0:3]
	s_barrier
	s_setprio 0
	s_add_i32 s63, s63, 2
	s_add_u32 s14, s14, 0x100
	s_addc_u32 s15, s15, 0
	s_add_u32 s61, s61, 0x100
	s_addc_u32 s62, s62, 0
	s_cmpk_gt_u32 s63, 0x53


; __device__ __forceinline__ float bflo(unsigned w) { return __uint_as_float(w << 16); }
; __device__ __forceinline__ float bfhi(unsigned w) { return __uint_as_float(w & 0xffff0000u); }
; #define ER_LOAD(g_, set_) do { const size_t off_ = (size_t)(row0 + ((g_) >> 2) * HALF + ((g_) & 3) * 16) * DM + col0; \
;         hv[set_][0] = *(const u32x4*)(HB + off_); hv[set_][1] = *(const u32x4*)(HB + off_ + HALF); } while (0)
;     __device__ __forceinline__ void operator()(const f32x4 (&acc)[2][2][4][2], const Unit& u, int wr, int wc, int fr, int fq, const Pre&) const {
;         const int row0 = ROW_X + u.pm * BM + wr * 64 + fr, col0 = u.pn * BM + wc * 32 + 8 * fq;
;         u32x4 hv[2][2]; float sprev = 0.f;
;     ...
;         ER_LOAD(0, 0);
; #pragma unroll
;         for (int g = 0; g < 8; ++g) { const int ai = g >> 2, m = g & 3; const int r = row0 + ai * HALF + m * 16; const size_t off = (size_t)r * DM + col0; float s = 0.f;
;             if (g + 1 < 8) ER_LOAD(g + 1, (g + 1) & 1);
; #pragma unroll
;             for (int bj = 0; bj < 2; ++bj) { const u32x4 w = hv[g & 1][bj];
;                 const f32x4 h0 = {bflo(w.x), bfhi(w.x), bflo(w.y), bfhi(w.y)}, h1 = {bflo(w.z), bfhi(w.z), bflo(w.w), bfhi(w.w)};
;                 const f32x4 o0 = h0 + acc[ai][bj][m][0] * alpha, o1 = h1 + acc[ai][bj][m][1] * alpha;
;                 if (FINAL) { float* op = OUT + (size_t)(r - ROW_X) * DM + col0 + bj * HALF; *(f32x4*)op = o0; *(f32x4*)(op + 4) = o1; }
;                 else { u32x4 q; q.x = cvtpk(o0[0], o0[1]); q.y = cvtpk(o0[2], o0[3]); q.z = cvtpk(o1[0], o1[1]); q.w = cvtpk(o1[2], o1[3]); *(u32x4*)(HB + off + bj * HALF) = q;
;                        s += ((o0[0] * o0[0] + o0[1] * o0[1]) + (o0[2] * o0[2] + o0[3] * o0[3])) + ((o1[0] * o1[0] + o1[1] * o1[1]) + (o1[2] * o1[2] + o1[3] * o1[3])); } }
;             if (!FINAL) { if (g > 0) { float t = sprev; t += __shfl_xor(t, 16); t += __shfl_xor(t, 32);
;                     if (fq == 0) __hip_atomic_fetch_add(ssq_out + row0 + ((g - 1) >> 2) * HALF + ((g - 1) & 3) * 16, t, __ATOMIC_RELAXED, __HIP_MEMORY_SCOPE_AGENT); }
;                 sprev = s; } }
;     ...
;         if (!FINAL) { float t = sprev; t += __shfl_xor(t, 16); t += __shfl_xor(t, 32);
;             if (fq == 0) __hip_atomic_fetch_add(ssq_out + row0 + HALF + 48, t, __ATOMIC_RELAXED, __HIP_MEMORY_SCOPE_AGENT); }
	s_cbranch_scc0 .LBB0_1411
	v_lshl_add_u32 v156, s59, 8, v160
	v_lshl_or_b32 v154, s60, 8, v161
	v_ashrrev_i32_e32 v157, 31, v156
	v_ashrrev_i32_e32 v155, 31, v154
	v_lshlrev_b64 v[128:129], 12, v[156:157]
	v_lshl_add_u64 v[128:129], s[8:9], 0, v[128:129]
	v_lshlrev_b64 v[130:131], 1, v[154:155]
	v_lshl_add_u64 v[176:177], v[128:129], 0, v[130:131]
	v_or_b32_e32 v128, 16, v156
	v_ashrrev_i32_e32 v129, 31, v128
	global_load_dwordx4 v[168:171], v[176:177], off
	global_load_dwordx4 v[172:175], v[176:177], off offset:256
	v_lshlrev_b64 v[128:129], 12, v[128:129]
	v_lshl_add_u64 v[128:129], s[8:9], 0, v[128:129]
	v_lshl_add_u64 v[188:189], v[128:129], 0, v[130:131]
	global_load_dwordx4 v[180:183], v[188:189], off
	global_load_dwordx4 v[184:187], v[188:189], off offset:256
	v_or_b32_e32 v128, 32, v156
	v_ashrrev_i32_e32 v129, 31, v128
	v_lshlrev_b64 v[128:129], 12, v[128:129]
	v_lshl_add_u64 v[128:129], s[8:9], 0, v[128:129]
	v_lshl_add_u64 v[158:159], v[128:129], 0, v[130:131]
	global_load_dwordx4 v[132:135], v[158:159], off
	global_load_dwordx4 v[128:131], v[158:159], off offset:256
	s_waitcnt vmcnt(0)
	v_lshlrev_b32_e32 v190, 16, v168
	v_and_b32_e32 v191, 0xffff0000, v168
	v_lshlrev_b32_e32 v168, 16, v169
	v_and_b32_e32 v169, 0xffff0000, v169
	v_lshlrev_b32_e32 v192, 16, v170
	v_and_b32_e32 v193, 0xffff0000, v170
	v_lshlrev_b32_e32 v170, 16, v171
	v_and_b32_e32 v171, 0xffff0000, v171
	v_lshlrev_b32_e32 v194, 16, v172
	v_and_b32_e32 v195, 0xffff0000, v172
	v_lshlrev_b32_e32 v172, 16, v173
	v_and_b32_e32 v173, 0xffff0000, v173
	v_lshlrev_b32_e32 v196, 16, v174
	v_and_b32_e32 v197, 0xffff0000, v174
	v_lshlrev_b32_e32 v174, 16, v175
	v_and_b32_e32 v175, 0xffff0000, v175
	v_pk_fma_f32 v[126:127], v[126:127], 0.5, v[168:169] op_sel_hi:[1,0,1]
	v_pk_fma_f32 v[124:125], v[124:125], 0.5, v[190:191] op_sel_hi:[1,0,1]
	v_pk_fma_f32 v[122:123], v[122:123], 0.5, v[170:171] op_sel_hi:[1,0,1]
	v_pk_fma_f32 v[168:169], v[120:121], 0.5, v[192:193] op_sel_hi:[1,0,1]
	v_pk_fma_f32 v[170:171], v[118:119], 0.5, v[172:173] op_sel_hi:[1,0,1]
	v_pk_fma_f32 v[172:173], v[116:117], 0.5, v[194:195] op_sel_hi:[1,0,1]
	v_pk_fma_f32 v[174:175], v[114:115], 0.5, v[174:175] op_sel_hi:[1,0,1]
	v_pk_fma_f32 v[190:191], v[112:113], 0.5, v[196:197] op_sel_hi:[1,0,1]
	v_cvt_pk_bf16_f32 v114, v124, v125
	v_cvt_pk_bf16_f32 v115, v126, v127
	v_cvt_pk_bf16_f32 v116, v168, v169
	v_cvt_pk_bf16_f32 v117, v122, v123
	v_mul_f32_e32 v125, v125, v125
	v_mul_f32_e32 v127, v127, v127
	v_mul_f32_e32 v167, v169, v169
	v_mul_f32_e32 v123, v123, v123
	v_cvt_pk_bf16_f32 v118, v172, v173
	v_cvt_pk_bf16_f32 v119, v170, v171
	v_cvt_pk_bf16_f32 v121, v174, v175
	v_mul_f32_e32 v169, v173, v173
	v_mul_f32_e32 v171, v171, v171
	v_mul_f32_e32 v173, v191, v191
	v_mul_f32_e32 v175, v175, v175
	v_lshlrev_b32_e32 v112, 16, v180
	v_and_b32_e32 v113, 0xffff0000, v180
	v_lshlrev_b32_e32 v192, 16, v182
	v_and_b32_e32 v193, 0xffff0000, v182
	v_lshlrev_b32_e32 v182, 16, v183
	v_and_b32_e32 v183, 0xffff0000, v183
	v_fmac_f32_e32 v125, v124, v124
	v_fmac_f32_e32 v127, v126, v126
	v_fmac_f32_e32 v167, v168, v168
	v_fmac_f32_e32 v123, v122, v122
	v_fmac_f32_e32 v169, v172, v172
	v_fmac_f32_e32 v171, v170, v170
	v_fmac_f32_e32 v173, v190, v190
	v_fmac_f32_e32 v175, v174, v174
	v_lshlrev_b32_e32 v180, 16, v181
	v_and_b32_e32 v181, 0xffff0000, v181
	v_pk_fma_f32 v[112:113], v[108:109], 0.5, v[112:113] op_sel_hi:[1,0,1]
	v_pk_fma_f32 v[108:109], v[106:107], 0.5, v[182:183] op_sel_hi:[1,0,1]
	global_store_dwordx4 v[176:177], v[114:117], off
	v_add_f32_e32 v106, v125, v127
	v_add_f32_e32 v107, v167, v123
	v_add_f32_e32 v114, v169, v171
	v_add_f32_e32 v115, v173, v175
	v_pk_fma_f32 v[110:111], v[110:111], 0.5, v[180:181] op_sel_hi:[1,0,1]
	v_add_f32_e32 v106, v106, v107
	v_add_f32_e32 v107, v114, v115
	v_pk_fma_f32 v[114:115], v[104:105], 0.5, v[192:193] op_sel_hi:[1,0,1]
	v_add_f32_e32 v125, v106, v107
	v_cvt_pk_bf16_f32 v104, v112, v113
	v_cvt_pk_bf16_f32 v105, v110, v111
	v_cvt_pk_bf16_f32 v106, v114, v115
	v_cvt_pk_bf16_f32 v107, v108, v109
	v_cvt_pk_bf16_f32 v120, v190, v191
	global_store_dwordx4 v[188:189], v[104:107], off
	global_store_dwordx4 v[176:177], v[118:121], off offset:256
	v_lshlrev_b32_e32 v122, 16, v186
	v_lshlrev_b32_e32 v104, 16, v184
	v_and_b32_e32 v105, 0xffff0000, v184
	v_pk_fma_f32 v[118:119], v[100:101], 0.5, v[104:105] op_sel_hi:[1,0,1]
	v_and_b32_e32 v101, 64, v166
	v_xor_b32_e32 v100, 16, v166
	v_add_u32_e32 v101, 64, v101
	v_cmp_lt_i32_e32 vcc, v100, v101
	v_and_b32_e32 v123, 0xffff0000, v186
	v_pk_fma_f32 v[122:123], v[96:97], 0.5, v[122:123] op_sel_hi:[1,0,1]
	v_cndmask_b32_e32 v100, v166, v100, vcc
	v_lshlrev_b32_e32 v124, 2, v100
	ds_bpermute_b32 v100, v124, v125
	v_xor_b32_e32 v97, 32, v166
	v_cmp_lt_i32_e32 vcc, v97, v101
	v_lshlrev_b32_e32 v106, 16, v185
	v_and_b32_e32 v107, 0xffff0000, v185
	v_cndmask_b32_e32 v97, v166, v97, vcc
	s_waitcnt lgkmcnt(0)
	v_add_f32_e32 v96, v125, v100
	v_lshlrev_b32_e32 v125, 2, v97
	ds_bpermute_b32 v97, v125, v96
	v_lshlrev_b32_e32 v120, 16, v187
	v_and_b32_e32 v121, 0xffff0000, v187
	v_pk_fma_f32 v[116:117], v[102:103], 0.5, v[106:107] op_sel_hi:[1,0,1]
	v_pk_fma_f32 v[120:121], v[98:99], 0.5, v[120:121] op_sel_hi:[1,0,1]
	v_cvt_pk_bf16_f32 v98, v118, v119
	v_cvt_pk_bf16_f32 v99, v116, v117
	v_cvt_pk_bf16_f32 v100, v122, v123
	v_cvt_pk_bf16_f32 v101, v120, v121
	v_lshl_add_u64 v[104:105], v[156:157], 2, s[10:11]
	global_store_dwordx4 v[188:189], v[98:101], off offset:256
	s_and_saveexec_b64 s[14:15], s[2:3]
	s_cbranch_execz .LBB0_1414
	s_waitcnt lgkmcnt(0)
	v_add_f32_e32 v96, v96, v97
	global_atomic_add_f32 v[104:105], v96, off

; #define PG8_STAGE(bufoff, gbase, voff) do { _Pragma("unroll") for (int _i = 0; _i < 2; ++_i) \
;         __builtin_amdgcn_global_load_lds((const unsigned*)((const char*)(gbase) + (voff)[_i]), (LAS unsigned*)(lds + (bufoff) + ldsw + _i * 8192), 16, 0, 0); } while (0)
; #define PG8_LDA(dst, b, h) do { _Pragma("unroll") for (int m = 0; m < 4; ++m) _Pragma("unroll") for (int k = 0; k < 2; ++k) dst[m][k] = *(const LAS bf16x8*)(lds + PG8_SA(b, h) + aoff + m * 2048 + k * 1024); } while (0)
; #define PG8_LDB(dst, b, h) do { _Pragma("unroll") for (int n = 0; n < 2; ++n) _Pragma("unroll") for (int k = 0; k < 2; ++k) dst[n][k] = *(const LAS bf16x8*)(lds + PG8_SB(b, h) + boff + n * 2048 + k * 1024); } while (0)
; #define PG8_MMA(ai, bj, At, Bt) do { __builtin_amdgcn_s_setprio(1); _Pragma("unroll") for (int m = 0; m < 4; ++m) _Pragma("unroll") for (int n = 0; n < 2; ++n) _Pragma("unroll") for (int k = 0; k < 2; ++k) \
;         acc[ai][bj][m][n] = __builtin_amdgcn_mfma_f32_16x16x32_bf16(Bt[n][k], At[m][k], acc[ai][bj][m][n], 0, 0, 0); __builtin_amdgcn_s_setprio(0); } while (0)
; #define PG8_WAIT_L(n) asm volatile("s_waitcnt lgkmcnt(" #n ")" ::: "memory")
; #define PG8_BAR __builtin_amdgcn_s_barrier()
; #define PG8_SCHED __builtin_amdgcn_sched_barrier(0)
; template <class Epi>
; __device__ __forceinline__ void gemm_phase(LAS unsigned char* lds, const Gemm g, const StaticOrder& S, const Epi& E) {
;     ...
;             const bool last = (t == nt - 2);
;             const char* a1 = cA + (size_t)(t + 1) * kstep;
;             const char* a2 = last ? nA : cA + (size_t)(t + 2) * kstep; const char* b2 = last ? nB : cB + (size_t)(t + 2) * kstep;
;             const char* a3 = a2 + kstep; const char* b3 = b2 + kstep;
;             PG8_LDB(B0, 0, 0); PG8_SCHED; PG8_LDA(At, 0, 0); PG8_STAGE(PG8_SA(1, 1), a1 + hstep, voffA);
;             PG8_WAIT_L(8); PG8_BAR; PG8_WAIT_L(0); PG8_MMA(0, 0, At, B0); PG8_BAR; PG8_SCHED;
.LBB0_1796:
	ds_read_b128 v[172:175], v157
	ds_read_b128 v[180:183], v157 offset:1024
	ds_read_b128 v[184:187], v157 offset:2048
	ds_read_b128 v[188:191], v157 offset:3072
	s_add_u32 s8, s6, 0xfff80080
	s_addc_u32 s9, s7, -1
	s_cmp_eq_u32 s37, 28
	s_cselect_b32 s11, s1, s9
	s_cselect_b32 s10, s5, s8
	s_cselect_b32 s9, s12, s35
	s_cselect_b32 s8, s13, s33
	v_lshl_add_u64 v[152:153], s[6:7], 0, v[142:143]
	s_add_i32 m0, s62, 0xc000
	ds_read_b128 v[192:195], v158
	ds_read_b128 v[196:199], v158 offset:1024
	ds_read_b128 v[200:203], v158 offset:2048
	ds_read_b128 v[204:207], v158 offset:3072
	ds_read_b128 v[208:211], v158 offset:4096
	ds_read_b128 v[212:215], v158 offset:5120
	ds_read_b128 v[216:219], v158 offset:6144
	ds_read_b128 v[220:223], v158 offset:7168
	global_load_lds_dwordx4 v[152:153], off
	v_lshl_add_u64 v[152:153], s[6:7], 0, v[144:145]
	s_add_i32 m0, s62, 0xe000
	s_nop 0
	global_load_lds_dwordx4 v[152:153], off
	s_waitcnt lgkmcnt(8)
	s_setprio 1
	s_barrier
	s_waitcnt lgkmcnt(0)


; #define PG8_MMA(ai, bj, At, Bt) do { __builtin_amdgcn_s_setprio(1); _Pragma("unroll") for (int m = 0; m < 4; ++m) _Pragma("unroll") for (int n = 0; n < 2; ++n) _Pragma("unroll") for (int k = 0; k < 2; ++k) \
;         acc[ai][bj][m][n] = __builtin_amdgcn_mfma_f32_16x16x32_bf16(Bt[n][k], At[m][k], acc[ai][bj][m][n], 0, 0, 0); __builtin_amdgcn_s_setprio(0); } while (0)
; #define PG8_WAIT_L(n) asm volatile("s_waitcnt lgkmcnt(" #n ")" ::: "memory")
; #define PG8_BAR __builtin_amdgcn_s_barrier()
; #define PG8_SCHED __builtin_amdgcn_sched_barrier(0)
; template <class Epi>
; __device__ __forceinline__ void gemm_phase(LAS unsigned char* lds, const Gemm g, const StaticOrder& S, const Epi& E) {
;     ...
;             PG8_WAIT_L(8); PG8_BAR; PG8_WAIT_L(0); PG8_MMA(0, 0, At, B0); PG8_BAR; PG8_SCHED;
	v_mfma_f32_16x16x32_bf16 v[116:119], v[172:175], v[192:195], v[116:119]
	v_mfma_f32_16x16x32_bf16 v[112:115], v[184:187], v[192:195], v[112:115]
	v_mfma_f32_16x16x32_bf16 v[100:103], v[172:175], v[200:203], v[100:103]
	v_mfma_f32_16x16x32_bf16 v[96:99], v[184:187], v[200:203], v[96:99]
	v_mfma_f32_16x16x32_bf16 v[84:87], v[172:175], v[208:211], v[84:87]
	v_mfma_f32_16x16x32_bf16 v[80:83], v[184:187], v[208:211], v[80:83]
	v_mfma_f32_16x16x32_bf16 v[68:71], v[172:175], v[216:219], v[68:71]
	v_mfma_f32_16x16x32_bf16 v[64:67], v[184:187], v[216:219], v[64:67]
	v_mfma_f32_16x16x32_bf16 v[116:119], v[180:183], v[196:199], v[116:119]
	v_mfma_f32_16x16x32_bf16 v[112:115], v[188:191], v[196:199], v[112:115]
	v_mfma_f32_16x16x32_bf16 v[100:103], v[180:183], v[204:207], v[100:103]
	v_mfma_f32_16x16x32_bf16 v[96:99], v[188:191], v[204:207], v[96:99]
	v_mfma_f32_16x16x32_bf16 v[84:87], v[180:183], v[212:215], v[84:87]
	v_mfma_f32_16x16x32_bf16 v[80:83], v[188:191], v[212:215], v[80:83]
	v_mfma_f32_16x16x32_bf16 v[68:71], v[180:183], v[220:223], v[68:71]
	v_mfma_f32_16x16x32_bf16 v[64:67], v[188:191], v[220:223], v[64:67]
	s_barrier
	s_setprio 0

; #define PG8_STAGE(bufoff, gbase, voff) do { _Pragma("unroll") for (int _i = 0; _i < 2; ++_i) \
;         __builtin_amdgcn_global_load_lds((const unsigned*)((const char*)(gbase) + (voff)[_i]), (LAS unsigned*)(lds + (bufoff) + ldsw + _i * 8192), 16, 0, 0); } while (0)
; #define PG8_LDB(dst, b, h) do { _Pragma("unroll") for (int n = 0; n < 2; ++n) _Pragma("unroll") for (int k = 0; k < 2; ++k) dst[n][k] = *(const LAS bf16x8*)(lds + PG8_SB(b, h) + boff + n * 2048 + k * 1024); } while (0)
; #define PG8_MMA(ai, bj, At, Bt) do { __builtin_amdgcn_s_setprio(1); _Pragma("unroll") for (int m = 0; m < 4; ++m) _Pragma("unroll") for (int n = 0; n < 2; ++n) _Pragma("unroll") for (int k = 0; k < 2; ++k) \
;         acc[ai][bj][m][n] = __builtin_amdgcn_mfma_f32_16x16x32_bf16(Bt[n][k], At[m][k], acc[ai][bj][m][n], 0, 0, 0); __builtin_amdgcn_s_setprio(0); } while (0)
; #define PG8_WAIT_L(n) asm volatile("s_waitcnt lgkmcnt(" #n ")" ::: "memory")
; #define PG8_BAR __builtin_amdgcn_s_barrier()
; template <class Epi>
; __device__ __forceinline__ void gemm_phase(LAS unsigned char* lds, const Gemm g, const StaticOrder& S, const Epi& E) {
;     ...
;             PG8_LDB(B1, 0, 1); PG8_STAGE(PG8_SB(0, 0), b2, voffB);
;             PG8_BAR; PG8_WAIT_L(0); PG8_MMA(0, 1, At, B1); PG8_BAR;
	s_add_i32 s42, s72, s57
	v_lshl_add_u64 v[152:153], s[8:9], 0, v[130:131]
	s_mov_b32 m0, s42
	ds_read_b128 v[224:227], v159
	ds_read_b128 v[228:231], v159 offset:1024
	ds_read_b128 v[232:235], v159 offset:2048
	ds_read_b128 v[236:239], v159 offset:3072
	global_load_lds_dwordx4 v[152:153], off
	v_lshl_add_u64 v[176:177], s[8:9], 0, v[134:135]
	s_add_i32 m0, s42, 0x2000
	s_nop 0
	global_load_lds_dwordx4 v[176:177], off
	s_waitcnt lgkmcnt(0)
	s_setprio 1
	s_barrier


; #define PG8_MMA(ai, bj, At, Bt) do { __builtin_amdgcn_s_setprio(1); _Pragma("unroll") for (int m = 0; m < 4; ++m) _Pragma("unroll") for (int n = 0; n < 2; ++n) _Pragma("unroll") for (int k = 0; k < 2; ++k) \
;         acc[ai][bj][m][n] = __builtin_amdgcn_mfma_f32_16x16x32_bf16(Bt[n][k], At[m][k], acc[ai][bj][m][n], 0, 0, 0); __builtin_amdgcn_s_setprio(0); } while (0)
; #define PG8_WAIT_L(n) asm volatile("s_waitcnt lgkmcnt(" #n ")" ::: "memory")
; #define PG8_BAR __builtin_amdgcn_s_barrier()
; template <class Epi>
; __device__ __forceinline__ void gemm_phase(LAS unsigned char* lds, const Gemm g, const StaticOrder& S, const Epi& E) {
;     ...
;             PG8_BAR; PG8_WAIT_L(0); PG8_MMA(0, 1, At, B1); PG8_BAR;
	v_mfma_f32_16x16x32_bf16 v[124:127], v[224:227], v[192:195], v[124:127]
	v_mfma_f32_16x16x32_bf16 v[120:123], v[232:235], v[192:195], v[120:123]
	v_mfma_f32_16x16x32_bf16 v[108:111], v[224:227], v[200:203], v[108:111]
	v_mfma_f32_16x16x32_bf16 v[104:107], v[232:235], v[200:203], v[104:107]
	v_mfma_f32_16x16x32_bf16 v[92:95], v[224:227], v[208:211], v[92:95]
	v_mfma_f32_16x16x32_bf16 v[88:91], v[232:235], v[208:211], v[88:91]
	v_mfma_f32_16x16x32_bf16 v[76:79], v[224:227], v[216:219], v[76:79]
	v_mfma_f32_16x16x32_bf16 v[72:75], v[232:235], v[216:219], v[72:75]
	v_mfma_f32_16x16x32_bf16 v[124:127], v[228:231], v[196:199], v[124:127]
	v_mfma_f32_16x16x32_bf16 v[120:123], v[236:239], v[196:199], v[120:123]
	v_mfma_f32_16x16x32_bf16 v[108:111], v[228:231], v[204:207], v[108:111]
	v_mfma_f32_16x16x32_bf16 v[104:107], v[236:239], v[204:207], v[104:107]
	v_mfma_f32_16x16x32_bf16 v[92:95], v[228:231], v[212:215], v[92:95]
	v_mfma_f32_16x16x32_bf16 v[88:91], v[236:239], v[212:215], v[88:91]
	v_mfma_f32_16x16x32_bf16 v[76:79], v[228:231], v[220:223], v[76:79]
	v_mfma_f32_16x16x32_bf16 v[72:75], v[236:239], v[220:223], v[72:75]
	s_barrier
	s_setprio 0
	s_mov_b32 m0, s62
	v_lshl_add_u64 v[240:241], s[10:11], 0, v[128:129]


; #define PG8_STAGE(bufoff, gbase, voff) do { _Pragma("unroll") for (int _i = 0; _i < 2; ++_i) \
;         __builtin_amdgcn_global_load_lds((const unsigned*)((const char*)(gbase) + (voff)[_i]), (LAS unsigned*)(lds + (bufoff) + ldsw + _i * 8192), 16, 0, 0); } while (0)
; #define PG8_LDA(dst, b, h) do { _Pragma("unroll") for (int m = 0; m < 4; ++m) _Pragma("unroll") for (int k = 0; k < 2; ++k) dst[m][k] = *(const LAS bf16x8*)(lds + PG8_SA(b, h) + aoff + m * 2048 + k * 1024); } while (0)
; #define PG8_MMA(ai, bj, At, Bt) do { __builtin_amdgcn_s_setprio(1); _Pragma("unroll") for (int m = 0; m < 4; ++m) _Pragma("unroll") for (int n = 0; n < 2; ++n) _Pragma("unroll") for (int k = 0; k < 2; ++k) \
;         acc[ai][bj][m][n] = __builtin_amdgcn_mfma_f32_16x16x32_bf16(Bt[n][k], At[m][k], acc[ai][bj][m][n], 0, 0, 0); __builtin_amdgcn_s_setprio(0); } while (0)
; #define PG8_WAIT_L(n) asm volatile("s_waitcnt lgkmcnt(" #n ")" ::: "memory")
; #define PG8_BAR __builtin_amdgcn_s_barrier()
; #define PG8_SCHED __builtin_amdgcn_sched_barrier(0)
; template <class Epi>
; __device__ __forceinline__ void gemm_phase(LAS unsigned char* lds, const Gemm g, const StaticOrder& S, const Epi& E) {
;     ...
;             PG8_LDA(At, 0, 1); PG8_STAGE(PG8_SA(0, 0), a2, voffA);
;             PG8_BAR; PG8_WAIT_L(0); PG8_MMA(1, 0, At, B0); PG8_BAR; PG8_SCHED;
	ds_read_b128 v[192:195], v158 offset:16384
	ds_read_b128 v[196:199], v158 offset:17408
	ds_read_b128 v[200:203], v158 offset:18432
	ds_read_b128 v[204:207], v158 offset:19456
	ds_read_b128 v[208:211], v158 offset:20480
	ds_read_b128 v[212:215], v158 offset:21504
	ds_read_b128 v[216:219], v158 offset:22528
	ds_read_b128 v[220:223], v158 offset:23552
	global_load_lds_dwordx4 v[240:241], off
	v_lshl_add_u64 v[242:243], s[10:11], 0, v[132:133]
	s_mov_b32 m0, s63
	s_nop 0
	global_load_lds_dwordx4 v[242:243], off
	s_waitcnt lgkmcnt(0)
	s_setprio 1
	s_barrier


; #define PG8_MMA(ai, bj, At, Bt) do { __builtin_amdgcn_s_setprio(1); _Pragma("unroll") for (int m = 0; m < 4; ++m) _Pragma("unroll") for (int n = 0; n < 2; ++n) _Pragma("unroll") for (int k = 0; k < 2; ++k) \
;         acc[ai][bj][m][n] = __builtin_amdgcn_mfma_f32_16x16x32_bf16(Bt[n][k], At[m][k], acc[ai][bj][m][n], 0, 0, 0); __builtin_amdgcn_s_setprio(0); } while (0)
; #define PG8_WAIT_L(n) asm volatile("s_waitcnt lgkmcnt(" #n ")" ::: "memory")
; #define PG8_BAR __builtin_amdgcn_s_barrier()
; #define PG8_SCHED __builtin_amdgcn_sched_barrier(0)
; template <class Epi>
; __device__ __forceinline__ void gemm_phase(LAS unsigned char* lds, const Gemm g, const StaticOrder& S, const Epi& E) {
;     ...
;             PG8_BAR; PG8_WAIT_L(0); PG8_MMA(1, 0, At, B0); PG8_BAR; PG8_SCHED;
	v_mfma_f32_16x16x32_bf16 v[52:55], v[172:175], v[192:195], v[52:55]
	v_mfma_f32_16x16x32_bf16 v[48:51], v[184:187], v[192:195], v[48:51]
	v_mfma_f32_16x16x32_bf16 v[36:39], v[172:175], v[200:203], v[36:39]
	v_mfma_f32_16x16x32_bf16 v[32:35], v[184:187], v[200:203], v[32:35]
	v_mfma_f32_16x16x32_bf16 v[20:23], v[172:175], v[208:211], v[20:23]
	v_mfma_f32_16x16x32_bf16 v[16:19], v[184:187], v[208:211], v[16:19]
	v_mfma_f32_16x16x32_bf16 v[4:7], v[172:175], v[216:219], v[4:7]
	v_mfma_f32_16x16x32_bf16 v[0:3], v[184:187], v[216:219], v[0:3]
	v_mfma_f32_16x16x32_bf16 v[52:55], v[180:183], v[196:199], v[52:55]
	v_mfma_f32_16x16x32_bf16 v[48:51], v[188:191], v[196:199], v[48:51]
	v_mfma_f32_16x16x32_bf16 v[36:39], v[180:183], v[204:207], v[36:39]
	v_mfma_f32_16x16x32_bf16 v[32:35], v[188:191], v[204:207], v[32:35]
	v_mfma_f32_16x16x32_bf16 v[20:23], v[180:183], v[212:215], v[20:23]
	v_mfma_f32_16x16x32_bf16 v[16:19], v[188:191], v[212:215], v[16:19]
	v_mfma_f32_16x16x32_bf16 v[4:7], v[180:183], v[220:223], v[4:7]
	v_mfma_f32_16x16x32_bf16 v[0:3], v[188:191], v[220:223], v[0:3]
	s_barrier
	s_setprio 0

; #define PG8_STAGE(bufoff, gbase, voff) do { _Pragma("unroll") for (int _i = 0; _i < 2; ++_i) \
;         __builtin_amdgcn_global_load_lds((const unsigned*)((const char*)(gbase) + (voff)[_i]), (LAS unsigned*)(lds + (bufoff) + ldsw + _i * 8192), 16, 0, 0); } while (0)
; #define PG8_MMA(ai, bj, At, Bt) do { __builtin_amdgcn_s_setprio(1); _Pragma("unroll") for (int m = 0; m < 4; ++m) _Pragma("unroll") for (int n = 0; n < 2; ++n) _Pragma("unroll") for (int k = 0; k < 2; ++k) \
;         acc[ai][bj][m][n] = __builtin_amdgcn_mfma_f32_16x16x32_bf16(Bt[n][k], At[m][k], acc[ai][bj][m][n], 0, 0, 0); __builtin_amdgcn_s_setprio(0); } while (0)
; #define PG8_WAIT_V(n) asm volatile("s_waitcnt vmcnt(" #n ")" ::: "memory")
; #define PG8_BAR __builtin_amdgcn_s_barrier()
; template <class Epi>
; __device__ __forceinline__ void gemm_phase(LAS unsigned char* lds, const Gemm g, const StaticOrder& S, const Epi& E) {
;     ...
;             PG8_STAGE(PG8_SB(0, 1), b2 + hstep, voffB);
;             PG8_WAIT_V(6); PG8_BAR; PG8_MMA(1, 1, At, B1); PG8_BAR;
	s_add_u32 s42, s8, 0x80000
	s_addc_u32 s43, s9, 0
	s_add_i32 s78, s73, s57
	v_lshl_add_u64 v[172:173], s[42:43], 0, v[130:131]
	s_mov_b32 m0, s78
	s_nop 0
	global_load_lds_dwordx4 v[172:173], off
	v_lshl_add_u64 v[172:173], s[42:43], 0, v[134:135]
	s_add_i32 m0, s78, 0x2000
	s_nop 0
	global_load_lds_dwordx4 v[172:173], off
	s_waitcnt vmcnt(6)
	s_setprio 1
	s_barrier

; #define PG8_MMA(ai, bj, At, Bt) do { __builtin_amdgcn_s_setprio(1); _Pragma("unroll") for (int m = 0; m < 4; ++m) _Pragma("unroll") for (int n = 0; n < 2; ++n) _Pragma("unroll") for (int k = 0; k < 2; ++k) \
;         acc[ai][bj][m][n] = __builtin_amdgcn_mfma_f32_16x16x32_bf16(Bt[n][k], At[m][k], acc[ai][bj][m][n], 0, 0, 0); __builtin_amdgcn_s_setprio(0); } while (0)
; #define PG8_WAIT_V(n) asm volatile("s_waitcnt vmcnt(" #n ")" ::: "memory")
; #define PG8_BAR __builtin_amdgcn_s_barrier()
; template <class Epi>
; __device__ __forceinline__ void gemm_phase(LAS unsigned char* lds, const Gemm g, const StaticOrder& S, const Epi& E) {
;     ...
;             PG8_WAIT_V(6); PG8_BAR; PG8_MMA(1, 1, At, B1); PG8_BAR;
	v_mfma_f32_16x16x32_bf16 v[60:63], v[224:227], v[192:195], v[60:63]
	v_mfma_f32_16x16x32_bf16 v[56:59], v[232:235], v[192:195], v[56:59]
	v_mfma_f32_16x16x32_bf16 v[44:47], v[224:227], v[200:203], v[44:47]
	v_mfma_f32_16x16x32_bf16 v[40:43], v[232:235], v[200:203], v[40:43]
	v_mfma_f32_16x16x32_bf16 v[28:31], v[224:227], v[208:211], v[28:31]
	v_mfma_f32_16x16x32_bf16 v[24:27], v[232:235], v[208:211], v[24:27]
	v_mfma_f32_16x16x32_bf16 v[12:15], v[224:227], v[216:219], v[12:15]
	v_mfma_f32_16x16x32_bf16 v[8:11], v[232:235], v[216:219], v[8:11]
	v_mfma_f32_16x16x32_bf16 v[60:63], v[228:231], v[196:199], v[60:63]
	v_mfma_f32_16x16x32_bf16 v[56:59], v[236:239], v[196:199], v[56:59]
	v_mfma_f32_16x16x32_bf16 v[44:47], v[228:231], v[204:207], v[44:47]
	v_mfma_f32_16x16x32_bf16 v[40:43], v[236:239], v[204:207], v[40:43]
	v_mfma_f32_16x16x32_bf16 v[28:31], v[228:231], v[212:215], v[28:31]
	v_mfma_f32_16x16x32_bf16 v[24:27], v[236:239], v[212:215], v[24:27]
	v_mfma_f32_16x16x32_bf16 v[12:15], v[228:231], v[220:223], v[12:15]
	v_mfma_f32_16x16x32_bf16 v[8:11], v[236:239], v[220:223], v[8:11]
	s_barrier
	s_setprio 0
	s_add_i32 s42, 0, 0x18000
	v_add_u32_e32 v136, s42, v155


; #define PG8_STAGE(bufoff, gbase, voff) do { _Pragma("unroll") for (int _i = 0; _i < 2; ++_i) \
;         __builtin_amdgcn_global_load_lds((const unsigned*)((const char*)(gbase) + (voff)[_i]), (LAS unsigned*)(lds + (bufoff) + ldsw + _i * 8192), 16, 0, 0); } while (0)
; #define PG8_LDA(dst, b, h) do { _Pragma("unroll") for (int m = 0; m < 4; ++m) _Pragma("unroll") for (int k = 0; k < 2; ++k) dst[m][k] = *(const LAS bf16x8*)(lds + PG8_SA(b, h) + aoff + m * 2048 + k * 1024); } while (0)
; #define PG8_LDB(dst, b, h) do { _Pragma("unroll") for (int n = 0; n < 2; ++n) _Pragma("unroll") for (int k = 0; k < 2; ++k) dst[n][k] = *(const LAS bf16x8*)(lds + PG8_SB(b, h) + boff + n * 2048 + k * 1024); } while (0)
; #define PG8_MMA(ai, bj, At, Bt) do { __builtin_amdgcn_s_setprio(1); _Pragma("unroll") for (int m = 0; m < 4; ++m) _Pragma("unroll") for (int n = 0; n < 2; ++n) _Pragma("unroll") for (int k = 0; k < 2; ++k) \
;         acc[ai][bj][m][n] = __builtin_amdgcn_mfma_f32_16x16x32_bf16(Bt[n][k], At[m][k], acc[ai][bj][m][n], 0, 0, 0); __builtin_amdgcn_s_setprio(0); } while (0)
; #define PG8_WAIT_L(n) asm volatile("s_waitcnt lgkmcnt(" #n ")" ::: "memory")
; #define PG8_BAR __builtin_amdgcn_s_barrier()
; #define PG8_SCHED __builtin_amdgcn_sched_barrier(0)
; template <class Epi>
; __device__ __forceinline__ void gemm_phase(LAS unsigned char* lds, const Gemm g, const StaticOrder& S, const Epi& E) {
;     ...
;             PG8_LDB(B0, 1, 0); PG8_SCHED; PG8_LDA(At, 1, 0); PG8_STAGE(PG8_SA(0, 1), a2 + hstep, voffA);
;             PG8_WAIT_L(8); PG8_BAR; PG8_WAIT_L(0); PG8_MMA(0, 0, At, B0); PG8_BAR; PG8_SCHED;
	ds_read_b128 v[172:175], v136
	ds_read_b128 v[180:183], v136 offset:1024
	ds_read_b128 v[184:187], v136 offset:2048
	ds_read_b128 v[188:191], v136 offset:3072
	s_add_u32 s10, s10, 0x80000
	s_addc_u32 s11, s11, 0
	s_mov_b32 m0, s64
	v_lshl_add_u64 v[224:225], s[10:11], 0, v[128:129]
	ds_read_b128 v[192:195], v158 offset:32768
	ds_read_b128 v[196:199], v158 offset:33792
	ds_read_b128 v[200:203], v158 offset:34816
	ds_read_b128 v[204:207], v158 offset:35840
	ds_read_b128 v[208:211], v158 offset:36864
	ds_read_b128 v[212:215], v158 offset:37888
	ds_read_b128 v[216:219], v158 offset:38912
	ds_read_b128 v[220:223], v158 offset:39936
	global_load_lds_dwordx4 v[224:225], off
	v_lshl_add_u64 v[224:225], s[10:11], 0, v[132:133]
	s_mov_b32 m0, s65
	s_nop 0
	global_load_lds_dwordx4 v[224:225], off
	s_waitcnt lgkmcnt(8)
	s_setprio 1
	s_barrier
	s_waitcnt lgkmcnt(0)


; #define PG8_MMA(ai, bj, At, Bt) do { __builtin_amdgcn_s_setprio(1); _Pragma("unroll") for (int m = 0; m < 4; ++m) _Pragma("unroll") for (int n = 0; n < 2; ++n) _Pragma("unroll") for (int k = 0; k < 2; ++k) \
;         acc[ai][bj][m][n] = __builtin_amdgcn_mfma_f32_16x16x32_bf16(Bt[n][k], At[m][k], acc[ai][bj][m][n], 0, 0, 0); __builtin_amdgcn_s_setprio(0); } while (0)
; #define PG8_WAIT_L(n) asm volatile("s_waitcnt lgkmcnt(" #n ")" ::: "memory")
; #define PG8_BAR __builtin_amdgcn_s_barrier()
; #define PG8_SCHED __builtin_amdgcn_sched_barrier(0)
; template <class Epi>
; __device__ __forceinline__ void gemm_phase(LAS unsigned char* lds, const Gemm g, const StaticOrder& S, const Epi& E) {
;     ...
;             PG8_WAIT_L(8); PG8_BAR; PG8_WAIT_L(0); PG8_MMA(0, 0, At, B0); PG8_BAR; PG8_SCHED;
	v_mfma_f32_16x16x32_bf16 v[116:119], v[172:175], v[192:195], v[116:119]
	v_mfma_f32_16x16x32_bf16 v[112:115], v[184:187], v[192:195], v[112:115]
	v_mfma_f32_16x16x32_bf16 v[100:103], v[172:175], v[200:203], v[100:103]
	v_mfma_f32_16x16x32_bf16 v[96:99], v[184:187], v[200:203], v[96:99]
	v_mfma_f32_16x16x32_bf16 v[84:87], v[172:175], v[208:211], v[84:87]
	v_mfma_f32_16x16x32_bf16 v[80:83], v[184:187], v[208:211], v[80:83]
	v_mfma_f32_16x16x32_bf16 v[68:71], v[172:175], v[216:219], v[68:71]
	v_mfma_f32_16x16x32_bf16 v[64:67], v[184:187], v[216:219], v[64:67]
	v_mfma_f32_16x16x32_bf16 v[116:119], v[180:183], v[196:199], v[116:119]
	v_mfma_f32_16x16x32_bf16 v[112:115], v[188:191], v[196:199], v[112:115]
	v_mfma_f32_16x16x32_bf16 v[100:103], v[180:183], v[204:207], v[100:103]
	v_mfma_f32_16x16x32_bf16 v[96:99], v[188:191], v[204:207], v[96:99]
	v_mfma_f32_16x16x32_bf16 v[84:87], v[180:183], v[212:215], v[84:87]
	v_mfma_f32_16x16x32_bf16 v[80:83], v[188:191], v[212:215], v[80:83]
	v_mfma_f32_16x16x32_bf16 v[68:71], v[180:183], v[220:223], v[68:71]
	v_mfma_f32_16x16x32_bf16 v[64:67], v[188:191], v[220:223], v[64:67]
	s_barrier
	s_setprio 0

; #define PG8_STAGE(bufoff, gbase, voff) do { _Pragma("unroll") for (int _i = 0; _i < 2; ++_i) \
;         __builtin_amdgcn_global_load_lds((const unsigned*)((const char*)(gbase) + (voff)[_i]), (LAS unsigned*)(lds + (bufoff) + ldsw + _i * 8192), 16, 0, 0); } while (0)
; #define PG8_LDB(dst, b, h) do { _Pragma("unroll") for (int n = 0; n < 2; ++n) _Pragma("unroll") for (int k = 0; k < 2; ++k) dst[n][k] = *(const LAS bf16x8*)(lds + PG8_SB(b, h) + boff + n * 2048 + k * 1024); } while (0)
; #define PG8_MMA(ai, bj, At, Bt) do { __builtin_amdgcn_s_setprio(1); _Pragma("unroll") for (int m = 0; m < 4; ++m) _Pragma("unroll") for (int n = 0; n < 2; ++n) _Pragma("unroll") for (int k = 0; k < 2; ++k) \
;         acc[ai][bj][m][n] = __builtin_amdgcn_mfma_f32_16x16x32_bf16(Bt[n][k], At[m][k], acc[ai][bj][m][n], 0, 0, 0); __builtin_amdgcn_s_setprio(0); } while (0)
; #define PG8_WAIT_L(n) asm volatile("s_waitcnt lgkmcnt(" #n ")" ::: "memory")
; #define PG8_BAR __builtin_amdgcn_s_barrier()
; template <class Epi>
; __device__ __forceinline__ void gemm_phase(LAS unsigned char* lds, const Gemm g, const StaticOrder& S, const Epi& E) {
;     ...
;             PG8_LDB(B1, 1, 1); PG8_STAGE(PG8_SB(1, 0), b3, voffB);
;             PG8_BAR; PG8_WAIT_L(0); PG8_MMA(0, 1, At, B1); PG8_BAR;
	s_add_i32 s10, 0, 0x1c000
	s_add_i32 s11, s42, s57
	v_add_u32_e32 v136, s10, v155
	v_lshl_add_u64 v[152:153], v[152:153], 0, s[24:25]
	s_mov_b32 m0, s11
	ds_read_b128 v[224:227], v136
	ds_read_b128 v[228:231], v136 offset:1024
	ds_read_b128 v[232:235], v136 offset:2048
	ds_read_b128 v[236:239], v136 offset:3072
	global_load_lds_dwordx4 v[152:153], off
	v_lshl_add_u64 v[152:153], v[176:177], 0, s[24:25]
	s_add_i32 m0, s11, 0x2000
	s_nop 0
	global_load_lds_dwordx4 v[152:153], off
	s_waitcnt lgkmcnt(0)
	s_setprio 1
	s_barrier


; #define PG8_MMA(ai, bj, At, Bt) do { __builtin_amdgcn_s_setprio(1); _Pragma("unroll") for (int m = 0; m < 4; ++m) _Pragma("unroll") for (int n = 0; n < 2; ++n) _Pragma("unroll") for (int k = 0; k < 2; ++k) \
;         acc[ai][bj][m][n] = __builtin_amdgcn_mfma_f32_16x16x32_bf16(Bt[n][k], At[m][k], acc[ai][bj][m][n], 0, 0, 0); __builtin_amdgcn_s_setprio(0); } while (0)
; #define PG8_WAIT_L(n) asm volatile("s_waitcnt lgkmcnt(" #n ")" ::: "memory")
; #define PG8_BAR __builtin_amdgcn_s_barrier()
; template <class Epi>
; __device__ __forceinline__ void gemm_phase(LAS unsigned char* lds, const Gemm g, const StaticOrder& S, const Epi& E) {
;     ...
;             PG8_BAR; PG8_WAIT_L(0); PG8_MMA(0, 1, At, B1); PG8_BAR;
	v_mfma_f32_16x16x32_bf16 v[124:127], v[224:227], v[192:195], v[124:127]
	v_mfma_f32_16x16x32_bf16 v[120:123], v[232:235], v[192:195], v[120:123]
	v_mfma_f32_16x16x32_bf16 v[108:111], v[224:227], v[200:203], v[108:111]
	v_mfma_f32_16x16x32_bf16 v[104:107], v[232:235], v[200:203], v[104:107]
	v_mfma_f32_16x16x32_bf16 v[92:95], v[224:227], v[208:211], v[92:95]
	v_mfma_f32_16x16x32_bf16 v[88:91], v[232:235], v[208:211], v[88:91]
	v_mfma_f32_16x16x32_bf16 v[76:79], v[224:227], v[216:219], v[76:79]
	v_mfma_f32_16x16x32_bf16 v[72:75], v[232:235], v[216:219], v[72:75]
	v_mfma_f32_16x16x32_bf16 v[124:127], v[228:231], v[196:199], v[124:127]
	v_mfma_f32_16x16x32_bf16 v[120:123], v[236:239], v[196:199], v[120:123]
	v_mfma_f32_16x16x32_bf16 v[108:111], v[228:231], v[204:207], v[108:111]
	v_mfma_f32_16x16x32_bf16 v[104:107], v[236:239], v[204:207], v[104:107]
	v_mfma_f32_16x16x32_bf16 v[92:95], v[228:231], v[212:215], v[92:95]
	v_mfma_f32_16x16x32_bf16 v[88:91], v[236:239], v[212:215], v[88:91]
	v_mfma_f32_16x16x32_bf16 v[76:79], v[228:231], v[220:223], v[76:79]
	v_mfma_f32_16x16x32_bf16 v[72:75], v[236:239], v[220:223], v[72:75]
	s_barrier
	s_setprio 0
	s_mov_b32 m0, s67
	v_lshl_add_u64 v[152:153], v[240:241], 0, s[24:25]


; #define PG8_STAGE(bufoff, gbase, voff) do { _Pragma("unroll") for (int _i = 0; _i < 2; ++_i) \
;         __builtin_amdgcn_global_load_lds((const unsigned*)((const char*)(gbase) + (voff)[_i]), (LAS unsigned*)(lds + (bufoff) + ldsw + _i * 8192), 16, 0, 0); } while (0)
; #define PG8_LDA(dst, b, h) do { _Pragma("unroll") for (int m = 0; m < 4; ++m) _Pragma("unroll") for (int k = 0; k < 2; ++k) dst[m][k] = *(const LAS bf16x8*)(lds + PG8_SA(b, h) + aoff + m * 2048 + k * 1024); } while (0)
; #define PG8_MMA(ai, bj, At, Bt) do { __builtin_amdgcn_s_setprio(1); _Pragma("unroll") for (int m = 0; m < 4; ++m) _Pragma("unroll") for (int n = 0; n < 2; ++n) _Pragma("unroll") for (int k = 0; k < 2; ++k) \
;         acc[ai][bj][m][n] = __builtin_amdgcn_mfma_f32_16x16x32_bf16(Bt[n][k], At[m][k], acc[ai][bj][m][n], 0, 0, 0); __builtin_amdgcn_s_setprio(0); } while (0)
; #define PG8_WAIT_L(n) asm volatile("s_waitcnt lgkmcnt(" #n ")" ::: "memory")
; #define PG8_BAR __builtin_amdgcn_s_barrier()
; #define PG8_SCHED __builtin_amdgcn_sched_barrier(0)
; template <class Epi>
; __device__ __forceinline__ void gemm_phase(LAS unsigned char* lds, const Gemm g, const StaticOrder& S, const Epi& E) {
;     ...
;             PG8_LDA(At, 1, 1); PG8_STAGE(PG8_SA(1, 0), a3, voffA);
;             PG8_BAR; PG8_WAIT_L(0); PG8_MMA(1, 0, At, B0); PG8_BAR; PG8_SCHED;
	ds_read_b128 v[192:195], v158 offset:49152
	ds_read_b128 v[196:199], v158 offset:50176
	ds_read_b128 v[200:203], v158 offset:51200
	ds_read_b128 v[204:207], v158 offset:52224
	ds_read_b128 v[208:211], v158 offset:53248
	ds_read_b128 v[212:215], v158 offset:54272
	ds_read_b128 v[216:219], v158 offset:55296
	ds_read_b128 v[220:223], v158 offset:56320
	global_load_lds_dwordx4 v[152:153], off
	v_lshl_add_u64 v[152:153], v[242:243], 0, s[24:25]
	s_mov_b32 m0, s68
	s_nop 0
	global_load_lds_dwordx4 v[152:153], off
	s_waitcnt lgkmcnt(0)
	s_setprio 1
	s_barrier


; #define PG8_MMA(ai, bj, At, Bt) do { __builtin_amdgcn_s_setprio(1); _Pragma("unroll") for (int m = 0; m < 4; ++m) _Pragma("unroll") for (int n = 0; n < 2; ++n) _Pragma("unroll") for (int k = 0; k < 2; ++k) \
;         acc[ai][bj][m][n] = __builtin_amdgcn_mfma_f32_16x16x32_bf16(Bt[n][k], At[m][k], acc[ai][bj][m][n], 0, 0, 0); __builtin_amdgcn_s_setprio(0); } while (0)
; #define PG8_WAIT_L(n) asm volatile("s_waitcnt lgkmcnt(" #n ")" ::: "memory")
; #define PG8_BAR __builtin_amdgcn_s_barrier()
; #define PG8_SCHED __builtin_amdgcn_sched_barrier(0)
; template <class Epi>
; __device__ __forceinline__ void gemm_phase(LAS unsigned char* lds, const Gemm g, const StaticOrder& S, const Epi& E) {
;     ...
;             PG8_BAR; PG8_WAIT_L(0); PG8_MMA(1, 0, At, B0); PG8_BAR; PG8_SCHED;
	v_mfma_f32_16x16x32_bf16 v[52:55], v[172:175], v[192:195], v[52:55]
	v_mfma_f32_16x16x32_bf16 v[48:51], v[184:187], v[192:195], v[48:51]
	v_mfma_f32_16x16x32_bf16 v[36:39], v[172:175], v[200:203], v[36:39]
	v_mfma_f32_16x16x32_bf16 v[32:35], v[184:187], v[200:203], v[32:35]
	v_mfma_f32_16x16x32_bf16 v[20:23], v[172:175], v[208:211], v[20:23]
	v_mfma_f32_16x16x32_bf16 v[16:19], v[184:187], v[208:211], v[16:19]
	v_mfma_f32_16x16x32_bf16 v[4:7], v[172:175], v[216:219], v[4:7]
	v_mfma_f32_16x16x32_bf16 v[0:3], v[184:187], v[216:219], v[0:3]
	v_mfma_f32_16x16x32_bf16 v[52:55], v[180:183], v[196:199], v[52:55]
	v_mfma_f32_16x16x32_bf16 v[48:51], v[188:191], v[196:199], v[48:51]
	v_mfma_f32_16x16x32_bf16 v[36:39], v[180:183], v[204:207], v[36:39]
	v_mfma_f32_16x16x32_bf16 v[32:35], v[188:191], v[204:207], v[32:35]
	v_mfma_f32_16x16x32_bf16 v[20:23], v[180:183], v[212:215], v[20:23]
	v_mfma_f32_16x16x32_bf16 v[16:19], v[188:191], v[212:215], v[16:19]
	v_mfma_f32_16x16x32_bf16 v[4:7], v[180:183], v[220:223], v[4:7]
	v_mfma_f32_16x16x32_bf16 v[0:3], v[188:191], v[220:223], v[0:3]
	s_barrier
	s_setprio 0

; #define PG8_STAGE(bufoff, gbase, voff) do { _Pragma("unroll") for (int _i = 0; _i < 2; ++_i) \
;         __builtin_amdgcn_global_load_lds((const unsigned*)((const char*)(gbase) + (voff)[_i]), (LAS unsigned*)(lds + (bufoff) + ldsw + _i * 8192), 16, 0, 0); } while (0)
; #define PG8_MMA(ai, bj, At, Bt) do { __builtin_amdgcn_s_setprio(1); _Pragma("unroll") for (int m = 0; m < 4; ++m) _Pragma("unroll") for (int n = 0; n < 2; ++n) _Pragma("unroll") for (int k = 0; k < 2; ++k) \
;         acc[ai][bj][m][n] = __builtin_amdgcn_mfma_f32_16x16x32_bf16(Bt[n][k], At[m][k], acc[ai][bj][m][n], 0, 0, 0); __builtin_amdgcn_s_setprio(0); } while (0)
; #define PG8_WAIT_V(n) asm volatile("s_waitcnt vmcnt(" #n ")" ::: "memory")
; #define PG8_BAR __builtin_amdgcn_s_barrier()
; template <class Epi>
; __device__ __forceinline__ void gemm_phase(LAS unsigned char* lds, const Gemm g, const StaticOrder& S, const Epi& E) {
;     ...
;             PG8_STAGE(PG8_SB(1, 1), b3 + hstep, voffB);
;             PG8_WAIT_V(6); PG8_BAR; PG8_MMA(1, 1, At, B1); PG8_BAR;
	s_add_u32 s8, s8, 0x80080
	s_addc_u32 s9, s9, 0
	s_add_i32 s10, s10, s57
	v_lshl_add_u64 v[152:153], s[8:9], 0, v[130:131]
	s_mov_b32 m0, s10
	s_nop 0
	global_load_lds_dwordx4 v[152:153], off
	v_lshl_add_u64 v[152:153], s[8:9], 0, v[134:135]
	s_add_i32 m0, s10, 0x2000
	s_nop 0
	global_load_lds_dwordx4 v[152:153], off
	s_waitcnt vmcnt(6)
	s_setprio 1
	s_barrier

; #define PG8_MMA(ai, bj, At, Bt) do { __builtin_amdgcn_s_setprio(1); _Pragma("unroll") for (int m = 0; m < 4; ++m) _Pragma("unroll") for (int n = 0; n < 2; ++n) _Pragma("unroll") for (int k = 0; k < 2; ++k) \
;         acc[ai][bj][m][n] = __builtin_amdgcn_mfma_f32_16x16x32_bf16(Bt[n][k], At[m][k], acc[ai][bj][m][n], 0, 0, 0); __builtin_amdgcn_s_setprio(0); } while (0)
; #define PG8_WAIT_V(n) asm volatile("s_waitcnt vmcnt(" #n ")" ::: "memory")
; #define PG8_BAR __builtin_amdgcn_s_barrier()
; template <class Epi>
; __device__ __forceinline__ void gemm_phase(LAS unsigned char* lds, const Gemm g, const StaticOrder& S, const Epi& E) {
;     ...
;             PG8_WAIT_V(6); PG8_BAR; PG8_MMA(1, 1, At, B1); PG8_BAR;
	v_mfma_f32_16x16x32_bf16 v[60:63], v[224:227], v[192:195], v[60:63]
	v_mfma_f32_16x16x32_bf16 v[56:59], v[232:235], v[192:195], v[56:59]
	v_mfma_f32_16x16x32_bf16 v[44:47], v[224:227], v[200:203], v[44:47]
	v_mfma_f32_16x16x32_bf16 v[40:43], v[232:235], v[200:203], v[40:43]
	v_mfma_f32_16x16x32_bf16 v[28:31], v[224:227], v[208:211], v[28:31]
	v_mfma_f32_16x16x32_bf16 v[24:27], v[232:235], v[208:211], v[24:27]
	v_mfma_f32_16x16x32_bf16 v[12:15], v[224:227], v[216:219], v[12:15]
	v_mfma_f32_16x16x32_bf16 v[8:11], v[232:235], v[216:219], v[8:11]
	v_mfma_f32_16x16x32_bf16 v[60:63], v[228:231], v[196:199], v[60:63]
	v_mfma_f32_16x16x32_bf16 v[56:59], v[236:239], v[196:199], v[56:59]
	v_mfma_f32_16x16x32_bf16 v[44:47], v[228:231], v[204:207], v[44:47]
	v_mfma_f32_16x16x32_bf16 v[40:43], v[236:239], v[204:207], v[40:43]
	v_mfma_f32_16x16x32_bf16 v[28:31], v[228:231], v[212:215], v[28:31]
	v_mfma_f32_16x16x32_bf16 v[24:27], v[236:239], v[212:215], v[24:27]
	v_mfma_f32_16x16x32_bf16 v[12:15], v[228:231], v[220:223], v[12:15]
	v_mfma_f32_16x16x32_bf16 v[8:11], v[236:239], v[220:223], v[8:11]
	s_barrier
	s_setprio 0
	s_add_i32 s37, s37, 2
	s_add_u32 s6, s6, 0x100
	s_addc_u32 s7, s7, 0
	s_add_u32 s33, s33, 0x100
	s_addc_u32 s35, s35, 0
	s_cmp_gt_u32 s37, 29


;     __device__ __forceinline__ void operator()(const f32x4 (&acc)[2][2][4][2], const Unit& u, int wr, int wc, int fr, int fq, const Pre& P) const {
;         const int sec = u.pn >> 3, row0 = ROW_X + u.pm * BM + wr * 64 + fr, colb = (u.pn & 7) * BM + wc * 32 + 8 * fq;
; #pragma unroll
;         for (int ai = 0; ai < 2; ++ai)
; #pragma unroll
;             for (int m = 0; m < 4; ++m) { const int r = row0 + ai * HALF + m * 16; const float rs = __builtin_amdgcn_rsqf(P.rs[ai * 4 + m] * (1.0f / DM) + RMS_EPS);
;                 if (sec == 4) {
	s_cbranch_scc0 .LBB0_1796
	s_lshl_b32 s1, s0, 8
	s_ashr_i32 s35, s0, 3
	s_and_b32 s1, s1, 0x700
	s_waitcnt vmcnt(0)
	v_fmamk_f32 v136, v151, 0x3a000000, v160
	s_cmp_lg_u32 s35, 4
	v_rsq_f32_e32 v171, v136
	s_cselect_b64 s[10:11], -1, 0
	s_cmp_eq_u32 s35, 3
	v_lshl_add_u32 v150, s4, 8, v154
	s_cselect_b64 s[4:5], -1, 0
	s_cmp_gt_u32 s0, 7
	v_or_b32_e32 v165, s1, v156
	s_cselect_b64 s[12:13], -1, 0
	s_cmp_eq_u32 s35, 4
	s_mov_b64 s[0:1], -1
	s_cbranch_scc1 .LBB0_1817
	s_and_b64 vcc, exec, s[12:13]
	s_mov_b64 s[0:1], s[14:15]
	s_cbranch_vccz .LBB0_1807
	s_cmp_lt_i32 s35, 2
	s_cbranch_scc1 .LBB0_1803
	s_cmp_eq_u32 s35, 2
	s_mov_b64 s[6:7], -1
	s_cbranch_scc0 .LBB0_1802
	s_mov_b64 s[6:7], 0

; #define PG8_STAGE(bufoff, gbase, voff) do { _Pragma("unroll") for (int _i = 0; _i < 2; ++_i) \
;         __builtin_amdgcn_global_load_lds((const unsigned*)((const char*)(gbase) + (voff)[_i]), (LAS unsigned*)(lds + (bufoff) + ldsw + _i * 8192), 16, 0, 0); } while (0)
; #define PG8_LDA(dst, b, h) do { _Pragma("unroll") for (int m = 0; m < 4; ++m) _Pragma("unroll") for (int k = 0; k < 2; ++k) dst[m][k] = *(const LAS bf16x8*)(lds + PG8_SA(b, h) + aoff + m * 2048 + k * 1024); } while (0)
; #define PG8_LDB(dst, b, h) do { _Pragma("unroll") for (int n = 0; n < 2; ++n) _Pragma("unroll") for (int k = 0; k < 2; ++k) dst[n][k] = *(const LAS bf16x8*)(lds + PG8_SB(b, h) + boff + n * 2048 + k * 1024); } while (0)
; #define PG8_MMA(ai, bj, At, Bt) do { __builtin_amdgcn_s_setprio(1); _Pragma("unroll") for (int m = 0; m < 4; ++m) _Pragma("unroll") for (int n = 0; n < 2; ++n) _Pragma("unroll") for (int k = 0; k < 2; ++k) \
;         acc[ai][bj][m][n] = __builtin_amdgcn_mfma_f32_16x16x32_bf16(Bt[n][k], At[m][k], acc[ai][bj][m][n], 0, 0, 0); __builtin_amdgcn_s_setprio(0); } while (0)
; #define PG8_WAIT_L(n) asm volatile("s_waitcnt lgkmcnt(" #n ")" ::: "memory")
; #define PG8_BAR __builtin_amdgcn_s_barrier()
; #define PG8_SCHED __builtin_amdgcn_sched_barrier(0)
; template <class Epi>
; __device__ __forceinline__ void gemm_phase(LAS unsigned char* lds, const Gemm g, const StaticOrder& S, const Epi& E) {
;     ...
;             const bool last = (t == nt - 2);
;             const char* a1 = cA + (size_t)(t + 1) * kstep;
;             const char* a2 = last ? nA : cA + (size_t)(t + 2) * kstep; const char* b2 = last ? nB : cB + (size_t)(t + 2) * kstep;
;             const char* a3 = a2 + kstep; const char* b3 = b2 + kstep;
;             PG8_LDB(B0, 0, 0); PG8_SCHED; PG8_LDA(At, 0, 0); PG8_STAGE(PG8_SA(1, 1), a1 + hstep, voffA);
;             PG8_WAIT_L(8); PG8_BAR; PG8_WAIT_L(0); PG8_MMA(0, 0, At, B0); PG8_BAR; PG8_SCHED;
.LBB0_2460:
	ds_read_b128 v[128:131], v161
	ds_read_b128 v[132:135], v161 offset:1024
	ds_read_b128 v[152:155], v161 offset:2048
	ds_read_b128 v[166:169], v161 offset:3072
	s_add_u32 s24, s22, 0xfff80080
	s_addc_u32 s25, s23, -1
	s_cmp_eq_u32 s61, 28
	s_cselect_b32 s31, s13, s25
	s_cselect_b32 s30, s19, s24
	s_cselect_b32 s25, s11, s60
	s_cselect_b32 s24, s58, s59
	v_lshl_add_u64 v[156:157], s[22:23], 0, v[144:145]
	s_add_i32 m0, s21, 0xc000
	ds_read_b128 v[170:173], v162
	ds_read_b128 v[174:177], v162 offset:1024
	ds_read_b128 v[180:183], v162 offset:2048
	ds_read_b128 v[184:187], v162 offset:3072
	ds_read_b128 v[188:191], v162 offset:4096
	ds_read_b128 v[192:195], v162 offset:5120
	ds_read_b128 v[196:199], v162 offset:6144
	ds_read_b128 v[200:203], v162 offset:7168
	global_load_lds_dwordx4 v[156:157], off
	v_lshl_add_u64 v[156:157], s[22:23], 0, v[146:147]
	s_add_i32 m0, s21, 0xe000
	s_nop 0
	global_load_lds_dwordx4 v[156:157], off
	s_waitcnt lgkmcnt(8)
	s_setprio 1
	s_barrier
	s_waitcnt lgkmcnt(0)


; #define PG8_MMA(ai, bj, At, Bt) do { __builtin_amdgcn_s_setprio(1); _Pragma("unroll") for (int m = 0; m < 4; ++m) _Pragma("unroll") for (int n = 0; n < 2; ++n) _Pragma("unroll") for (int k = 0; k < 2; ++k) \
;         acc[ai][bj][m][n] = __builtin_amdgcn_mfma_f32_16x16x32_bf16(Bt[n][k], At[m][k], acc[ai][bj][m][n], 0, 0, 0); __builtin_amdgcn_s_setprio(0); } while (0)
; #define PG8_WAIT_L(n) asm volatile("s_waitcnt lgkmcnt(" #n ")" ::: "memory")
; #define PG8_BAR __builtin_amdgcn_s_barrier()
; #define PG8_SCHED __builtin_amdgcn_sched_barrier(0)
; template <class Epi>
; __device__ __forceinline__ void gemm_phase(LAS unsigned char* lds, const Gemm g, const StaticOrder& S, const Epi& E) {
;     ...
;             PG8_WAIT_L(8); PG8_BAR; PG8_WAIT_L(0); PG8_MMA(0, 0, At, B0); PG8_BAR; PG8_SCHED;
	v_mfma_f32_16x16x32_bf16 v[124:127], v[128:131], v[170:173], v[124:127]
	v_mfma_f32_16x16x32_bf16 v[120:123], v[152:155], v[170:173], v[120:123]
	v_mfma_f32_16x16x32_bf16 v[108:111], v[128:131], v[180:183], v[108:111]
	v_mfma_f32_16x16x32_bf16 v[104:107], v[152:155], v[180:183], v[104:107]
	v_mfma_f32_16x16x32_bf16 v[92:95], v[128:131], v[188:191], v[92:95]
	v_mfma_f32_16x16x32_bf16 v[88:91], v[152:155], v[188:191], v[88:91]
	v_mfma_f32_16x16x32_bf16 v[76:79], v[128:131], v[196:199], v[76:79]
	v_mfma_f32_16x16x32_bf16 v[72:75], v[152:155], v[196:199], v[72:75]
	v_mfma_f32_16x16x32_bf16 v[124:127], v[132:135], v[174:177], v[124:127]
	v_mfma_f32_16x16x32_bf16 v[120:123], v[166:169], v[174:177], v[120:123]
	v_mfma_f32_16x16x32_bf16 v[108:111], v[132:135], v[184:187], v[108:111]
	v_mfma_f32_16x16x32_bf16 v[104:107], v[166:169], v[184:187], v[104:107]
	v_mfma_f32_16x16x32_bf16 v[92:95], v[132:135], v[192:195], v[92:95]
	v_mfma_f32_16x16x32_bf16 v[88:91], v[166:169], v[192:195], v[88:91]
	v_mfma_f32_16x16x32_bf16 v[76:79], v[132:135], v[200:203], v[76:79]
	v_mfma_f32_16x16x32_bf16 v[72:75], v[166:169], v[200:203], v[72:75]
	s_barrier
	s_setprio 0

; #define PG8_STAGE(bufoff, gbase, voff) do { _Pragma("unroll") for (int _i = 0; _i < 2; ++_i) \
;         __builtin_amdgcn_global_load_lds((const unsigned*)((const char*)(gbase) + (voff)[_i]), (LAS unsigned*)(lds + (bufoff) + ldsw + _i * 8192), 16, 0, 0); } while (0)
; #define PG8_LDB(dst, b, h) do { _Pragma("unroll") for (int n = 0; n < 2; ++n) _Pragma("unroll") for (int k = 0; k < 2; ++k) dst[n][k] = *(const LAS bf16x8*)(lds + PG8_SB(b, h) + boff + n * 2048 + k * 1024); } while (0)
; #define PG8_MMA(ai, bj, At, Bt) do { __builtin_amdgcn_s_setprio(1); _Pragma("unroll") for (int m = 0; m < 4; ++m) _Pragma("unroll") for (int n = 0; n < 2; ++n) _Pragma("unroll") for (int k = 0; k < 2; ++k) \
;         acc[ai][bj][m][n] = __builtin_amdgcn_mfma_f32_16x16x32_bf16(Bt[n][k], At[m][k], acc[ai][bj][m][n], 0, 0, 0); __builtin_amdgcn_s_setprio(0); } while (0)
; #define PG8_WAIT_L(n) asm volatile("s_waitcnt lgkmcnt(" #n ")" ::: "memory")
; #define PG8_BAR __builtin_amdgcn_s_barrier()
; template <class Epi>
; __device__ __forceinline__ void gemm_phase(LAS unsigned char* lds, const Gemm g, const StaticOrder& S, const Epi& E) {
;     ...
;             PG8_LDB(B1, 0, 1); PG8_STAGE(PG8_SB(0, 0), b2, voffB);
;             PG8_BAR; PG8_WAIT_L(0); PG8_MMA(0, 1, At, B1); PG8_BAR;
	s_add_i32 s62, s56, s38
	v_lshl_add_u64 v[156:157], s[24:25], 0, v[138:139]
	s_mov_b32 m0, s62
	ds_read_b128 v[204:207], v163
	ds_read_b128 v[208:211], v163 offset:1024
	ds_read_b128 v[212:215], v163 offset:2048
	ds_read_b128 v[216:219], v163 offset:3072
	global_load_lds_dwordx4 v[156:157], off
	v_lshl_add_u64 v[220:221], s[24:25], 0, v[142:143]
	s_add_i32 m0, s62, 0x2000
	s_nop 0
	global_load_lds_dwordx4 v[220:221], off
	s_waitcnt lgkmcnt(0)
	s_setprio 1
	s_barrier


; #define PG8_MMA(ai, bj, At, Bt) do { __builtin_amdgcn_s_setprio(1); _Pragma("unroll") for (int m = 0; m < 4; ++m) _Pragma("unroll") for (int n = 0; n < 2; ++n) _Pragma("unroll") for (int k = 0; k < 2; ++k) \
;         acc[ai][bj][m][n] = __builtin_amdgcn_mfma_f32_16x16x32_bf16(Bt[n][k], At[m][k], acc[ai][bj][m][n], 0, 0, 0); __builtin_amdgcn_s_setprio(0); } while (0)
; #define PG8_WAIT_L(n) asm volatile("s_waitcnt lgkmcnt(" #n ")" ::: "memory")
; #define PG8_BAR __builtin_amdgcn_s_barrier()
; template <class Epi>
; __device__ __forceinline__ void gemm_phase(LAS unsigned char* lds, const Gemm g, const StaticOrder& S, const Epi& E) {
;     ...
;             PG8_BAR; PG8_WAIT_L(0); PG8_MMA(0, 1, At, B1); PG8_BAR;
	v_mfma_f32_16x16x32_bf16 v[116:119], v[204:207], v[170:173], v[116:119]
	v_mfma_f32_16x16x32_bf16 v[112:115], v[212:215], v[170:173], v[112:115]
	v_mfma_f32_16x16x32_bf16 v[100:103], v[204:207], v[180:183], v[100:103]
	v_mfma_f32_16x16x32_bf16 v[96:99], v[212:215], v[180:183], v[96:99]
	v_mfma_f32_16x16x32_bf16 v[84:87], v[204:207], v[188:191], v[84:87]
	v_mfma_f32_16x16x32_bf16 v[80:83], v[212:215], v[188:191], v[80:83]
	v_mfma_f32_16x16x32_bf16 v[68:71], v[204:207], v[196:199], v[68:71]
	v_mfma_f32_16x16x32_bf16 v[64:67], v[212:215], v[196:199], v[64:67]
	v_mfma_f32_16x16x32_bf16 v[116:119], v[208:211], v[174:177], v[116:119]
	v_mfma_f32_16x16x32_bf16 v[112:115], v[216:219], v[174:177], v[112:115]
	v_mfma_f32_16x16x32_bf16 v[100:103], v[208:211], v[184:187], v[100:103]
	v_mfma_f32_16x16x32_bf16 v[96:99], v[216:219], v[184:187], v[96:99]
	v_mfma_f32_16x16x32_bf16 v[84:87], v[208:211], v[192:195], v[84:87]
	v_mfma_f32_16x16x32_bf16 v[80:83], v[216:219], v[192:195], v[80:83]
	v_mfma_f32_16x16x32_bf16 v[68:71], v[208:211], v[200:203], v[68:71]
	v_mfma_f32_16x16x32_bf16 v[64:67], v[216:219], v[200:203], v[64:67]
	s_barrier
	s_setprio 0
	s_mov_b32 m0, s21
	v_lshl_add_u64 v[222:223], s[30:31], 0, v[136:137]


; #define PG8_STAGE(bufoff, gbase, voff) do { _Pragma("unroll") for (int _i = 0; _i < 2; ++_i) \
;         __builtin_amdgcn_global_load_lds((const unsigned*)((const char*)(gbase) + (voff)[_i]), (LAS unsigned*)(lds + (bufoff) + ldsw + _i * 8192), 16, 0, 0); } while (0)
; #define PG8_LDA(dst, b, h) do { _Pragma("unroll") for (int m = 0; m < 4; ++m) _Pragma("unroll") for (int k = 0; k < 2; ++k) dst[m][k] = *(const LAS bf16x8*)(lds + PG8_SA(b, h) + aoff + m * 2048 + k * 1024); } while (0)
; #define PG8_MMA(ai, bj, At, Bt) do { __builtin_amdgcn_s_setprio(1); _Pragma("unroll") for (int m = 0; m < 4; ++m) _Pragma("unroll") for (int n = 0; n < 2; ++n) _Pragma("unroll") for (int k = 0; k < 2; ++k) \
;         acc[ai][bj][m][n] = __builtin_amdgcn_mfma_f32_16x16x32_bf16(Bt[n][k], At[m][k], acc[ai][bj][m][n], 0, 0, 0); __builtin_amdgcn_s_setprio(0); } while (0)
; #define PG8_WAIT_L(n) asm volatile("s_waitcnt lgkmcnt(" #n ")" ::: "memory")
; #define PG8_BAR __builtin_amdgcn_s_barrier()
; #define PG8_SCHED __builtin_amdgcn_sched_barrier(0)
; template <class Epi>
; __device__ __forceinline__ void gemm_phase(LAS unsigned char* lds, const Gemm g, const StaticOrder& S, const Epi& E) {
;     ...
;             PG8_LDA(At, 0, 1); PG8_STAGE(PG8_SA(0, 0), a2, voffA);
;             PG8_BAR; PG8_WAIT_L(0); PG8_MMA(1, 0, At, B0); PG8_BAR; PG8_SCHED;
	ds_read_b128 v[170:173], v162 offset:16384
	ds_read_b128 v[174:177], v162 offset:17408
	ds_read_b128 v[180:183], v162 offset:18432
	ds_read_b128 v[184:187], v162 offset:19456
	ds_read_b128 v[188:191], v162 offset:20480
	ds_read_b128 v[192:195], v162 offset:21504
	ds_read_b128 v[196:199], v162 offset:22528
	ds_read_b128 v[200:203], v162 offset:23552
	global_load_lds_dwordx4 v[222:223], off
	v_lshl_add_u64 v[224:225], s[30:31], 0, v[140:141]
	s_mov_b32 m0, s39
	s_nop 0
	global_load_lds_dwordx4 v[224:225], off
	s_waitcnt lgkmcnt(0)
	s_setprio 1
	s_barrier


; #define PG8_STAGE(bufoff, gbase, voff) do { _Pragma("unroll") for (int _i = 0; _i < 2; ++_i) \
;         __builtin_amdgcn_global_load_lds((const unsigned*)((const char*)(gbase) + (voff)[_i]), (LAS unsigned*)(lds + (bufoff) + ldsw + _i * 8192), 16, 0, 0); } while (0)
; #define PG8_MMA(ai, bj, At, Bt) do { __builtin_amdgcn_s_setprio(1); _Pragma("unroll") for (int m = 0; m < 4; ++m) _Pragma("unroll") for (int n = 0; n < 2; ++n) _Pragma("unroll") for (int k = 0; k < 2; ++k) \
;         acc[ai][bj][m][n] = __builtin_amdgcn_mfma_f32_16x16x32_bf16(Bt[n][k], At[m][k], acc[ai][bj][m][n], 0, 0, 0); __builtin_amdgcn_s_setprio(0); } while (0)
; #define PG8_WAIT_L(n) asm volatile("s_waitcnt lgkmcnt(" #n ")" ::: "memory")
; #define PG8_BAR __builtin_amdgcn_s_barrier()
; #define PG8_SCHED __builtin_amdgcn_sched_barrier(0)
; template <class Epi>
; __device__ __forceinline__ void gemm_phase(LAS unsigned char* lds, const Gemm g, const StaticOrder& S, const Epi& E) {
;     ...
;             PG8_BAR; PG8_WAIT_L(0); PG8_MMA(1, 0, At, B0); PG8_BAR; PG8_SCHED;
;             PG8_STAGE(PG8_SB(0, 1), b2 + hstep, voffB);
	v_mfma_f32_16x16x32_bf16 v[60:63], v[128:131], v[170:173], v[60:63]
	v_mfma_f32_16x16x32_bf16 v[56:59], v[152:155], v[170:173], v[56:59]
	v_mfma_f32_16x16x32_bf16 v[44:47], v[128:131], v[180:183], v[44:47]
	v_mfma_f32_16x16x32_bf16 v[40:43], v[152:155], v[180:183], v[40:43]
	v_mfma_f32_16x16x32_bf16 v[28:31], v[128:131], v[188:191], v[28:31]
	v_mfma_f32_16x16x32_bf16 v[24:27], v[152:155], v[188:191], v[24:27]
	v_mfma_f32_16x16x32_bf16 v[12:15], v[128:131], v[196:199], v[12:15]
	v_mfma_f32_16x16x32_bf16 v[8:11], v[152:155], v[196:199], v[8:11]
	v_mfma_f32_16x16x32_bf16 v[60:63], v[132:135], v[174:177], v[60:63]
	v_mfma_f32_16x16x32_bf16 v[56:59], v[166:169], v[174:177], v[56:59]
	v_mfma_f32_16x16x32_bf16 v[44:47], v[132:135], v[184:187], v[44:47]
	v_mfma_f32_16x16x32_bf16 v[40:43], v[166:169], v[184:187], v[40:43]
	v_mfma_f32_16x16x32_bf16 v[28:31], v[132:135], v[192:195], v[28:31]
	v_mfma_f32_16x16x32_bf16 v[24:27], v[166:169], v[192:195], v[24:27]
	v_mfma_f32_16x16x32_bf16 v[12:15], v[132:135], v[200:203], v[12:15]
	v_mfma_f32_16x16x32_bf16 v[8:11], v[166:169], v[200:203], v[8:11]
	s_barrier
	s_setprio 0

; #define PG8_STAGE(bufoff, gbase, voff) do { _Pragma("unroll") for (int _i = 0; _i < 2; ++_i) \
;         __builtin_amdgcn_global_load_lds((const unsigned*)((const char*)(gbase) + (voff)[_i]), (LAS unsigned*)(lds + (bufoff) + ldsw + _i * 8192), 16, 0, 0); } while (0)
; #define PG8_MMA(ai, bj, At, Bt) do { __builtin_amdgcn_s_setprio(1); _Pragma("unroll") for (int m = 0; m < 4; ++m) _Pragma("unroll") for (int n = 0; n < 2; ++n) _Pragma("unroll") for (int k = 0; k < 2; ++k) \
;         acc[ai][bj][m][n] = __builtin_amdgcn_mfma_f32_16x16x32_bf16(Bt[n][k], At[m][k], acc[ai][bj][m][n], 0, 0, 0); __builtin_amdgcn_s_setprio(0); } while (0)
; #define PG8_WAIT_V(n) asm volatile("s_waitcnt vmcnt(" #n ")" ::: "memory")
; #define PG8_BAR __builtin_amdgcn_s_barrier()
; template <class Epi>
; __device__ __forceinline__ void gemm_phase(LAS unsigned char* lds, const Gemm g, const StaticOrder& S, const Epi& E) {
;     ...
;             PG8_STAGE(PG8_SB(0, 1), b2 + hstep, voffB);
;             PG8_WAIT_V(6); PG8_BAR; PG8_MMA(1, 1, At, B1); PG8_BAR;
	s_add_u32 s62, s24, 0x80000
	s_addc_u32 s63, s25, 0
	s_add_i32 s64, s57, s38
	v_lshl_add_u64 v[128:129], s[62:63], 0, v[138:139]
	s_mov_b32 m0, s64
	s_nop 0
	global_load_lds_dwordx4 v[128:129], off
	v_lshl_add_u64 v[128:129], s[62:63], 0, v[142:143]
	s_add_i32 m0, s64, 0x2000
	s_nop 0
	global_load_lds_dwordx4 v[128:129], off
	s_waitcnt vmcnt(6)
	s_setprio 1
	s_barrier

; #define PG8_STAGE(bufoff, gbase, voff) do { _Pragma("unroll") for (int _i = 0; _i < 2; ++_i) \
;         __builtin_amdgcn_global_load_lds((const unsigned*)((const char*)(gbase) + (voff)[_i]), (LAS unsigned*)(lds + (bufoff) + ldsw + _i * 8192), 16, 0, 0); } while (0)
; #define PG8_LDA(dst, b, h) do { _Pragma("unroll") for (int m = 0; m < 4; ++m) _Pragma("unroll") for (int k = 0; k < 2; ++k) dst[m][k] = *(const LAS bf16x8*)(lds + PG8_SA(b, h) + aoff + m * 2048 + k * 1024); } while (0)
; #define PG8_LDB(dst, b, h) do { _Pragma("unroll") for (int n = 0; n < 2; ++n) _Pragma("unroll") for (int k = 0; k < 2; ++k) dst[n][k] = *(const LAS bf16x8*)(lds + PG8_SB(b, h) + boff + n * 2048 + k * 1024); } while (0)
; #define PG8_MMA(ai, bj, At, Bt) do { __builtin_amdgcn_s_setprio(1); _Pragma("unroll") for (int m = 0; m < 4; ++m) _Pragma("unroll") for (int n = 0; n < 2; ++n) _Pragma("unroll") for (int k = 0; k < 2; ++k) \
;         acc[ai][bj][m][n] = __builtin_amdgcn_mfma_f32_16x16x32_bf16(Bt[n][k], At[m][k], acc[ai][bj][m][n], 0, 0, 0); __builtin_amdgcn_s_setprio(0); } while (0)
; #define PG8_WAIT_V(n) asm volatile("s_waitcnt vmcnt(" #n ")" ::: "memory")
; #define PG8_BAR __builtin_amdgcn_s_barrier()
; #define PG8_SCHED __builtin_amdgcn_sched_barrier(0)
; template <class Epi>
; __device__ __forceinline__ void gemm_phase(LAS unsigned char* lds, const Gemm g, const StaticOrder& S, const Epi& E) {
;     ...
;             PG8_WAIT_V(6); PG8_BAR; PG8_MMA(1, 1, At, B1); PG8_BAR;
;             PG8_LDB(B0, 1, 0); PG8_SCHED; PG8_LDA(At, 1, 0); PG8_STAGE(PG8_SA(0, 1), a2 + hstep, voffA);
	v_mfma_f32_16x16x32_bf16 v[52:55], v[204:207], v[170:173], v[52:55]
	v_mfma_f32_16x16x32_bf16 v[48:51], v[212:215], v[170:173], v[48:51]
	v_mfma_f32_16x16x32_bf16 v[36:39], v[204:207], v[180:183], v[36:39]
	v_mfma_f32_16x16x32_bf16 v[32:35], v[212:215], v[180:183], v[32:35]
	v_mfma_f32_16x16x32_bf16 v[20:23], v[204:207], v[188:191], v[20:23]
	v_mfma_f32_16x16x32_bf16 v[16:19], v[212:215], v[188:191], v[16:19]
	v_mfma_f32_16x16x32_bf16 v[4:7], v[204:207], v[196:199], v[4:7]
	v_mfma_f32_16x16x32_bf16 v[0:3], v[212:215], v[196:199], v[0:3]
	v_mfma_f32_16x16x32_bf16 v[52:55], v[208:211], v[174:177], v[52:55]
	v_mfma_f32_16x16x32_bf16 v[48:51], v[216:219], v[174:177], v[48:51]
	v_mfma_f32_16x16x32_bf16 v[36:39], v[208:211], v[184:187], v[36:39]
	v_mfma_f32_16x16x32_bf16 v[32:35], v[216:219], v[184:187], v[32:35]
	v_mfma_f32_16x16x32_bf16 v[20:23], v[208:211], v[192:195], v[20:23]
	v_mfma_f32_16x16x32_bf16 v[16:19], v[216:219], v[192:195], v[16:19]
	v_mfma_f32_16x16x32_bf16 v[4:7], v[208:211], v[200:203], v[4:7]
	v_mfma_f32_16x16x32_bf16 v[0:3], v[216:219], v[200:203], v[0:3]
	s_barrier
	s_setprio 0
	s_add_i32 s62, 0, 0x18000
	v_add_u32_e32 v165, s62, v158


; #define PG8_STAGE(bufoff, gbase, voff) do { _Pragma("unroll") for (int _i = 0; _i < 2; ++_i) \
;         __builtin_amdgcn_global_load_lds((const unsigned*)((const char*)(gbase) + (voff)[_i]), (LAS unsigned*)(lds + (bufoff) + ldsw + _i * 8192), 16, 0, 0); } while (0)
; #define PG8_LDA(dst, b, h) do { _Pragma("unroll") for (int m = 0; m < 4; ++m) _Pragma("unroll") for (int k = 0; k < 2; ++k) dst[m][k] = *(const LAS bf16x8*)(lds + PG8_SA(b, h) + aoff + m * 2048 + k * 1024); } while (0)
; #define PG8_LDB(dst, b, h) do { _Pragma("unroll") for (int n = 0; n < 2; ++n) _Pragma("unroll") for (int k = 0; k < 2; ++k) dst[n][k] = *(const LAS bf16x8*)(lds + PG8_SB(b, h) + boff + n * 2048 + k * 1024); } while (0)
; #define PG8_MMA(ai, bj, At, Bt) do { __builtin_amdgcn_s_setprio(1); _Pragma("unroll") for (int m = 0; m < 4; ++m) _Pragma("unroll") for (int n = 0; n < 2; ++n) _Pragma("unroll") for (int k = 0; k < 2; ++k) \
;         acc[ai][bj][m][n] = __builtin_amdgcn_mfma_f32_16x16x32_bf16(Bt[n][k], At[m][k], acc[ai][bj][m][n], 0, 0, 0); __builtin_amdgcn_s_setprio(0); } while (0)
; #define PG8_WAIT_L(n) asm volatile("s_waitcnt lgkmcnt(" #n ")" ::: "memory")
; #define PG8_BAR __builtin_amdgcn_s_barrier()
; #define PG8_SCHED __builtin_amdgcn_sched_barrier(0)
; template <class Epi>
; __device__ __forceinline__ void gemm_phase(LAS unsigned char* lds, const Gemm g, const StaticOrder& S, const Epi& E) {
;     ...
;             PG8_LDB(B0, 1, 0); PG8_SCHED; PG8_LDA(At, 1, 0); PG8_STAGE(PG8_SA(0, 1), a2 + hstep, voffA);
;             PG8_WAIT_L(8); PG8_BAR; PG8_WAIT_L(0); PG8_MMA(0, 0, At, B0); PG8_BAR; PG8_SCHED;
	ds_read_b128 v[128:131], v165
	ds_read_b128 v[132:135], v165 offset:1024
	ds_read_b128 v[152:155], v165 offset:2048
	ds_read_b128 v[166:169], v165 offset:3072
	s_add_u32 s30, s30, 0x80000
	s_addc_u32 s31, s31, 0
	s_mov_b32 m0, s40
	v_lshl_add_u64 v[204:205], s[30:31], 0, v[136:137]
	ds_read_b128 v[170:173], v162 offset:32768
	ds_read_b128 v[174:177], v162 offset:33792
	ds_read_b128 v[180:183], v162 offset:34816
	ds_read_b128 v[184:187], v162 offset:35840
	ds_read_b128 v[188:191], v162 offset:36864
	ds_read_b128 v[192:195], v162 offset:37888
	ds_read_b128 v[196:199], v162 offset:38912
	ds_read_b128 v[200:203], v162 offset:39936
	global_load_lds_dwordx4 v[204:205], off
	v_lshl_add_u64 v[204:205], s[30:31], 0, v[140:141]
	s_mov_b32 m0, s41
	s_nop 0
	global_load_lds_dwordx4 v[204:205], off
	s_waitcnt lgkmcnt(8)
	s_setprio 1
	s_barrier
	s_waitcnt lgkmcnt(0)


; #define PG8_MMA(ai, bj, At, Bt) do { __builtin_amdgcn_s_setprio(1); _Pragma("unroll") for (int m = 0; m < 4; ++m) _Pragma("unroll") for (int n = 0; n < 2; ++n) _Pragma("unroll") for (int k = 0; k < 2; ++k) \
;         acc[ai][bj][m][n] = __builtin_amdgcn_mfma_f32_16x16x32_bf16(Bt[n][k], At[m][k], acc[ai][bj][m][n], 0, 0, 0); __builtin_amdgcn_s_setprio(0); } while (0)
; #define PG8_WAIT_L(n) asm volatile("s_waitcnt lgkmcnt(" #n ")" ::: "memory")
; #define PG8_BAR __builtin_amdgcn_s_barrier()
; #define PG8_SCHED __builtin_amdgcn_sched_barrier(0)
; template <class Epi>
; __device__ __forceinline__ void gemm_phase(LAS unsigned char* lds, const Gemm g, const StaticOrder& S, const Epi& E) {
;     ...
;             PG8_WAIT_L(8); PG8_BAR; PG8_WAIT_L(0); PG8_MMA(0, 0, At, B0); PG8_BAR; PG8_SCHED;
	v_mfma_f32_16x16x32_bf16 v[124:127], v[128:131], v[170:173], v[124:127]
	v_mfma_f32_16x16x32_bf16 v[120:123], v[152:155], v[170:173], v[120:123]
	v_mfma_f32_16x16x32_bf16 v[108:111], v[128:131], v[180:183], v[108:111]
	v_mfma_f32_16x16x32_bf16 v[104:107], v[152:155], v[180:183], v[104:107]
	v_mfma_f32_16x16x32_bf16 v[92:95], v[128:131], v[188:191], v[92:95]
	v_mfma_f32_16x16x32_bf16 v[88:91], v[152:155], v[188:191], v[88:91]
	v_mfma_f32_16x16x32_bf16 v[76:79], v[128:131], v[196:199], v[76:79]
	v_mfma_f32_16x16x32_bf16 v[72:75], v[152:155], v[196:199], v[72:75]
	v_mfma_f32_16x16x32_bf16 v[124:127], v[132:135], v[174:177], v[124:127]
	v_mfma_f32_16x16x32_bf16 v[120:123], v[166:169], v[174:177], v[120:123]
	v_mfma_f32_16x16x32_bf16 v[108:111], v[132:135], v[184:187], v[108:111]
	v_mfma_f32_16x16x32_bf16 v[104:107], v[166:169], v[184:187], v[104:107]
	v_mfma_f32_16x16x32_bf16 v[92:95], v[132:135], v[192:195], v[92:95]
	v_mfma_f32_16x16x32_bf16 v[88:91], v[166:169], v[192:195], v[88:91]
	v_mfma_f32_16x16x32_bf16 v[76:79], v[132:135], v[200:203], v[76:79]
	v_mfma_f32_16x16x32_bf16 v[72:75], v[166:169], v[200:203], v[72:75]
	s_barrier
	s_setprio 0

; #define PG8_STAGE(bufoff, gbase, voff) do { _Pragma("unroll") for (int _i = 0; _i < 2; ++_i) \
;         __builtin_amdgcn_global_load_lds((const unsigned*)((const char*)(gbase) + (voff)[_i]), (LAS unsigned*)(lds + (bufoff) + ldsw + _i * 8192), 16, 0, 0); } while (0)
; #define PG8_LDB(dst, b, h) do { _Pragma("unroll") for (int n = 0; n < 2; ++n) _Pragma("unroll") for (int k = 0; k < 2; ++k) dst[n][k] = *(const LAS bf16x8*)(lds + PG8_SB(b, h) + boff + n * 2048 + k * 1024); } while (0)
; #define PG8_MMA(ai, bj, At, Bt) do { __builtin_amdgcn_s_setprio(1); _Pragma("unroll") for (int m = 0; m < 4; ++m) _Pragma("unroll") for (int n = 0; n < 2; ++n) _Pragma("unroll") for (int k = 0; k < 2; ++k) \
;         acc[ai][bj][m][n] = __builtin_amdgcn_mfma_f32_16x16x32_bf16(Bt[n][k], At[m][k], acc[ai][bj][m][n], 0, 0, 0); __builtin_amdgcn_s_setprio(0); } while (0)
; #define PG8_WAIT_L(n) asm volatile("s_waitcnt lgkmcnt(" #n ")" ::: "memory")
; #define PG8_BAR __builtin_amdgcn_s_barrier()
; template <class Epi>
; __device__ __forceinline__ void gemm_phase(LAS unsigned char* lds, const Gemm g, const StaticOrder& S, const Epi& E) {
;     ...
;             PG8_LDB(B1, 1, 1); PG8_STAGE(PG8_SB(1, 0), b3, voffB);
;             PG8_BAR; PG8_WAIT_L(0); PG8_MMA(0, 1, At, B1); PG8_BAR;
	s_add_i32 s30, 0, 0x1c000
	s_add_i32 s31, s62, s38
	v_add_u32_e32 v165, s30, v158
	v_lshl_add_u64 v[156:157], v[156:157], 0, s[8:9]
	s_mov_b32 m0, s31
	ds_read_b128 v[204:207], v165
	ds_read_b128 v[208:211], v165 offset:1024
	ds_read_b128 v[212:215], v165 offset:2048
	ds_read_b128 v[216:219], v165 offset:3072
	global_load_lds_dwordx4 v[156:157], off
	v_lshl_add_u64 v[156:157], v[220:221], 0, s[8:9]
	s_add_i32 m0, s31, 0x2000
	s_nop 0
	global_load_lds_dwordx4 v[156:157], off
	s_waitcnt lgkmcnt(0)
	s_setprio 1
	s_barrier


; #define PG8_STAGE(bufoff, gbase, voff) do { _Pragma("unroll") for (int _i = 0; _i < 2; ++_i) \
;         __builtin_amdgcn_global_load_lds((const unsigned*)((const char*)(gbase) + (voff)[_i]), (LAS unsigned*)(lds + (bufoff) + ldsw + _i * 8192), 16, 0, 0); } while (0)
; #define PG8_LDA(dst, b, h) do { _Pragma("unroll") for (int m = 0; m < 4; ++m) _Pragma("unroll") for (int k = 0; k < 2; ++k) dst[m][k] = *(const LAS bf16x8*)(lds + PG8_SA(b, h) + aoff + m * 2048 + k * 1024); } while (0)
; #define PG8_MMA(ai, bj, At, Bt) do { __builtin_amdgcn_s_setprio(1); _Pragma("unroll") for (int m = 0; m < 4; ++m) _Pragma("unroll") for (int n = 0; n < 2; ++n) _Pragma("unroll") for (int k = 0; k < 2; ++k) \
;         acc[ai][bj][m][n] = __builtin_amdgcn_mfma_f32_16x16x32_bf16(Bt[n][k], At[m][k], acc[ai][bj][m][n], 0, 0, 0); __builtin_amdgcn_s_setprio(0); } while (0)
; #define PG8_WAIT_L(n) asm volatile("s_waitcnt lgkmcnt(" #n ")" ::: "memory")
; #define PG8_BAR __builtin_amdgcn_s_barrier()
; template <class Epi>
; __device__ __forceinline__ void gemm_phase(LAS unsigned char* lds, const Gemm g, const StaticOrder& S, const Epi& E) {
;     ...
;             PG8_BAR; PG8_WAIT_L(0); PG8_MMA(0, 1, At, B1); PG8_BAR;
;             PG8_LDA(At, 1, 1); PG8_STAGE(PG8_SA(1, 0), a3, voffA);
	v_mfma_f32_16x16x32_bf16 v[116:119], v[204:207], v[170:173], v[116:119]
	v_mfma_f32_16x16x32_bf16 v[112:115], v[212:215], v[170:173], v[112:115]
	v_mfma_f32_16x16x32_bf16 v[100:103], v[204:207], v[180:183], v[100:103]
	v_mfma_f32_16x16x32_bf16 v[96:99], v[212:215], v[180:183], v[96:99]
	v_mfma_f32_16x16x32_bf16 v[84:87], v[204:207], v[188:191], v[84:87]
	v_mfma_f32_16x16x32_bf16 v[80:83], v[212:215], v[188:191], v[80:83]
	v_mfma_f32_16x16x32_bf16 v[68:71], v[204:207], v[196:199], v[68:71]
	v_mfma_f32_16x16x32_bf16 v[64:67], v[212:215], v[196:199], v[64:67]
	v_mfma_f32_16x16x32_bf16 v[116:119], v[208:211], v[174:177], v[116:119]
	v_mfma_f32_16x16x32_bf16 v[112:115], v[216:219], v[174:177], v[112:115]
	v_mfma_f32_16x16x32_bf16 v[100:103], v[208:211], v[184:187], v[100:103]
	v_mfma_f32_16x16x32_bf16 v[96:99], v[216:219], v[184:187], v[96:99]
	v_mfma_f32_16x16x32_bf16 v[84:87], v[208:211], v[192:195], v[84:87]
	v_mfma_f32_16x16x32_bf16 v[80:83], v[216:219], v[192:195], v[80:83]
	v_mfma_f32_16x16x32_bf16 v[68:71], v[208:211], v[200:203], v[68:71]
	v_mfma_f32_16x16x32_bf16 v[64:67], v[216:219], v[200:203], v[64:67]
	s_barrier
	s_setprio 0
	s_mov_b32 m0, s43
	v_lshl_add_u64 v[156:157], v[222:223], 0, s[8:9]


; #define PG8_STAGE(bufoff, gbase, voff) do { _Pragma("unroll") for (int _i = 0; _i < 2; ++_i) \
;         __builtin_amdgcn_global_load_lds((const unsigned*)((const char*)(gbase) + (voff)[_i]), (LAS unsigned*)(lds + (bufoff) + ldsw + _i * 8192), 16, 0, 0); } while (0)
; #define PG8_LDA(dst, b, h) do { _Pragma("unroll") for (int m = 0; m < 4; ++m) _Pragma("unroll") for (int k = 0; k < 2; ++k) dst[m][k] = *(const LAS bf16x8*)(lds + PG8_SA(b, h) + aoff + m * 2048 + k * 1024); } while (0)
; #define PG8_MMA(ai, bj, At, Bt) do { __builtin_amdgcn_s_setprio(1); _Pragma("unroll") for (int m = 0; m < 4; ++m) _Pragma("unroll") for (int n = 0; n < 2; ++n) _Pragma("unroll") for (int k = 0; k < 2; ++k) \
;         acc[ai][bj][m][n] = __builtin_amdgcn_mfma_f32_16x16x32_bf16(Bt[n][k], At[m][k], acc[ai][bj][m][n], 0, 0, 0); __builtin_amdgcn_s_setprio(0); } while (0)
; #define PG8_WAIT_L(n) asm volatile("s_waitcnt lgkmcnt(" #n ")" ::: "memory")
; #define PG8_BAR __builtin_amdgcn_s_barrier()
; #define PG8_SCHED __builtin_amdgcn_sched_barrier(0)
; template <class Epi>
; __device__ __forceinline__ void gemm_phase(LAS unsigned char* lds, const Gemm g, const StaticOrder& S, const Epi& E) {
;     ...
;             PG8_LDA(At, 1, 1); PG8_STAGE(PG8_SA(1, 0), a3, voffA);
;             PG8_BAR; PG8_WAIT_L(0); PG8_MMA(1, 0, At, B0); PG8_BAR; PG8_SCHED;
	ds_read_b128 v[170:173], v162 offset:49152
	ds_read_b128 v[174:177], v162 offset:50176
	ds_read_b128 v[180:183], v162 offset:51200
	ds_read_b128 v[184:187], v162 offset:52224
	ds_read_b128 v[188:191], v162 offset:53248
	ds_read_b128 v[192:195], v162 offset:54272
	ds_read_b128 v[196:199], v162 offset:55296
	ds_read_b128 v[200:203], v162 offset:56320
	global_load_lds_dwordx4 v[156:157], off
	v_lshl_add_u64 v[156:157], v[224:225], 0, s[8:9]
	s_mov_b32 m0, s44
	s_nop 0
	global_load_lds_dwordx4 v[156:157], off
	s_waitcnt lgkmcnt(0)
	s_setprio 1
	s_barrier


; #define PG8_MMA(ai, bj, At, Bt) do { __builtin_amdgcn_s_setprio(1); _Pragma("unroll") for (int m = 0; m < 4; ++m) _Pragma("unroll") for (int n = 0; n < 2; ++n) _Pragma("unroll") for (int k = 0; k < 2; ++k) \
;         acc[ai][bj][m][n] = __builtin_amdgcn_mfma_f32_16x16x32_bf16(Bt[n][k], At[m][k], acc[ai][bj][m][n], 0, 0, 0); __builtin_amdgcn_s_setprio(0); } while (0)
; #define PG8_WAIT_L(n) asm volatile("s_waitcnt lgkmcnt(" #n ")" ::: "memory")
; #define PG8_BAR __builtin_amdgcn_s_barrier()
; #define PG8_SCHED __builtin_amdgcn_sched_barrier(0)
; template <class Epi>
; __device__ __forceinline__ void gemm_phase(LAS unsigned char* lds, const Gemm g, const StaticOrder& S, const Epi& E) {
;     ...
;             PG8_BAR; PG8_WAIT_L(0); PG8_MMA(1, 0, At, B0); PG8_BAR; PG8_SCHED;
	v_mfma_f32_16x16x32_bf16 v[60:63], v[128:131], v[170:173], v[60:63]
	v_mfma_f32_16x16x32_bf16 v[56:59], v[152:155], v[170:173], v[56:59]
	v_mfma_f32_16x16x32_bf16 v[44:47], v[128:131], v[180:183], v[44:47]
	v_mfma_f32_16x16x32_bf16 v[40:43], v[152:155], v[180:183], v[40:43]
	v_mfma_f32_16x16x32_bf16 v[28:31], v[128:131], v[188:191], v[28:31]
	v_mfma_f32_16x16x32_bf16 v[24:27], v[152:155], v[188:191], v[24:27]
	v_mfma_f32_16x16x32_bf16 v[12:15], v[128:131], v[196:199], v[12:15]
	v_mfma_f32_16x16x32_bf16 v[8:11], v[152:155], v[196:199], v[8:11]
	v_mfma_f32_16x16x32_bf16 v[60:63], v[132:135], v[174:177], v[60:63]
	v_mfma_f32_16x16x32_bf16 v[56:59], v[166:169], v[174:177], v[56:59]
	v_mfma_f32_16x16x32_bf16 v[44:47], v[132:135], v[184:187], v[44:47]
	v_mfma_f32_16x16x32_bf16 v[40:43], v[166:169], v[184:187], v[40:43]
	v_mfma_f32_16x16x32_bf16 v[28:31], v[132:135], v[192:195], v[28:31]
	v_mfma_f32_16x16x32_bf16 v[24:27], v[166:169], v[192:195], v[24:27]
	v_mfma_f32_16x16x32_bf16 v[12:15], v[132:135], v[200:203], v[12:15]
	v_mfma_f32_16x16x32_bf16 v[8:11], v[166:169], v[200:203], v[8:11]
	s_barrier
	s_setprio 0

; #define PG8_STAGE(bufoff, gbase, voff) do { _Pragma("unroll") for (int _i = 0; _i < 2; ++_i) \
;         __builtin_amdgcn_global_load_lds((const unsigned*)((const char*)(gbase) + (voff)[_i]), (LAS unsigned*)(lds + (bufoff) + ldsw + _i * 8192), 16, 0, 0); } while (0)
; #define PG8_MMA(ai, bj, At, Bt) do { __builtin_amdgcn_s_setprio(1); _Pragma("unroll") for (int m = 0; m < 4; ++m) _Pragma("unroll") for (int n = 0; n < 2; ++n) _Pragma("unroll") for (int k = 0; k < 2; ++k) \
;         acc[ai][bj][m][n] = __builtin_amdgcn_mfma_f32_16x16x32_bf16(Bt[n][k], At[m][k], acc[ai][bj][m][n], 0, 0, 0); __builtin_amdgcn_s_setprio(0); } while (0)
; #define PG8_WAIT_V(n) asm volatile("s_waitcnt vmcnt(" #n ")" ::: "memory")
; #define PG8_BAR __builtin_amdgcn_s_barrier()
; template <class Epi>
; __device__ __forceinline__ void gemm_phase(LAS unsigned char* lds, const Gemm g, const StaticOrder& S, const Epi& E) {
;     ...
;             PG8_STAGE(PG8_SB(1, 1), b3 + hstep, voffB);
;             PG8_WAIT_V(6); PG8_BAR; PG8_MMA(1, 1, At, B1); PG8_BAR;
	s_add_u32 s24, s24, 0x80080
	s_addc_u32 s25, s25, 0
	s_add_i32 s30, s30, s38
	v_lshl_add_u64 v[128:129], s[24:25], 0, v[138:139]
	s_mov_b32 m0, s30
	s_nop 0
	global_load_lds_dwordx4 v[128:129], off
	v_lshl_add_u64 v[128:129], s[24:25], 0, v[142:143]
	s_add_i32 m0, s30, 0x2000
	s_nop 0
	global_load_lds_dwordx4 v[128:129], off
	s_waitcnt vmcnt(6)
	s_setprio 1
	s_barrier

; #define PG8_MMA(ai, bj, At, Bt) do { __builtin_amdgcn_s_setprio(1); _Pragma("unroll") for (int m = 0; m < 4; ++m) _Pragma("unroll") for (int n = 0; n < 2; ++n) _Pragma("unroll") for (int k = 0; k < 2; ++k) \
;         acc[ai][bj][m][n] = __builtin_amdgcn_mfma_f32_16x16x32_bf16(Bt[n][k], At[m][k], acc[ai][bj][m][n], 0, 0, 0); __builtin_amdgcn_s_setprio(0); } while (0)
; #define PG8_WAIT_V(n) asm volatile("s_waitcnt vmcnt(" #n ")" ::: "memory")
; #define PG8_BAR __builtin_amdgcn_s_barrier()
; template <class Epi>
; __device__ __forceinline__ void gemm_phase(LAS unsigned char* lds, const Gemm g, const StaticOrder& S, const Epi& E) {
;     ...
;             PG8_WAIT_V(6); PG8_BAR; PG8_MMA(1, 1, At, B1); PG8_BAR;
;         }
	v_mfma_f32_16x16x32_bf16 v[52:55], v[204:207], v[170:173], v[52:55]
	v_mfma_f32_16x16x32_bf16 v[48:51], v[212:215], v[170:173], v[48:51]
	v_mfma_f32_16x16x32_bf16 v[36:39], v[204:207], v[180:183], v[36:39]
	v_mfma_f32_16x16x32_bf16 v[32:35], v[212:215], v[180:183], v[32:35]
	v_mfma_f32_16x16x32_bf16 v[20:23], v[204:207], v[188:191], v[20:23]
	v_mfma_f32_16x16x32_bf16 v[16:19], v[212:215], v[188:191], v[16:19]
	v_mfma_f32_16x16x32_bf16 v[4:7], v[204:207], v[196:199], v[4:7]
	v_mfma_f32_16x16x32_bf16 v[0:3], v[212:215], v[196:199], v[0:3]
	v_mfma_f32_16x16x32_bf16 v[52:55], v[208:211], v[174:177], v[52:55]
	v_mfma_f32_16x16x32_bf16 v[48:51], v[216:219], v[174:177], v[48:51]
	v_mfma_f32_16x16x32_bf16 v[36:39], v[208:211], v[184:187], v[36:39]
	v_mfma_f32_16x16x32_bf16 v[32:35], v[216:219], v[184:187], v[32:35]
	v_mfma_f32_16x16x32_bf16 v[20:23], v[208:211], v[192:195], v[20:23]
	v_mfma_f32_16x16x32_bf16 v[16:19], v[216:219], v[192:195], v[16:19]
	v_mfma_f32_16x16x32_bf16 v[4:7], v[208:211], v[200:203], v[4:7]
	v_mfma_f32_16x16x32_bf16 v[0:3], v[216:219], v[200:203], v[0:3]
	s_barrier
	s_setprio 0
	s_add_i32 s61, s61, 2
	s_add_u32 s22, s22, 0x100
	s_addc_u32 s23, s23, 0
	s_add_u32 s59, s59, 0x100
	s_addc_u32 s60, s60, 0
	s_cmp_gt_u32 s61, 29


; __device__ __forceinline__ float bflo(unsigned w) { return __uint_as_float(w << 16); }
; __device__ __forceinline__ float bfhi(unsigned w) { return __uint_as_float(w & 0xffff0000u); }
; #define ER_LOAD(g_, set_) do { const size_t off_ = (size_t)(row0 + ((g_) >> 2) * HALF + ((g_) & 3) * 16) * DM + col0; \
;         hv[set_][0] = *(const u32x4*)(HB + off_); hv[set_][1] = *(const u32x4*)(HB + off_ + HALF); } while (0)
;     __device__ __forceinline__ void operator()(const f32x4 (&acc)[2][2][4][2], const Unit& u, int wr, int wc, int fr, int fq, const Pre&) const {
;         const int row0 = ROW_X + u.pm * BM + wr * 64 + fr, col0 = u.pn * BM + wc * 32 + 8 * fq;
;         u32x4 hv[2][2]; float sprev = 0.f;
;     ...
;         ER_LOAD(0, 0);
; #pragma unroll
;         for (int g = 0; g < 8; ++g) { const int ai = g >> 2, m = g & 3; const int r = row0 + ai * HALF + m * 16; const size_t off = (size_t)r * DM + col0; float s = 0.f;
;             if (g + 1 < 8) ER_LOAD(g + 1, (g + 1) & 1);
; #pragma unroll
;             for (int bj = 0; bj < 2; ++bj) { const u32x4 w = hv[g & 1][bj];
;                 const f32x4 h0 = {bflo(w.x), bfhi(w.x), bflo(w.y), bfhi(w.y)}, h1 = {bflo(w.z), bfhi(w.z), bflo(w.w), bfhi(w.w)};
;                 const f32x4 o0 = h0 + acc[ai][bj][m][0] * alpha, o1 = h1 + acc[ai][bj][m][1] * alpha;
;                 if (FINAL) { float* op = OUT + (size_t)(r - ROW_X) * DM + col0 + bj * HALF; *(f32x4*)op = o0; *(f32x4*)(op + 4) = o1; }
;                 else { u32x4 q; q.x = cvtpk(o0[0], o0[1]); q.y = cvtpk(o0[2], o0[3]); q.z = cvtpk(o1[0], o1[1]); q.w = cvtpk(o1[2], o1[3]); *(u32x4*)(HB + off + bj * HALF) = q;
;                        s += ((o0[0] * o0[0] + o0[1] * o0[1]) + (o0[2] * o0[2] + o0[3] * o0[3])) + ((o1[0] * o1[0] + o1[1] * o1[1]) + (o1[2] * o1[2] + o1[3] * o1[3])); } }
;             if (!FINAL) { if (g > 0) { float t = sprev; t += __shfl_xor(t, 16); t += __shfl_xor(t, 32);
;                     if (fq == 0) __hip_atomic_fetch_add(ssq_out + row0 + ((g - 1) >> 2) * HALF + ((g - 1) & 3) * 16, t, __ATOMIC_RELAXED, __HIP_MEMORY_SCOPE_AGENT); }
;                 sprev = s; } }
	s_cbranch_scc0 .LBB0_2460
	v_lshl_add_u32 v154, s18, 8, v159
	v_lshl_or_b32 v152, s20, 8, v160
	v_ashrrev_i32_e32 v155, 31, v154
	v_ashrrev_i32_e32 v153, 31, v152
	v_lshlrev_b64 v[128:129], 12, v[154:155]
	v_lshl_add_u64 v[128:129], s[0:1], 0, v[128:129]
	v_lshlrev_b64 v[130:131], 1, v[152:153]
	v_lshl_add_u64 v[184:185], v[128:129], 0, v[130:131]
	v_or_b32_e32 v128, 16, v154
	v_ashrrev_i32_e32 v129, 31, v128
	global_load_dwordx4 v[166:169], v[184:185], off
	global_load_dwordx4 v[170:173], v[184:185], off offset:256
	v_lshlrev_b64 v[128:129], 12, v[128:129]
	v_lshl_add_u64 v[128:129], s[0:1], 0, v[128:129]
	v_lshl_add_u64 v[186:187], v[128:129], 0, v[130:131]
	global_load_dwordx4 v[174:177], v[186:187], off
	global_load_dwordx4 v[180:183], v[186:187], off offset:256
	v_or_b32_e32 v128, 32, v154
	v_ashrrev_i32_e32 v129, 31, v128
	v_lshlrev_b64 v[128:129], 12, v[128:129]
	v_lshl_add_u64 v[128:129], s[0:1], 0, v[128:129]
	v_lshl_add_u64 v[156:157], v[128:129], 0, v[130:131]
	global_load_dwordx4 v[132:135], v[156:157], off
	global_load_dwordx4 v[128:131], v[156:157], off offset:256
	s_waitcnt vmcnt(0)
	v_lshlrev_b32_e32 v188, 16, v166
	v_and_b32_e32 v189, 0xffff0000, v166
	v_lshlrev_b32_e32 v166, 16, v167
	v_and_b32_e32 v167, 0xffff0000, v167
	v_lshlrev_b32_e32 v190, 16, v168
	v_and_b32_e32 v191, 0xffff0000, v168
	v_lshlrev_b32_e32 v168, 16, v169
	v_and_b32_e32 v169, 0xffff0000, v169
	v_lshlrev_b32_e32 v192, 16, v170
	v_and_b32_e32 v193, 0xffff0000, v170
	v_lshlrev_b32_e32 v170, 16, v171
	v_and_b32_e32 v171, 0xffff0000, v171
	v_lshlrev_b32_e32 v194, 16, v172
	v_and_b32_e32 v195, 0xffff0000, v172
	v_lshlrev_b32_e32 v172, 16, v173
	v_and_b32_e32 v173, 0xffff0000, v173
	v_pk_add_f32 v[126:127], v[126:127], v[166:167]
	v_pk_add_f32 v[124:125], v[124:125], v[188:189]
	v_pk_add_f32 v[122:123], v[122:123], v[168:169]
	v_pk_add_f32 v[166:167], v[120:121], v[190:191]
	v_pk_add_f32 v[168:169], v[118:119], v[170:171]
	v_pk_add_f32 v[170:171], v[116:117], v[192:193]
	v_pk_add_f32 v[172:173], v[114:115], v[172:173]
	v_pk_add_f32 v[188:189], v[112:113], v[194:195]
	v_cvt_pk_bf16_f32 v114, v124, v125
	v_cvt_pk_bf16_f32 v115, v126, v127
	v_cvt_pk_bf16_f32 v116, v166, v167
	v_cvt_pk_bf16_f32 v117, v122, v123
	v_mul_f32_e32 v125, v125, v125
	v_mul_f32_e32 v127, v127, v127
	v_mul_f32_e32 v165, v167, v167
	v_mul_f32_e32 v123, v123, v123
	v_cvt_pk_bf16_f32 v118, v170, v171
	v_cvt_pk_bf16_f32 v119, v168, v169
	v_cvt_pk_bf16_f32 v121, v172, v173
	v_mul_f32_e32 v167, v171, v171
	v_mul_f32_e32 v169, v169, v169
	v_mul_f32_e32 v171, v189, v189
	v_mul_f32_e32 v173, v173, v173
	v_lshlrev_b32_e32 v112, 16, v174
	v_and_b32_e32 v113, 0xffff0000, v174
	v_lshlrev_b32_e32 v190, 16, v176
	v_and_b32_e32 v191, 0xffff0000, v176
	v_lshlrev_b32_e32 v176, 16, v177
	v_and_b32_e32 v177, 0xffff0000, v177
	v_fmac_f32_e32 v125, v124, v124
	v_fmac_f32_e32 v127, v126, v126
	v_fmac_f32_e32 v165, v166, v166
	v_fmac_f32_e32 v123, v122, v122
	v_fmac_f32_e32 v167, v170, v170
	v_fmac_f32_e32 v169, v168, v168
	v_fmac_f32_e32 v171, v188, v188
	v_fmac_f32_e32 v173, v172, v172
	v_lshlrev_b32_e32 v174, 16, v175
	v_and_b32_e32 v175, 0xffff0000, v175
	v_pk_add_f32 v[112:113], v[108:109], v[112:113]
	v_pk_add_f32 v[108:109], v[106:107], v[176:177]
	global_store_dwordx4 v[184:185], v[114:117], off
	v_add_f32_e32 v106, v125, v127
	v_add_f32_e32 v107, v165, v123
	v_add_f32_e32 v114, v167, v169
	v_add_f32_e32 v115, v171, v173
	v_pk_add_f32 v[110:111], v[110:111], v[174:175]
	v_add_f32_e32 v106, v106, v107
	v_add_f32_e32 v107, v114, v115
	v_pk_add_f32 v[114:115], v[104:105], v[190:191]
	v_add_f32_e32 v125, v106, v107
	v_cvt_pk_bf16_f32 v104, v112, v113
	v_cvt_pk_bf16_f32 v105, v110, v111
	v_cvt_pk_bf16_f32 v106, v114, v115
	v_cvt_pk_bf16_f32 v107, v108, v109
	v_cvt_pk_bf16_f32 v120, v188, v189
	global_store_dwordx4 v[186:187], v[104:107], off
	global_store_dwordx4 v[184:185], v[118:121], off offset:256
	v_lshlrev_b32_e32 v122, 16, v182
	v_lshlrev_b32_e32 v104, 16, v180
	v_and_b32_e32 v105, 0xffff0000, v180
	v_pk_add_f32 v[118:119], v[100:101], v[104:105]
	v_and_b32_e32 v101, 64, v164
	v_xor_b32_e32 v100, 16, v164
	v_add_u32_e32 v101, 64, v101
	v_cmp_lt_i32_e32 vcc, v100, v101
	v_and_b32_e32 v123, 0xffff0000, v182
	v_pk_add_f32 v[122:123], v[96:97], v[122:123]
	v_cndmask_b32_e32 v100, v164, v100, vcc
	v_lshlrev_b32_e32 v124, 2, v100
	ds_bpermute_b32 v100, v124, v125
	v_xor_b32_e32 v97, 32, v164
	v_cmp_lt_i32_e32 vcc, v97, v101
	v_lshlrev_b32_e32 v106, 16, v181
	v_and_b32_e32 v107, 0xffff0000, v181
	v_cndmask_b32_e32 v97, v164, v97, vcc
	s_waitcnt lgkmcnt(0)
	v_add_f32_e32 v96, v125, v100
	v_lshlrev_b32_e32 v125, 2, v97
	ds_bpermute_b32 v97, v125, v96
	v_lshlrev_b32_e32 v120, 16, v183
	v_and_b32_e32 v121, 0xffff0000, v183
	v_pk_add_f32 v[116:117], v[102:103], v[106:107]
	v_pk_add_f32 v[120:121], v[98:99], v[120:121]
	v_cvt_pk_bf16_f32 v98, v118, v119
	v_cvt_pk_bf16_f32 v99, v116, v117
	v_cvt_pk_bf16_f32 v100, v122, v123
	v_cvt_pk_bf16_f32 v101, v120, v121
	v_lshl_add_u64 v[104:105], v[154:155], 2, s[6:7]
	global_store_dwordx4 v[186:187], v[98:101], off offset:256
	s_and_saveexec_b64 s[18:19], s[2:3]
	s_cbranch_execz .LBB0_2463
	s_waitcnt lgkmcnt(0)
	v_add_f32_e32 v96, v96, v97
	global_atomic_add_f32 v[104:105], v96, off

; #define PG8_STAGE(bufoff, gbase, voff) do { _Pragma("unroll") for (int _i = 0; _i < 2; ++_i) \
;         __builtin_amdgcn_global_load_lds((const unsigned*)((const char*)(gbase) + (voff)[_i]), (LAS unsigned*)(lds + (bufoff) + ldsw + _i * 8192), 16, 0, 0); } while (0)
; #define PG8_LDA(dst, b, h) do { _Pragma("unroll") for (int m = 0; m < 4; ++m) _Pragma("unroll") for (int k = 0; k < 2; ++k) dst[m][k] = *(const LAS bf16x8*)(lds + PG8_SA(b, h) + aoff + m * 2048 + k * 1024); } while (0)
; #define PG8_LDB(dst, b, h) do { _Pragma("unroll") for (int n = 0; n < 2; ++n) _Pragma("unroll") for (int k = 0; k < 2; ++k) dst[n][k] = *(const LAS bf16x8*)(lds + PG8_SB(b, h) + boff + n * 2048 + k * 1024); } while (0)
; #define PG8_MMA(ai, bj, At, Bt) do { __builtin_amdgcn_s_setprio(1); _Pragma("unroll") for (int m = 0; m < 4; ++m) _Pragma("unroll") for (int n = 0; n < 2; ++n) _Pragma("unroll") for (int k = 0; k < 2; ++k) \
;         acc[ai][bj][m][n] = __builtin_amdgcn_mfma_f32_16x16x32_bf16(Bt[n][k], At[m][k], acc[ai][bj][m][n], 0, 0, 0); __builtin_amdgcn_s_setprio(0); } while (0)
; #define PG8_WAIT_L(n) asm volatile("s_waitcnt lgkmcnt(" #n ")" ::: "memory")
; #define PG8_BAR __builtin_amdgcn_s_barrier()
; #define PG8_SCHED __builtin_amdgcn_sched_barrier(0)
; template <class Epi>
; __device__ __forceinline__ void gemm_phase(LAS unsigned char* lds, const Gemm g, const StaticOrder& S, const Epi& E) {
;     ...
;             PG8_LDB(B0, 0, 0); PG8_SCHED; PG8_LDA(At, 0, 0); PG8_STAGE(PG8_SA(1, 1), a1 + hstep, voffA);
;             PG8_WAIT_L(8); PG8_BAR; PG8_WAIT_L(0); PG8_MMA(0, 0, At, B0); PG8_BAR; PG8_SCHED;
.LBB0_2546:
	ds_read_b128 v[160:163], v148
	ds_read_b128 v[164:167], v148 offset:1024
	ds_read_b128 v[168:171], v148 offset:2048
	ds_read_b128 v[172:175], v148 offset:3072
	s_add_u32 s18, s16, 0xfff80080
	s_addc_u32 s19, s17, -1
	s_cmp_eq_u32 s59, 28
	s_cselect_b32 s21, s9, s19
	s_cselect_b32 s20, s47, s18
	s_cselect_b32 s19, s7, s58
	s_cselect_b32 s18, s56, s57
	v_lshl_add_u64 v[176:177], s[16:17], 0, v[136:137]
	s_add_i32 m0, s35, 0xc000
	ds_read_b128 v[180:183], v149
	ds_read_b128 v[184:187], v149 offset:1024
	ds_read_b128 v[188:191], v149 offset:2048
	ds_read_b128 v[192:195], v149 offset:3072
	ds_read_b128 v[196:199], v149 offset:4096
	ds_read_b128 v[200:203], v149 offset:5120
	ds_read_b128 v[204:207], v149 offset:6144
	ds_read_b128 v[208:211], v149 offset:7168
	global_load_lds_dwordx4 v[176:177], off
	v_lshl_add_u64 v[176:177], s[16:17], 0, v[138:139]
	s_add_i32 m0, s35, 0xe000
	s_nop 0
	global_load_lds_dwordx4 v[176:177], off
	s_waitcnt lgkmcnt(8)
	s_setprio 1
	s_barrier
	s_waitcnt lgkmcnt(0)


; #define PG8_MMA(ai, bj, At, Bt) do { __builtin_amdgcn_s_setprio(1); _Pragma("unroll") for (int m = 0; m < 4; ++m) _Pragma("unroll") for (int n = 0; n < 2; ++n) _Pragma("unroll") for (int k = 0; k < 2; ++k) \
;         acc[ai][bj][m][n] = __builtin_amdgcn_mfma_f32_16x16x32_bf16(Bt[n][k], At[m][k], acc[ai][bj][m][n], 0, 0, 0); __builtin_amdgcn_s_setprio(0); } while (0)
; #define PG8_WAIT_L(n) asm volatile("s_waitcnt lgkmcnt(" #n ")" ::: "memory")
; #define PG8_BAR __builtin_amdgcn_s_barrier()
; #define PG8_SCHED __builtin_amdgcn_sched_barrier(0)
; template <class Epi>
; __device__ __forceinline__ void gemm_phase(LAS unsigned char* lds, const Gemm g, const StaticOrder& S, const Epi& E) {
;     ...
;             PG8_WAIT_L(8); PG8_BAR; PG8_WAIT_L(0); PG8_MMA(0, 0, At, B0); PG8_BAR; PG8_SCHED;
	v_mfma_f32_16x16x32_bf16 v[124:127], v[160:163], v[180:183], v[124:127]
	v_mfma_f32_16x16x32_bf16 v[116:119], v[168:171], v[180:183], v[116:119]
	v_mfma_f32_16x16x32_bf16 v[108:111], v[160:163], v[188:191], v[108:111]
	v_mfma_f32_16x16x32_bf16 v[100:103], v[168:171], v[188:191], v[100:103]
	v_mfma_f32_16x16x32_bf16 v[92:95], v[160:163], v[196:199], v[92:95]
	v_mfma_f32_16x16x32_bf16 v[84:87], v[168:171], v[196:199], v[84:87]
	v_mfma_f32_16x16x32_bf16 v[76:79], v[160:163], v[204:207], v[76:79]
	v_mfma_f32_16x16x32_bf16 v[68:71], v[168:171], v[204:207], v[68:71]
	v_mfma_f32_16x16x32_bf16 v[124:127], v[164:167], v[184:187], v[124:127]
	v_mfma_f32_16x16x32_bf16 v[116:119], v[172:175], v[184:187], v[116:119]
	v_mfma_f32_16x16x32_bf16 v[108:111], v[164:167], v[192:195], v[108:111]
	v_mfma_f32_16x16x32_bf16 v[100:103], v[172:175], v[192:195], v[100:103]
	v_mfma_f32_16x16x32_bf16 v[92:95], v[164:167], v[200:203], v[92:95]
	v_mfma_f32_16x16x32_bf16 v[84:87], v[172:175], v[200:203], v[84:87]
	v_mfma_f32_16x16x32_bf16 v[76:79], v[164:167], v[208:211], v[76:79]
	v_mfma_f32_16x16x32_bf16 v[68:71], v[172:175], v[208:211], v[68:71]
	s_barrier
	s_setprio 0

; #define PG8_STAGE(bufoff, gbase, voff) do { _Pragma("unroll") for (int _i = 0; _i < 2; ++_i) \
;         __builtin_amdgcn_global_load_lds((const unsigned*)((const char*)(gbase) + (voff)[_i]), (LAS unsigned*)(lds + (bufoff) + ldsw + _i * 8192), 16, 0, 0); } while (0)
; #define PG8_LDB(dst, b, h) do { _Pragma("unroll") for (int n = 0; n < 2; ++n) _Pragma("unroll") for (int k = 0; k < 2; ++k) dst[n][k] = *(const LAS bf16x8*)(lds + PG8_SB(b, h) + boff + n * 2048 + k * 1024); } while (0)
; #define PG8_MMA(ai, bj, At, Bt) do { __builtin_amdgcn_s_setprio(1); _Pragma("unroll") for (int m = 0; m < 4; ++m) _Pragma("unroll") for (int n = 0; n < 2; ++n) _Pragma("unroll") for (int k = 0; k < 2; ++k) \
;         acc[ai][bj][m][n] = __builtin_amdgcn_mfma_f32_16x16x32_bf16(Bt[n][k], At[m][k], acc[ai][bj][m][n], 0, 0, 0); __builtin_amdgcn_s_setprio(0); } while (0)
; #define PG8_WAIT_L(n) asm volatile("s_waitcnt lgkmcnt(" #n ")" ::: "memory")
; #define PG8_BAR __builtin_amdgcn_s_barrier()
; template <class Epi>
; __device__ __forceinline__ void gemm_phase(LAS unsigned char* lds, const Gemm g, const StaticOrder& S, const Epi& E) {
;     ...
;             PG8_LDB(B1, 0, 1); PG8_STAGE(PG8_SB(0, 0), b2, voffB);
;             PG8_BAR; PG8_WAIT_L(0); PG8_MMA(0, 1, At, B1); PG8_BAR;
	s_add_i32 s60, s44, s31
	v_lshl_add_u64 v[176:177], s[18:19], 0, v[132:133]
	s_mov_b32 m0, s60
	ds_read_b128 v[212:215], v150
	ds_read_b128 v[216:219], v150 offset:1024
	ds_read_b128 v[220:223], v150 offset:2048
	ds_read_b128 v[224:227], v150 offset:3072
	global_load_lds_dwordx4 v[176:177], off
	v_lshl_add_u64 v[228:229], s[18:19], 0, v[128:129]
	s_add_i32 m0, s60, 0x2000
	s_nop 0
	global_load_lds_dwordx4 v[228:229], off
	s_waitcnt lgkmcnt(0)
	s_setprio 1
	s_barrier


; #define PG8_STAGE(bufoff, gbase, voff) do { _Pragma("unroll") for (int _i = 0; _i < 2; ++_i) \
;         __builtin_amdgcn_global_load_lds((const unsigned*)((const char*)(gbase) + (voff)[_i]), (LAS unsigned*)(lds + (bufoff) + ldsw + _i * 8192), 16, 0, 0); } while (0)
; #define PG8_LDA(dst, b, h) do { _Pragma("unroll") for (int m = 0; m < 4; ++m) _Pragma("unroll") for (int k = 0; k < 2; ++k) dst[m][k] = *(const LAS bf16x8*)(lds + PG8_SA(b, h) + aoff + m * 2048 + k * 1024); } while (0)
; #define PG8_MMA(ai, bj, At, Bt) do { __builtin_amdgcn_s_setprio(1); _Pragma("unroll") for (int m = 0; m < 4; ++m) _Pragma("unroll") for (int n = 0; n < 2; ++n) _Pragma("unroll") for (int k = 0; k < 2; ++k) \
;         acc[ai][bj][m][n] = __builtin_amdgcn_mfma_f32_16x16x32_bf16(Bt[n][k], At[m][k], acc[ai][bj][m][n], 0, 0, 0); __builtin_amdgcn_s_setprio(0); } while (0)
; #define PG8_WAIT_L(n) asm volatile("s_waitcnt lgkmcnt(" #n ")" ::: "memory")
; #define PG8_BAR __builtin_amdgcn_s_barrier()
; template <class Epi>
; __device__ __forceinline__ void gemm_phase(LAS unsigned char* lds, const Gemm g, const StaticOrder& S, const Epi& E) {
;     ...
;             PG8_BAR; PG8_WAIT_L(0); PG8_MMA(0, 1, At, B1); PG8_BAR;
;             PG8_LDA(At, 0, 1); PG8_STAGE(PG8_SA(0, 0), a2, voffA);
	v_mfma_f32_16x16x32_bf16 v[120:123], v[212:215], v[180:183], v[120:123]
	v_mfma_f32_16x16x32_bf16 v[112:115], v[220:223], v[180:183], v[112:115]
	v_mfma_f32_16x16x32_bf16 v[104:107], v[212:215], v[188:191], v[104:107]
	v_mfma_f32_16x16x32_bf16 v[96:99], v[220:223], v[188:191], v[96:99]
	v_mfma_f32_16x16x32_bf16 v[88:91], v[212:215], v[196:199], v[88:91]
	v_mfma_f32_16x16x32_bf16 v[80:83], v[220:223], v[196:199], v[80:83]
	v_mfma_f32_16x16x32_bf16 v[72:75], v[212:215], v[204:207], v[72:75]
	v_mfma_f32_16x16x32_bf16 v[64:67], v[220:223], v[204:207], v[64:67]
	v_mfma_f32_16x16x32_bf16 v[120:123], v[216:219], v[184:187], v[120:123]
	v_mfma_f32_16x16x32_bf16 v[112:115], v[224:227], v[184:187], v[112:115]
	v_mfma_f32_16x16x32_bf16 v[104:107], v[216:219], v[192:195], v[104:107]
	v_mfma_f32_16x16x32_bf16 v[96:99], v[224:227], v[192:195], v[96:99]
	v_mfma_f32_16x16x32_bf16 v[88:91], v[216:219], v[200:203], v[88:91]
	v_mfma_f32_16x16x32_bf16 v[80:83], v[224:227], v[200:203], v[80:83]
	v_mfma_f32_16x16x32_bf16 v[72:75], v[216:219], v[208:211], v[72:75]
	v_mfma_f32_16x16x32_bf16 v[64:67], v[224:227], v[208:211], v[64:67]
	s_barrier
	s_setprio 0
	s_mov_b32 m0, s35
	v_lshl_add_u64 v[230:231], s[20:21], 0, v[134:135]


; #define PG8_STAGE(bufoff, gbase, voff) do { _Pragma("unroll") for (int _i = 0; _i < 2; ++_i) \
;         __builtin_amdgcn_global_load_lds((const unsigned*)((const char*)(gbase) + (voff)[_i]), (LAS unsigned*)(lds + (bufoff) + ldsw + _i * 8192), 16, 0, 0); } while (0)
; #define PG8_LDA(dst, b, h) do { _Pragma("unroll") for (int m = 0; m < 4; ++m) _Pragma("unroll") for (int k = 0; k < 2; ++k) dst[m][k] = *(const LAS bf16x8*)(lds + PG8_SA(b, h) + aoff + m * 2048 + k * 1024); } while (0)
; #define PG8_MMA(ai, bj, At, Bt) do { __builtin_amdgcn_s_setprio(1); _Pragma("unroll") for (int m = 0; m < 4; ++m) _Pragma("unroll") for (int n = 0; n < 2; ++n) _Pragma("unroll") for (int k = 0; k < 2; ++k) \
;         acc[ai][bj][m][n] = __builtin_amdgcn_mfma_f32_16x16x32_bf16(Bt[n][k], At[m][k], acc[ai][bj][m][n], 0, 0, 0); __builtin_amdgcn_s_setprio(0); } while (0)
; #define PG8_WAIT_L(n) asm volatile("s_waitcnt lgkmcnt(" #n ")" ::: "memory")
; #define PG8_BAR __builtin_amdgcn_s_barrier()
; #define PG8_SCHED __builtin_amdgcn_sched_barrier(0)
; template <class Epi>
; __device__ __forceinline__ void gemm_phase(LAS unsigned char* lds, const Gemm g, const StaticOrder& S, const Epi& E) {
;     ...
;             PG8_LDA(At, 0, 1); PG8_STAGE(PG8_SA(0, 0), a2, voffA);
;             PG8_BAR; PG8_WAIT_L(0); PG8_MMA(1, 0, At, B0); PG8_BAR; PG8_SCHED;
	ds_read_b128 v[180:183], v149 offset:16384
	ds_read_b128 v[184:187], v149 offset:17408
	ds_read_b128 v[188:191], v149 offset:18432
	ds_read_b128 v[192:195], v149 offset:19456
	ds_read_b128 v[196:199], v149 offset:20480
	ds_read_b128 v[200:203], v149 offset:21504
	ds_read_b128 v[204:207], v149 offset:22528
	ds_read_b128 v[208:211], v149 offset:23552
	global_load_lds_dwordx4 v[230:231], off
	v_lshl_add_u64 v[232:233], s[20:21], 0, v[130:131]
	s_mov_b32 m0, s36
	s_nop 0
	global_load_lds_dwordx4 v[232:233], off
	s_waitcnt lgkmcnt(0)
	s_setprio 1
	s_barrier


; #define PG8_STAGE(bufoff, gbase, voff) do { _Pragma("unroll") for (int _i = 0; _i < 2; ++_i) \
;         __builtin_amdgcn_global_load_lds((const unsigned*)((const char*)(gbase) + (voff)[_i]), (LAS unsigned*)(lds + (bufoff) + ldsw + _i * 8192), 16, 0, 0); } while (0)
; #define PG8_MMA(ai, bj, At, Bt) do { __builtin_amdgcn_s_setprio(1); _Pragma("unroll") for (int m = 0; m < 4; ++m) _Pragma("unroll") for (int n = 0; n < 2; ++n) _Pragma("unroll") for (int k = 0; k < 2; ++k) \
;         acc[ai][bj][m][n] = __builtin_amdgcn_mfma_f32_16x16x32_bf16(Bt[n][k], At[m][k], acc[ai][bj][m][n], 0, 0, 0); __builtin_amdgcn_s_setprio(0); } while (0)
; #define PG8_WAIT_L(n) asm volatile("s_waitcnt lgkmcnt(" #n ")" ::: "memory")
; #define PG8_BAR __builtin_amdgcn_s_barrier()
; #define PG8_SCHED __builtin_amdgcn_sched_barrier(0)
; template <class Epi>
; __device__ __forceinline__ void gemm_phase(LAS unsigned char* lds, const Gemm g, const StaticOrder& S, const Epi& E) {
;     ...
;             PG8_BAR; PG8_WAIT_L(0); PG8_MMA(1, 0, At, B0); PG8_BAR; PG8_SCHED;
;             PG8_STAGE(PG8_SB(0, 1), b2 + hstep, voffB);
	v_mfma_f32_16x16x32_bf16 v[60:63], v[160:163], v[180:183], v[60:63]
	v_mfma_f32_16x16x32_bf16 v[52:55], v[168:171], v[180:183], v[52:55]
	v_mfma_f32_16x16x32_bf16 v[44:47], v[160:163], v[188:191], v[44:47]
	v_mfma_f32_16x16x32_bf16 v[36:39], v[168:171], v[188:191], v[36:39]
	v_mfma_f32_16x16x32_bf16 v[28:31], v[160:163], v[196:199], v[28:31]
	v_mfma_f32_16x16x32_bf16 v[20:23], v[168:171], v[196:199], v[20:23]
	v_mfma_f32_16x16x32_bf16 v[12:15], v[160:163], v[204:207], v[12:15]
	v_mfma_f32_16x16x32_bf16 v[4:7], v[168:171], v[204:207], v[4:7]
	v_mfma_f32_16x16x32_bf16 v[60:63], v[164:167], v[184:187], v[60:63]
	v_mfma_f32_16x16x32_bf16 v[52:55], v[172:175], v[184:187], v[52:55]
	v_mfma_f32_16x16x32_bf16 v[44:47], v[164:167], v[192:195], v[44:47]
	v_mfma_f32_16x16x32_bf16 v[36:39], v[172:175], v[192:195], v[36:39]
	v_mfma_f32_16x16x32_bf16 v[28:31], v[164:167], v[200:203], v[28:31]
	v_mfma_f32_16x16x32_bf16 v[20:23], v[172:175], v[200:203], v[20:23]
	v_mfma_f32_16x16x32_bf16 v[12:15], v[164:167], v[208:211], v[12:15]
	v_mfma_f32_16x16x32_bf16 v[4:7], v[172:175], v[208:211], v[4:7]
	s_barrier
	s_setprio 0

; #define PG8_STAGE(bufoff, gbase, voff) do { _Pragma("unroll") for (int _i = 0; _i < 2; ++_i) \
;         __builtin_amdgcn_global_load_lds((const unsigned*)((const char*)(gbase) + (voff)[_i]), (LAS unsigned*)(lds + (bufoff) + ldsw + _i * 8192), 16, 0, 0); } while (0)
; #define PG8_MMA(ai, bj, At, Bt) do { __builtin_amdgcn_s_setprio(1); _Pragma("unroll") for (int m = 0; m < 4; ++m) _Pragma("unroll") for (int n = 0; n < 2; ++n) _Pragma("unroll") for (int k = 0; k < 2; ++k) \
;         acc[ai][bj][m][n] = __builtin_amdgcn_mfma_f32_16x16x32_bf16(Bt[n][k], At[m][k], acc[ai][bj][m][n], 0, 0, 0); __builtin_amdgcn_s_setprio(0); } while (0)
; #define PG8_WAIT_V(n) asm volatile("s_waitcnt vmcnt(" #n ")" ::: "memory")
; #define PG8_BAR __builtin_amdgcn_s_barrier()
; template <class Epi>
; __device__ __forceinline__ void gemm_phase(LAS unsigned char* lds, const Gemm g, const StaticOrder& S, const Epi& E) {
;     ...
;             PG8_STAGE(PG8_SB(0, 1), b2 + hstep, voffB);
;             PG8_WAIT_V(6); PG8_BAR; PG8_MMA(1, 1, At, B1); PG8_BAR;
	s_add_u32 s60, s18, 0x80000
	s_addc_u32 s61, s19, 0
	s_add_i32 s62, s45, s31
	v_lshl_add_u64 v[160:161], s[60:61], 0, v[132:133]
	s_mov_b32 m0, s62
	s_nop 0
	global_load_lds_dwordx4 v[160:161], off
	v_lshl_add_u64 v[160:161], s[60:61], 0, v[128:129]
	s_add_i32 m0, s62, 0x2000
	s_nop 0
	global_load_lds_dwordx4 v[160:161], off
	s_waitcnt vmcnt(6)
	s_setprio 1
	s_barrier

; #define PG8_STAGE(bufoff, gbase, voff) do { _Pragma("unroll") for (int _i = 0; _i < 2; ++_i) \
;         __builtin_amdgcn_global_load_lds((const unsigned*)((const char*)(gbase) + (voff)[_i]), (LAS unsigned*)(lds + (bufoff) + ldsw + _i * 8192), 16, 0, 0); } while (0)
; #define PG8_LDA(dst, b, h) do { _Pragma("unroll") for (int m = 0; m < 4; ++m) _Pragma("unroll") for (int k = 0; k < 2; ++k) dst[m][k] = *(const LAS bf16x8*)(lds + PG8_SA(b, h) + aoff + m * 2048 + k * 1024); } while (0)
; #define PG8_LDB(dst, b, h) do { _Pragma("unroll") for (int n = 0; n < 2; ++n) _Pragma("unroll") for (int k = 0; k < 2; ++k) dst[n][k] = *(const LAS bf16x8*)(lds + PG8_SB(b, h) + boff + n * 2048 + k * 1024); } while (0)
; #define PG8_MMA(ai, bj, At, Bt) do { __builtin_amdgcn_s_setprio(1); _Pragma("unroll") for (int m = 0; m < 4; ++m) _Pragma("unroll") for (int n = 0; n < 2; ++n) _Pragma("unroll") for (int k = 0; k < 2; ++k) \
;         acc[ai][bj][m][n] = __builtin_amdgcn_mfma_f32_16x16x32_bf16(Bt[n][k], At[m][k], acc[ai][bj][m][n], 0, 0, 0); __builtin_amdgcn_s_setprio(0); } while (0)
; #define PG8_WAIT_V(n) asm volatile("s_waitcnt vmcnt(" #n ")" ::: "memory")
; #define PG8_BAR __builtin_amdgcn_s_barrier()
; #define PG8_SCHED __builtin_amdgcn_sched_barrier(0)
; template <class Epi>
; __device__ __forceinline__ void gemm_phase(LAS unsigned char* lds, const Gemm g, const StaticOrder& S, const Epi& E) {
;     ...
;             PG8_WAIT_V(6); PG8_BAR; PG8_MMA(1, 1, At, B1); PG8_BAR;
;             PG8_LDB(B0, 1, 0); PG8_SCHED; PG8_LDA(At, 1, 0); PG8_STAGE(PG8_SA(0, 1), a2 + hstep, voffA);
	v_mfma_f32_16x16x32_bf16 v[56:59], v[212:215], v[180:183], v[56:59]
	v_mfma_f32_16x16x32_bf16 v[48:51], v[220:223], v[180:183], v[48:51]
	v_mfma_f32_16x16x32_bf16 v[40:43], v[212:215], v[188:191], v[40:43]
	v_mfma_f32_16x16x32_bf16 v[32:35], v[220:223], v[188:191], v[32:35]
	v_mfma_f32_16x16x32_bf16 v[24:27], v[212:215], v[196:199], v[24:27]
	v_mfma_f32_16x16x32_bf16 v[16:19], v[220:223], v[196:199], v[16:19]
	v_mfma_f32_16x16x32_bf16 v[8:11], v[212:215], v[204:207], v[8:11]
	v_mfma_f32_16x16x32_bf16 v[0:3], v[220:223], v[204:207], v[0:3]
	v_mfma_f32_16x16x32_bf16 v[56:59], v[216:219], v[184:187], v[56:59]
	v_mfma_f32_16x16x32_bf16 v[48:51], v[224:227], v[184:187], v[48:51]
	v_mfma_f32_16x16x32_bf16 v[40:43], v[216:219], v[192:195], v[40:43]
	v_mfma_f32_16x16x32_bf16 v[32:35], v[224:227], v[192:195], v[32:35]
	v_mfma_f32_16x16x32_bf16 v[24:27], v[216:219], v[200:203], v[24:27]
	v_mfma_f32_16x16x32_bf16 v[16:19], v[224:227], v[200:203], v[16:19]
	v_mfma_f32_16x16x32_bf16 v[8:11], v[216:219], v[208:211], v[8:11]
	v_mfma_f32_16x16x32_bf16 v[0:3], v[224:227], v[208:211], v[0:3]
	s_barrier
	s_setprio 0
	s_add_i32 s60, 0, 0x18000
	v_add_u32_e32 v159, s60, v145


; #define PG8_STAGE(bufoff, gbase, voff) do { _Pragma("unroll") for (int _i = 0; _i < 2; ++_i) \
;         __builtin_amdgcn_global_load_lds((const unsigned*)((const char*)(gbase) + (voff)[_i]), (LAS unsigned*)(lds + (bufoff) + ldsw + _i * 8192), 16, 0, 0); } while (0)
; #define PG8_LDA(dst, b, h) do { _Pragma("unroll") for (int m = 0; m < 4; ++m) _Pragma("unroll") for (int k = 0; k < 2; ++k) dst[m][k] = *(const LAS bf16x8*)(lds + PG8_SA(b, h) + aoff + m * 2048 + k * 1024); } while (0)
; #define PG8_LDB(dst, b, h) do { _Pragma("unroll") for (int n = 0; n < 2; ++n) _Pragma("unroll") for (int k = 0; k < 2; ++k) dst[n][k] = *(const LAS bf16x8*)(lds + PG8_SB(b, h) + boff + n * 2048 + k * 1024); } while (0)
; #define PG8_MMA(ai, bj, At, Bt) do { __builtin_amdgcn_s_setprio(1); _Pragma("unroll") for (int m = 0; m < 4; ++m) _Pragma("unroll") for (int n = 0; n < 2; ++n) _Pragma("unroll") for (int k = 0; k < 2; ++k) \
;         acc[ai][bj][m][n] = __builtin_amdgcn_mfma_f32_16x16x32_bf16(Bt[n][k], At[m][k], acc[ai][bj][m][n], 0, 0, 0); __builtin_amdgcn_s_setprio(0); } while (0)
; #define PG8_WAIT_L(n) asm volatile("s_waitcnt lgkmcnt(" #n ")" ::: "memory")
; #define PG8_BAR __builtin_amdgcn_s_barrier()
; #define PG8_SCHED __builtin_amdgcn_sched_barrier(0)
; template <class Epi>
; __device__ __forceinline__ void gemm_phase(LAS unsigned char* lds, const Gemm g, const StaticOrder& S, const Epi& E) {
;     ...
;             PG8_LDB(B0, 1, 0); PG8_SCHED; PG8_LDA(At, 1, 0); PG8_STAGE(PG8_SA(0, 1), a2 + hstep, voffA);
;             PG8_WAIT_L(8); PG8_BAR; PG8_WAIT_L(0); PG8_MMA(0, 0, At, B0); PG8_BAR; PG8_SCHED;
	ds_read_b128 v[160:163], v159
	ds_read_b128 v[164:167], v159 offset:1024
	ds_read_b128 v[168:171], v159 offset:2048
	ds_read_b128 v[172:175], v159 offset:3072
	s_add_u32 s20, s20, 0x80000
	s_addc_u32 s21, s21, 0
	s_mov_b32 m0, s37
	v_lshl_add_u64 v[212:213], s[20:21], 0, v[134:135]
	ds_read_b128 v[180:183], v149 offset:32768
	ds_read_b128 v[184:187], v149 offset:33792
	ds_read_b128 v[188:191], v149 offset:34816
	ds_read_b128 v[192:195], v149 offset:35840
	ds_read_b128 v[196:199], v149 offset:36864
	ds_read_b128 v[200:203], v149 offset:37888
	ds_read_b128 v[204:207], v149 offset:38912
	ds_read_b128 v[208:211], v149 offset:39936
	global_load_lds_dwordx4 v[212:213], off
	v_lshl_add_u64 v[212:213], s[20:21], 0, v[130:131]
	s_mov_b32 m0, s38
	s_nop 0
	global_load_lds_dwordx4 v[212:213], off
	s_waitcnt lgkmcnt(8)
	s_setprio 1
	s_barrier
	s_waitcnt lgkmcnt(0)


; #define PG8_MMA(ai, bj, At, Bt) do { __builtin_amdgcn_s_setprio(1); _Pragma("unroll") for (int m = 0; m < 4; ++m) _Pragma("unroll") for (int n = 0; n < 2; ++n) _Pragma("unroll") for (int k = 0; k < 2; ++k) \
;         acc[ai][bj][m][n] = __builtin_amdgcn_mfma_f32_16x16x32_bf16(Bt[n][k], At[m][k], acc[ai][bj][m][n], 0, 0, 0); __builtin_amdgcn_s_setprio(0); } while (0)
; #define PG8_WAIT_L(n) asm volatile("s_waitcnt lgkmcnt(" #n ")" ::: "memory")
; #define PG8_BAR __builtin_amdgcn_s_barrier()
; #define PG8_SCHED __builtin_amdgcn_sched_barrier(0)
; template <class Epi>
; __device__ __forceinline__ void gemm_phase(LAS unsigned char* lds, const Gemm g, const StaticOrder& S, const Epi& E) {
;     ...
;             PG8_WAIT_L(8); PG8_BAR; PG8_WAIT_L(0); PG8_MMA(0, 0, At, B0); PG8_BAR; PG8_SCHED;
	v_mfma_f32_16x16x32_bf16 v[124:127], v[160:163], v[180:183], v[124:127]
	v_mfma_f32_16x16x32_bf16 v[116:119], v[168:171], v[180:183], v[116:119]
	v_mfma_f32_16x16x32_bf16 v[108:111], v[160:163], v[188:191], v[108:111]
	v_mfma_f32_16x16x32_bf16 v[100:103], v[168:171], v[188:191], v[100:103]
	v_mfma_f32_16x16x32_bf16 v[92:95], v[160:163], v[196:199], v[92:95]
	v_mfma_f32_16x16x32_bf16 v[84:87], v[168:171], v[196:199], v[84:87]
	v_mfma_f32_16x16x32_bf16 v[76:79], v[160:163], v[204:207], v[76:79]
	v_mfma_f32_16x16x32_bf16 v[68:71], v[168:171], v[204:207], v[68:71]
	v_mfma_f32_16x16x32_bf16 v[124:127], v[164:167], v[184:187], v[124:127]
	v_mfma_f32_16x16x32_bf16 v[116:119], v[172:175], v[184:187], v[116:119]
	v_mfma_f32_16x16x32_bf16 v[108:111], v[164:167], v[192:195], v[108:111]
	v_mfma_f32_16x16x32_bf16 v[100:103], v[172:175], v[192:195], v[100:103]
	v_mfma_f32_16x16x32_bf16 v[92:95], v[164:167], v[200:203], v[92:95]
	v_mfma_f32_16x16x32_bf16 v[84:87], v[172:175], v[200:203], v[84:87]
	v_mfma_f32_16x16x32_bf16 v[76:79], v[164:167], v[208:211], v[76:79]
	v_mfma_f32_16x16x32_bf16 v[68:71], v[172:175], v[208:211], v[68:71]
	s_barrier
	s_setprio 0

; #define PG8_STAGE(bufoff, gbase, voff) do { _Pragma("unroll") for (int _i = 0; _i < 2; ++_i) \
;         __builtin_amdgcn_global_load_lds((const unsigned*)((const char*)(gbase) + (voff)[_i]), (LAS unsigned*)(lds + (bufoff) + ldsw + _i * 8192), 16, 0, 0); } while (0)
; #define PG8_LDB(dst, b, h) do { _Pragma("unroll") for (int n = 0; n < 2; ++n) _Pragma("unroll") for (int k = 0; k < 2; ++k) dst[n][k] = *(const LAS bf16x8*)(lds + PG8_SB(b, h) + boff + n * 2048 + k * 1024); } while (0)
; #define PG8_MMA(ai, bj, At, Bt) do { __builtin_amdgcn_s_setprio(1); _Pragma("unroll") for (int m = 0; m < 4; ++m) _Pragma("unroll") for (int n = 0; n < 2; ++n) _Pragma("unroll") for (int k = 0; k < 2; ++k) \
;         acc[ai][bj][m][n] = __builtin_amdgcn_mfma_f32_16x16x32_bf16(Bt[n][k], At[m][k], acc[ai][bj][m][n], 0, 0, 0); __builtin_amdgcn_s_setprio(0); } while (0)
; #define PG8_WAIT_L(n) asm volatile("s_waitcnt lgkmcnt(" #n ")" ::: "memory")
; #define PG8_BAR __builtin_amdgcn_s_barrier()
; template <class Epi>
; __device__ __forceinline__ void gemm_phase(LAS unsigned char* lds, const Gemm g, const StaticOrder& S, const Epi& E) {
;     ...
;             PG8_LDB(B1, 1, 1); PG8_STAGE(PG8_SB(1, 0), b3, voffB);
;             PG8_BAR; PG8_WAIT_L(0); PG8_MMA(0, 1, At, B1); PG8_BAR;
	s_add_i32 s20, 0, 0x1c000
	s_add_i32 s21, s60, s31
	v_add_u32_e32 v159, s20, v145
	v_lshl_add_u64 v[176:177], v[176:177], 0, s[4:5]
	s_mov_b32 m0, s21
	ds_read_b128 v[212:215], v159
	ds_read_b128 v[216:219], v159 offset:1024
	ds_read_b128 v[220:223], v159 offset:2048
	ds_read_b128 v[224:227], v159 offset:3072
	global_load_lds_dwordx4 v[176:177], off
	v_lshl_add_u64 v[176:177], v[228:229], 0, s[4:5]
	s_add_i32 m0, s21, 0x2000
	s_nop 0
	global_load_lds_dwordx4 v[176:177], off
	s_waitcnt lgkmcnt(0)
	s_setprio 1
	s_barrier


; #define PG8_STAGE(bufoff, gbase, voff) do { _Pragma("unroll") for (int _i = 0; _i < 2; ++_i) \
;         __builtin_amdgcn_global_load_lds((const unsigned*)((const char*)(gbase) + (voff)[_i]), (LAS unsigned*)(lds + (bufoff) + ldsw + _i * 8192), 16, 0, 0); } while (0)
; #define PG8_LDA(dst, b, h) do { _Pragma("unroll") for (int m = 0; m < 4; ++m) _Pragma("unroll") for (int k = 0; k < 2; ++k) dst[m][k] = *(const LAS bf16x8*)(lds + PG8_SA(b, h) + aoff + m * 2048 + k * 1024); } while (0)
; #define PG8_MMA(ai, bj, At, Bt) do { __builtin_amdgcn_s_setprio(1); _Pragma("unroll") for (int m = 0; m < 4; ++m) _Pragma("unroll") for (int n = 0; n < 2; ++n) _Pragma("unroll") for (int k = 0; k < 2; ++k) \
;         acc[ai][bj][m][n] = __builtin_amdgcn_mfma_f32_16x16x32_bf16(Bt[n][k], At[m][k], acc[ai][bj][m][n], 0, 0, 0); __builtin_amdgcn_s_setprio(0); } while (0)
; #define PG8_WAIT_L(n) asm volatile("s_waitcnt lgkmcnt(" #n ")" ::: "memory")
; #define PG8_BAR __builtin_amdgcn_s_barrier()
; template <class Epi>
; __device__ __forceinline__ void gemm_phase(LAS unsigned char* lds, const Gemm g, const StaticOrder& S, const Epi& E) {
;     ...
;             PG8_BAR; PG8_WAIT_L(0); PG8_MMA(0, 1, At, B1); PG8_BAR;
;             PG8_LDA(At, 1, 1); PG8_STAGE(PG8_SA(1, 0), a3, voffA);
	v_mfma_f32_16x16x32_bf16 v[120:123], v[212:215], v[180:183], v[120:123]
	v_mfma_f32_16x16x32_bf16 v[112:115], v[220:223], v[180:183], v[112:115]
	v_mfma_f32_16x16x32_bf16 v[104:107], v[212:215], v[188:191], v[104:107]
	v_mfma_f32_16x16x32_bf16 v[96:99], v[220:223], v[188:191], v[96:99]
	v_mfma_f32_16x16x32_bf16 v[88:91], v[212:215], v[196:199], v[88:91]
	v_mfma_f32_16x16x32_bf16 v[80:83], v[220:223], v[196:199], v[80:83]
	v_mfma_f32_16x16x32_bf16 v[72:75], v[212:215], v[204:207], v[72:75]
	v_mfma_f32_16x16x32_bf16 v[64:67], v[220:223], v[204:207], v[64:67]
	v_mfma_f32_16x16x32_bf16 v[120:123], v[216:219], v[184:187], v[120:123]
	v_mfma_f32_16x16x32_bf16 v[112:115], v[224:227], v[184:187], v[112:115]
	v_mfma_f32_16x16x32_bf16 v[104:107], v[216:219], v[192:195], v[104:107]
	v_mfma_f32_16x16x32_bf16 v[96:99], v[224:227], v[192:195], v[96:99]
	v_mfma_f32_16x16x32_bf16 v[88:91], v[216:219], v[200:203], v[88:91]
	v_mfma_f32_16x16x32_bf16 v[80:83], v[224:227], v[200:203], v[80:83]
	v_mfma_f32_16x16x32_bf16 v[72:75], v[216:219], v[208:211], v[72:75]
	v_mfma_f32_16x16x32_bf16 v[64:67], v[224:227], v[208:211], v[64:67]
	s_barrier
	s_setprio 0
	s_mov_b32 m0, s40
	v_lshl_add_u64 v[176:177], v[230:231], 0, s[4:5]


; #define PG8_STAGE(bufoff, gbase, voff) do { _Pragma("unroll") for (int _i = 0; _i < 2; ++_i) \
;         __builtin_amdgcn_global_load_lds((const unsigned*)((const char*)(gbase) + (voff)[_i]), (LAS unsigned*)(lds + (bufoff) + ldsw + _i * 8192), 16, 0, 0); } while (0)
; #define PG8_LDA(dst, b, h) do { _Pragma("unroll") for (int m = 0; m < 4; ++m) _Pragma("unroll") for (int k = 0; k < 2; ++k) dst[m][k] = *(const LAS bf16x8*)(lds + PG8_SA(b, h) + aoff + m * 2048 + k * 1024); } while (0)
; #define PG8_MMA(ai, bj, At, Bt) do { __builtin_amdgcn_s_setprio(1); _Pragma("unroll") for (int m = 0; m < 4; ++m) _Pragma("unroll") for (int n = 0; n < 2; ++n) _Pragma("unroll") for (int k = 0; k < 2; ++k) \
;         acc[ai][bj][m][n] = __builtin_amdgcn_mfma_f32_16x16x32_bf16(Bt[n][k], At[m][k], acc[ai][bj][m][n], 0, 0, 0); __builtin_amdgcn_s_setprio(0); } while (0)
; #define PG8_WAIT_L(n) asm volatile("s_waitcnt lgkmcnt(" #n ")" ::: "memory")
; #define PG8_BAR __builtin_amdgcn_s_barrier()
; #define PG8_SCHED __builtin_amdgcn_sched_barrier(0)
; template <class Epi>
; __device__ __forceinline__ void gemm_phase(LAS unsigned char* lds, const Gemm g, const StaticOrder& S, const Epi& E) {
;     ...
;             PG8_LDA(At, 1, 1); PG8_STAGE(PG8_SA(1, 0), a3, voffA);
;             PG8_BAR; PG8_WAIT_L(0); PG8_MMA(1, 0, At, B0); PG8_BAR; PG8_SCHED;
	ds_read_b128 v[180:183], v149 offset:49152
	ds_read_b128 v[184:187], v149 offset:50176
	ds_read_b128 v[188:191], v149 offset:51200
	ds_read_b128 v[192:195], v149 offset:52224
	ds_read_b128 v[196:199], v149 offset:53248
	ds_read_b128 v[200:203], v149 offset:54272
	ds_read_b128 v[204:207], v149 offset:55296
	ds_read_b128 v[208:211], v149 offset:56320
	global_load_lds_dwordx4 v[176:177], off
	v_lshl_add_u64 v[176:177], v[232:233], 0, s[4:5]
	s_mov_b32 m0, s41
	s_nop 0
	global_load_lds_dwordx4 v[176:177], off
	s_waitcnt lgkmcnt(0)
	s_setprio 1
	s_barrier


; #define PG8_MMA(ai, bj, At, Bt) do { __builtin_amdgcn_s_setprio(1); _Pragma("unroll") for (int m = 0; m < 4; ++m) _Pragma("unroll") for (int n = 0; n < 2; ++n) _Pragma("unroll") for (int k = 0; k < 2; ++k) \
;         acc[ai][bj][m][n] = __builtin_amdgcn_mfma_f32_16x16x32_bf16(Bt[n][k], At[m][k], acc[ai][bj][m][n], 0, 0, 0); __builtin_amdgcn_s_setprio(0); } while (0)
; #define PG8_WAIT_L(n) asm volatile("s_waitcnt lgkmcnt(" #n ")" ::: "memory")
; #define PG8_BAR __builtin_amdgcn_s_barrier()
; #define PG8_SCHED __builtin_amdgcn_sched_barrier(0)
; template <class Epi>
; __device__ __forceinline__ void gemm_phase(LAS unsigned char* lds, const Gemm g, const StaticOrder& S, const Epi& E) {
;     ...
;             PG8_BAR; PG8_WAIT_L(0); PG8_MMA(1, 0, At, B0); PG8_BAR; PG8_SCHED;
	v_mfma_f32_16x16x32_bf16 v[60:63], v[160:163], v[180:183], v[60:63]
	v_mfma_f32_16x16x32_bf16 v[52:55], v[168:171], v[180:183], v[52:55]
	v_mfma_f32_16x16x32_bf16 v[44:47], v[160:163], v[188:191], v[44:47]
	v_mfma_f32_16x16x32_bf16 v[36:39], v[168:171], v[188:191], v[36:39]
	v_mfma_f32_16x16x32_bf16 v[28:31], v[160:163], v[196:199], v[28:31]
	v_mfma_f32_16x16x32_bf16 v[20:23], v[168:171], v[196:199], v[20:23]
	v_mfma_f32_16x16x32_bf16 v[12:15], v[160:163], v[204:207], v[12:15]
	v_mfma_f32_16x16x32_bf16 v[4:7], v[168:171], v[204:207], v[4:7]
	v_mfma_f32_16x16x32_bf16 v[60:63], v[164:167], v[184:187], v[60:63]
	v_mfma_f32_16x16x32_bf16 v[52:55], v[172:175], v[184:187], v[52:55]
	v_mfma_f32_16x16x32_bf16 v[44:47], v[164:167], v[192:195], v[44:47]
	v_mfma_f32_16x16x32_bf16 v[36:39], v[172:175], v[192:195], v[36:39]
	v_mfma_f32_16x16x32_bf16 v[28:31], v[164:167], v[200:203], v[28:31]
	v_mfma_f32_16x16x32_bf16 v[20:23], v[172:175], v[200:203], v[20:23]
	v_mfma_f32_16x16x32_bf16 v[12:15], v[164:167], v[208:211], v[12:15]
	v_mfma_f32_16x16x32_bf16 v[4:7], v[172:175], v[208:211], v[4:7]
	s_barrier
	s_setprio 0

; #define PG8_STAGE(bufoff, gbase, voff) do { _Pragma("unroll") for (int _i = 0; _i < 2; ++_i) \
;         __builtin_amdgcn_global_load_lds((const unsigned*)((const char*)(gbase) + (voff)[_i]), (LAS unsigned*)(lds + (bufoff) + ldsw + _i * 8192), 16, 0, 0); } while (0)
; #define PG8_MMA(ai, bj, At, Bt) do { __builtin_amdgcn_s_setprio(1); _Pragma("unroll") for (int m = 0; m < 4; ++m) _Pragma("unroll") for (int n = 0; n < 2; ++n) _Pragma("unroll") for (int k = 0; k < 2; ++k) \
;         acc[ai][bj][m][n] = __builtin_amdgcn_mfma_f32_16x16x32_bf16(Bt[n][k], At[m][k], acc[ai][bj][m][n], 0, 0, 0); __builtin_amdgcn_s_setprio(0); } while (0)
; #define PG8_WAIT_V(n) asm volatile("s_waitcnt vmcnt(" #n ")" ::: "memory")
; #define PG8_BAR __builtin_amdgcn_s_barrier()
; template <class Epi>
; __device__ __forceinline__ void gemm_phase(LAS unsigned char* lds, const Gemm g, const StaticOrder& S, const Epi& E) {
;     ...
;             PG8_STAGE(PG8_SB(1, 1), b3 + hstep, voffB);
;             PG8_WAIT_V(6); PG8_BAR; PG8_MMA(1, 1, At, B1); PG8_BAR;
	s_add_u32 s18, s18, 0x80080
	s_addc_u32 s19, s19, 0
	s_add_i32 s20, s20, s31
	v_lshl_add_u64 v[160:161], s[18:19], 0, v[132:133]
	s_mov_b32 m0, s20
	s_nop 0
	global_load_lds_dwordx4 v[160:161], off
	v_lshl_add_u64 v[160:161], s[18:19], 0, v[128:129]
	s_add_i32 m0, s20, 0x2000
	s_nop 0
	global_load_lds_dwordx4 v[160:161], off
	s_waitcnt vmcnt(6)
	s_setprio 1
	s_barrier

; #define PG8_MMA(ai, bj, At, Bt) do { __builtin_amdgcn_s_setprio(1); _Pragma("unroll") for (int m = 0; m < 4; ++m) _Pragma("unroll") for (int n = 0; n < 2; ++n) _Pragma("unroll") for (int k = 0; k < 2; ++k) \
;         acc[ai][bj][m][n] = __builtin_amdgcn_mfma_f32_16x16x32_bf16(Bt[n][k], At[m][k], acc[ai][bj][m][n], 0, 0, 0); __builtin_amdgcn_s_setprio(0); } while (0)
; #define PG8_WAIT_V(n) asm volatile("s_waitcnt vmcnt(" #n ")" ::: "memory")
; #define PG8_BAR __builtin_amdgcn_s_barrier()
; template <class Epi>
; __device__ __forceinline__ void gemm_phase(LAS unsigned char* lds, const Gemm g, const StaticOrder& S, const Epi& E) {
;     ...
;             PG8_WAIT_V(6); PG8_BAR; PG8_MMA(1, 1, At, B1); PG8_BAR;
;         }
	v_mfma_f32_16x16x32_bf16 v[56:59], v[212:215], v[180:183], v[56:59]
	v_mfma_f32_16x16x32_bf16 v[48:51], v[220:223], v[180:183], v[48:51]
	v_mfma_f32_16x16x32_bf16 v[40:43], v[212:215], v[188:191], v[40:43]
	v_mfma_f32_16x16x32_bf16 v[32:35], v[220:223], v[188:191], v[32:35]
	v_mfma_f32_16x16x32_bf16 v[24:27], v[212:215], v[196:199], v[24:27]
	v_mfma_f32_16x16x32_bf16 v[16:19], v[220:223], v[196:199], v[16:19]
	v_mfma_f32_16x16x32_bf16 v[8:11], v[212:215], v[204:207], v[8:11]
	v_mfma_f32_16x16x32_bf16 v[0:3], v[220:223], v[204:207], v[0:3]
	v_mfma_f32_16x16x32_bf16 v[56:59], v[216:219], v[184:187], v[56:59]
	v_mfma_f32_16x16x32_bf16 v[48:51], v[224:227], v[184:187], v[48:51]
	v_mfma_f32_16x16x32_bf16 v[40:43], v[216:219], v[192:195], v[40:43]
	v_mfma_f32_16x16x32_bf16 v[32:35], v[224:227], v[192:195], v[32:35]
	v_mfma_f32_16x16x32_bf16 v[24:27], v[216:219], v[200:203], v[24:27]
	v_mfma_f32_16x16x32_bf16 v[16:19], v[224:227], v[200:203], v[16:19]
	v_mfma_f32_16x16x32_bf16 v[8:11], v[216:219], v[208:211], v[8:11]
	v_mfma_f32_16x16x32_bf16 v[0:3], v[224:227], v[208:211], v[0:3]
	s_barrier
	s_setprio 0
	s_add_i32 s59, s59, 2
	s_add_u32 s16, s16, 0x100
	s_addc_u32 s17, s17, 0
	s_add_u32 s57, s57, 0x100
	s_addc_u32 s58, s58, 0
	s_cmp_gt_u32 s59, 29


; __device__ __forceinline__ float sigmoidf_(float x) { return __builtin_amdgcn_rcpf(1.0f + fexp(-x)); }
;     __device__ __forceinline__ void operator()(const f32x4 (&acc)[2][2][4][2], const Unit& u, int wr, int wc, int fr, int fq, const Pre& P) const {
;         const int row0 = ROW_X + u.pm * BM + wr * 64 + fr, col0 = u.pn * HALF + wc * 32 + 8 * fq;
; #pragma unroll
;         for (int ai = 0; ai < 2; ++ai)
; #pragma unroll
;             for (int m = 0; m < 4; ++m) { const int r = row0 + ai * HALF + m * 16; const float rs = __builtin_amdgcn_rsqf(P.rs[ai * 4 + m] * (1.0f / DM) + RMS_EPS);
;                 float y[8];
; #pragma unroll
;                 for (int n = 0; n < 2; ++n)
; #pragma unroll
;                     for (int j = 0; j < 4; ++j) { const float a = acc[ai][0][m][n][j] * rs, b = acc[ai][1][m][n][j] * rs; y[n * 4 + j] = a * b * sigmoidf_(a); }
;                 u32x4 w; w.x = cvtpk(y[0], y[1]); w.y = cvtpk(y[2], y[3]); w.z = cvtpk(y[4], y[5]); w.w = cvtpk(y[6], y[7]);
;                 *(u32x4*)(O + (size_t)r * FF + col0) = w; }
	s_cbranch_scc0 .LBB0_2546
	s_waitcnt vmcnt(0)
	v_fmamk_f32 v158, v158, 0x3a000000, v151
	v_rsq_f32_e32 v158, v158
	v_lshl_or_b32 v162, s15, 7, v146
	v_ashrrev_i32_e32 v163, 31, v162
	s_and_b64 vcc, vcc, exec
	v_pk_mul_f32 v[160:161], v[158:159], v[124:125] op_sel_hi:[0,1]
	v_mul_f32_e32 v124, 0xbfb8aa3b, v160
	v_mul_f32_e32 v125, 0xbfb8aa3b, v161
	v_exp_f32_e32 v159, v124
	v_exp_f32_e32 v125, v125
	v_lshl_add_u32 v124, s14, 8, v144
	v_add_f32_e32 v159, 1.0, v159
	v_add_f32_e32 v125, 1.0, v125
	v_rcp_f32_e32 v164, v159
	v_rcp_f32_e32 v165, v125
	v_pk_mul_f32 v[120:121], v[158:159], v[120:121] op_sel_hi:[0,1]
	v_pk_mul_f32 v[120:121], v[160:161], v[120:121]
	v_pk_mul_f32 v[126:127], v[158:159], v[126:127] op_sel_hi:[0,1]
	v_pk_mul_f32 v[120:121], v[164:165], v[120:121]
	v_mul_f32_e32 v125, 0xbfb8aa3b, v126
	v_cvt_pk_bf16_f32 v120, v120, v121
	v_mul_f32_e32 v121, 0xbfb8aa3b, v127
	v_exp_f32_e32 v125, v125
	v_exp_f32_e32 v121, v121
	v_pk_mul_f32 v[122:123], v[158:159], v[122:123] op_sel_hi:[0,1]
	v_pk_mul_f32 v[116:117], v[158:159], v[116:117] op_sel_hi:[0,1]
	v_add_f32_e32 v125, 1.0, v125
	v_add_f32_e32 v121, 1.0, v121
	v_rcp_f32_e32 v160, v125
	v_rcp_f32_e32 v161, v121
	v_pk_mul_f32 v[122:123], v[126:127], v[122:123]
	v_mul_f32_e32 v121, 0xbfb8aa3b, v116
	v_exp_f32_e32 v125, v121
	v_pk_mul_f32 v[122:123], v[160:161], v[122:123]
	v_pk_mul_f32 v[112:113], v[158:159], v[112:113] op_sel_hi:[0,1]
	v_cvt_pk_bf16_f32 v121, v122, v123
	v_mul_f32_e32 v123, 0xbfb8aa3b, v117
	v_exp_f32_e32 v123, v123
	v_add_f32_e32 v122, 1.0, v125
	v_pk_mul_f32 v[112:113], v[116:117], v[112:113]
	v_rcp_f32_e32 v122, v122
	v_add_f32_e32 v116, 1.0, v123
	v_rcp_f32_e32 v123, v116
	v_pk_mul_f32 v[116:117], v[158:159], v[118:119] op_sel_hi:[0,1]
	v_mul_f32_e32 v118, 0xbfb8aa3b, v116
	v_mul_f32_e32 v119, 0xbfb8aa3b, v117
	v_exp_f32_e32 v118, v118
	v_exp_f32_e32 v119, v119
	v_pk_mul_f32 v[112:113], v[122:123], v[112:113]
	v_add_f32_e32 v118, 1.0, v118
	v_cvt_pk_bf16_f32 v122, v112, v113
	v_pk_mul_f32 v[112:113], v[158:159], v[114:115] op_sel_hi:[0,1]
	v_fmamk_f32 v114, v157, 0x3a000000, v151
	v_pk_mul_f32 v[112:113], v[116:117], v[112:113]
	v_rsq_f32_e32 v116, v114
	v_add_f32_e32 v119, 1.0, v119
	v_rcp_f32_e32 v118, v118
	v_rcp_f32_e32 v119, v119
	v_pk_mul_f32 v[108:109], v[116:117], v[108:109] op_sel_hi:[0,1]
	v_mul_f32_e32 v117, 0xbfb8aa3b, v108
	v_exp_f32_e32 v117, v117
	v_mul_f32_e32 v125, 0xbfb8aa3b, v109
	v_pk_mul_f32 v[112:113], v[118:119], v[112:113]
	v_exp_f32_e32 v125, v125
	v_cvt_pk_bf16_f32 v123, v112, v113
	v_mov_b64_e32 v[112:113], s[2:3]
	v_mad_i64_i32 v[118:119], s[14:15], v124, s46, v[112:113]
	v_lshlrev_b64 v[114:115], 1, v[162:163]
	v_lshl_add_u64 v[118:119], v[118:119], 0, v[114:115]
	v_add_f32_e32 v117, 1.0, v117
	global_store_dwordx4 v[118:119], v[120:123], off
	v_rcp_f32_e32 v118, v117
	v_add_f32_e32 v117, 1.0, v125
	v_rcp_f32_e32 v119, v117
	v_or_b32_e32 v117, 16, v124
	v_pk_mul_f32 v[104:105], v[116:117], v[104:105] op_sel_hi:[0,1]
	v_pk_mul_f32 v[104:105], v[108:109], v[104:105]
	v_pk_mul_f32 v[108:109], v[116:117], v[110:111] op_sel_hi:[0,1]
	v_pk_mul_f32 v[104:105], v[118:119], v[104:105]
	v_mul_f32_e32 v110, 0xbfb8aa3b, v108
	v_cvt_pk_bf16_f32 v104, v104, v105
	v_mul_f32_e32 v105, 0xbfb8aa3b, v109
	v_exp_f32_e32 v110, v110
	v_exp_f32_e32 v105, v105
	v_pk_mul_f32 v[106:107], v[116:117], v[106:107] op_sel_hi:[0,1]
	v_pk_mul_f32 v[100:101], v[116:117], v[100:101] op_sel_hi:[0,1]
	v_add_f32_e32 v110, 1.0, v110
	v_add_f32_e32 v105, 1.0, v105
	v_rcp_f32_e32 v110, v110
	v_rcp_f32_e32 v111, v105
	v_pk_mul_f32 v[106:107], v[108:109], v[106:107]
	v_mul_f32_e32 v105, 0xbfb8aa3b, v100
	v_exp_f32_e32 v118, v105
	v_pk_mul_f32 v[106:107], v[110:111], v[106:107]
	v_pk_mul_f32 v[96:97], v[116:117], v[96:97] op_sel_hi:[0,1]
	v_cvt_pk_bf16_f32 v105, v106, v107
	v_mul_f32_e32 v107, 0xbfb8aa3b, v101
	v_exp_f32_e32 v107, v107
	v_pk_mul_f32 v[96:97], v[100:101], v[96:97]
	v_add_f32_e32 v106, 1.0, v118
	v_rcp_f32_e32 v106, v106
	v_add_f32_e32 v100, 1.0, v107
	v_rcp_f32_e32 v107, v100
	v_pk_mul_f32 v[100:101], v[116:117], v[102:103] op_sel_hi:[0,1]
	v_mul_f32_e32 v102, 0xbfb8aa3b, v100
	v_mul_f32_e32 v103, 0xbfb8aa3b, v101
	v_exp_f32_e32 v102, v102
	v_exp_f32_e32 v103, v103
	v_pk_mul_f32 v[96:97], v[106:107], v[96:97]
	v_add_f32_e32 v102, 1.0, v102
	v_add_f32_e32 v103, 1.0, v103
	v_rcp_f32_e32 v102, v102
	v_rcp_f32_e32 v103, v103
	v_cvt_pk_bf16_f32 v106, v96, v97
	v_pk_mul_f32 v[96:97], v[116:117], v[98:99] op_sel_hi:[0,1]
	v_pk_mul_f32 v[96:97], v[100:101], v[96:97]
	v_mad_i64_i32 v[98:99], s[14:15], v117, s46, v[112:113]
	v_pk_mul_f32 v[96:97], v[102:103], v[96:97]
	v_lshl_add_u64 v[98:99], v[98:99], 0, v[114:115]
	v_cvt_pk_bf16_f32 v107, v96, v97
	v_fmamk_f32 v96, v156, 0x3a000000, v151
	v_rsq_f32_e32 v96, v96
	global_store_dwordx4 v[98:99], v[104:107], off
	v_pk_mul_f32 v[92:93], v[96:97], v[92:93] op_sel_hi:[0,1]
	v_mul_f32_e32 v97, 0xbfb8aa3b, v92
	v_exp_f32_e32 v97, v97
	v_mul_f32_e32 v100, 0xbfb8aa3b, v93
	v_exp_f32_e32 v100, v100
	v_add_f32_e32 v97, 1.0, v97
	v_rcp_f32_e32 v98, v97
	v_add_f32_e32 v97, 1.0, v100
	v_rcp_f32_e32 v99, v97
	v_or_b32_e32 v97, 32, v124
	v_pk_mul_f32 v[88:89], v[96:97], v[88:89] op_sel_hi:[0,1]
	v_pk_mul_f32 v[88:89], v[92:93], v[88:89]
	v_pk_mul_f32 v[92:93], v[96:97], v[94:95] op_sel_hi:[0,1]
	v_pk_mul_f32 v[88:89], v[98:99], v[88:89]
	v_mul_f32_e32 v94, 0xbfb8aa3b, v92
	v_cvt_pk_bf16_f32 v88, v88, v89
	v_mul_f32_e32 v89, 0xbfb8aa3b, v93
	v_exp_f32_e32 v94, v94
	v_exp_f32_e32 v89, v89
	v_pk_mul_f32 v[90:91], v[96:97], v[90:91] op_sel_hi:[0,1]
	v_pk_mul_f32 v[84:85], v[96:97], v[84:85] op_sel_hi:[0,1]
	v_add_f32_e32 v94, 1.0, v94
; __device__ __forceinline__ float sigmoidf_(float x) { return __builtin_amdgcn_rcpf(1.0f + fexp(-x)); }
;     __device__ __forceinline__ void operator()(const f32x4 (&acc)[2][2][4][2], const Unit& u, int wr, int wc, int fr, int fq, const Pre& P) const {
;         const int row0 = ROW_X + u.pm * BM + wr * 64 + fr, col0 = u.pn * HALF + wc * 32 + 8 * fq;
; #pragma unroll
;         for (int ai = 0; ai < 2; ++ai)
; #pragma unroll
;             for (int m = 0; m < 4; ++m) { const int r = row0 + ai * HALF + m * 16; const float rs = __builtin_amdgcn_rsqf(P.rs[ai * 4 + m] * (1.0f / DM) + RMS_EPS);
;                 float y[8];
; #pragma unroll
;                 for (int n = 0; n < 2; ++n)
; #pragma unroll
;                     for (int j = 0; j < 4; ++j) { const float a = acc[ai][0][m][n][j] * rs, b = acc[ai][1][m][n][j] * rs; y[n * 4 + j] = a * b * sigmoidf_(a); }
;                 u32x4 w; w.x = cvtpk(y[0], y[1]); w.y = cvtpk(y[2], y[3]); w.z = cvtpk(y[4], y[5]); w.w = cvtpk(y[6], y[7]);
;                 *(u32x4*)(O + (size_t)r * FF + col0) = w; }
	v_add_f32_e32 v89, 1.0, v89
	v_rcp_f32_e32 v94, v94
	v_rcp_f32_e32 v95, v89
	v_pk_mul_f32 v[90:91], v[92:93], v[90:91]
	v_mul_f32_e32 v89, 0xbfb8aa3b, v84
	v_exp_f32_e32 v98, v89
	v_pk_mul_f32 v[90:91], v[94:95], v[90:91]
	v_pk_mul_f32 v[80:81], v[96:97], v[80:81] op_sel_hi:[0,1]
	v_cvt_pk_bf16_f32 v89, v90, v91
	v_mul_f32_e32 v91, 0xbfb8aa3b, v85
	v_exp_f32_e32 v91, v91
	v_pk_mul_f32 v[80:81], v[84:85], v[80:81]
	v_add_f32_e32 v90, 1.0, v98
	v_rcp_f32_e32 v90, v90
	v_add_f32_e32 v84, 1.0, v91
	v_rcp_f32_e32 v91, v84
	v_pk_mul_f32 v[84:85], v[96:97], v[86:87] op_sel_hi:[0,1]
	v_mul_f32_e32 v86, 0xbfb8aa3b, v84
	v_mul_f32_e32 v87, 0xbfb8aa3b, v85
	v_exp_f32_e32 v86, v86
	v_exp_f32_e32 v87, v87
	v_pk_mul_f32 v[80:81], v[90:91], v[80:81]
	v_add_f32_e32 v86, 1.0, v86
	v_add_f32_e32 v87, 1.0, v87
	v_rcp_f32_e32 v86, v86
	v_rcp_f32_e32 v87, v87
	v_cvt_pk_bf16_f32 v90, v80, v81
	v_pk_mul_f32 v[80:81], v[96:97], v[82:83] op_sel_hi:[0,1]
	v_pk_mul_f32 v[80:81], v[84:85], v[80:81]
	v_mad_i64_i32 v[82:83], s[14:15], v97, s46, v[112:113]
	v_pk_mul_f32 v[80:81], v[86:87], v[80:81]
	v_lshl_add_u64 v[82:83], v[82:83], 0, v[114:115]
	v_cvt_pk_bf16_f32 v91, v80, v81
	v_fmamk_f32 v80, v155, 0x3a000000, v151
	v_rsq_f32_e32 v80, v80
	global_store_dwordx4 v[82:83], v[88:91], off
	v_pk_mul_f32 v[76:77], v[80:81], v[76:77] op_sel_hi:[0,1]
	v_mul_f32_e32 v81, 0xbfb8aa3b, v76
	v_exp_f32_e32 v81, v81
	v_mul_f32_e32 v84, 0xbfb8aa3b, v77
	v_exp_f32_e32 v84, v84
	v_add_f32_e32 v81, 1.0, v81
	v_rcp_f32_e32 v82, v81
	v_add_f32_e32 v81, 1.0, v84
	v_rcp_f32_e32 v83, v81
	v_or_b32_e32 v81, 48, v124
	v_pk_mul_f32 v[72:73], v[80:81], v[72:73] op_sel_hi:[0,1]
	v_pk_mul_f32 v[72:73], v[76:77], v[72:73]
	v_pk_mul_f32 v[76:77], v[80:81], v[78:79] op_sel_hi:[0,1]
	v_pk_mul_f32 v[72:73], v[82:83], v[72:73]
	v_mul_f32_e32 v78, 0xbfb8aa3b, v76
	v_cvt_pk_bf16_f32 v72, v72, v73
	v_mul_f32_e32 v73, 0xbfb8aa3b, v77
	v_exp_f32_e32 v78, v78
	v_exp_f32_e32 v73, v73
	v_pk_mul_f32 v[74:75], v[80:81], v[74:75] op_sel_hi:[0,1]
	v_pk_mul_f32 v[68:69], v[80:81], v[68:69] op_sel_hi:[0,1]
	v_add_f32_e32 v78, 1.0, v78
	v_add_f32_e32 v73, 1.0, v73
	v_rcp_f32_e32 v78, v78
	v_rcp_f32_e32 v79, v73
	v_pk_mul_f32 v[74:75], v[76:77], v[74:75]
	v_mul_f32_e32 v73, 0xbfb8aa3b, v68
	v_exp_f32_e32 v82, v73
	v_pk_mul_f32 v[74:75], v[78:79], v[74:75]
	v_pk_mul_f32 v[64:65], v[80:81], v[64:65] op_sel_hi:[0,1]
	v_cvt_pk_bf16_f32 v73, v74, v75
	v_mul_f32_e32 v75, 0xbfb8aa3b, v69
	v_exp_f32_e32 v75, v75
	v_pk_mul_f32 v[64:65], v[68:69], v[64:65]
	v_add_f32_e32 v74, 1.0, v82
	v_rcp_f32_e32 v74, v74
	v_add_f32_e32 v68, 1.0, v75
	v_rcp_f32_e32 v75, v68
	v_pk_mul_f32 v[68:69], v[80:81], v[70:71] op_sel_hi:[0,1]
	v_mul_f32_e32 v70, 0xbfb8aa3b, v68
	v_mul_f32_e32 v71, 0xbfb8aa3b, v69
	v_exp_f32_e32 v70, v70
	v_exp_f32_e32 v71, v71
	v_pk_mul_f32 v[64:65], v[74:75], v[64:65]
	v_add_f32_e32 v70, 1.0, v70
	v_add_f32_e32 v71, 1.0, v71
	v_rcp_f32_e32 v70, v70
	v_rcp_f32_e32 v71, v71
	v_cvt_pk_bf16_f32 v74, v64, v65
	v_pk_mul_f32 v[64:65], v[80:81], v[66:67] op_sel_hi:[0,1]
	v_pk_mul_f32 v[64:65], v[68:69], v[64:65]
	v_mad_i64_i32 v[66:67], s[14:15], v81, s46, v[112:113]
	v_pk_mul_f32 v[64:65], v[70:71], v[64:65]
	v_lshl_add_u64 v[66:67], v[66:67], 0, v[114:115]
	v_cvt_pk_bf16_f32 v75, v64, v65
	v_fmamk_f32 v64, v154, 0x3a000000, v151
	v_rsq_f32_e32 v64, v64
	global_store_dwordx4 v[66:67], v[72:75], off
	v_pk_mul_f32 v[60:61], v[64:65], v[60:61] op_sel_hi:[0,1]
	v_mul_f32_e32 v65, 0xbfb8aa3b, v60
	v_exp_f32_e32 v65, v65
	v_mul_f32_e32 v68, 0xbfb8aa3b, v61
	v_exp_f32_e32 v68, v68
	v_add_f32_e32 v65, 1.0, v65
	v_rcp_f32_e32 v66, v65
	v_add_f32_e32 v65, 1.0, v68
	v_rcp_f32_e32 v67, v65
	v_add_u32_e32 v65, 0x80, v124
	v_pk_mul_f32 v[56:57], v[64:65], v[56:57] op_sel_hi:[0,1]
	v_pk_mul_f32 v[56:57], v[60:61], v[56:57]
	v_pk_mul_f32 v[60:61], v[64:65], v[62:63] op_sel_hi:[0,1]
	v_pk_mul_f32 v[56:57], v[66:67], v[56:57]
	v_mul_f32_e32 v62, 0xbfb8aa3b, v60
	v_cvt_pk_bf16_f32 v56, v56, v57
	v_mul_f32_e32 v57, 0xbfb8aa3b, v61
	v_exp_f32_e32 v62, v62
	v_exp_f32_e32 v57, v57
	v_pk_mul_f32 v[58:59], v[64:65], v[58:59] op_sel_hi:[0,1]
	v_pk_mul_f32 v[52:53], v[64:65], v[52:53] op_sel_hi:[0,1]
	v_add_f32_e32 v62, 1.0, v62
	v_add_f32_e32 v57, 1.0, v57
	v_rcp_f32_e32 v62, v62
	v_rcp_f32_e32 v63, v57
	v_pk_mul_f32 v[58:59], v[60:61], v[58:59]
	v_mul_f32_e32 v57, 0xbfb8aa3b, v52
	v_exp_f32_e32 v66, v57
	v_pk_mul_f32 v[58:59], v[62:63], v[58:59]
	v_pk_mul_f32 v[48:49], v[64:65], v[48:49] op_sel_hi:[0,1]
	v_cvt_pk_bf16_f32 v57, v58, v59
	v_mul_f32_e32 v59, 0xbfb8aa3b, v53
	v_exp_f32_e32 v59, v59
	v_pk_mul_f32 v[48:49], v[52:53], v[48:49]
	v_add_f32_e32 v58, 1.0, v66
	v_rcp_f32_e32 v58, v58
	v_add_f32_e32 v52, 1.0, v59
	v_rcp_f32_e32 v59, v52
	v_pk_mul_f32 v[52:53], v[64:65], v[54:55] op_sel_hi:[0,1]
	v_mul_f32_e32 v54, 0xbfb8aa3b, v52
	v_mul_f32_e32 v55, 0xbfb8aa3b, v53
	v_exp_f32_e32 v54, v54
	v_exp_f32_e32 v55, v55
	v_pk_mul_f32 v[48:49], v[58:59], v[48:49]
	v_add_f32_e32 v54, 1.0, v54
	v_add_f32_e32 v55, 1.0, v55
	v_rcp_f32_e32 v54, v54
	v_rcp_f32_e32 v55, v55
	v_cvt_pk_bf16_f32 v58, v48, v49
	v_pk_mul_f32 v[48:49], v[64:65], v[50:51] op_sel_hi:[0,1]
	v_pk_mul_f32 v[48:49], v[52:53], v[48:49]
	v_mad_i64_i32 v[50:51], s[14:15], v65, s46, v[112:113]
	v_pk_mul_f32 v[48:49], v[54:55], v[48:49]
	v_lshl_add_u64 v[50:51], v[50:51], 0, v[114:115]
	v_cvt_pk_bf16_f32 v59, v48, v49
	v_fmamk_f32 v48, v153, 0x3a000000, v151
	v_rsq_f32_e32 v48, v48
	global_store_dwordx4 v[50:51], v[56:59], off
	v_pk_mul_f32 v[44:45], v[48:49], v[44:45] op_sel_hi:[0,1]
	v_mul_f32_e32 v49, 0xbfb8aa3b, v44
	v_exp_f32_e32 v49, v49
	v_mul_f32_e32 v52, 0xbfb8aa3b, v45
; __device__ __forceinline__ float sigmoidf_(float x) { return __builtin_amdgcn_rcpf(1.0f + fexp(-x)); }
; __device__ __forceinline__ PreRs load_rs(const float* ssq, int pm, int wr, int fr) { PreRs p;
; #pragma unroll
;     for (int ai = 0; ai < 2; ++ai)
; #pragma unroll
;         for (int m = 0; m < 4; ++m) p.rs[ai * 4 + m] = ssq[ROW_X + pm * BM + ai * HALF + wr * 64 + m * 16 + fr];
;     return p; }
;     __device__ __forceinline__ void operator()(const f32x4 (&acc)[2][2][4][2], const Unit& u, int wr, int wc, int fr, int fq, const Pre& P) const {
;         const int row0 = ROW_X + u.pm * BM + wr * 64 + fr, col0 = u.pn * HALF + wc * 32 + 8 * fq;
; #pragma unroll
;         for (int ai = 0; ai < 2; ++ai)
; #pragma unroll
;             for (int m = 0; m < 4; ++m) { const int r = row0 + ai * HALF + m * 16; const float rs = __builtin_amdgcn_rsqf(P.rs[ai * 4 + m] * (1.0f / DM) + RMS_EPS);
;                 float y[8];
; #pragma unroll
;                 for (int n = 0; n < 2; ++n)
; #pragma unroll
;                     for (int j = 0; j < 4; ++j) { const float a = acc[ai][0][m][n][j] * rs, b = acc[ai][1][m][n][j] * rs; y[n * 4 + j] = a * b * sigmoidf_(a); }
;                 u32x4 w; w.x = cvtpk(y[0], y[1]); w.y = cvtpk(y[2], y[3]); w.z = cvtpk(y[4], y[5]); w.w = cvtpk(y[6], y[7]);
;                 *(u32x4*)(O + (size_t)r * FF + col0) = w; }
	v_exp_f32_e32 v52, v52
	v_add_f32_e32 v49, 1.0, v49
	v_rcp_f32_e32 v50, v49
	v_add_f32_e32 v49, 1.0, v52
	v_rcp_f32_e32 v51, v49
	v_add_u32_e32 v49, 0x90, v124
	v_pk_mul_f32 v[40:41], v[48:49], v[40:41] op_sel_hi:[0,1]
	v_pk_mul_f32 v[40:41], v[44:45], v[40:41]
	v_pk_mul_f32 v[44:45], v[48:49], v[46:47] op_sel_hi:[0,1]
	v_pk_mul_f32 v[40:41], v[50:51], v[40:41]
	v_mul_f32_e32 v46, 0xbfb8aa3b, v44
	v_cvt_pk_bf16_f32 v40, v40, v41
	v_mul_f32_e32 v41, 0xbfb8aa3b, v45
	v_exp_f32_e32 v46, v46
	v_exp_f32_e32 v41, v41
	v_pk_mul_f32 v[42:43], v[48:49], v[42:43] op_sel_hi:[0,1]
	v_pk_mul_f32 v[36:37], v[48:49], v[36:37] op_sel_hi:[0,1]
	v_add_f32_e32 v46, 1.0, v46
	v_add_f32_e32 v41, 1.0, v41
	v_rcp_f32_e32 v46, v46
	v_rcp_f32_e32 v47, v41
	v_pk_mul_f32 v[42:43], v[44:45], v[42:43]
	v_mul_f32_e32 v41, 0xbfb8aa3b, v36
	v_exp_f32_e32 v50, v41
	v_pk_mul_f32 v[42:43], v[46:47], v[42:43]
	v_pk_mul_f32 v[32:33], v[48:49], v[32:33] op_sel_hi:[0,1]
	v_cvt_pk_bf16_f32 v41, v42, v43
	v_mul_f32_e32 v43, 0xbfb8aa3b, v37
	v_exp_f32_e32 v43, v43
	v_pk_mul_f32 v[32:33], v[36:37], v[32:33]
	v_add_f32_e32 v42, 1.0, v50
	v_rcp_f32_e32 v42, v42
	v_add_f32_e32 v36, 1.0, v43
	v_rcp_f32_e32 v43, v36
	v_pk_mul_f32 v[36:37], v[48:49], v[38:39] op_sel_hi:[0,1]
	v_mul_f32_e32 v38, 0xbfb8aa3b, v36
	v_mul_f32_e32 v39, 0xbfb8aa3b, v37
	v_exp_f32_e32 v38, v38
	v_exp_f32_e32 v39, v39
	v_pk_mul_f32 v[32:33], v[42:43], v[32:33]
	v_add_f32_e32 v38, 1.0, v38
	v_add_f32_e32 v39, 1.0, v39
	v_rcp_f32_e32 v38, v38
	v_rcp_f32_e32 v39, v39
	v_cvt_pk_bf16_f32 v42, v32, v33
	v_pk_mul_f32 v[32:33], v[48:49], v[34:35] op_sel_hi:[0,1]
	v_pk_mul_f32 v[32:33], v[36:37], v[32:33]
	v_mad_i64_i32 v[34:35], s[14:15], v49, s46, v[112:113]
	v_pk_mul_f32 v[32:33], v[38:39], v[32:33]
	v_lshl_add_u64 v[34:35], v[34:35], 0, v[114:115]
	v_cvt_pk_bf16_f32 v43, v32, v33
	v_fmamk_f32 v32, v152, 0x3a000000, v151
	v_rsq_f32_e32 v32, v32
	global_store_dwordx4 v[34:35], v[40:43], off
	v_pk_mul_f32 v[28:29], v[32:33], v[28:29] op_sel_hi:[0,1]
	v_mul_f32_e32 v33, 0xbfb8aa3b, v28
	v_exp_f32_e32 v33, v33
	v_mul_f32_e32 v36, 0xbfb8aa3b, v29
	v_exp_f32_e32 v36, v36
	v_add_f32_e32 v33, 1.0, v33
	v_rcp_f32_e32 v34, v33
	v_add_f32_e32 v33, 1.0, v36
	v_rcp_f32_e32 v35, v33
	v_add_u32_e32 v33, 0xa0, v124
	v_pk_mul_f32 v[24:25], v[32:33], v[24:25] op_sel_hi:[0,1]
	v_pk_mul_f32 v[24:25], v[28:29], v[24:25]
	v_pk_mul_f32 v[28:29], v[32:33], v[30:31] op_sel_hi:[0,1]
	v_pk_mul_f32 v[24:25], v[34:35], v[24:25]
	v_mul_f32_e32 v30, 0xbfb8aa3b, v28
	v_cvt_pk_bf16_f32 v24, v24, v25
	v_mul_f32_e32 v25, 0xbfb8aa3b, v29
	v_exp_f32_e32 v30, v30
	v_exp_f32_e32 v25, v25
	v_pk_mul_f32 v[26:27], v[32:33], v[26:27] op_sel_hi:[0,1]
	v_pk_mul_f32 v[20:21], v[32:33], v[20:21] op_sel_hi:[0,1]
	v_add_f32_e32 v30, 1.0, v30
	v_add_f32_e32 v25, 1.0, v25
	v_rcp_f32_e32 v30, v30
	v_rcp_f32_e32 v31, v25
	v_pk_mul_f32 v[26:27], v[28:29], v[26:27]
	v_mul_f32_e32 v25, 0xbfb8aa3b, v20
	v_exp_f32_e32 v34, v25
	v_pk_mul_f32 v[26:27], v[30:31], v[26:27]
	v_pk_mul_f32 v[16:17], v[32:33], v[16:17] op_sel_hi:[0,1]
	v_cvt_pk_bf16_f32 v25, v26, v27
	v_mul_f32_e32 v27, 0xbfb8aa3b, v21
	v_exp_f32_e32 v27, v27
	v_pk_mul_f32 v[16:17], v[20:21], v[16:17]
	v_add_f32_e32 v26, 1.0, v34
	v_rcp_f32_e32 v26, v26
	v_add_f32_e32 v20, 1.0, v27
	v_rcp_f32_e32 v27, v20
	v_pk_mul_f32 v[20:21], v[32:33], v[22:23] op_sel_hi:[0,1]
	v_mul_f32_e32 v22, 0xbfb8aa3b, v20
	v_mul_f32_e32 v23, 0xbfb8aa3b, v21
	v_exp_f32_e32 v22, v22
	v_exp_f32_e32 v23, v23
	v_pk_mul_f32 v[16:17], v[26:27], v[16:17]
	v_add_f32_e32 v22, 1.0, v22
	v_add_f32_e32 v23, 1.0, v23
	v_rcp_f32_e32 v22, v22
	v_rcp_f32_e32 v23, v23
	v_cvt_pk_bf16_f32 v26, v16, v17
	v_pk_mul_f32 v[16:17], v[32:33], v[18:19] op_sel_hi:[0,1]
	v_pk_mul_f32 v[16:17], v[20:21], v[16:17]
	v_mad_i64_i32 v[18:19], s[14:15], v33, s46, v[112:113]
	v_pk_mul_f32 v[16:17], v[22:23], v[16:17]
	v_lshl_add_u64 v[18:19], v[18:19], 0, v[114:115]
	v_cvt_pk_bf16_f32 v27, v16, v17
	v_fmamk_f32 v16, v147, 0x3a000000, v151
	v_rsq_f32_e32 v16, v16
	global_store_dwordx4 v[18:19], v[24:27], off
	v_pk_mul_f32 v[12:13], v[16:17], v[12:13] op_sel_hi:[0,1]
	v_mul_f32_e32 v17, 0xbfb8aa3b, v12
	v_exp_f32_e32 v17, v17
	v_mul_f32_e32 v20, 0xbfb8aa3b, v13
	v_exp_f32_e32 v20, v20
	v_add_f32_e32 v17, 1.0, v17
	v_rcp_f32_e32 v18, v17
	v_add_f32_e32 v17, 1.0, v20
	v_rcp_f32_e32 v19, v17
	v_add_u32_e32 v17, 0xb0, v124
	v_pk_mul_f32 v[8:9], v[16:17], v[8:9] op_sel_hi:[0,1]
	v_pk_mul_f32 v[8:9], v[12:13], v[8:9]
	v_pk_mul_f32 v[12:13], v[16:17], v[14:15] op_sel_hi:[0,1]
	v_pk_mul_f32 v[8:9], v[18:19], v[8:9]
	v_mul_f32_e32 v14, 0xbfb8aa3b, v12
	v_cvt_pk_bf16_f32 v8, v8, v9
	v_mul_f32_e32 v9, 0xbfb8aa3b, v13
	v_exp_f32_e32 v14, v14
	v_exp_f32_e32 v9, v9
	v_pk_mul_f32 v[10:11], v[16:17], v[10:11] op_sel_hi:[0,1]
	v_pk_mul_f32 v[4:5], v[16:17], v[4:5] op_sel_hi:[0,1]
	v_add_f32_e32 v14, 1.0, v14
	v_add_f32_e32 v9, 1.0, v9
	v_rcp_f32_e32 v14, v14
	v_rcp_f32_e32 v15, v9
	v_pk_mul_f32 v[10:11], v[12:13], v[10:11]
	v_mul_f32_e32 v9, 0xbfb8aa3b, v4
	v_exp_f32_e32 v18, v9
	v_pk_mul_f32 v[10:11], v[14:15], v[10:11]
	v_pk_mul_f32 v[0:1], v[16:17], v[0:1] op_sel_hi:[0,1]
	v_cvt_pk_bf16_f32 v9, v10, v11
	v_mul_f32_e32 v11, 0xbfb8aa3b, v5
	v_exp_f32_e32 v11, v11
	v_pk_mul_f32 v[0:1], v[4:5], v[0:1]
	v_add_f32_e32 v10, 1.0, v18
	v_rcp_f32_e32 v10, v10
	v_add_f32_e32 v4, 1.0, v11
	v_rcp_f32_e32 v11, v4
	v_pk_mul_f32 v[4:5], v[16:17], v[6:7] op_sel_hi:[0,1]
	v_mul_f32_e32 v6, 0xbfb8aa3b, v4
	v_mul_f32_e32 v7, 0xbfb8aa3b, v5
	v_exp_f32_e32 v6, v6
	v_exp_f32_e32 v7, v7
	v_pk_mul_f32 v[0:1], v[10:11], v[0:1]
	v_add_f32_e32 v6, 1.0, v6
	v_add_f32_e32 v7, 1.0, v7
	v_rcp_f32_e32 v6, v6
	v_rcp_f32_e32 v7, v7
	v_cvt_pk_bf16_f32 v10, v0, v1
	v_pk_mul_f32 v[0:1], v[16:17], v[2:3] op_sel_hi:[0,1]
	v_pk_mul_f32 v[0:1], v[4:5], v[0:1]
	s_nop 0
	v_pk_mul_f32 v[0:1], v[6:7], v[0:1]
	s_nop 0
	v_cvt_pk_bf16_f32 v11, v0, v1
	v_mad_i64_i32 v[0:1], s[14:15], v17, s46, v[112:113]
	v_lshl_add_u64 v[0:1], v[0:1], 0, v[114:115]
	s_mov_b64 s[14:15], -1
	global_store_dwordx4 v[0:1], v[8:11], off
	s_cbranch_vccz .LBB0_2542
	v_lshl_add_u32 v0, s8, 8, v144
	v_ashrrev_i32_e32 v1, 31, v0
	v_lshl_add_u64 v[2:3], v[0:1], 2, s[0:1]
	v_add_u32_e32 v4, 0x80, v0
	v_add_u32_e32 v6, 0x90, v0
	v_add_u32_e32 v8, 0xa0, v0
	v_add_u32_e32 v0, 0xb0, v0
	v_ashrrev_i32_e32 v5, 31, v4
	v_ashrrev_i32_e32 v7, 31, v6
	v_ashrrev_i32_e32 v9, 31, v8
	v_ashrrev_i32_e32 v1, 31, v0
	v_lshl_add_u64 v[4:5], v[4:5], 2, s[0:1]
	v_lshl_add_u64 v[6:7], v[6:7], 2, s[0:1]
	v_lshl_add_u64 v[8:9], v[8:9], 2, s[0:1]
	v_lshl_add_u64 v[0:1], v[0:1], 2, s[0:1]
	global_load_dword v158, v[2:3], off
	global_load_dword v157, v[2:3], off offset:64
	global_load_dword v156, v[2:3], off offset:128
	global_load_dword v155, v[2:3], off offset:192
	global_load_dword v154, v[4:5], off
	global_load_dword v153, v[6:7], off
	global_load_dword v152, v[8:9], off
	global_load_dword v147, v[0:1], off
	s_mov_b64 s[14:15], 0
	s_branch .LBB0_2542

; #define PG8_STAGE(bufoff, gbase, voff) do { _Pragma("unroll") for (int _i = 0; _i < 2; ++_i) \
;         __builtin_amdgcn_global_load_lds((const unsigned*)((const char*)(gbase) + (voff)[_i]), (LAS unsigned*)(lds + (bufoff) + ldsw + _i * 8192), 16, 0, 0); } while (0)
; #define PG8_LDA(dst, b, h) do { _Pragma("unroll") for (int m = 0; m < 4; ++m) _Pragma("unroll") for (int k = 0; k < 2; ++k) dst[m][k] = *(const LAS bf16x8*)(lds + PG8_SA(b, h) + aoff + m * 2048 + k * 1024); } while (0)
; #define PG8_LDB(dst, b, h) do { _Pragma("unroll") for (int n = 0; n < 2; ++n) _Pragma("unroll") for (int k = 0; k < 2; ++k) dst[n][k] = *(const LAS bf16x8*)(lds + PG8_SB(b, h) + boff + n * 2048 + k * 1024); } while (0)
; #define PG8_MMA(ai, bj, At, Bt) do { __builtin_amdgcn_s_setprio(1); _Pragma("unroll") for (int m = 0; m < 4; ++m) _Pragma("unroll") for (int n = 0; n < 2; ++n) _Pragma("unroll") for (int k = 0; k < 2; ++k) \
;         acc[ai][bj][m][n] = __builtin_amdgcn_mfma_f32_16x16x32_bf16(Bt[n][k], At[m][k], acc[ai][bj][m][n], 0, 0, 0); __builtin_amdgcn_s_setprio(0); } while (0)
; #define PG8_WAIT_L(n) asm volatile("s_waitcnt lgkmcnt(" #n ")" ::: "memory")
; #define PG8_BAR __builtin_amdgcn_s_barrier()
; #define PG8_SCHED __builtin_amdgcn_sched_barrier(0)
; template <class Epi>
; __device__ __forceinline__ void gemm_phase(LAS unsigned char* lds, const Gemm g, const StaticOrder& S, const Epi& E) {
;     ...
;             PG8_LDB(B0, 0, 0); PG8_SCHED; PG8_LDA(At, 0, 0); PG8_STAGE(PG8_SA(1, 1), a1 + hstep, voffA);
;             PG8_WAIT_L(8); PG8_BAR; PG8_WAIT_L(0); PG8_MMA(0, 0, At, B0); PG8_BAR; PG8_SCHED;
.LBB0_2626:
	ds_read_b128 v[144:147], v153
	ds_read_b128 v[156:159], v153 offset:1024
	ds_read_b128 v[160:163], v153 offset:2048
	ds_read_b128 v[164:167], v153 offset:3072
	s_add_u32 s20, s18, 0xffea8080
	s_addc_u32 s21, s19, -1
	s_cmpk_eq_i32 s64, 0x52
	s_cselect_b32 s23, s1, s21
	s_cselect_b32 s22, s0, s20
	s_cselect_b32 s21, s5, s63
	s_cselect_b32 s20, s4, s62
	v_lshl_add_u64 v[148:149], s[18:19], 0, v[136:137]
	s_add_i32 m0, s36, 0xc000
	ds_read_b128 v[168:171], v154
	ds_read_b128 v[172:175], v154 offset:1024
	ds_read_b128 v[176:179], v154 offset:2048
	ds_read_b128 v[180:183], v154 offset:3072
	ds_read_b128 v[184:187], v154 offset:4096
	ds_read_b128 v[188:191], v154 offset:5120
	ds_read_b128 v[192:195], v154 offset:6144
	ds_read_b128 v[196:199], v154 offset:7168
	global_load_lds_dwordx4 v[148:149], off
	v_lshl_add_u64 v[148:149], s[18:19], 0, v[138:139]
	s_add_i32 m0, s36, 0xe000
	s_nop 0
	global_load_lds_dwordx4 v[148:149], off
	s_waitcnt lgkmcnt(8)
	s_setprio 1
	s_barrier
	s_waitcnt lgkmcnt(0)


; #define PG8_MMA(ai, bj, At, Bt) do { __builtin_amdgcn_s_setprio(1); _Pragma("unroll") for (int m = 0; m < 4; ++m) _Pragma("unroll") for (int n = 0; n < 2; ++n) _Pragma("unroll") for (int k = 0; k < 2; ++k) \
;         acc[ai][bj][m][n] = __builtin_amdgcn_mfma_f32_16x16x32_bf16(Bt[n][k], At[m][k], acc[ai][bj][m][n], 0, 0, 0); __builtin_amdgcn_s_setprio(0); } while (0)
; #define PG8_WAIT_L(n) asm volatile("s_waitcnt lgkmcnt(" #n ")" ::: "memory")
; #define PG8_BAR __builtin_amdgcn_s_barrier()
; #define PG8_SCHED __builtin_amdgcn_sched_barrier(0)
; template <class Epi>
; __device__ __forceinline__ void gemm_phase(LAS unsigned char* lds, const Gemm g, const StaticOrder& S, const Epi& E) {
;     ...
;             PG8_WAIT_L(8); PG8_BAR; PG8_WAIT_L(0); PG8_MMA(0, 0, At, B0); PG8_BAR; PG8_SCHED;
	v_mfma_f32_16x16x32_bf16 v[124:127], v[144:147], v[168:171], v[124:127]
	v_mfma_f32_16x16x32_bf16 v[120:123], v[160:163], v[168:171], v[120:123]
	v_mfma_f32_16x16x32_bf16 v[112:115], v[144:147], v[176:179], v[112:115]
	v_mfma_f32_16x16x32_bf16 v[104:107], v[160:163], v[176:179], v[104:107]
	v_mfma_f32_16x16x32_bf16 v[92:95], v[144:147], v[184:187], v[92:95]
	v_mfma_f32_16x16x32_bf16 v[88:91], v[160:163], v[184:187], v[88:91]
	v_mfma_f32_16x16x32_bf16 v[80:83], v[144:147], v[192:195], v[80:83]
	v_mfma_f32_16x16x32_bf16 v[72:75], v[160:163], v[192:195], v[72:75]
	v_mfma_f32_16x16x32_bf16 v[124:127], v[156:159], v[172:175], v[124:127]
	v_mfma_f32_16x16x32_bf16 v[120:123], v[164:167], v[172:175], v[120:123]
	v_mfma_f32_16x16x32_bf16 v[112:115], v[156:159], v[180:183], v[112:115]
	v_mfma_f32_16x16x32_bf16 v[104:107], v[164:167], v[180:183], v[104:107]
	v_mfma_f32_16x16x32_bf16 v[92:95], v[156:159], v[188:191], v[92:95]
	v_mfma_f32_16x16x32_bf16 v[88:91], v[164:167], v[188:191], v[88:91]
	v_mfma_f32_16x16x32_bf16 v[80:83], v[156:159], v[196:199], v[80:83]
	v_mfma_f32_16x16x32_bf16 v[72:75], v[164:167], v[196:199], v[72:75]
	s_barrier
	s_setprio 0

; #define PG8_STAGE(bufoff, gbase, voff) do { _Pragma("unroll") for (int _i = 0; _i < 2; ++_i) \
;         __builtin_amdgcn_global_load_lds((const unsigned*)((const char*)(gbase) + (voff)[_i]), (LAS unsigned*)(lds + (bufoff) + ldsw + _i * 8192), 16, 0, 0); } while (0)
; #define PG8_LDB(dst, b, h) do { _Pragma("unroll") for (int n = 0; n < 2; ++n) _Pragma("unroll") for (int k = 0; k < 2; ++k) dst[n][k] = *(const LAS bf16x8*)(lds + PG8_SB(b, h) + boff + n * 2048 + k * 1024); } while (0)
; #define PG8_MMA(ai, bj, At, Bt) do { __builtin_amdgcn_s_setprio(1); _Pragma("unroll") for (int m = 0; m < 4; ++m) _Pragma("unroll") for (int n = 0; n < 2; ++n) _Pragma("unroll") for (int k = 0; k < 2; ++k) \
;         acc[ai][bj][m][n] = __builtin_amdgcn_mfma_f32_16x16x32_bf16(Bt[n][k], At[m][k], acc[ai][bj][m][n], 0, 0, 0); __builtin_amdgcn_s_setprio(0); } while (0)
; #define PG8_WAIT_L(n) asm volatile("s_waitcnt lgkmcnt(" #n ")" ::: "memory")
; #define PG8_BAR __builtin_amdgcn_s_barrier()
; template <class Epi>
; __device__ __forceinline__ void gemm_phase(LAS unsigned char* lds, const Gemm g, const StaticOrder& S, const Epi& E) {
;     ...
;             PG8_LDB(B1, 0, 1); PG8_STAGE(PG8_SB(0, 0), b2, voffB);
;             PG8_BAR; PG8_WAIT_L(0); PG8_MMA(0, 1, At, B1); PG8_BAR;
	s_add_i32 s65, s45, s35
	v_lshl_add_u64 v[148:149], s[20:21], 0, v[130:131]
	s_mov_b32 m0, s65
	ds_read_b128 v[200:203], v155
	ds_read_b128 v[204:207], v155 offset:1024
	ds_read_b128 v[208:211], v155 offset:2048
	ds_read_b128 v[212:215], v155 offset:3072
	global_load_lds_dwordx4 v[148:149], off
	v_lshl_add_u64 v[216:217], s[20:21], 0, v[134:135]
	s_add_i32 m0, s65, 0x2000
	s_nop 0
	global_load_lds_dwordx4 v[216:217], off
	s_waitcnt lgkmcnt(0)
	s_setprio 1
	s_barrier


; #define PG8_STAGE(bufoff, gbase, voff) do { _Pragma("unroll") for (int _i = 0; _i < 2; ++_i) \
;         __builtin_amdgcn_global_load_lds((const unsigned*)((const char*)(gbase) + (voff)[_i]), (LAS unsigned*)(lds + (bufoff) + ldsw + _i * 8192), 16, 0, 0); } while (0)
; #define PG8_LDA(dst, b, h) do { _Pragma("unroll") for (int m = 0; m < 4; ++m) _Pragma("unroll") for (int k = 0; k < 2; ++k) dst[m][k] = *(const LAS bf16x8*)(lds + PG8_SA(b, h) + aoff + m * 2048 + k * 1024); } while (0)
; #define PG8_MMA(ai, bj, At, Bt) do { __builtin_amdgcn_s_setprio(1); _Pragma("unroll") for (int m = 0; m < 4; ++m) _Pragma("unroll") for (int n = 0; n < 2; ++n) _Pragma("unroll") for (int k = 0; k < 2; ++k) \
;         acc[ai][bj][m][n] = __builtin_amdgcn_mfma_f32_16x16x32_bf16(Bt[n][k], At[m][k], acc[ai][bj][m][n], 0, 0, 0); __builtin_amdgcn_s_setprio(0); } while (0)
; #define PG8_WAIT_L(n) asm volatile("s_waitcnt lgkmcnt(" #n ")" ::: "memory")
; #define PG8_BAR __builtin_amdgcn_s_barrier()
; template <class Epi>
; __device__ __forceinline__ void gemm_phase(LAS unsigned char* lds, const Gemm g, const StaticOrder& S, const Epi& E) {
;     ...
;             PG8_BAR; PG8_WAIT_L(0); PG8_MMA(0, 1, At, B1); PG8_BAR;
;             PG8_LDA(At, 0, 1); PG8_STAGE(PG8_SA(0, 0), a2, voffA);
	v_mfma_f32_16x16x32_bf16 v[116:119], v[200:203], v[168:171], v[116:119]
	v_mfma_f32_16x16x32_bf16 v[108:111], v[208:211], v[168:171], v[108:111]
	v_mfma_f32_16x16x32_bf16 v[100:103], v[200:203], v[176:179], v[100:103]
	v_mfma_f32_16x16x32_bf16 v[96:99], v[208:211], v[176:179], v[96:99]
	v_mfma_f32_16x16x32_bf16 v[84:87], v[200:203], v[184:187], v[84:87]
	v_mfma_f32_16x16x32_bf16 v[76:79], v[208:211], v[184:187], v[76:79]
	v_mfma_f32_16x16x32_bf16 v[68:71], v[200:203], v[192:195], v[68:71]
	v_mfma_f32_16x16x32_bf16 v[64:67], v[208:211], v[192:195], v[64:67]
	v_mfma_f32_16x16x32_bf16 v[116:119], v[204:207], v[172:175], v[116:119]
	v_mfma_f32_16x16x32_bf16 v[108:111], v[212:215], v[172:175], v[108:111]
	v_mfma_f32_16x16x32_bf16 v[100:103], v[204:207], v[180:183], v[100:103]
	v_mfma_f32_16x16x32_bf16 v[96:99], v[212:215], v[180:183], v[96:99]
	v_mfma_f32_16x16x32_bf16 v[84:87], v[204:207], v[188:191], v[84:87]
	v_mfma_f32_16x16x32_bf16 v[76:79], v[212:215], v[188:191], v[76:79]
	v_mfma_f32_16x16x32_bf16 v[68:71], v[204:207], v[196:199], v[68:71]
	v_mfma_f32_16x16x32_bf16 v[64:67], v[212:215], v[196:199], v[64:67]
	s_barrier
	s_setprio 0
	s_mov_b32 m0, s36
	v_lshl_add_u64 v[218:219], s[22:23], 0, v[128:129]


; #define PG8_STAGE(bufoff, gbase, voff) do { _Pragma("unroll") for (int _i = 0; _i < 2; ++_i) \
;         __builtin_amdgcn_global_load_lds((const unsigned*)((const char*)(gbase) + (voff)[_i]), (LAS unsigned*)(lds + (bufoff) + ldsw + _i * 8192), 16, 0, 0); } while (0)
; #define PG8_LDA(dst, b, h) do { _Pragma("unroll") for (int m = 0; m < 4; ++m) _Pragma("unroll") for (int k = 0; k < 2; ++k) dst[m][k] = *(const LAS bf16x8*)(lds + PG8_SA(b, h) + aoff + m * 2048 + k * 1024); } while (0)
; #define PG8_MMA(ai, bj, At, Bt) do { __builtin_amdgcn_s_setprio(1); _Pragma("unroll") for (int m = 0; m < 4; ++m) _Pragma("unroll") for (int n = 0; n < 2; ++n) _Pragma("unroll") for (int k = 0; k < 2; ++k) \
;         acc[ai][bj][m][n] = __builtin_amdgcn_mfma_f32_16x16x32_bf16(Bt[n][k], At[m][k], acc[ai][bj][m][n], 0, 0, 0); __builtin_amdgcn_s_setprio(0); } while (0)
; #define PG8_WAIT_L(n) asm volatile("s_waitcnt lgkmcnt(" #n ")" ::: "memory")
; #define PG8_BAR __builtin_amdgcn_s_barrier()
; #define PG8_SCHED __builtin_amdgcn_sched_barrier(0)
; template <class Epi>
; __device__ __forceinline__ void gemm_phase(LAS unsigned char* lds, const Gemm g, const StaticOrder& S, const Epi& E) {
;     ...
;             PG8_LDA(At, 0, 1); PG8_STAGE(PG8_SA(0, 0), a2, voffA);
;             PG8_BAR; PG8_WAIT_L(0); PG8_MMA(1, 0, At, B0); PG8_BAR; PG8_SCHED;
	ds_read_b128 v[168:171], v154 offset:16384
	ds_read_b128 v[172:175], v154 offset:17408
	ds_read_b128 v[176:179], v154 offset:18432
	ds_read_b128 v[180:183], v154 offset:19456
	ds_read_b128 v[184:187], v154 offset:20480
	ds_read_b128 v[188:191], v154 offset:21504
	ds_read_b128 v[192:195], v154 offset:22528
	ds_read_b128 v[196:199], v154 offset:23552
	global_load_lds_dwordx4 v[218:219], off
	v_lshl_add_u64 v[220:221], s[22:23], 0, v[132:133]
	s_mov_b32 m0, s37
	s_nop 0
	global_load_lds_dwordx4 v[220:221], off
	s_waitcnt lgkmcnt(0)
	s_setprio 1
	s_barrier


; #define PG8_STAGE(bufoff, gbase, voff) do { _Pragma("unroll") for (int _i = 0; _i < 2; ++_i) \
;         __builtin_amdgcn_global_load_lds((const unsigned*)((const char*)(gbase) + (voff)[_i]), (LAS unsigned*)(lds + (bufoff) + ldsw + _i * 8192), 16, 0, 0); } while (0)
; #define PG8_MMA(ai, bj, At, Bt) do { __builtin_amdgcn_s_setprio(1); _Pragma("unroll") for (int m = 0; m < 4; ++m) _Pragma("unroll") for (int n = 0; n < 2; ++n) _Pragma("unroll") for (int k = 0; k < 2; ++k) \
;         acc[ai][bj][m][n] = __builtin_amdgcn_mfma_f32_16x16x32_bf16(Bt[n][k], At[m][k], acc[ai][bj][m][n], 0, 0, 0); __builtin_amdgcn_s_setprio(0); } while (0)
; #define PG8_WAIT_L(n) asm volatile("s_waitcnt lgkmcnt(" #n ")" ::: "memory")
; #define PG8_BAR __builtin_amdgcn_s_barrier()
; #define PG8_SCHED __builtin_amdgcn_sched_barrier(0)
; template <class Epi>
; __device__ __forceinline__ void gemm_phase(LAS unsigned char* lds, const Gemm g, const StaticOrder& S, const Epi& E) {
;     ...
;             PG8_BAR; PG8_WAIT_L(0); PG8_MMA(1, 0, At, B0); PG8_BAR; PG8_SCHED;
;             PG8_STAGE(PG8_SB(0, 1), b2 + hstep, voffB);
	v_mfma_f32_16x16x32_bf16 v[60:63], v[144:147], v[168:171], v[60:63]
	v_mfma_f32_16x16x32_bf16 v[56:59], v[160:163], v[168:171], v[56:59]
	v_mfma_f32_16x16x32_bf16 v[48:51], v[144:147], v[176:179], v[48:51]
	v_mfma_f32_16x16x32_bf16 v[40:43], v[160:163], v[176:179], v[40:43]
	v_mfma_f32_16x16x32_bf16 v[28:31], v[144:147], v[184:187], v[28:31]
	v_mfma_f32_16x16x32_bf16 v[24:27], v[160:163], v[184:187], v[24:27]
	v_mfma_f32_16x16x32_bf16 v[20:23], v[144:147], v[192:195], v[20:23]
	v_mfma_f32_16x16x32_bf16 v[12:15], v[160:163], v[192:195], v[12:15]
	v_mfma_f32_16x16x32_bf16 v[60:63], v[156:159], v[172:175], v[60:63]
	v_mfma_f32_16x16x32_bf16 v[56:59], v[164:167], v[172:175], v[56:59]
	v_mfma_f32_16x16x32_bf16 v[48:51], v[156:159], v[180:183], v[48:51]
	v_mfma_f32_16x16x32_bf16 v[40:43], v[164:167], v[180:183], v[40:43]
	v_mfma_f32_16x16x32_bf16 v[28:31], v[156:159], v[188:191], v[28:31]
	v_mfma_f32_16x16x32_bf16 v[24:27], v[164:167], v[188:191], v[24:27]
	v_mfma_f32_16x16x32_bf16 v[20:23], v[156:159], v[196:199], v[20:23]
	v_mfma_f32_16x16x32_bf16 v[12:15], v[164:167], v[196:199], v[12:15]
	s_barrier
	s_setprio 0

; #define PG8_STAGE(bufoff, gbase, voff) do { _Pragma("unroll") for (int _i = 0; _i < 2; ++_i) \
;         __builtin_amdgcn_global_load_lds((const unsigned*)((const char*)(gbase) + (voff)[_i]), (LAS unsigned*)(lds + (bufoff) + ldsw + _i * 8192), 16, 0, 0); } while (0)
; #define PG8_MMA(ai, bj, At, Bt) do { __builtin_amdgcn_s_setprio(1); _Pragma("unroll") for (int m = 0; m < 4; ++m) _Pragma("unroll") for (int n = 0; n < 2; ++n) _Pragma("unroll") for (int k = 0; k < 2; ++k) \
;         acc[ai][bj][m][n] = __builtin_amdgcn_mfma_f32_16x16x32_bf16(Bt[n][k], At[m][k], acc[ai][bj][m][n], 0, 0, 0); __builtin_amdgcn_s_setprio(0); } while (0)
; #define PG8_WAIT_V(n) asm volatile("s_waitcnt vmcnt(" #n ")" ::: "memory")
; #define PG8_BAR __builtin_amdgcn_s_barrier()
; template <class Epi>
; __device__ __forceinline__ void gemm_phase(LAS unsigned char* lds, const Gemm g, const StaticOrder& S, const Epi& E) {
;     ...
;             PG8_STAGE(PG8_SB(0, 1), b2 + hstep, voffB);
;             PG8_WAIT_V(6); PG8_BAR; PG8_MMA(1, 1, At, B1); PG8_BAR;
	s_add_u32 s66, s20, 0x158000
	s_addc_u32 s67, s21, 0
	s_add_i32 s65, s46, s35
	v_lshl_add_u64 v[144:145], s[66:67], 0, v[130:131]
	s_mov_b32 m0, s65
	s_nop 0
	global_load_lds_dwordx4 v[144:145], off
	v_lshl_add_u64 v[144:145], s[66:67], 0, v[134:135]
	s_add_i32 m0, s65, 0x2000
	s_nop 0
	global_load_lds_dwordx4 v[144:145], off
	s_waitcnt vmcnt(6)
	s_setprio 1
	s_barrier

; #define PG8_STAGE(bufoff, gbase, voff) do { _Pragma("unroll") for (int _i = 0; _i < 2; ++_i) \
;         __builtin_amdgcn_global_load_lds((const unsigned*)((const char*)(gbase) + (voff)[_i]), (LAS unsigned*)(lds + (bufoff) + ldsw + _i * 8192), 16, 0, 0); } while (0)
; #define PG8_LDA(dst, b, h) do { _Pragma("unroll") for (int m = 0; m < 4; ++m) _Pragma("unroll") for (int k = 0; k < 2; ++k) dst[m][k] = *(const LAS bf16x8*)(lds + PG8_SA(b, h) + aoff + m * 2048 + k * 1024); } while (0)
; #define PG8_LDB(dst, b, h) do { _Pragma("unroll") for (int n = 0; n < 2; ++n) _Pragma("unroll") for (int k = 0; k < 2; ++k) dst[n][k] = *(const LAS bf16x8*)(lds + PG8_SB(b, h) + boff + n * 2048 + k * 1024); } while (0)
; #define PG8_MMA(ai, bj, At, Bt) do { __builtin_amdgcn_s_setprio(1); _Pragma("unroll") for (int m = 0; m < 4; ++m) _Pragma("unroll") for (int n = 0; n < 2; ++n) _Pragma("unroll") for (int k = 0; k < 2; ++k) \
;         acc[ai][bj][m][n] = __builtin_amdgcn_mfma_f32_16x16x32_bf16(Bt[n][k], At[m][k], acc[ai][bj][m][n], 0, 0, 0); __builtin_amdgcn_s_setprio(0); } while (0)
; #define PG8_WAIT_V(n) asm volatile("s_waitcnt vmcnt(" #n ")" ::: "memory")
; #define PG8_BAR __builtin_amdgcn_s_barrier()
; #define PG8_SCHED __builtin_amdgcn_sched_barrier(0)
; template <class Epi>
; __device__ __forceinline__ void gemm_phase(LAS unsigned char* lds, const Gemm g, const StaticOrder& S, const Epi& E) {
;     ...
;             PG8_WAIT_V(6); PG8_BAR; PG8_MMA(1, 1, At, B1); PG8_BAR;
;             PG8_LDB(B0, 1, 0); PG8_SCHED; PG8_LDA(At, 1, 0); PG8_STAGE(PG8_SA(0, 1), a2 + hstep, voffA);
	v_mfma_f32_16x16x32_bf16 v[52:55], v[200:203], v[168:171], v[52:55]
	v_mfma_f32_16x16x32_bf16 v[44:47], v[208:211], v[168:171], v[44:47]
	v_mfma_f32_16x16x32_bf16 v[36:39], v[200:203], v[176:179], v[36:39]
	v_mfma_f32_16x16x32_bf16 v[32:35], v[208:211], v[176:179], v[32:35]
	v_mfma_f32_16x16x32_bf16 v[16:19], v[200:203], v[184:187], v[16:19]
	v_mfma_f32_16x16x32_bf16 v[8:11], v[208:211], v[184:187], v[8:11]
	v_mfma_f32_16x16x32_bf16 v[4:7], v[200:203], v[192:195], v[4:7]
	v_mfma_f32_16x16x32_bf16 v[0:3], v[208:211], v[192:195], v[0:3]
	v_mfma_f32_16x16x32_bf16 v[52:55], v[204:207], v[172:175], v[52:55]
	v_mfma_f32_16x16x32_bf16 v[44:47], v[212:215], v[172:175], v[44:47]
	v_mfma_f32_16x16x32_bf16 v[36:39], v[204:207], v[180:183], v[36:39]
	v_mfma_f32_16x16x32_bf16 v[32:35], v[212:215], v[180:183], v[32:35]
	v_mfma_f32_16x16x32_bf16 v[16:19], v[204:207], v[188:191], v[16:19]
	v_mfma_f32_16x16x32_bf16 v[8:11], v[212:215], v[188:191], v[8:11]
	v_mfma_f32_16x16x32_bf16 v[4:7], v[204:207], v[196:199], v[4:7]
	v_mfma_f32_16x16x32_bf16 v[0:3], v[212:215], v[196:199], v[0:3]
	s_barrier
	s_setprio 0
	s_add_i32 s65, 0, 0x18000
	v_add_u32_e32 v164, s65, v150


; #define PG8_STAGE(bufoff, gbase, voff) do { _Pragma("unroll") for (int _i = 0; _i < 2; ++_i) \
;         __builtin_amdgcn_global_load_lds((const unsigned*)((const char*)(gbase) + (voff)[_i]), (LAS unsigned*)(lds + (bufoff) + ldsw + _i * 8192), 16, 0, 0); } while (0)
; #define PG8_LDA(dst, b, h) do { _Pragma("unroll") for (int m = 0; m < 4; ++m) _Pragma("unroll") for (int k = 0; k < 2; ++k) dst[m][k] = *(const LAS bf16x8*)(lds + PG8_SA(b, h) + aoff + m * 2048 + k * 1024); } while (0)
; #define PG8_LDB(dst, b, h) do { _Pragma("unroll") for (int n = 0; n < 2; ++n) _Pragma("unroll") for (int k = 0; k < 2; ++k) dst[n][k] = *(const LAS bf16x8*)(lds + PG8_SB(b, h) + boff + n * 2048 + k * 1024); } while (0)
; #define PG8_MMA(ai, bj, At, Bt) do { __builtin_amdgcn_s_setprio(1); _Pragma("unroll") for (int m = 0; m < 4; ++m) _Pragma("unroll") for (int n = 0; n < 2; ++n) _Pragma("unroll") for (int k = 0; k < 2; ++k) \
;         acc[ai][bj][m][n] = __builtin_amdgcn_mfma_f32_16x16x32_bf16(Bt[n][k], At[m][k], acc[ai][bj][m][n], 0, 0, 0); __builtin_amdgcn_s_setprio(0); } while (0)
; #define PG8_WAIT_L(n) asm volatile("s_waitcnt lgkmcnt(" #n ")" ::: "memory")
; #define PG8_BAR __builtin_amdgcn_s_barrier()
; #define PG8_SCHED __builtin_amdgcn_sched_barrier(0)
; template <class Epi>
; __device__ __forceinline__ void gemm_phase(LAS unsigned char* lds, const Gemm g, const StaticOrder& S, const Epi& E) {
;     ...
;             PG8_LDB(B0, 1, 0); PG8_SCHED; PG8_LDA(At, 1, 0); PG8_STAGE(PG8_SA(0, 1), a2 + hstep, voffA);
;             PG8_WAIT_L(8); PG8_BAR; PG8_WAIT_L(0); PG8_MMA(0, 0, At, B0); PG8_BAR; PG8_SCHED;
	ds_read_b128 v[144:147], v164
	ds_read_b128 v[156:159], v164 offset:1024
	ds_read_b128 v[160:163], v164 offset:2048
	ds_read_b128 v[164:167], v164 offset:3072
	s_add_u32 s22, s22, 0x158000
	s_addc_u32 s23, s23, 0
	s_mov_b32 m0, s38
	v_lshl_add_u64 v[200:201], s[22:23], 0, v[128:129]
	ds_read_b128 v[168:171], v154 offset:32768
	ds_read_b128 v[172:175], v154 offset:33792
	ds_read_b128 v[176:179], v154 offset:34816
	ds_read_b128 v[180:183], v154 offset:35840
	ds_read_b128 v[184:187], v154 offset:36864
	ds_read_b128 v[188:191], v154 offset:37888
	ds_read_b128 v[192:195], v154 offset:38912
	ds_read_b128 v[196:199], v154 offset:39936
	global_load_lds_dwordx4 v[200:201], off
	v_lshl_add_u64 v[200:201], s[22:23], 0, v[132:133]
	s_mov_b32 m0, s39
	s_nop 0
	global_load_lds_dwordx4 v[200:201], off
	s_waitcnt lgkmcnt(8)
	s_setprio 1
	s_barrier
	s_waitcnt lgkmcnt(0)


; #define PG8_MMA(ai, bj, At, Bt) do { __builtin_amdgcn_s_setprio(1); _Pragma("unroll") for (int m = 0; m < 4; ++m) _Pragma("unroll") for (int n = 0; n < 2; ++n) _Pragma("unroll") for (int k = 0; k < 2; ++k) \
;         acc[ai][bj][m][n] = __builtin_amdgcn_mfma_f32_16x16x32_bf16(Bt[n][k], At[m][k], acc[ai][bj][m][n], 0, 0, 0); __builtin_amdgcn_s_setprio(0); } while (0)
; #define PG8_WAIT_L(n) asm volatile("s_waitcnt lgkmcnt(" #n ")" ::: "memory")
; #define PG8_BAR __builtin_amdgcn_s_barrier()
; #define PG8_SCHED __builtin_amdgcn_sched_barrier(0)
; template <class Epi>
; __device__ __forceinline__ void gemm_phase(LAS unsigned char* lds, const Gemm g, const StaticOrder& S, const Epi& E) {
;     ...
;             PG8_WAIT_L(8); PG8_BAR; PG8_WAIT_L(0); PG8_MMA(0, 0, At, B0); PG8_BAR; PG8_SCHED;
	v_mfma_f32_16x16x32_bf16 v[124:127], v[144:147], v[168:171], v[124:127]
	v_mfma_f32_16x16x32_bf16 v[120:123], v[160:163], v[168:171], v[120:123]
	v_mfma_f32_16x16x32_bf16 v[112:115], v[144:147], v[176:179], v[112:115]
	v_mfma_f32_16x16x32_bf16 v[104:107], v[160:163], v[176:179], v[104:107]
	v_mfma_f32_16x16x32_bf16 v[92:95], v[144:147], v[184:187], v[92:95]
	v_mfma_f32_16x16x32_bf16 v[88:91], v[160:163], v[184:187], v[88:91]
	v_mfma_f32_16x16x32_bf16 v[80:83], v[144:147], v[192:195], v[80:83]
	v_mfma_f32_16x16x32_bf16 v[72:75], v[160:163], v[192:195], v[72:75]
	v_mfma_f32_16x16x32_bf16 v[124:127], v[156:159], v[172:175], v[124:127]
	v_mfma_f32_16x16x32_bf16 v[120:123], v[164:167], v[172:175], v[120:123]
	v_mfma_f32_16x16x32_bf16 v[112:115], v[156:159], v[180:183], v[112:115]
	v_mfma_f32_16x16x32_bf16 v[104:107], v[164:167], v[180:183], v[104:107]
	v_mfma_f32_16x16x32_bf16 v[92:95], v[156:159], v[188:191], v[92:95]
	v_mfma_f32_16x16x32_bf16 v[88:91], v[164:167], v[188:191], v[88:91]
	v_mfma_f32_16x16x32_bf16 v[80:83], v[156:159], v[196:199], v[80:83]
	v_mfma_f32_16x16x32_bf16 v[72:75], v[164:167], v[196:199], v[72:75]
	s_barrier
	s_setprio 0

; #define PG8_STAGE(bufoff, gbase, voff) do { _Pragma("unroll") for (int _i = 0; _i < 2; ++_i) \
;         __builtin_amdgcn_global_load_lds((const unsigned*)((const char*)(gbase) + (voff)[_i]), (LAS unsigned*)(lds + (bufoff) + ldsw + _i * 8192), 16, 0, 0); } while (0)
; #define PG8_LDB(dst, b, h) do { _Pragma("unroll") for (int n = 0; n < 2; ++n) _Pragma("unroll") for (int k = 0; k < 2; ++k) dst[n][k] = *(const LAS bf16x8*)(lds + PG8_SB(b, h) + boff + n * 2048 + k * 1024); } while (0)
; #define PG8_MMA(ai, bj, At, Bt) do { __builtin_amdgcn_s_setprio(1); _Pragma("unroll") for (int m = 0; m < 4; ++m) _Pragma("unroll") for (int n = 0; n < 2; ++n) _Pragma("unroll") for (int k = 0; k < 2; ++k) \
;         acc[ai][bj][m][n] = __builtin_amdgcn_mfma_f32_16x16x32_bf16(Bt[n][k], At[m][k], acc[ai][bj][m][n], 0, 0, 0); __builtin_amdgcn_s_setprio(0); } while (0)
; #define PG8_WAIT_L(n) asm volatile("s_waitcnt lgkmcnt(" #n ")" ::: "memory")
; #define PG8_BAR __builtin_amdgcn_s_barrier()
; template <class Epi>
; __device__ __forceinline__ void gemm_phase(LAS unsigned char* lds, const Gemm g, const StaticOrder& S, const Epi& E) {
;     ...
;             PG8_LDB(B1, 1, 1); PG8_STAGE(PG8_SB(1, 0), b3, voffB);
;             PG8_BAR; PG8_WAIT_L(0); PG8_MMA(0, 1, At, B1); PG8_BAR;
	s_add_i32 s22, 0, 0x1c000
	s_add_i32 s23, s65, s35
	v_add_u32_e32 v212, s22, v150
	v_lshl_add_u64 v[148:149], v[148:149], 0, s[8:9]
	s_mov_b32 m0, s23
	ds_read_b128 v[200:203], v212
	ds_read_b128 v[204:207], v212 offset:1024
	ds_read_b128 v[208:211], v212 offset:2048
	ds_read_b128 v[212:215], v212 offset:3072
	global_load_lds_dwordx4 v[148:149], off
	v_lshl_add_u64 v[148:149], v[216:217], 0, s[8:9]
	s_add_i32 m0, s23, 0x2000
	s_nop 0
	global_load_lds_dwordx4 v[148:149], off
	s_waitcnt lgkmcnt(0)
	s_setprio 1
	s_barrier


; #define PG8_STAGE(bufoff, gbase, voff) do { _Pragma("unroll") for (int _i = 0; _i < 2; ++_i) \
;         __builtin_amdgcn_global_load_lds((const unsigned*)((const char*)(gbase) + (voff)[_i]), (LAS unsigned*)(lds + (bufoff) + ldsw + _i * 8192), 16, 0, 0); } while (0)
; #define PG8_LDA(dst, b, h) do { _Pragma("unroll") for (int m = 0; m < 4; ++m) _Pragma("unroll") for (int k = 0; k < 2; ++k) dst[m][k] = *(const LAS bf16x8*)(lds + PG8_SA(b, h) + aoff + m * 2048 + k * 1024); } while (0)
; #define PG8_MMA(ai, bj, At, Bt) do { __builtin_amdgcn_s_setprio(1); _Pragma("unroll") for (int m = 0; m < 4; ++m) _Pragma("unroll") for (int n = 0; n < 2; ++n) _Pragma("unroll") for (int k = 0; k < 2; ++k) \
;         acc[ai][bj][m][n] = __builtin_amdgcn_mfma_f32_16x16x32_bf16(Bt[n][k], At[m][k], acc[ai][bj][m][n], 0, 0, 0); __builtin_amdgcn_s_setprio(0); } while (0)
; #define PG8_WAIT_L(n) asm volatile("s_waitcnt lgkmcnt(" #n ")" ::: "memory")
; #define PG8_BAR __builtin_amdgcn_s_barrier()
; template <class Epi>
; __device__ __forceinline__ void gemm_phase(LAS unsigned char* lds, const Gemm g, const StaticOrder& S, const Epi& E) {
;     ...
;             PG8_BAR; PG8_WAIT_L(0); PG8_MMA(0, 1, At, B1); PG8_BAR;
;             PG8_LDA(At, 1, 1); PG8_STAGE(PG8_SA(1, 0), a3, voffA);
	v_mfma_f32_16x16x32_bf16 v[116:119], v[200:203], v[168:171], v[116:119]
	v_mfma_f32_16x16x32_bf16 v[108:111], v[208:211], v[168:171], v[108:111]
	v_mfma_f32_16x16x32_bf16 v[100:103], v[200:203], v[176:179], v[100:103]
	v_mfma_f32_16x16x32_bf16 v[96:99], v[208:211], v[176:179], v[96:99]
	v_mfma_f32_16x16x32_bf16 v[84:87], v[200:203], v[184:187], v[84:87]
	v_mfma_f32_16x16x32_bf16 v[76:79], v[208:211], v[184:187], v[76:79]
	v_mfma_f32_16x16x32_bf16 v[68:71], v[200:203], v[192:195], v[68:71]
	v_mfma_f32_16x16x32_bf16 v[64:67], v[208:211], v[192:195], v[64:67]
	v_mfma_f32_16x16x32_bf16 v[116:119], v[204:207], v[172:175], v[116:119]
	v_mfma_f32_16x16x32_bf16 v[108:111], v[212:215], v[172:175], v[108:111]
	v_mfma_f32_16x16x32_bf16 v[100:103], v[204:207], v[180:183], v[100:103]
	v_mfma_f32_16x16x32_bf16 v[96:99], v[212:215], v[180:183], v[96:99]
	v_mfma_f32_16x16x32_bf16 v[84:87], v[204:207], v[188:191], v[84:87]
	v_mfma_f32_16x16x32_bf16 v[76:79], v[212:215], v[188:191], v[76:79]
	v_mfma_f32_16x16x32_bf16 v[68:71], v[204:207], v[196:199], v[68:71]
	v_mfma_f32_16x16x32_bf16 v[64:67], v[212:215], v[196:199], v[64:67]
	s_barrier
	s_setprio 0
	s_mov_b32 m0, s41
	v_lshl_add_u64 v[148:149], v[218:219], 0, s[8:9]


; #define PG8_STAGE(bufoff, gbase, voff) do { _Pragma("unroll") for (int _i = 0; _i < 2; ++_i) \
;         __builtin_amdgcn_global_load_lds((const unsigned*)((const char*)(gbase) + (voff)[_i]), (LAS unsigned*)(lds + (bufoff) + ldsw + _i * 8192), 16, 0, 0); } while (0)
; #define PG8_LDA(dst, b, h) do { _Pragma("unroll") for (int m = 0; m < 4; ++m) _Pragma("unroll") for (int k = 0; k < 2; ++k) dst[m][k] = *(const LAS bf16x8*)(lds + PG8_SA(b, h) + aoff + m * 2048 + k * 1024); } while (0)
; #define PG8_MMA(ai, bj, At, Bt) do { __builtin_amdgcn_s_setprio(1); _Pragma("unroll") for (int m = 0; m < 4; ++m) _Pragma("unroll") for (int n = 0; n < 2; ++n) _Pragma("unroll") for (int k = 0; k < 2; ++k) \
;         acc[ai][bj][m][n] = __builtin_amdgcn_mfma_f32_16x16x32_bf16(Bt[n][k], At[m][k], acc[ai][bj][m][n], 0, 0, 0); __builtin_amdgcn_s_setprio(0); } while (0)
; #define PG8_WAIT_L(n) asm volatile("s_waitcnt lgkmcnt(" #n ")" ::: "memory")
; #define PG8_BAR __builtin_amdgcn_s_barrier()
; #define PG8_SCHED __builtin_amdgcn_sched_barrier(0)
; template <class Epi>
; __device__ __forceinline__ void gemm_phase(LAS unsigned char* lds, const Gemm g, const StaticOrder& S, const Epi& E) {
;     ...
;             PG8_LDA(At, 1, 1); PG8_STAGE(PG8_SA(1, 0), a3, voffA);
;             PG8_BAR; PG8_WAIT_L(0); PG8_MMA(1, 0, At, B0); PG8_BAR; PG8_SCHED;
	ds_read_b128 v[168:171], v154 offset:49152
	ds_read_b128 v[172:175], v154 offset:50176
	ds_read_b128 v[176:179], v154 offset:51200
	ds_read_b128 v[180:183], v154 offset:52224
	ds_read_b128 v[184:187], v154 offset:53248
	ds_read_b128 v[188:191], v154 offset:54272
	ds_read_b128 v[192:195], v154 offset:55296
	ds_read_b128 v[196:199], v154 offset:56320
	global_load_lds_dwordx4 v[148:149], off
	v_lshl_add_u64 v[148:149], v[220:221], 0, s[8:9]
	s_mov_b32 m0, s42
	s_nop 0
	global_load_lds_dwordx4 v[148:149], off
	s_waitcnt lgkmcnt(0)
	s_setprio 1
	s_barrier


; #define PG8_MMA(ai, bj, At, Bt) do { __builtin_amdgcn_s_setprio(1); _Pragma("unroll") for (int m = 0; m < 4; ++m) _Pragma("unroll") for (int n = 0; n < 2; ++n) _Pragma("unroll") for (int k = 0; k < 2; ++k) \
;         acc[ai][bj][m][n] = __builtin_amdgcn_mfma_f32_16x16x32_bf16(Bt[n][k], At[m][k], acc[ai][bj][m][n], 0, 0, 0); __builtin_amdgcn_s_setprio(0); } while (0)
; #define PG8_WAIT_L(n) asm volatile("s_waitcnt lgkmcnt(" #n ")" ::: "memory")
; #define PG8_BAR __builtin_amdgcn_s_barrier()
; #define PG8_SCHED __builtin_amdgcn_sched_barrier(0)
; template <class Epi>
; __device__ __forceinline__ void gemm_phase(LAS unsigned char* lds, const Gemm g, const StaticOrder& S, const Epi& E) {
;     ...
;             PG8_BAR; PG8_WAIT_L(0); PG8_MMA(1, 0, At, B0); PG8_BAR; PG8_SCHED;
	v_mfma_f32_16x16x32_bf16 v[60:63], v[144:147], v[168:171], v[60:63]
	v_mfma_f32_16x16x32_bf16 v[56:59], v[160:163], v[168:171], v[56:59]
	v_mfma_f32_16x16x32_bf16 v[48:51], v[144:147], v[176:179], v[48:51]
	v_mfma_f32_16x16x32_bf16 v[40:43], v[160:163], v[176:179], v[40:43]
	v_mfma_f32_16x16x32_bf16 v[28:31], v[144:147], v[184:187], v[28:31]
	v_mfma_f32_16x16x32_bf16 v[24:27], v[160:163], v[184:187], v[24:27]
	v_mfma_f32_16x16x32_bf16 v[20:23], v[144:147], v[192:195], v[20:23]
	v_mfma_f32_16x16x32_bf16 v[12:15], v[160:163], v[192:195], v[12:15]
	v_mfma_f32_16x16x32_bf16 v[60:63], v[156:159], v[172:175], v[60:63]
	v_mfma_f32_16x16x32_bf16 v[56:59], v[164:167], v[172:175], v[56:59]
	v_mfma_f32_16x16x32_bf16 v[48:51], v[156:159], v[180:183], v[48:51]
	v_mfma_f32_16x16x32_bf16 v[40:43], v[164:167], v[180:183], v[40:43]
	v_mfma_f32_16x16x32_bf16 v[28:31], v[156:159], v[188:191], v[28:31]
	v_mfma_f32_16x16x32_bf16 v[24:27], v[164:167], v[188:191], v[24:27]
	v_mfma_f32_16x16x32_bf16 v[20:23], v[156:159], v[196:199], v[20:23]
	v_mfma_f32_16x16x32_bf16 v[12:15], v[164:167], v[196:199], v[12:15]
	s_barrier
	s_setprio 0

; #define PG8_STAGE(bufoff, gbase, voff) do { _Pragma("unroll") for (int _i = 0; _i < 2; ++_i) \
;         __builtin_amdgcn_global_load_lds((const unsigned*)((const char*)(gbase) + (voff)[_i]), (LAS unsigned*)(lds + (bufoff) + ldsw + _i * 8192), 16, 0, 0); } while (0)
; #define PG8_MMA(ai, bj, At, Bt) do { __builtin_amdgcn_s_setprio(1); _Pragma("unroll") for (int m = 0; m < 4; ++m) _Pragma("unroll") for (int n = 0; n < 2; ++n) _Pragma("unroll") for (int k = 0; k < 2; ++k) \
;         acc[ai][bj][m][n] = __builtin_amdgcn_mfma_f32_16x16x32_bf16(Bt[n][k], At[m][k], acc[ai][bj][m][n], 0, 0, 0); __builtin_amdgcn_s_setprio(0); } while (0)
; #define PG8_WAIT_V(n) asm volatile("s_waitcnt vmcnt(" #n ")" ::: "memory")
; #define PG8_BAR __builtin_amdgcn_s_barrier()
; template <class Epi>
; __device__ __forceinline__ void gemm_phase(LAS unsigned char* lds, const Gemm g, const StaticOrder& S, const Epi& E) {
;     ...
;             PG8_STAGE(PG8_SB(1, 1), b3 + hstep, voffB);
;             PG8_WAIT_V(6); PG8_BAR; PG8_MMA(1, 1, At, B1); PG8_BAR;
	s_add_u32 s20, s20, 0x158080
	s_addc_u32 s21, s21, 0
	s_add_i32 s22, s22, s35
	v_lshl_add_u64 v[144:145], s[20:21], 0, v[130:131]
	s_mov_b32 m0, s22
	s_nop 0
	global_load_lds_dwordx4 v[144:145], off
	v_lshl_add_u64 v[144:145], s[20:21], 0, v[134:135]
	s_add_i32 m0, s22, 0x2000
	s_nop 0
	global_load_lds_dwordx4 v[144:145], off
	s_waitcnt vmcnt(6)
	s_setprio 1
	s_barrier

; #define PG8_MMA(ai, bj, At, Bt) do { __builtin_amdgcn_s_setprio(1); _Pragma("unroll") for (int m = 0; m < 4; ++m) _Pragma("unroll") for (int n = 0; n < 2; ++n) _Pragma("unroll") for (int k = 0; k < 2; ++k) \
;         acc[ai][bj][m][n] = __builtin_amdgcn_mfma_f32_16x16x32_bf16(Bt[n][k], At[m][k], acc[ai][bj][m][n], 0, 0, 0); __builtin_amdgcn_s_setprio(0); } while (0)
; #define PG8_WAIT_V(n) asm volatile("s_waitcnt vmcnt(" #n ")" ::: "memory")
; #define PG8_BAR __builtin_amdgcn_s_barrier()
; template <class Epi>
; __device__ __forceinline__ void gemm_phase(LAS unsigned char* lds, const Gemm g, const StaticOrder& S, const Epi& E) {
;     ...
;             PG8_WAIT_V(6); PG8_BAR; PG8_MMA(1, 1, At, B1); PG8_BAR;
;         }
	v_mfma_f32_16x16x32_bf16 v[52:55], v[200:203], v[168:171], v[52:55]
	v_mfma_f32_16x16x32_bf16 v[44:47], v[208:211], v[168:171], v[44:47]
	v_mfma_f32_16x16x32_bf16 v[36:39], v[200:203], v[176:179], v[36:39]
	v_mfma_f32_16x16x32_bf16 v[32:35], v[208:211], v[176:179], v[32:35]
	v_mfma_f32_16x16x32_bf16 v[16:19], v[200:203], v[184:187], v[16:19]
	v_mfma_f32_16x16x32_bf16 v[8:11], v[208:211], v[184:187], v[8:11]
	v_mfma_f32_16x16x32_bf16 v[4:7], v[200:203], v[192:195], v[4:7]
	v_mfma_f32_16x16x32_bf16 v[0:3], v[208:211], v[192:195], v[0:3]
	v_mfma_f32_16x16x32_bf16 v[52:55], v[204:207], v[172:175], v[52:55]
	v_mfma_f32_16x16x32_bf16 v[44:47], v[212:215], v[172:175], v[44:47]
	v_mfma_f32_16x16x32_bf16 v[36:39], v[204:207], v[180:183], v[36:39]
	v_mfma_f32_16x16x32_bf16 v[32:35], v[212:215], v[180:183], v[32:35]
	v_mfma_f32_16x16x32_bf16 v[16:19], v[204:207], v[188:191], v[16:19]
	v_mfma_f32_16x16x32_bf16 v[8:11], v[212:215], v[188:191], v[8:11]
	v_mfma_f32_16x16x32_bf16 v[4:7], v[204:207], v[196:199], v[4:7]
	v_mfma_f32_16x16x32_bf16 v[0:3], v[212:215], v[196:199], v[0:3]
	s_barrier
	s_setprio 0
	s_add_i32 s64, s64, 2
	s_add_u32 s18, s18, 0x100
	s_addc_u32 s19, s19, 0
	s_add_u32 s62, s62, 0x100
	s_addc_u32 s63, s63, 0
	s_cmpk_gt_u32 s64, 0x53


; __device__ __forceinline__ float bflo(unsigned w) { return __uint_as_float(w << 16); }
; __device__ __forceinline__ float bfhi(unsigned w) { return __uint_as_float(w & 0xffff0000u); }
; #define ER_LOAD(g_, set_) do { const size_t off_ = (size_t)(row0 + ((g_) >> 2) * HALF + ((g_) & 3) * 16) * DM + col0; \
;         hv[set_][0] = *(const u32x4*)(HB + off_); hv[set_][1] = *(const u32x4*)(HB + off_ + HALF); } while (0)
;     __device__ __forceinline__ void operator()(const f32x4 (&acc)[2][2][4][2], const Unit& u, int wr, int wc, int fr, int fq, const Pre&) const {
;         const int row0 = ROW_X + u.pm * BM + wr * 64 + fr, col0 = u.pn * BM + wc * 32 + 8 * fq;
;         u32x4 hv[2][2]; float sprev = 0.f;
;     ...
;         ER_LOAD(0, 0);
; #pragma unroll
;         for (int g = 0; g < 8; ++g) { const int ai = g >> 2, m = g & 3; const int r = row0 + ai * HALF + m * 16; const size_t off = (size_t)r * DM + col0; float s = 0.f;
;             if (g + 1 < 8) ER_LOAD(g + 1, (g + 1) & 1);
; #pragma unroll
;             for (int bj = 0; bj < 2; ++bj) { const u32x4 w = hv[g & 1][bj];
;                 const f32x4 h0 = {bflo(w.x), bfhi(w.x), bflo(w.y), bfhi(w.y)}, h1 = {bflo(w.z), bfhi(w.z), bflo(w.w), bfhi(w.w)};
;                 const f32x4 o0 = h0 + acc[ai][bj][m][0] * alpha, o1 = h1 + acc[ai][bj][m][1] * alpha;
;                 if (FINAL) { float* op = OUT + (size_t)(r - ROW_X) * DM + col0 + bj * HALF; *(f32x4*)op = o0; *(f32x4*)(op + 4) = o1; }
;                 else { u32x4 q; q.x = cvtpk(o0[0], o0[1]); q.y = cvtpk(o0[2], o0[3]); q.z = cvtpk(o1[0], o1[1]); q.w = cvtpk(o1[2], o1[3]); *(u32x4*)(HB + off + bj * HALF) = q;
;                        s += ((o0[0] * o0[0] + o0[1] * o0[1]) + (o0[2] * o0[2] + o0[3] * o0[3])) + ((o1[0] * o1[0] + o1[1] * o1[1]) + (o1[2] * o1[2] + o1[3] * o1[3])); } }
	s_cbranch_scc0 .LBB0_2626
	v_lshl_add_u32 v144, s60, 8, v151
	v_lshl_or_b32 v148, s61, 8, v152
	v_ashrrev_i32_e32 v145, 31, v144
	v_ashrrev_i32_e32 v149, 31, v148
	v_lshlrev_b64 v[146:147], 12, v[144:145]
	v_or_b32_e32 v164, 16, v144
	v_lshl_add_u64 v[146:147], s[6:7], 0, v[146:147]
	v_lshlrev_b64 v[172:173], 1, v[148:149]
	v_ashrrev_i32_e32 v165, 31, v164
	v_lshl_add_u64 v[146:147], v[146:147], 0, v[172:173]
	v_lshlrev_b64 v[164:165], 12, v[164:165]
	global_load_dwordx4 v[156:159], v[146:147], off
	global_load_dwordx4 v[160:163], v[146:147], off offset:256
	v_lshl_add_u64 v[164:165], s[6:7], 0, v[164:165]
	v_lshl_add_u64 v[168:169], v[164:165], 0, v[172:173]
	global_load_dwordx4 v[164:167], v[168:169], off
	s_nop 0
	global_load_dwordx4 v[168:171], v[168:169], off offset:256
	v_or_b32_e32 v176, 32, v144
	v_or_b32_e32 v180, 48, v144
	v_add_u32_e32 v174, 0xffffff00, v144
	v_ashrrev_i32_e32 v177, 31, v176
	v_ashrrev_i32_e32 v181, 31, v180
	v_ashrrev_i32_e32 v175, 31, v174
	v_lshlrev_b64 v[176:177], 12, v[176:177]
	v_lshlrev_b64 v[180:181], 12, v[180:181]
	v_add_u32_e32 v178, 0xffffff10, v144
	v_lshlrev_b64 v[174:175], 13, v[174:175]
	v_lshl_add_u64 v[176:177], s[6:7], 0, v[176:177]
	v_lshl_add_u64 v[180:181], s[6:7], 0, v[180:181]
	v_lshlrev_b64 v[148:149], 2, v[148:149]
	v_ashrrev_i32_e32 v179, 31, v178
	v_lshl_add_u64 v[174:175], s[48:49], 0, v[174:175]
	v_lshl_add_u64 v[176:177], v[176:177], 0, v[172:173]
	v_lshl_add_u64 v[172:173], v[180:181], 0, v[172:173]
	v_lshlrev_b64 v[178:179], 13, v[178:179]
	v_lshl_add_u64 v[174:175], v[174:175], 0, v[148:149]
	v_lshl_add_u64 v[178:179], s[48:49], 0, v[178:179]
	v_lshl_add_u64 v[178:179], v[178:179], 0, v[148:149]
	s_mov_b32 s60, s59
	s_mov_b32 s61, s58
	s_mov_b64 s[20:21], s[4:5]
	s_mov_b64 s[18:19], s[0:1]
	s_waitcnt vmcnt(0)
	v_lshlrev_b32_e32 v180, 16, v156
	v_and_b32_e32 v181, 0xffff0000, v156
	v_lshlrev_b32_e32 v156, 16, v157
	v_and_b32_e32 v157, 0xffff0000, v157
	v_lshlrev_b32_e32 v182, 16, v158
	v_and_b32_e32 v183, 0xffff0000, v158
	v_lshlrev_b32_e32 v158, 16, v159
	v_and_b32_e32 v159, 0xffff0000, v159
	v_lshlrev_b32_e32 v184, 16, v160
	v_and_b32_e32 v185, 0xffff0000, v160
	v_lshlrev_b32_e32 v160, 16, v161
	v_and_b32_e32 v161, 0xffff0000, v161
	v_lshlrev_b32_e32 v186, 16, v162
	v_and_b32_e32 v187, 0xffff0000, v162
	v_lshlrev_b32_e32 v162, 16, v163
	v_and_b32_e32 v163, 0xffff0000, v163
	v_pk_fma_f32 v[126:127], v[126:127], 0.5, v[156:157] op_sel_hi:[1,0,1]
	v_pk_fma_f32 v[124:125], v[124:125], 0.5, v[180:181] op_sel_hi:[1,0,1]
	v_pk_fma_f32 v[122:123], v[122:123], 0.5, v[158:159] op_sel_hi:[1,0,1]
	v_pk_fma_f32 v[120:121], v[120:121], 0.5, v[182:183] op_sel_hi:[1,0,1]
	v_pk_fma_f32 v[118:119], v[118:119], 0.5, v[160:161] op_sel_hi:[1,0,1]
	v_pk_fma_f32 v[116:117], v[116:117], 0.5, v[184:185] op_sel_hi:[1,0,1]
	v_pk_fma_f32 v[110:111], v[110:111], 0.5, v[162:163] op_sel_hi:[1,0,1]
	v_pk_fma_f32 v[108:109], v[108:109], 0.5, v[186:187] op_sel_hi:[1,0,1]
	v_lshlrev_b32_e32 v156, 16, v164
	v_and_b32_e32 v157, 0xffff0000, v164
	v_lshlrev_b32_e32 v158, 16, v165
	v_and_b32_e32 v159, 0xffff0000, v165
	global_store_dwordx4 v[174:175], v[124:127], off
	global_store_dwordx4 v[174:175], v[120:123], off offset:16
	global_store_dwordx4 v[174:175], v[116:119], off offset:512
	global_store_dwordx4 v[174:175], v[108:111], off offset:528
	v_lshlrev_b32_e32 v160, 16, v166
	v_and_b32_e32 v161, 0xffff0000, v166
	global_load_dwordx4 v[108:111], v[176:177], off
	global_load_dwordx4 v[116:119], v[176:177], off offset:256
	v_lshlrev_b32_e32 v120, 16, v167
	v_and_b32_e32 v121, 0xffff0000, v167
	v_lshlrev_b32_e32 v122, 16, v168
	v_and_b32_e32 v123, 0xffff0000, v168
	v_lshlrev_b32_e32 v124, 16, v169
	v_and_b32_e32 v125, 0xffff0000, v169
	v_lshlrev_b32_e32 v126, 16, v170
	v_and_b32_e32 v127, 0xffff0000, v170
	v_lshlrev_b32_e32 v162, 16, v171
	v_and_b32_e32 v163, 0xffff0000, v171
	v_pk_fma_f32 v[114:115], v[114:115], 0.5, v[158:159] op_sel_hi:[1,0,1]
	v_pk_fma_f32 v[112:113], v[112:113], 0.5, v[156:157] op_sel_hi:[1,0,1]
	v_pk_fma_f32 v[106:107], v[106:107], 0.5, v[120:121] op_sel_hi:[1,0,1]
	v_pk_fma_f32 v[104:105], v[104:105], 0.5, v[160:161] op_sel_hi:[1,0,1]
	v_pk_fma_f32 v[102:103], v[102:103], 0.5, v[124:125] op_sel_hi:[1,0,1]
	v_pk_fma_f32 v[100:101], v[100:101], 0.5, v[122:123] op_sel_hi:[1,0,1]
	v_pk_fma_f32 v[98:99], v[98:99], 0.5, v[162:163] op_sel_hi:[1,0,1]
	v_pk_fma_f32 v[96:97], v[96:97], 0.5, v[126:127] op_sel_hi:[1,0,1]
	global_store_dwordx4 v[178:179], v[112:115], off
	global_store_dwordx4 v[178:179], v[104:107], off offset:16
	global_store_dwordx4 v[178:179], v[100:103], off offset:512
	global_store_dwordx4 v[178:179], v[96:99], off offset:528
	global_load_dwordx4 v[96:99], v[172:173], off
	s_nop 0
	global_load_dwordx4 v[100:103], v[172:173], off offset:256
	v_add_u32_e32 v104, 0xffffff20, v144
	v_add_u32_e32 v106, 0xffffff30, v144
	v_ashrrev_i32_e32 v105, 31, v104
	v_ashrrev_i32_e32 v107, 31, v106
	v_lshlrev_b64 v[104:105], 13, v[104:105]
	v_lshlrev_b64 v[106:107], 13, v[106:107]
	v_lshl_add_u64 v[104:105], s[48:49], 0, v[104:105]
	v_add_co_u32_e32 v114, vcc, s47, v146
	v_lshl_add_u64 v[106:107], s[48:49], 0, v[106:107]
	v_lshl_add_u64 v[104:105], v[104:105], 0, v[148:149]
	v_addc_co_u32_e32 v115, vcc, 0, v147, vcc
	v_lshl_add_u64 v[112:113], v[146:147], 0, s[10:11]
	v_lshl_add_u64 v[106:107], v[106:107], 0, v[148:149]
	v_add_co_u32_e32 v120, vcc, s52, v146
	s_waitcnt vmcnt(0)
; __device__ __forceinline__ float bflo(unsigned w) { return __uint_as_float(w << 16); }
; __device__ __forceinline__ float bfhi(unsigned w) { return __uint_as_float(w & 0xffff0000u); }
; #define ER_LOAD(g_, set_) do { const size_t off_ = (size_t)(row0 + ((g_) >> 2) * HALF + ((g_) & 3) * 16) * DM + col0; \
;         hv[set_][0] = *(const u32x4*)(HB + off_); hv[set_][1] = *(const u32x4*)(HB + off_ + HALF); } while (0)
;     __device__ __forceinline__ void operator()(const f32x4 (&acc)[2][2][4][2], const Unit& u, int wr, int wc, int fr, int fq, const Pre&) const {
;         const int row0 = ROW_X + u.pm * BM + wr * 64 + fr, col0 = u.pn * BM + wc * 32 + 8 * fq;
;         u32x4 hv[2][2]; float sprev = 0.f;
;     ...
;         ER_LOAD(0, 0);
; #pragma unroll
;         for (int g = 0; g < 8; ++g) { const int ai = g >> 2, m = g & 3; const int r = row0 + ai * HALF + m * 16; const size_t off = (size_t)r * DM + col0; float s = 0.f;
;             if (g + 1 < 8) ER_LOAD(g + 1, (g + 1) & 1);
; #pragma unroll
;             for (int bj = 0; bj < 2; ++bj) { const u32x4 w = hv[g & 1][bj];
;                 const f32x4 h0 = {bflo(w.x), bfhi(w.x), bflo(w.y), bfhi(w.y)}, h1 = {bflo(w.z), bfhi(w.z), bflo(w.w), bfhi(w.w)};
;                 const f32x4 o0 = h0 + acc[ai][bj][m][0] * alpha, o1 = h1 + acc[ai][bj][m][1] * alpha;
;                 if (FINAL) { float* op = OUT + (size_t)(r - ROW_X) * DM + col0 + bj * HALF; *(f32x4*)op = o0; *(f32x4*)(op + 4) = o1; }
;                 else { u32x4 q; q.x = cvtpk(o0[0], o0[1]); q.y = cvtpk(o0[2], o0[3]); q.z = cvtpk(o1[0], o1[1]); q.w = cvtpk(o1[2], o1[3]); *(u32x4*)(HB + off + bj * HALF) = q;
;                        s += ((o0[0] * o0[0] + o0[1] * o0[1]) + (o0[2] * o0[2] + o0[3] * o0[3])) + ((o1[0] * o1[0] + o1[1] * o1[1]) + (o1[2] * o1[2] + o1[3] * o1[3])); } }
	v_lshlrev_b32_e32 v122, 16, v108
	v_and_b32_e32 v123, 0xffff0000, v108
	v_lshlrev_b32_e32 v108, 16, v109
	v_and_b32_e32 v109, 0xffff0000, v109
	v_lshlrev_b32_e32 v124, 16, v110
	v_and_b32_e32 v125, 0xffff0000, v110
	v_lshlrev_b32_e32 v110, 16, v111
	v_and_b32_e32 v111, 0xffff0000, v111
	v_lshlrev_b32_e32 v126, 16, v116
	v_and_b32_e32 v127, 0xffff0000, v116
	v_lshlrev_b32_e32 v116, 16, v117
	v_and_b32_e32 v117, 0xffff0000, v117
	v_lshlrev_b32_e32 v156, 16, v118
	v_and_b32_e32 v157, 0xffff0000, v118
	v_lshlrev_b32_e32 v118, 16, v119
	v_and_b32_e32 v119, 0xffff0000, v119
	v_pk_fma_f32 v[94:95], v[94:95], 0.5, v[108:109] op_sel_hi:[1,0,1]
	v_pk_fma_f32 v[92:93], v[92:93], 0.5, v[122:123] op_sel_hi:[1,0,1]
	v_pk_fma_f32 v[90:91], v[90:91], 0.5, v[110:111] op_sel_hi:[1,0,1]
	v_pk_fma_f32 v[88:89], v[88:89], 0.5, v[124:125] op_sel_hi:[1,0,1]
	v_lshlrev_b32_e32 v108, 16, v96
	v_and_b32_e32 v109, 0xffff0000, v96
	v_lshlrev_b32_e32 v96, 16, v97
	v_and_b32_e32 v97, 0xffff0000, v97
	v_pk_fma_f32 v[86:87], v[86:87], 0.5, v[116:117] op_sel_hi:[1,0,1]
	v_pk_fma_f32 v[84:85], v[84:85], 0.5, v[126:127] op_sel_hi:[1,0,1]
	v_pk_fma_f32 v[78:79], v[78:79], 0.5, v[118:119] op_sel_hi:[1,0,1]
	v_pk_fma_f32 v[76:77], v[76:77], 0.5, v[156:157] op_sel_hi:[1,0,1]
	v_lshlrev_b32_e32 v110, 16, v98
	v_and_b32_e32 v111, 0xffff0000, v98
	global_store_dwordx4 v[104:105], v[92:95], off
	global_store_dwordx4 v[104:105], v[88:91], off offset:16
	global_store_dwordx4 v[104:105], v[84:87], off offset:512
	global_store_dwordx4 v[104:105], v[76:79], off offset:528
	v_lshlrev_b32_e32 v88, 16, v99
	v_and_b32_e32 v89, 0xffff0000, v99
	v_lshlrev_b32_e32 v90, 16, v100
	v_and_b32_e32 v91, 0xffff0000, v100
	v_lshlrev_b32_e32 v92, 16, v101
	v_and_b32_e32 v93, 0xffff0000, v101
	v_lshlrev_b32_e32 v94, 16, v102
	v_and_b32_e32 v95, 0xffff0000, v102
	v_lshlrev_b32_e32 v98, 16, v103
	v_and_b32_e32 v99, 0xffff0000, v103
	v_pk_fma_f32 v[82:83], v[82:83], 0.5, v[96:97] op_sel_hi:[1,0,1]
	v_pk_fma_f32 v[80:81], v[80:81], 0.5, v[108:109] op_sel_hi:[1,0,1]
	v_addc_co_u32_e32 v121, vcc, 0, v147, vcc
	global_load_dwordx4 v[76:79], v[114:115], off
	global_load_dwordx4 v[84:87], v[112:113], off offset:256
	v_pk_fma_f32 v[74:75], v[74:75], 0.5, v[88:89] op_sel_hi:[1,0,1]
	v_pk_fma_f32 v[72:73], v[72:73], 0.5, v[110:111] op_sel_hi:[1,0,1]
	v_pk_fma_f32 v[70:71], v[70:71], 0.5, v[92:93] op_sel_hi:[1,0,1]
	v_pk_fma_f32 v[68:69], v[68:69], 0.5, v[90:91] op_sel_hi:[1,0,1]
	v_pk_fma_f32 v[66:67], v[66:67], 0.5, v[98:99] op_sel_hi:[1,0,1]
	v_pk_fma_f32 v[64:65], v[64:65], 0.5, v[94:95] op_sel_hi:[1,0,1]
	global_store_dwordx4 v[106:107], v[80:83], off
	global_store_dwordx4 v[106:107], v[72:75], off offset:16
	global_store_dwordx4 v[106:107], v[68:71], off offset:512
	global_store_dwordx4 v[106:107], v[64:67], off offset:528
	global_load_dwordx4 v[64:67], v[120:121], off
	v_lshl_add_u64 v[68:69], v[146:147], 0, s[12:13]
	global_load_dwordx4 v[68:71], v[68:69], off offset:256
	v_add_u32_e32 v72, 0xffffff80, v144
	v_add_u32_e32 v74, 0xffffff90, v144
	v_ashrrev_i32_e32 v73, 31, v72
	v_ashrrev_i32_e32 v75, 31, v74
	v_lshlrev_b64 v[72:73], 13, v[72:73]
	v_lshlrev_b64 v[74:75], 13, v[74:75]
	v_lshl_add_u64 v[72:73], s[48:49], 0, v[72:73]
	v_add_co_u32_e32 v82, vcc, s56, v146
	v_lshl_add_u64 v[74:75], s[48:49], 0, v[74:75]
	v_lshl_add_u64 v[72:73], v[72:73], 0, v[148:149]
	v_addc_co_u32_e32 v83, vcc, 0, v147, vcc
	v_lshl_add_u64 v[80:81], v[146:147], 0, s[14:15]
	v_lshl_add_u64 v[74:75], v[74:75], 0, v[148:149]
	v_add_co_u32_e32 v88, vcc, s57, v146
	s_waitcnt vmcnt(0)
; __device__ __forceinline__ float bflo(unsigned w) { return __uint_as_float(w << 16); }
; __device__ __forceinline__ float bfhi(unsigned w) { return __uint_as_float(w & 0xffff0000u); }
; #define PG8_WAIT_V(n) asm volatile("s_waitcnt vmcnt(" #n ")" ::: "memory")
; #define PG8_BAR __builtin_amdgcn_s_barrier()
; #define ER_LOAD(g_, set_) do { const size_t off_ = (size_t)(row0 + ((g_) >> 2) * HALF + ((g_) & 3) * 16) * DM + col0; \
;         hv[set_][0] = *(const u32x4*)(HB + off_); hv[set_][1] = *(const u32x4*)(HB + off_ + HALF); } while (0)
; template <class Epi>
; __device__ __forceinline__ void gemm_phase(LAS unsigned char* lds, const Gemm g, const StaticOrder& S, const Epi& E) {
;     ...
;         cur = nxt; cA = nA; cB = nB; ++ui;
;     }
;     PG8_WAIT_V(0);
;     if (wr == 0) PG8_BAR;
;     __device__ __forceinline__ void operator()(const f32x4 (&acc)[2][2][4][2], const Unit& u, int wr, int wc, int fr, int fq, const Pre&) const {
;         const int row0 = ROW_X + u.pm * BM + wr * 64 + fr, col0 = u.pn * BM + wc * 32 + 8 * fq;
;         u32x4 hv[2][2]; float sprev = 0.f;
;     ...
;         ER_LOAD(0, 0);
; #pragma unroll
;         for (int g = 0; g < 8; ++g) { const int ai = g >> 2, m = g & 3; const int r = row0 + ai * HALF + m * 16; const size_t off = (size_t)r * DM + col0; float s = 0.f;
;             if (g + 1 < 8) ER_LOAD(g + 1, (g + 1) & 1);
; #pragma unroll
;             for (int bj = 0; bj < 2; ++bj) { const u32x4 w = hv[g & 1][bj];
;                 const f32x4 h0 = {bflo(w.x), bfhi(w.x), bflo(w.y), bfhi(w.y)}, h1 = {bflo(w.z), bfhi(w.z), bflo(w.w), bfhi(w.w)};
;                 const f32x4 o0 = h0 + acc[ai][bj][m][0] * alpha, o1 = h1 + acc[ai][bj][m][1] * alpha;
;                 if (FINAL) { float* op = OUT + (size_t)(r - ROW_X) * DM + col0 + bj * HALF; *(f32x4*)op = o0; *(f32x4*)(op + 4) = o1; }
;                 else { u32x4 q; q.x = cvtpk(o0[0], o0[1]); q.y = cvtpk(o0[2], o0[3]); q.z = cvtpk(o1[0], o1[1]); q.w = cvtpk(o1[2], o1[3]); *(u32x4*)(HB + off + bj * HALF) = q;
;                        s += ((o0[0] * o0[0] + o0[1] * o0[1]) + (o0[2] * o0[2] + o0[3] * o0[3])) + ((o1[0] * o1[0] + o1[1] * o1[1]) + (o1[2] * o1[2] + o1[3] * o1[3])); } }
	v_lshlrev_b32_e32 v90, 16, v76
	v_and_b32_e32 v91, 0xffff0000, v76
	v_lshlrev_b32_e32 v76, 16, v77
	v_and_b32_e32 v77, 0xffff0000, v77
	v_lshlrev_b32_e32 v92, 16, v78
	v_and_b32_e32 v93, 0xffff0000, v78
	v_lshlrev_b32_e32 v78, 16, v79
	v_and_b32_e32 v79, 0xffff0000, v79
	v_lshlrev_b32_e32 v94, 16, v84
	v_and_b32_e32 v95, 0xffff0000, v84
	v_lshlrev_b32_e32 v84, 16, v85
	v_and_b32_e32 v85, 0xffff0000, v85
	v_lshlrev_b32_e32 v96, 16, v86
	v_and_b32_e32 v97, 0xffff0000, v86
	v_lshlrev_b32_e32 v86, 16, v87
	v_and_b32_e32 v87, 0xffff0000, v87
	v_pk_fma_f32 v[62:63], v[62:63], 0.5, v[76:77] op_sel_hi:[1,0,1]
	v_pk_fma_f32 v[60:61], v[60:61], 0.5, v[90:91] op_sel_hi:[1,0,1]
	v_pk_fma_f32 v[58:59], v[58:59], 0.5, v[78:79] op_sel_hi:[1,0,1]
	v_pk_fma_f32 v[56:57], v[56:57], 0.5, v[92:93] op_sel_hi:[1,0,1]
	v_lshlrev_b32_e32 v76, 16, v64
	v_and_b32_e32 v77, 0xffff0000, v64
	v_lshlrev_b32_e32 v64, 16, v65
	v_and_b32_e32 v65, 0xffff0000, v65
	v_pk_fma_f32 v[54:55], v[54:55], 0.5, v[84:85] op_sel_hi:[1,0,1]
	v_pk_fma_f32 v[52:53], v[52:53], 0.5, v[94:95] op_sel_hi:[1,0,1]
	v_pk_fma_f32 v[46:47], v[46:47], 0.5, v[86:87] op_sel_hi:[1,0,1]
	v_pk_fma_f32 v[44:45], v[44:45], 0.5, v[96:97] op_sel_hi:[1,0,1]
	v_lshlrev_b32_e32 v78, 16, v66
	v_and_b32_e32 v79, 0xffff0000, v66
	global_store_dwordx4 v[72:73], v[60:63], off
	global_store_dwordx4 v[72:73], v[56:59], off offset:16
	global_store_dwordx4 v[72:73], v[52:55], off offset:512
	global_store_dwordx4 v[72:73], v[44:47], off offset:528
	v_lshlrev_b32_e32 v56, 16, v67
	v_and_b32_e32 v57, 0xffff0000, v67
	v_lshlrev_b32_e32 v58, 16, v68
	v_and_b32_e32 v59, 0xffff0000, v68
	v_lshlrev_b32_e32 v60, 16, v69
	v_and_b32_e32 v61, 0xffff0000, v69
	v_lshlrev_b32_e32 v62, 16, v70
	v_and_b32_e32 v63, 0xffff0000, v70
	v_lshlrev_b32_e32 v66, 16, v71
	v_and_b32_e32 v67, 0xffff0000, v71
	v_pk_fma_f32 v[50:51], v[50:51], 0.5, v[64:65] op_sel_hi:[1,0,1]
	v_pk_fma_f32 v[48:49], v[48:49], 0.5, v[76:77] op_sel_hi:[1,0,1]
	v_addc_co_u32_e32 v89, vcc, 0, v147, vcc
	global_load_dwordx4 v[44:47], v[82:83], off
	global_load_dwordx4 v[52:55], v[80:81], off offset:256
	v_pk_fma_f32 v[42:43], v[42:43], 0.5, v[56:57] op_sel_hi:[1,0,1]
	v_pk_fma_f32 v[40:41], v[40:41], 0.5, v[78:79] op_sel_hi:[1,0,1]
	v_pk_fma_f32 v[38:39], v[38:39], 0.5, v[60:61] op_sel_hi:[1,0,1]
	v_pk_fma_f32 v[36:37], v[36:37], 0.5, v[58:59] op_sel_hi:[1,0,1]
	v_pk_fma_f32 v[34:35], v[34:35], 0.5, v[66:67] op_sel_hi:[1,0,1]
	v_pk_fma_f32 v[32:33], v[32:33], 0.5, v[62:63] op_sel_hi:[1,0,1]
	global_store_dwordx4 v[74:75], v[48:51], off
	global_store_dwordx4 v[74:75], v[40:43], off offset:16
	global_store_dwordx4 v[74:75], v[36:39], off offset:512
	global_store_dwordx4 v[74:75], v[32:35], off offset:528
	global_load_dwordx4 v[32:35], v[88:89], off
	v_lshl_add_u64 v[36:37], v[146:147], 0, s[16:17]
	global_load_dwordx4 v[36:39], v[36:37], off offset:256
	v_add_u32_e32 v40, 0xffffffa0, v144
	v_add_u32_e32 v42, 0xffffffb0, v144
	v_ashrrev_i32_e32 v41, 31, v40
	v_ashrrev_i32_e32 v43, 31, v42
	v_lshlrev_b64 v[40:41], 13, v[40:41]
	v_lshlrev_b64 v[42:43], 13, v[42:43]
	v_lshl_add_u64 v[40:41], s[48:49], 0, v[40:41]
	v_lshl_add_u64 v[42:43], s[48:49], 0, v[42:43]
	v_lshl_add_u64 v[40:41], v[40:41], 0, v[148:149]
	s_and_b64 vcc, exec, s[2:3]
	v_lshl_add_u64 v[42:43], v[42:43], 0, v[148:149]
	s_waitcnt vmcnt(0)
	v_lshlrev_b32_e32 v48, 16, v44
	v_and_b32_e32 v49, 0xffff0000, v44
	v_lshlrev_b32_e32 v44, 16, v45
	v_and_b32_e32 v45, 0xffff0000, v45
	v_lshlrev_b32_e32 v58, 16, v54
	v_and_b32_e32 v59, 0xffff0000, v54
	v_lshlrev_b32_e32 v54, 16, v55
	v_and_b32_e32 v55, 0xffff0000, v55
	v_lshlrev_b32_e32 v50, 16, v46
	v_and_b32_e32 v51, 0xffff0000, v46
	v_lshlrev_b32_e32 v46, 16, v47
	v_and_b32_e32 v47, 0xffff0000, v47
	v_lshlrev_b32_e32 v56, 16, v52
	v_and_b32_e32 v57, 0xffff0000, v52
	v_lshlrev_b32_e32 v52, 16, v53
	v_and_b32_e32 v53, 0xffff0000, v53
	v_pk_fma_f32 v[30:31], v[30:31], 0.5, v[44:45] op_sel_hi:[1,0,1]
	v_pk_fma_f32 v[28:29], v[28:29], 0.5, v[48:49] op_sel_hi:[1,0,1]
	v_pk_fma_f32 v[10:11], v[10:11], 0.5, v[54:55] op_sel_hi:[1,0,1]
	v_pk_fma_f32 v[8:9], v[8:9], 0.5, v[58:59] op_sel_hi:[1,0,1]
	v_lshlrev_b32_e32 v44, 16, v32
	v_and_b32_e32 v45, 0xffff0000, v32
	v_lshlrev_b32_e32 v32, 16, v33
	v_and_b32_e32 v33, 0xffff0000, v33
	v_pk_fma_f32 v[26:27], v[26:27], 0.5, v[46:47] op_sel_hi:[1,0,1]
	v_pk_fma_f32 v[24:25], v[24:25], 0.5, v[50:51] op_sel_hi:[1,0,1]
	v_pk_fma_f32 v[18:19], v[18:19], 0.5, v[52:53] op_sel_hi:[1,0,1]
	v_pk_fma_f32 v[16:17], v[16:17], 0.5, v[56:57] op_sel_hi:[1,0,1]
	v_lshlrev_b32_e32 v46, 16, v34
	v_and_b32_e32 v47, 0xffff0000, v34
	v_lshlrev_b32_e32 v34, 16, v35
	v_and_b32_e32 v35, 0xffff0000, v35
	v_lshlrev_b32_e32 v48, 16, v36
	v_and_b32_e32 v49, 0xffff0000, v36
	v_lshlrev_b32_e32 v36, 16, v37
	v_and_b32_e32 v37, 0xffff0000, v37
	v_lshlrev_b32_e32 v50, 16, v38
	v_and_b32_e32 v51, 0xffff0000, v38
	v_lshlrev_b32_e32 v38, 16, v39
	v_and_b32_e32 v39, 0xffff0000, v39
	global_store_dwordx4 v[40:41], v[28:31], off
	global_store_dwordx4 v[40:41], v[24:27], off offset:16
	global_store_dwordx4 v[40:41], v[16:19], off offset:512
	global_store_dwordx4 v[40:41], v[8:11], off offset:528
	v_pk_fma_f32 v[14:15], v[14:15], 0.5, v[34:35] op_sel_hi:[1,0,1]
	v_pk_fma_f32 v[12:13], v[12:13], 0.5, v[46:47] op_sel_hi:[1,0,1]
	v_pk_fma_f32 v[10:11], v[22:23], 0.5, v[32:33] op_sel_hi:[1,0,1]
	v_pk_fma_f32 v[8:9], v[20:21], 0.5, v[44:45] op_sel_hi:[1,0,1]
	v_pk_fma_f32 v[6:7], v[6:7], 0.5, v[36:37] op_sel_hi:[1,0,1]
	v_pk_fma_f32 v[4:5], v[4:5], 0.5, v[48:49] op_sel_hi:[1,0,1]
	v_pk_fma_f32 v[2:3], v[2:3], 0.5, v[38:39] op_sel_hi:[1,0,1]
	v_pk_fma_f32 v[0:1], v[0:1], 0.5, v[50:51] op_sel_hi:[1,0,1]
	global_store_dwordx4 v[42:43], v[8:11], off
	global_store_dwordx4 v[42:43], v[12:15], off offset:16
	global_store_dwordx4 v[42:43], v[4:7], off offset:512
	global_store_dwordx4 v[42:43], v[0:3], off offset:528
	s_cbranch_vccz .LBB0_2615
	s_waitcnt vmcnt(0)
	s_cmpk_gt_u32 s24, 0xff
	s_cbranch_scc1 .LBB0_2630
	s_barrier
